# peel + K-loop DMA addresses via SGPR base + 32-bit VGPR offset (saddr form) instead of VALU 64-bit adds in the load segments
# speedup vs baseline: 1.0262x; 1.0079x over previous
; template <class Epi, class Sched, bool ALIGN_EPI = false, bool SP2 = false, bool ATILED = false>
; __device__ __forceinline__ void gemm_phase(PG8_LAS unsigned char* lds, const Gemm g, const Sched& S, const Epi& E) {
;     ...
;         const bool has_next = S.next(ui + 1, nxt);
;         const char* nA = has_next ? (const char*)g.A + (size_t)nxt.pm * tstepA : cA; const char* nB = has_next ? (const char*)g.Bt + (size_t)nxt.pn * tstep : cB;
;         for (int t = 0; t < nt; t += 2) {
;             const bool last = (t == nt - 2);
;             const char* a1 = cA + (size_t)(t + 1) * kstepA;
;             const char* a2 = last ? nA : cA + (size_t)(t + 2) * kstepA; const char* b2 = last ? nB : cB + (size_t)(t + 2) * kstep;
;             const char* a3 = a2 + kstepA; const char* b3 = b2 + kstep;
.LBB0_132:
	s_ashr_i32 s43, s42, 31
	s_lshl_b64 s[44:45], s[42:43], 19
	s_add_u32 s44, s26, s44
	s_addc_u32 s45, s27, s45
	s_and_b64 s[46:47], s[0:1], exec
	s_cselect_b32 s43, s45, s61
	s_cselect_b32 s83, s44, s60
	s_ashr_i32 s41, s40, 31
	s_lshl_b64 s[46:47], s[40:41], 19
	s_add_u32 s46, s6, s46
	s_addc_u32 s47, s7, s47
	s_and_b64 s[64:65], s[0:1], exec
	s_cselect_b32 s41, s47, s63
	s_cselect_b32 s84, s46, s62
	s_add_u32 s60, s60, 0x40080
	s_addc_u32 s61, s61, 0
	s_add_u32 s85, s62, 0x100
	s_addc_u32 s86, s63, 0
	s_mov_b32 s87, -2
	ds_read_b128 v[150:153], v156
	ds_read_b128 v[162:165], v156 offset:1024
	ds_read_b128 v[166:169], v156 offset:2048
	ds_read_b128 v[170:173], v156 offset:3072
	ds_read_b128 v[174:177], v157
	ds_read_b128 v[178:181], v157 offset:1024
	ds_read_b128 v[182:185], v157 offset:2048
	ds_read_b128 v[186:189], v157 offset:3072
	s_add_u32 s62, s60, 0xfffc0080
	s_addc_u32 s63, s61, -1
	s_cmp_eq_u32 s87, 12
	s_cselect_b32 s65, s43, s63
	s_cselect_b32 s64, s83, s62
	s_cselect_b32 s63, s41, s86
	s_cselect_b32 s62, s84, s85

; #define PG8_STAGE(bufoff, gbase, voff) do { _Pragma("unroll") for (int _i = 0; _i < 2; ++_i) \
;         __builtin_amdgcn_global_load_lds((const unsigned*)((const char*)(gbase) + (voff)[_i]), (PG8_LAS unsigned*)(lds + (bufoff) + ldsw + _i * 8192), 16, 0, 0); } while (0)
; #define PG8_LDA(dst, b, h) do { _Pragma("unroll") for (int m = 0; m < 4; ++m) _Pragma("unroll") for (int k = 0; k < 2; ++k) dst[m][k] = *(const PG8_LAS bf16x8*)(lds + PG8_SA(b, h) + aoff + m * 2048 + k * 1024); } while (0)
; #define PG8_LDB(dst, b, h) do { _Pragma("unroll") for (int n = 0; n < 2; ++n) _Pragma("unroll") for (int k = 0; k < 2; ++k) dst[n][k] = *(const PG8_LAS bf16x8*)(lds + PG8_SB(b, h) + boff + n * 2048 + k * 1024); } while (0)
; #define PG8_SCHED __builtin_amdgcn_sched_barrier(0)
; template <class Epi, class Sched, bool ALIGN_EPI = false, bool SP2 = false, bool ATILED = false>
; __device__ __forceinline__ void gemm_phase(PG8_LAS unsigned char* lds, const Gemm g, const Sched& S, const Epi& E) {
;     ...
;             PG8_LDB(B0, 0, 0); PG8_LDB(B1, 0, 1); PG8_SCHED; PG8_LDA(At, 0, 0); PG8_STAGE(PG8_SA(1, 1), a1 + hstepA, voffA);
	s_add_i32 m0, s49, 0xc000
	ds_read_b128 v[190:193], v158
	ds_read_b128 v[194:197], v158 offset:1024
	ds_read_b128 v[200:203], v158 offset:2048
	ds_read_b128 v[204:207], v158 offset:3072
	ds_read_b128 v[208:211], v158 offset:4096
	ds_read_b128 v[212:215], v158 offset:5120
	ds_read_b128 v[216:219], v158 offset:6144
	ds_read_b128 v[220:223], v158 offset:7168
	global_load_lds_dwordx4 v140, s[60:61]

; #define PG8_STAGE(bufoff, gbase, voff) do { _Pragma("unroll") for (int _i = 0; _i < 2; ++_i) \
;         __builtin_amdgcn_global_load_lds((const unsigned*)((const char*)(gbase) + (voff)[_i]), (PG8_LAS unsigned*)(lds + (bufoff) + ldsw + _i * 8192), 16, 0, 0); } while (0)
; #define PG8_LDA(dst, b, h) do { _Pragma("unroll") for (int m = 0; m < 4; ++m) _Pragma("unroll") for (int k = 0; k < 2; ++k) dst[m][k] = *(const PG8_LAS bf16x8*)(lds + PG8_SA(b, h) + aoff + m * 2048 + k * 1024); } while (0)
; #define PG8_LDB(dst, b, h) do { _Pragma("unroll") for (int n = 0; n < 2; ++n) _Pragma("unroll") for (int k = 0; k < 2; ++k) dst[n][k] = *(const PG8_LAS bf16x8*)(lds + PG8_SB(b, h) + boff + n * 2048 + k * 1024); } while (0)
; #define PG8_MMA(ai, bj, At, Bt) do { __builtin_amdgcn_s_setprio(1); _Pragma("unroll") for (int m = 0; m < 4; ++m) _Pragma("unroll") for (int n = 0; n < 2; ++n) _Pragma("unroll") for (int k = 0; k < 2; ++k) \
;         acc[ai][bj][m][n] = __builtin_amdgcn_mfma_f32_16x16x32_bf16(Bt[n][k], At[m][k], acc[ai][bj][m][n], 0, 0, 0); __builtin_amdgcn_s_setprio(0); } while (0)
; #define PG8_WAIT_V(n) asm volatile("s_waitcnt vmcnt(" #n ")" ::: "memory")
; #define PG8_WAIT_L(n) asm volatile("s_waitcnt lgkmcnt(" #n ")" ::: "memory")
; #define PG8_BAR __builtin_amdgcn_s_barrier()
; #define PG8_SCHED __builtin_amdgcn_sched_barrier(0)
; template <class Epi, class Sched, bool ALIGN_EPI = false, bool SP2 = false, bool ATILED = false>
; __device__ __forceinline__ void gemm_phase(PG8_LAS unsigned char* lds, const Gemm g, const Sched& S, const Epi& E) {
;     ...
;             const char* a3 = a2 + kstepA; const char* b3 = b2 + kstep;
;     ...
;             PG8_LDB(B0, 0, 0); PG8_LDB(B1, 0, 1); PG8_SCHED; PG8_LDA(At, 0, 0); PG8_STAGE(PG8_SA(1, 1), a1 + hstepA, voffA);
;             PG8_WAIT_V(8); PG8_WAIT_L(0); PG8_BAR; PG8_MMA(0, 0, At, B0); PG8_MMA(0, 1, At, B1); PG8_BAR; PG8_SCHED;
;             PG8_LDA(At, 0, 1); PG8_STAGE(PG8_SB(0, 0), b2, voffB); PG8_STAGE(PG8_SB(0, 1), b2 + hstep, voffB); PG8_STAGE(PG8_SA(0, 0), a2, voffA);
	s_add_i32 m0, s49, 0xe000
	s_nop 0
	global_load_lds_dwordx4 v142, s[60:61]
	s_waitcnt vmcnt(8)
	s_waitcnt lgkmcnt(0)
	s_barrier
	s_setprio 1
	s_waitcnt lgkmcnt(0)
	v_mfma_f32_16x16x32_bf16 v[124:127], v[150:153], v[190:193], 0
	v_mfma_f32_16x16x32_bf16 v[120:123], v[166:169], v[190:193], 0
	v_mfma_f32_16x16x32_bf16 v[108:111], v[150:153], v[200:203], 0
	v_mfma_f32_16x16x32_bf16 v[104:107], v[166:169], v[200:203], 0
	v_mfma_f32_16x16x32_bf16 v[92:95], v[150:153], v[208:211], 0
	v_mfma_f32_16x16x32_bf16 v[88:91], v[166:169], v[208:211], 0
	v_mfma_f32_16x16x32_bf16 v[76:79], v[150:153], v[216:219], 0
	v_mfma_f32_16x16x32_bf16 v[72:75], v[166:169], v[216:219], 0
	v_mfma_f32_16x16x32_bf16 v[124:127], v[162:165], v[194:197], v[124:127]
	v_mfma_f32_16x16x32_bf16 v[120:123], v[170:173], v[194:197], v[120:123]
	v_mfma_f32_16x16x32_bf16 v[108:111], v[162:165], v[204:207], v[108:111]
	v_mfma_f32_16x16x32_bf16 v[104:107], v[170:173], v[204:207], v[104:107]
	v_mfma_f32_16x16x32_bf16 v[92:95], v[162:165], v[212:215], v[92:95]
	v_mfma_f32_16x16x32_bf16 v[88:91], v[170:173], v[212:215], v[88:91]
	v_mfma_f32_16x16x32_bf16 v[76:79], v[162:165], v[220:223], v[76:79]
	v_mfma_f32_16x16x32_bf16 v[72:75], v[170:173], v[220:223], v[72:75]
	s_setprio 0
	s_setprio 1
	v_mfma_f32_16x16x32_bf16 v[116:119], v[174:177], v[190:193], 0
	v_mfma_f32_16x16x32_bf16 v[112:115], v[182:185], v[190:193], 0
	v_mfma_f32_16x16x32_bf16 v[100:103], v[174:177], v[200:203], 0
	v_mfma_f32_16x16x32_bf16 v[96:99], v[182:185], v[200:203], 0
	v_mfma_f32_16x16x32_bf16 v[84:87], v[174:177], v[208:211], 0
	v_mfma_f32_16x16x32_bf16 v[80:83], v[182:185], v[208:211], 0
	v_mfma_f32_16x16x32_bf16 v[68:71], v[174:177], v[216:219], 0
	v_mfma_f32_16x16x32_bf16 v[64:67], v[182:185], v[216:219], 0
	v_mfma_f32_16x16x32_bf16 v[116:119], v[178:181], v[194:197], v[116:119]
	v_mfma_f32_16x16x32_bf16 v[112:115], v[186:189], v[194:197], v[112:115]
	v_mfma_f32_16x16x32_bf16 v[100:103], v[178:181], v[204:207], v[100:103]
	v_mfma_f32_16x16x32_bf16 v[96:99], v[186:189], v[204:207], v[96:99]
	v_mfma_f32_16x16x32_bf16 v[84:87], v[178:181], v[212:215], v[84:87]
	v_mfma_f32_16x16x32_bf16 v[80:83], v[186:189], v[212:215], v[80:83]
	v_mfma_f32_16x16x32_bf16 v[68:71], v[178:181], v[220:223], v[68:71]
	v_mfma_f32_16x16x32_bf16 v[64:67], v[186:189], v[220:223], v[64:67]
	s_setprio 0
	s_barrier
	s_add_u32 s98, s62, s8
	s_addc_u32 s99, s63, s9
	s_add_u32 s100, s64, s8
	s_addc_u32 s101, s65, s9
	s_add_i32 s88, s78, s66

; #define PG8_STAGE(bufoff, gbase, voff) do { _Pragma("unroll") for (int _i = 0; _i < 2; ++_i) \
;         __builtin_amdgcn_global_load_lds((const unsigned*)((const char*)(gbase) + (voff)[_i]), (PG8_LAS unsigned*)(lds + (bufoff) + ldsw + _i * 8192), 16, 0, 0); } while (0)
; #define PG8_LDA(dst, b, h) do { _Pragma("unroll") for (int m = 0; m < 4; ++m) _Pragma("unroll") for (int k = 0; k < 2; ++k) dst[m][k] = *(const PG8_LAS bf16x8*)(lds + PG8_SA(b, h) + aoff + m * 2048 + k * 1024); } while (0)
; template <class Epi, class Sched, bool ALIGN_EPI = false, bool SP2 = false, bool ATILED = false>
; __device__ __forceinline__ void gemm_phase(PG8_LAS unsigned char* lds, const Gemm g, const Sched& S, const Epi& E) {
;     ...
;             PG8_LDA(At, 0, 1); PG8_STAGE(PG8_SB(0, 0), b2, voffB); PG8_STAGE(PG8_SB(0, 1), b2 + hstep, voffB); PG8_STAGE(PG8_SA(0, 0), a2, voffA);
	s_mov_b32 m0, s88
	ds_read_b128 v[190:193], v158 offset:16384
	ds_read_b128 v[194:197], v158 offset:17408
	ds_read_b128 v[200:203], v158 offset:18432
	ds_read_b128 v[204:207], v158 offset:19456
	ds_read_b128 v[208:211], v158 offset:20480
	ds_read_b128 v[212:215], v158 offset:21504
	ds_read_b128 v[216:219], v158 offset:22528
	ds_read_b128 v[220:223], v158 offset:23552
	global_load_lds_dwordx4 v130, s[62:63]
	s_add_i32 m0, s88, 0x2000
	s_add_u32 s88, s62, 0x40000

; #define PG8_STAGE(bufoff, gbase, voff) do { _Pragma("unroll") for (int _i = 0; _i < 2; ++_i) \
;         __builtin_amdgcn_global_load_lds((const unsigned*)((const char*)(gbase) + (voff)[_i]), (PG8_LAS unsigned*)(lds + (bufoff) + ldsw + _i * 8192), 16, 0, 0); } while (0)
; #define PG8_LDA(dst, b, h) do { _Pragma("unroll") for (int m = 0; m < 4; ++m) _Pragma("unroll") for (int k = 0; k < 2; ++k) dst[m][k] = *(const PG8_LAS bf16x8*)(lds + PG8_SA(b, h) + aoff + m * 2048 + k * 1024); } while (0)
; template <class Epi, class Sched, bool ALIGN_EPI = false, bool SP2 = false, bool ATILED = false>
; __device__ __forceinline__ void gemm_phase(PG8_LAS unsigned char* lds, const Gemm g, const Sched& S, const Epi& E) {
;     ...
;             PG8_LDA(At, 0, 1); PG8_STAGE(PG8_SB(0, 0), b2, voffB); PG8_STAGE(PG8_SB(0, 1), b2 + hstep, voffB); PG8_STAGE(PG8_SA(0, 0), a2, voffA);
	s_addc_u32 s89, s63, 0
	s_add_i32 s90, s79, s66
	global_load_lds_dwordx4 v134, s[62:63]

; #define PG8_STAGE(bufoff, gbase, voff) do { _Pragma("unroll") for (int _i = 0; _i < 2; ++_i) \
;         __builtin_amdgcn_global_load_lds((const unsigned*)((const char*)(gbase) + (voff)[_i]), (PG8_LAS unsigned*)(lds + (bufoff) + ldsw + _i * 8192), 16, 0, 0); } while (0)
; #define PG8_LDA(dst, b, h) do { _Pragma("unroll") for (int m = 0; m < 4; ++m) _Pragma("unroll") for (int k = 0; k < 2; ++k) dst[m][k] = *(const PG8_LAS bf16x8*)(lds + PG8_SA(b, h) + aoff + m * 2048 + k * 1024); } while (0)
; template <class Epi, class Sched, bool ALIGN_EPI = false, bool SP2 = false, bool ATILED = false>
; __device__ __forceinline__ void gemm_phase(PG8_LAS unsigned char* lds, const Gemm g, const Sched& S, const Epi& E) {
;     ...
;             PG8_LDA(At, 0, 1); PG8_STAGE(PG8_SB(0, 0), b2, voffB); PG8_STAGE(PG8_SB(0, 1), b2 + hstep, voffB); PG8_STAGE(PG8_SA(0, 0), a2, voffA);
	s_mov_b32 m0, s90

; #define PG8_STAGE(bufoff, gbase, voff) do { _Pragma("unroll") for (int _i = 0; _i < 2; ++_i) \
;         __builtin_amdgcn_global_load_lds((const unsigned*)((const char*)(gbase) + (voff)[_i]), (PG8_LAS unsigned*)(lds + (bufoff) + ldsw + _i * 8192), 16, 0, 0); } while (0)
; #define PG8_LDA(dst, b, h) do { _Pragma("unroll") for (int m = 0; m < 4; ++m) _Pragma("unroll") for (int k = 0; k < 2; ++k) dst[m][k] = *(const PG8_LAS bf16x8*)(lds + PG8_SA(b, h) + aoff + m * 2048 + k * 1024); } while (0)
; template <class Epi, class Sched, bool ALIGN_EPI = false, bool SP2 = false, bool ATILED = false>
; __device__ __forceinline__ void gemm_phase(PG8_LAS unsigned char* lds, const Gemm g, const Sched& S, const Epi& E) {
;     ...
;             PG8_LDA(At, 0, 1); PG8_STAGE(PG8_SB(0, 0), b2, voffB); PG8_STAGE(PG8_SB(0, 1), b2 + hstep, voffB); PG8_STAGE(PG8_SA(0, 0), a2, voffA);
	s_nop 0
	global_load_lds_dwordx4 v130, s[88:89]

; #define PG8_STAGE(bufoff, gbase, voff) do { _Pragma("unroll") for (int _i = 0; _i < 2; ++_i) \
;         __builtin_amdgcn_global_load_lds((const unsigned*)((const char*)(gbase) + (voff)[_i]), (PG8_LAS unsigned*)(lds + (bufoff) + ldsw + _i * 8192), 16, 0, 0); } while (0)
; #define PG8_LDA(dst, b, h) do { _Pragma("unroll") for (int m = 0; m < 4; ++m) _Pragma("unroll") for (int k = 0; k < 2; ++k) dst[m][k] = *(const PG8_LAS bf16x8*)(lds + PG8_SA(b, h) + aoff + m * 2048 + k * 1024); } while (0)
; template <class Epi, class Sched, bool ALIGN_EPI = false, bool SP2 = false, bool ATILED = false>
; __device__ __forceinline__ void gemm_phase(PG8_LAS unsigned char* lds, const Gemm g, const Sched& S, const Epi& E) {
;     ...
;             PG8_LDA(At, 0, 1); PG8_STAGE(PG8_SB(0, 0), b2, voffB); PG8_STAGE(PG8_SB(0, 1), b2 + hstep, voffB); PG8_STAGE(PG8_SA(0, 0), a2, voffA);
	s_add_i32 m0, s90, 0x2000
	s_nop 0
	global_load_lds_dwordx4 v134, s[88:89]

; #define PG8_STAGE(bufoff, gbase, voff) do { _Pragma("unroll") for (int _i = 0; _i < 2; ++_i) \
;         __builtin_amdgcn_global_load_lds((const unsigned*)((const char*)(gbase) + (voff)[_i]), (PG8_LAS unsigned*)(lds + (bufoff) + ldsw + _i * 8192), 16, 0, 0); } while (0)
; #define PG8_LDA(dst, b, h) do { _Pragma("unroll") for (int m = 0; m < 4; ++m) _Pragma("unroll") for (int k = 0; k < 2; ++k) dst[m][k] = *(const PG8_LAS bf16x8*)(lds + PG8_SA(b, h) + aoff + m * 2048 + k * 1024); } while (0)
; #define PG8_LDB(dst, b, h) do { _Pragma("unroll") for (int n = 0; n < 2; ++n) _Pragma("unroll") for (int k = 0; k < 2; ++k) dst[n][k] = *(const PG8_LAS bf16x8*)(lds + PG8_SB(b, h) + boff + n * 2048 + k * 1024); } while (0)
; #define PG8_MMA(ai, bj, At, Bt) do { __builtin_amdgcn_s_setprio(1); _Pragma("unroll") for (int m = 0; m < 4; ++m) _Pragma("unroll") for (int n = 0; n < 2; ++n) _Pragma("unroll") for (int k = 0; k < 2; ++k) \
;         acc[ai][bj][m][n] = __builtin_amdgcn_mfma_f32_16x16x32_bf16(Bt[n][k], At[m][k], acc[ai][bj][m][n], 0, 0, 0); __builtin_amdgcn_s_setprio(0); } while (0)
; #define PG8_WAIT_V(n) asm volatile("s_waitcnt vmcnt(" #n ")" ::: "memory")
; #define PG8_WAIT_L(n) asm volatile("s_waitcnt lgkmcnt(" #n ")" ::: "memory")
; #define PG8_BAR __builtin_amdgcn_s_barrier()
; #define PG8_SCHED __builtin_amdgcn_sched_barrier(0)
; template <class Epi, class Sched, bool ALIGN_EPI = false, bool SP2 = false, bool ATILED = false>
; __device__ __forceinline__ void gemm_phase(PG8_LAS unsigned char* lds, const Gemm g, const Sched& S, const Epi& E) {
;     ...
;             PG8_LDA(At, 0, 1); PG8_STAGE(PG8_SB(0, 0), b2, voffB); PG8_STAGE(PG8_SB(0, 1), b2 + hstep, voffB); PG8_STAGE(PG8_SA(0, 0), a2, voffA);
;             PG8_WAIT_V(8); PG8_WAIT_L(0); PG8_BAR; PG8_MMA(1, 0, At, B0); PG8_MMA(1, 1, At, B1); PG8_BAR; PG8_SCHED;
;             PG8_LDB(B0, 1, 0); PG8_LDB(B1, 1, 1); PG8_SCHED; PG8_LDA(At, 1, 0); PG8_STAGE(PG8_SA(0, 1), a2 + hstepA, voffA);
	s_mov_b32 m0, s49
	s_nop 0
	global_load_lds_dwordx4 v128, s[64:65]
	s_mov_b32 m0, s68
	s_nop 0
	global_load_lds_dwordx4 v132, s[64:65]
	s_waitcnt vmcnt(8)
	s_waitcnt lgkmcnt(0)
	s_barrier
	s_setprio 1
	s_waitcnt lgkmcnt(0)
	v_mfma_f32_16x16x32_bf16 v[60:63], v[150:153], v[190:193], 0
	v_mfma_f32_16x16x32_bf16 v[56:59], v[166:169], v[190:193], 0
	v_mfma_f32_16x16x32_bf16 v[44:47], v[150:153], v[200:203], 0
	v_mfma_f32_16x16x32_bf16 v[40:43], v[166:169], v[200:203], 0
	v_mfma_f32_16x16x32_bf16 v[28:31], v[150:153], v[208:211], 0
	v_mfma_f32_16x16x32_bf16 v[24:27], v[166:169], v[208:211], 0
	v_mfma_f32_16x16x32_bf16 v[12:15], v[150:153], v[216:219], 0
	v_mfma_f32_16x16x32_bf16 v[8:11], v[166:169], v[216:219], 0
	v_mfma_f32_16x16x32_bf16 v[60:63], v[162:165], v[194:197], v[60:63]
	v_mfma_f32_16x16x32_bf16 v[56:59], v[170:173], v[194:197], v[56:59]
	v_mfma_f32_16x16x32_bf16 v[44:47], v[162:165], v[204:207], v[44:47]
	v_mfma_f32_16x16x32_bf16 v[40:43], v[170:173], v[204:207], v[40:43]
	v_mfma_f32_16x16x32_bf16 v[28:31], v[162:165], v[212:215], v[28:31]
	v_mfma_f32_16x16x32_bf16 v[24:27], v[170:173], v[212:215], v[24:27]
	v_mfma_f32_16x16x32_bf16 v[12:15], v[162:165], v[220:223], v[12:15]
	v_mfma_f32_16x16x32_bf16 v[8:11], v[170:173], v[220:223], v[8:11]
	s_setprio 0
	s_setprio 1
	v_mfma_f32_16x16x32_bf16 v[52:55], v[174:177], v[190:193], 0
	v_mfma_f32_16x16x32_bf16 v[48:51], v[182:185], v[190:193], 0
	v_mfma_f32_16x16x32_bf16 v[36:39], v[174:177], v[200:203], 0
	v_mfma_f32_16x16x32_bf16 v[32:35], v[182:185], v[200:203], 0
	v_mfma_f32_16x16x32_bf16 v[20:23], v[174:177], v[208:211], 0
	v_mfma_f32_16x16x32_bf16 v[16:19], v[182:185], v[208:211], 0
	v_mfma_f32_16x16x32_bf16 v[4:7], v[174:177], v[216:219], 0
	v_mfma_f32_16x16x32_bf16 v[0:3], v[182:185], v[216:219], 0
	v_mfma_f32_16x16x32_bf16 v[52:55], v[178:181], v[194:197], v[52:55]
	v_mfma_f32_16x16x32_bf16 v[48:51], v[186:189], v[194:197], v[48:51]
	v_mfma_f32_16x16x32_bf16 v[36:39], v[178:181], v[204:207], v[36:39]
	v_mfma_f32_16x16x32_bf16 v[32:35], v[186:189], v[204:207], v[32:35]
	v_mfma_f32_16x16x32_bf16 v[20:23], v[178:181], v[212:215], v[20:23]
	v_mfma_f32_16x16x32_bf16 v[16:19], v[186:189], v[212:215], v[16:19]
	v_mfma_f32_16x16x32_bf16 v[4:7], v[178:181], v[220:223], v[4:7]
	v_mfma_f32_16x16x32_bf16 v[0:3], v[186:189], v[220:223], v[0:3]
	s_setprio 0
	s_barrier
	s_add_i32 s88, 0, 0x18000
	v_add_u32_e32 v136, s88, v155
	s_add_i32 s89, 0, 0x1c000
	ds_read_b128 v[150:153], v136
	ds_read_b128 v[162:165], v136 offset:1024
	ds_read_b128 v[166:169], v136 offset:2048
	ds_read_b128 v[170:173], v136 offset:3072
	v_add_u32_e32 v136, s89, v155
	ds_read_b128 v[174:177], v136
	ds_read_b128 v[178:181], v136 offset:1024
	ds_read_b128 v[182:185], v136 offset:2048
	ds_read_b128 v[186:189], v136 offset:3072
	s_add_u32 s64, s64, 0x40000
	s_addc_u32 s65, s65, 0
	s_mov_b32 m0, s69

; #define PG8_STAGE(bufoff, gbase, voff) do { _Pragma("unroll") for (int _i = 0; _i < 2; ++_i) \
;         __builtin_amdgcn_global_load_lds((const unsigned*)((const char*)(gbase) + (voff)[_i]), (PG8_LAS unsigned*)(lds + (bufoff) + ldsw + _i * 8192), 16, 0, 0); } while (0)
; #define PG8_LDA(dst, b, h) do { _Pragma("unroll") for (int m = 0; m < 4; ++m) _Pragma("unroll") for (int k = 0; k < 2; ++k) dst[m][k] = *(const PG8_LAS bf16x8*)(lds + PG8_SA(b, h) + aoff + m * 2048 + k * 1024); } while (0)
; #define PG8_LDB(dst, b, h) do { _Pragma("unroll") for (int n = 0; n < 2; ++n) _Pragma("unroll") for (int k = 0; k < 2; ++k) dst[n][k] = *(const PG8_LAS bf16x8*)(lds + PG8_SB(b, h) + boff + n * 2048 + k * 1024); } while (0)
; #define PG8_SCHED __builtin_amdgcn_sched_barrier(0)
; template <class Epi, class Sched, bool ALIGN_EPI = false, bool SP2 = false, bool ATILED = false>
; __device__ __forceinline__ void gemm_phase(PG8_LAS unsigned char* lds, const Gemm g, const Sched& S, const Epi& E) {
;     ...
;             PG8_LDB(B0, 1, 0); PG8_LDB(B1, 1, 1); PG8_SCHED; PG8_LDA(At, 1, 0); PG8_STAGE(PG8_SA(0, 1), a2 + hstepA, voffA);
	ds_read_b128 v[190:193], v158 offset:32768
	ds_read_b128 v[194:197], v158 offset:33792
	ds_read_b128 v[200:203], v158 offset:34816
	ds_read_b128 v[204:207], v158 offset:35840
	ds_read_b128 v[208:211], v158 offset:36864
	ds_read_b128 v[212:215], v158 offset:37888
	ds_read_b128 v[216:219], v158 offset:38912
	ds_read_b128 v[220:223], v158 offset:39936
	global_load_lds_dwordx4 v128, s[64:65]

; #define PG8_STAGE(bufoff, gbase, voff) do { _Pragma("unroll") for (int _i = 0; _i < 2; ++_i) \
;         __builtin_amdgcn_global_load_lds((const unsigned*)((const char*)(gbase) + (voff)[_i]), (PG8_LAS unsigned*)(lds + (bufoff) + ldsw + _i * 8192), 16, 0, 0); } while (0)
; #define PG8_LDA(dst, b, h) do { _Pragma("unroll") for (int m = 0; m < 4; ++m) _Pragma("unroll") for (int k = 0; k < 2; ++k) dst[m][k] = *(const PG8_LAS bf16x8*)(lds + PG8_SA(b, h) + aoff + m * 2048 + k * 1024); } while (0)
; #define PG8_LDB(dst, b, h) do { _Pragma("unroll") for (int n = 0; n < 2; ++n) _Pragma("unroll") for (int k = 0; k < 2; ++k) dst[n][k] = *(const PG8_LAS bf16x8*)(lds + PG8_SB(b, h) + boff + n * 2048 + k * 1024); } while (0)
; #define PG8_MMA(ai, bj, At, Bt) do { __builtin_amdgcn_s_setprio(1); _Pragma("unroll") for (int m = 0; m < 4; ++m) _Pragma("unroll") for (int n = 0; n < 2; ++n) _Pragma("unroll") for (int k = 0; k < 2; ++k) \
;         acc[ai][bj][m][n] = __builtin_amdgcn_mfma_f32_16x16x32_bf16(Bt[n][k], At[m][k], acc[ai][bj][m][n], 0, 0, 0); __builtin_amdgcn_s_setprio(0); } while (0)
; #define PG8_WAIT_V(n) asm volatile("s_waitcnt vmcnt(" #n ")" ::: "memory")
; #define PG8_WAIT_L(n) asm volatile("s_waitcnt lgkmcnt(" #n ")" ::: "memory")
; #define PG8_BAR __builtin_amdgcn_s_barrier()
; #define PG8_SCHED __builtin_amdgcn_sched_barrier(0)
; template <class Epi, class Sched, bool ALIGN_EPI = false, bool SP2 = false, bool ATILED = false>
; __device__ __forceinline__ void gemm_phase(PG8_LAS unsigned char* lds, const Gemm g, const Sched& S, const Epi& E) {
;     ...
;             PG8_LDB(B0, 1, 0); PG8_LDB(B1, 1, 1); PG8_SCHED; PG8_LDA(At, 1, 0); PG8_STAGE(PG8_SA(0, 1), a2 + hstepA, voffA);
;             PG8_WAIT_V(8); PG8_WAIT_L(0); PG8_BAR; PG8_MMA(0, 0, At, B0); PG8_MMA(0, 1, At, B1); PG8_BAR; PG8_SCHED;
;             PG8_LDA(At, 1, 1); PG8_STAGE(PG8_SB(1, 0), b3, voffB); PG8_STAGE(PG8_SB(1, 1), b3 + hstep, voffB); PG8_STAGE(PG8_SA(1, 0), a3, voffA);
	s_mov_b32 m0, s70
	s_nop 0
	global_load_lds_dwordx4 v132, s[64:65]
	s_waitcnt vmcnt(8)
	s_waitcnt lgkmcnt(0)
	s_barrier
	s_setprio 1
	s_waitcnt lgkmcnt(0)
	v_mfma_f32_16x16x32_bf16 v[124:127], v[150:153], v[190:193], v[124:127]
	v_mfma_f32_16x16x32_bf16 v[120:123], v[166:169], v[190:193], v[120:123]
	v_mfma_f32_16x16x32_bf16 v[108:111], v[150:153], v[200:203], v[108:111]
	v_mfma_f32_16x16x32_bf16 v[104:107], v[166:169], v[200:203], v[104:107]
	v_mfma_f32_16x16x32_bf16 v[92:95], v[150:153], v[208:211], v[92:95]
	v_mfma_f32_16x16x32_bf16 v[88:91], v[166:169], v[208:211], v[88:91]
	v_mfma_f32_16x16x32_bf16 v[76:79], v[150:153], v[216:219], v[76:79]
	v_mfma_f32_16x16x32_bf16 v[72:75], v[166:169], v[216:219], v[72:75]
	v_mfma_f32_16x16x32_bf16 v[124:127], v[162:165], v[194:197], v[124:127]
	v_mfma_f32_16x16x32_bf16 v[120:123], v[170:173], v[194:197], v[120:123]
	v_mfma_f32_16x16x32_bf16 v[108:111], v[162:165], v[204:207], v[108:111]
	v_mfma_f32_16x16x32_bf16 v[104:107], v[170:173], v[204:207], v[104:107]
	v_mfma_f32_16x16x32_bf16 v[92:95], v[162:165], v[212:215], v[92:95]
	v_mfma_f32_16x16x32_bf16 v[88:91], v[170:173], v[212:215], v[88:91]
	v_mfma_f32_16x16x32_bf16 v[76:79], v[162:165], v[220:223], v[76:79]
	v_mfma_f32_16x16x32_bf16 v[72:75], v[170:173], v[220:223], v[72:75]
	s_setprio 0
	s_setprio 1
	v_mfma_f32_16x16x32_bf16 v[116:119], v[174:177], v[190:193], v[116:119]
	v_mfma_f32_16x16x32_bf16 v[112:115], v[182:185], v[190:193], v[112:115]
	v_mfma_f32_16x16x32_bf16 v[100:103], v[174:177], v[200:203], v[100:103]
	v_mfma_f32_16x16x32_bf16 v[96:99], v[182:185], v[200:203], v[96:99]
	v_mfma_f32_16x16x32_bf16 v[84:87], v[174:177], v[208:211], v[84:87]
	v_mfma_f32_16x16x32_bf16 v[80:83], v[182:185], v[208:211], v[80:83]
	v_mfma_f32_16x16x32_bf16 v[68:71], v[174:177], v[216:219], v[68:71]
	v_mfma_f32_16x16x32_bf16 v[64:67], v[182:185], v[216:219], v[64:67]
	v_mfma_f32_16x16x32_bf16 v[116:119], v[178:181], v[194:197], v[116:119]
	v_mfma_f32_16x16x32_bf16 v[112:115], v[186:189], v[194:197], v[112:115]
	v_mfma_f32_16x16x32_bf16 v[100:103], v[178:181], v[204:207], v[100:103]
	v_mfma_f32_16x16x32_bf16 v[96:99], v[186:189], v[204:207], v[96:99]
	v_mfma_f32_16x16x32_bf16 v[84:87], v[178:181], v[212:215], v[84:87]
	v_mfma_f32_16x16x32_bf16 v[80:83], v[186:189], v[212:215], v[80:83]
	v_mfma_f32_16x16x32_bf16 v[68:71], v[178:181], v[220:223], v[68:71]
	v_mfma_f32_16x16x32_bf16 v[64:67], v[186:189], v[220:223], v[64:67]
	s_setprio 0
	s_barrier
	s_add_i32 s64, s88, s66

; #define PG8_STAGE(bufoff, gbase, voff) do { _Pragma("unroll") for (int _i = 0; _i < 2; ++_i) \
;         __builtin_amdgcn_global_load_lds((const unsigned*)((const char*)(gbase) + (voff)[_i]), (PG8_LAS unsigned*)(lds + (bufoff) + ldsw + _i * 8192), 16, 0, 0); } while (0)
; #define PG8_LDA(dst, b, h) do { _Pragma("unroll") for (int m = 0; m < 4; ++m) _Pragma("unroll") for (int k = 0; k < 2; ++k) dst[m][k] = *(const PG8_LAS bf16x8*)(lds + PG8_SA(b, h) + aoff + m * 2048 + k * 1024); } while (0)
; template <class Epi, class Sched, bool ALIGN_EPI = false, bool SP2 = false, bool ATILED = false>
; __device__ __forceinline__ void gemm_phase(PG8_LAS unsigned char* lds, const Gemm g, const Sched& S, const Epi& E) {
;     ...
;             PG8_LDA(At, 1, 1); PG8_STAGE(PG8_SB(1, 0), b3, voffB); PG8_STAGE(PG8_SB(1, 1), b3 + hstep, voffB); PG8_STAGE(PG8_SA(1, 0), a3, voffA);
	s_mov_b32 m0, s64
	ds_read_b128 v[190:193], v158 offset:49152
	ds_read_b128 v[194:197], v158 offset:50176
	ds_read_b128 v[200:203], v158 offset:51200
	ds_read_b128 v[204:207], v158 offset:52224
	ds_read_b128 v[208:211], v158 offset:53248
	ds_read_b128 v[212:215], v158 offset:54272
	ds_read_b128 v[216:219], v158 offset:55296
	ds_read_b128 v[220:223], v158 offset:56320
	global_load_lds_dwordx4 v130, s[98:99]
	s_add_i32 m0, s64, 0x2000
	s_add_u32 s62, s62, 0x40080

; #define PG8_STAGE(bufoff, gbase, voff) do { _Pragma("unroll") for (int _i = 0; _i < 2; ++_i) \
;         __builtin_amdgcn_global_load_lds((const unsigned*)((const char*)(gbase) + (voff)[_i]), (PG8_LAS unsigned*)(lds + (bufoff) + ldsw + _i * 8192), 16, 0, 0); } while (0)
; #define PG8_LDA(dst, b, h) do { _Pragma("unroll") for (int m = 0; m < 4; ++m) _Pragma("unroll") for (int k = 0; k < 2; ++k) dst[m][k] = *(const PG8_LAS bf16x8*)(lds + PG8_SA(b, h) + aoff + m * 2048 + k * 1024); } while (0)
; template <class Epi, class Sched, bool ALIGN_EPI = false, bool SP2 = false, bool ATILED = false>
; __device__ __forceinline__ void gemm_phase(PG8_LAS unsigned char* lds, const Gemm g, const Sched& S, const Epi& E) {
;     ...
;             PG8_LDA(At, 1, 1); PG8_STAGE(PG8_SB(1, 0), b3, voffB); PG8_STAGE(PG8_SB(1, 1), b3 + hstep, voffB); PG8_STAGE(PG8_SA(1, 0), a3, voffA);
	s_addc_u32 s63, s63, 0
	s_add_i32 s64, s89, s66
	global_load_lds_dwordx4 v134, s[98:99]

; #define PG8_STAGE(bufoff, gbase, voff) do { _Pragma("unroll") for (int _i = 0; _i < 2; ++_i) \
;         __builtin_amdgcn_global_load_lds((const unsigned*)((const char*)(gbase) + (voff)[_i]), (PG8_LAS unsigned*)(lds + (bufoff) + ldsw + _i * 8192), 16, 0, 0); } while (0)
; #define PG8_LDA(dst, b, h) do { _Pragma("unroll") for (int m = 0; m < 4; ++m) _Pragma("unroll") for (int k = 0; k < 2; ++k) dst[m][k] = *(const PG8_LAS bf16x8*)(lds + PG8_SA(b, h) + aoff + m * 2048 + k * 1024); } while (0)
; template <class Epi, class Sched, bool ALIGN_EPI = false, bool SP2 = false, bool ATILED = false>
; __device__ __forceinline__ void gemm_phase(PG8_LAS unsigned char* lds, const Gemm g, const Sched& S, const Epi& E) {
;     ...
;             PG8_LDA(At, 1, 1); PG8_STAGE(PG8_SB(1, 0), b3, voffB); PG8_STAGE(PG8_SB(1, 1), b3 + hstep, voffB); PG8_STAGE(PG8_SA(1, 0), a3, voffA);
	s_mov_b32 m0, s64
	s_nop 0
	global_load_lds_dwordx4 v130, s[62:63]

; #define PG8_STAGE(bufoff, gbase, voff) do { _Pragma("unroll") for (int _i = 0; _i < 2; ++_i) \
;         __builtin_amdgcn_global_load_lds((const unsigned*)((const char*)(gbase) + (voff)[_i]), (PG8_LAS unsigned*)(lds + (bufoff) + ldsw + _i * 8192), 16, 0, 0); } while (0)
; #define PG8_LDA(dst, b, h) do { _Pragma("unroll") for (int m = 0; m < 4; ++m) _Pragma("unroll") for (int k = 0; k < 2; ++k) dst[m][k] = *(const PG8_LAS bf16x8*)(lds + PG8_SA(b, h) + aoff + m * 2048 + k * 1024); } while (0)
; template <class Epi, class Sched, bool ALIGN_EPI = false, bool SP2 = false, bool ATILED = false>
; __device__ __forceinline__ void gemm_phase(PG8_LAS unsigned char* lds, const Gemm g, const Sched& S, const Epi& E) {
;     ...
;             PG8_LDA(At, 1, 1); PG8_STAGE(PG8_SB(1, 0), b3, voffB); PG8_STAGE(PG8_SB(1, 1), b3 + hstep, voffB); PG8_STAGE(PG8_SA(1, 0), a3, voffA);
	s_add_i32 m0, s64, 0x2000
	s_nop 0
	global_load_lds_dwordx4 v134, s[62:63]

; #define PG8_STAGE(bufoff, gbase, voff) do { _Pragma("unroll") for (int _i = 0; _i < 2; ++_i) \
;         __builtin_amdgcn_global_load_lds((const unsigned*)((const char*)(gbase) + (voff)[_i]), (PG8_LAS unsigned*)(lds + (bufoff) + ldsw + _i * 8192), 16, 0, 0); } while (0)
; #define PG8_LDA(dst, b, h) do { _Pragma("unroll") for (int m = 0; m < 4; ++m) _Pragma("unroll") for (int k = 0; k < 2; ++k) dst[m][k] = *(const PG8_LAS bf16x8*)(lds + PG8_SA(b, h) + aoff + m * 2048 + k * 1024); } while (0)
; template <class Epi, class Sched, bool ALIGN_EPI = false, bool SP2 = false, bool ATILED = false>
; __device__ __forceinline__ void gemm_phase(PG8_LAS unsigned char* lds, const Gemm g, const Sched& S, const Epi& E) {
;     ...
;             PG8_LDA(At, 1, 1); PG8_STAGE(PG8_SB(1, 0), b3, voffB); PG8_STAGE(PG8_SB(1, 1), b3 + hstep, voffB); PG8_STAGE(PG8_SA(1, 0), a3, voffA);
	s_mov_b32 m0, s76
	s_nop 0
	global_load_lds_dwordx4 v128, s[100:101]

; #define PG8_STAGE(bufoff, gbase, voff) do { _Pragma("unroll") for (int _i = 0; _i < 2; ++_i) \
;         __builtin_amdgcn_global_load_lds((const unsigned*)((const char*)(gbase) + (voff)[_i]), (PG8_LAS unsigned*)(lds + (bufoff) + ldsw + _i * 8192), 16, 0, 0); } while (0)
; #define PG8_LDA(dst, b, h) do { _Pragma("unroll") for (int m = 0; m < 4; ++m) _Pragma("unroll") for (int k = 0; k < 2; ++k) dst[m][k] = *(const PG8_LAS bf16x8*)(lds + PG8_SA(b, h) + aoff + m * 2048 + k * 1024); } while (0)
; #define PG8_LDB(dst, b, h) do { _Pragma("unroll") for (int n = 0; n < 2; ++n) _Pragma("unroll") for (int k = 0; k < 2; ++k) dst[n][k] = *(const PG8_LAS bf16x8*)(lds + PG8_SB(b, h) + boff + n * 2048 + k * 1024); } while (0)
; #define PG8_BAR __builtin_amdgcn_s_barrier()
; template <class Epi, class Sched, bool ALIGN_EPI = false, bool SP2 = false, bool ATILED = false>
; __device__ __forceinline__ void gemm_phase(PG8_LAS unsigned char* lds, const Gemm g, const Sched& S, const Epi& E) {
;     ...
;             const char* a1 = cA + (size_t)(t + 1) * kstepA;
;             const char* a2 = last ? nA : cA + (size_t)(t + 2) * kstepA; const char* b2 = last ? nB : cB + (size_t)(t + 2) * kstep;
;             const char* a3 = a2 + kstepA; const char* b3 = b2 + kstep;
;             if (last && has_next) S.a_ready(nxt);
;             if constexpr (SP2) {
;             PG8_LDB(B0, 0, 0); PG8_LDB(B1, 0, 1); PG8_SCHED; PG8_LDA(At, 0, 0); PG8_STAGE(PG8_SA(1, 1), a1 + hstepA, voffA);
;             PG8_WAIT_V(8); PG8_WAIT_L(0); PG8_BAR; PG8_MMA(0, 0, At, B0); PG8_MMA(0, 1, At, B1); PG8_BAR; PG8_SCHED;
;             PG8_LDA(At, 0, 1); PG8_STAGE(PG8_SB(0, 0), b2, voffB); PG8_STAGE(PG8_SB(0, 1), b2 + hstep, voffB); PG8_STAGE(PG8_SA(0, 0), a2, voffA);
;             PG8_WAIT_V(8); PG8_WAIT_L(0); PG8_BAR; PG8_MMA(1, 0, At, B0); PG8_MMA(1, 1, At, B1); PG8_BAR; PG8_SCHED;
;             PG8_LDB(B0, 1, 0); PG8_LDB(B1, 1, 1); PG8_SCHED; PG8_LDA(At, 1, 0); PG8_STAGE(PG8_SA(0, 1), a2 + hstepA, voffA);
;             PG8_WAIT_V(8); PG8_WAIT_L(0); PG8_BAR; PG8_MMA(0, 0, At, B0); PG8_MMA(0, 1, At, B1); PG8_BAR; PG8_SCHED;
;             PG8_LDA(At, 1, 1); PG8_STAGE(PG8_SB(1, 0), b3, voffB); PG8_STAGE(PG8_SB(1, 1), b3 + hstep, voffB); PG8_STAGE(PG8_SA(1, 0), a3, voffA);
;             PG8_WAIT_V(8); PG8_WAIT_L(0); PG8_BAR; PG8_MMA(1, 0, At, B0); PG8_MMA(1, 1, At, B1); PG8_BAR; PG8_SCHED;
	s_mov_b32 m0, s77
	s_nop 0
	global_load_lds_dwordx4 v132, s[100:101]
	s_waitcnt vmcnt(8)
	s_waitcnt lgkmcnt(0)
	s_barrier
	s_setprio 1
	s_waitcnt lgkmcnt(0)
	v_mfma_f32_16x16x32_bf16 v[60:63], v[150:153], v[190:193], v[60:63]
	v_mfma_f32_16x16x32_bf16 v[56:59], v[166:169], v[190:193], v[56:59]
	v_mfma_f32_16x16x32_bf16 v[44:47], v[150:153], v[200:203], v[44:47]
	v_mfma_f32_16x16x32_bf16 v[40:43], v[166:169], v[200:203], v[40:43]
	v_mfma_f32_16x16x32_bf16 v[28:31], v[150:153], v[208:211], v[28:31]
	v_mfma_f32_16x16x32_bf16 v[24:27], v[166:169], v[208:211], v[24:27]
	v_mfma_f32_16x16x32_bf16 v[12:15], v[150:153], v[216:219], v[12:15]
	v_mfma_f32_16x16x32_bf16 v[8:11], v[166:169], v[216:219], v[8:11]
	v_mfma_f32_16x16x32_bf16 v[60:63], v[162:165], v[194:197], v[60:63]
	v_mfma_f32_16x16x32_bf16 v[56:59], v[170:173], v[194:197], v[56:59]
	v_mfma_f32_16x16x32_bf16 v[44:47], v[162:165], v[204:207], v[44:47]
	v_mfma_f32_16x16x32_bf16 v[40:43], v[170:173], v[204:207], v[40:43]
	v_mfma_f32_16x16x32_bf16 v[28:31], v[162:165], v[212:215], v[28:31]
	v_mfma_f32_16x16x32_bf16 v[24:27], v[170:173], v[212:215], v[24:27]
	v_mfma_f32_16x16x32_bf16 v[12:15], v[162:165], v[220:223], v[12:15]
	v_mfma_f32_16x16x32_bf16 v[8:11], v[170:173], v[220:223], v[8:11]
	s_setprio 0
	s_setprio 1
	v_mfma_f32_16x16x32_bf16 v[52:55], v[174:177], v[190:193], v[52:55]
	v_mfma_f32_16x16x32_bf16 v[48:51], v[182:185], v[190:193], v[48:51]
	v_mfma_f32_16x16x32_bf16 v[36:39], v[174:177], v[200:203], v[36:39]
	v_mfma_f32_16x16x32_bf16 v[32:35], v[182:185], v[200:203], v[32:35]
	v_mfma_f32_16x16x32_bf16 v[20:23], v[174:177], v[208:211], v[20:23]
	v_mfma_f32_16x16x32_bf16 v[16:19], v[182:185], v[208:211], v[16:19]
	v_mfma_f32_16x16x32_bf16 v[4:7], v[174:177], v[216:219], v[4:7]
	v_mfma_f32_16x16x32_bf16 v[0:3], v[182:185], v[216:219], v[0:3]
	v_mfma_f32_16x16x32_bf16 v[52:55], v[178:181], v[194:197], v[52:55]
	v_mfma_f32_16x16x32_bf16 v[48:51], v[186:189], v[194:197], v[48:51]
	v_mfma_f32_16x16x32_bf16 v[36:39], v[178:181], v[204:207], v[36:39]
	v_mfma_f32_16x16x32_bf16 v[32:35], v[186:189], v[204:207], v[32:35]
	v_mfma_f32_16x16x32_bf16 v[20:23], v[178:181], v[212:215], v[20:23]
	v_mfma_f32_16x16x32_bf16 v[16:19], v[186:189], v[212:215], v[16:19]
	v_mfma_f32_16x16x32_bf16 v[4:7], v[178:181], v[220:223], v[4:7]
	v_mfma_f32_16x16x32_bf16 v[0:3], v[186:189], v[220:223], v[0:3]
	s_setprio 0
	s_barrier
	s_add_i32 s87, s87, 2
	s_add_u32 s60, s60, 0x100
	s_addc_u32 s61, s61, 0
	s_add_u32 s85, s85, 0x100
	s_addc_u32 s86, s86, 0
	s_cmp_gt_u32 s87, 13
.LBB0_133:
	ds_read_b128 v[150:153], v156
	ds_read_b128 v[162:165], v156 offset:1024
	ds_read_b128 v[166:169], v156 offset:2048
	ds_read_b128 v[170:173], v156 offset:3072
	ds_read_b128 v[174:177], v157
	ds_read_b128 v[178:181], v157 offset:1024
	ds_read_b128 v[182:185], v157 offset:2048
	ds_read_b128 v[186:189], v157 offset:3072
	s_add_u32 s62, s60, 0xfffc0080
	s_addc_u32 s63, s61, -1
	s_cmp_eq_u32 s87, 12
	s_cselect_b32 s65, s43, s63
	s_cselect_b32 s64, s83, s62
	s_cselect_b32 s63, s41, s86
	s_cselect_b32 s62, s84, s85

; #define PG8_STAGE(bufoff, gbase, voff) do { _Pragma("unroll") for (int _i = 0; _i < 2; ++_i) \
;         __builtin_amdgcn_global_load_lds((const unsigned*)((const char*)(gbase) + (voff)[_i]), (PG8_LAS unsigned*)(lds + (bufoff) + ldsw + _i * 8192), 16, 0, 0); } while (0)
; #define PG8_LDA(dst, b, h) do { _Pragma("unroll") for (int m = 0; m < 4; ++m) _Pragma("unroll") for (int k = 0; k < 2; ++k) dst[m][k] = *(const PG8_LAS bf16x8*)(lds + PG8_SA(b, h) + aoff + m * 2048 + k * 1024); } while (0)
; #define PG8_LDB(dst, b, h) do { _Pragma("unroll") for (int n = 0; n < 2; ++n) _Pragma("unroll") for (int k = 0; k < 2; ++k) dst[n][k] = *(const PG8_LAS bf16x8*)(lds + PG8_SB(b, h) + boff + n * 2048 + k * 1024); } while (0)
; #define PG8_SCHED __builtin_amdgcn_sched_barrier(0)
; template <class Epi, class Sched, bool ALIGN_EPI = false, bool SP2 = false, bool ATILED = false>
; __device__ __forceinline__ void gemm_phase(PG8_LAS unsigned char* lds, const Gemm g, const Sched& S, const Epi& E) {
;     ...
;             PG8_LDB(B0, 0, 0); PG8_LDB(B1, 0, 1); PG8_SCHED; PG8_LDA(At, 0, 0); PG8_STAGE(PG8_SA(1, 1), a1 + hstepA, voffA);
	s_add_i32 m0, s49, 0xc000
	ds_read_b128 v[190:193], v158
	ds_read_b128 v[194:197], v158 offset:1024
	ds_read_b128 v[200:203], v158 offset:2048
	ds_read_b128 v[204:207], v158 offset:3072
	ds_read_b128 v[208:211], v158 offset:4096
	ds_read_b128 v[212:215], v158 offset:5120
	ds_read_b128 v[216:219], v158 offset:6144
	ds_read_b128 v[220:223], v158 offset:7168
	global_load_lds_dwordx4 v140, s[60:61]

; #define PG8_STAGE(bufoff, gbase, voff) do { _Pragma("unroll") for (int _i = 0; _i < 2; ++_i) \
;         __builtin_amdgcn_global_load_lds((const unsigned*)((const char*)(gbase) + (voff)[_i]), (PG8_LAS unsigned*)(lds + (bufoff) + ldsw + _i * 8192), 16, 0, 0); } while (0)
; #define PG8_LDA(dst, b, h) do { _Pragma("unroll") for (int m = 0; m < 4; ++m) _Pragma("unroll") for (int k = 0; k < 2; ++k) dst[m][k] = *(const PG8_LAS bf16x8*)(lds + PG8_SA(b, h) + aoff + m * 2048 + k * 1024); } while (0)
; #define PG8_LDB(dst, b, h) do { _Pragma("unroll") for (int n = 0; n < 2; ++n) _Pragma("unroll") for (int k = 0; k < 2; ++k) dst[n][k] = *(const PG8_LAS bf16x8*)(lds + PG8_SB(b, h) + boff + n * 2048 + k * 1024); } while (0)
; #define PG8_MMA(ai, bj, At, Bt) do { __builtin_amdgcn_s_setprio(1); _Pragma("unroll") for (int m = 0; m < 4; ++m) _Pragma("unroll") for (int n = 0; n < 2; ++n) _Pragma("unroll") for (int k = 0; k < 2; ++k) \
;         acc[ai][bj][m][n] = __builtin_amdgcn_mfma_f32_16x16x32_bf16(Bt[n][k], At[m][k], acc[ai][bj][m][n], 0, 0, 0); __builtin_amdgcn_s_setprio(0); } while (0)
; #define PG8_WAIT_V(n) asm volatile("s_waitcnt vmcnt(" #n ")" ::: "memory")
; #define PG8_WAIT_L(n) asm volatile("s_waitcnt lgkmcnt(" #n ")" ::: "memory")
; #define PG8_BAR __builtin_amdgcn_s_barrier()
; #define PG8_SCHED __builtin_amdgcn_sched_barrier(0)
; template <class Epi, class Sched, bool ALIGN_EPI = false, bool SP2 = false, bool ATILED = false>
; __device__ __forceinline__ void gemm_phase(PG8_LAS unsigned char* lds, const Gemm g, const Sched& S, const Epi& E) {
;     ...
;             PG8_LDB(B0, 0, 0); PG8_LDB(B1, 0, 1); PG8_SCHED; PG8_LDA(At, 0, 0); PG8_STAGE(PG8_SA(1, 1), a1 + hstepA, voffA);
;             PG8_WAIT_V(8); PG8_WAIT_L(0); PG8_BAR; PG8_MMA(0, 0, At, B0); PG8_MMA(0, 1, At, B1); PG8_BAR; PG8_SCHED;
	s_add_i32 m0, s49, 0xe000
	s_nop 0
	global_load_lds_dwordx4 v142, s[60:61]
	s_waitcnt vmcnt(8)
	s_waitcnt lgkmcnt(0)
	s_barrier
	s_setprio 1
	s_waitcnt lgkmcnt(0)
	v_mfma_f32_16x16x32_bf16 v[124:127], v[150:153], v[190:193], v[124:127]
	v_mfma_f32_16x16x32_bf16 v[120:123], v[166:169], v[190:193], v[120:123]
	v_mfma_f32_16x16x32_bf16 v[108:111], v[150:153], v[200:203], v[108:111]
	v_mfma_f32_16x16x32_bf16 v[104:107], v[166:169], v[200:203], v[104:107]
	v_mfma_f32_16x16x32_bf16 v[92:95], v[150:153], v[208:211], v[92:95]
	v_mfma_f32_16x16x32_bf16 v[88:91], v[166:169], v[208:211], v[88:91]
	v_mfma_f32_16x16x32_bf16 v[76:79], v[150:153], v[216:219], v[76:79]
	v_mfma_f32_16x16x32_bf16 v[72:75], v[166:169], v[216:219], v[72:75]
	v_mfma_f32_16x16x32_bf16 v[124:127], v[162:165], v[194:197], v[124:127]
	v_mfma_f32_16x16x32_bf16 v[120:123], v[170:173], v[194:197], v[120:123]
	v_mfma_f32_16x16x32_bf16 v[108:111], v[162:165], v[204:207], v[108:111]
	v_mfma_f32_16x16x32_bf16 v[104:107], v[170:173], v[204:207], v[104:107]
	v_mfma_f32_16x16x32_bf16 v[92:95], v[162:165], v[212:215], v[92:95]
	v_mfma_f32_16x16x32_bf16 v[88:91], v[170:173], v[212:215], v[88:91]
	v_mfma_f32_16x16x32_bf16 v[76:79], v[162:165], v[220:223], v[76:79]
	v_mfma_f32_16x16x32_bf16 v[72:75], v[170:173], v[220:223], v[72:75]
	s_setprio 0
	s_setprio 1
	v_mfma_f32_16x16x32_bf16 v[116:119], v[174:177], v[190:193], v[116:119]
	v_mfma_f32_16x16x32_bf16 v[112:115], v[182:185], v[190:193], v[112:115]
	v_mfma_f32_16x16x32_bf16 v[100:103], v[174:177], v[200:203], v[100:103]
	v_mfma_f32_16x16x32_bf16 v[96:99], v[182:185], v[200:203], v[96:99]
	v_mfma_f32_16x16x32_bf16 v[84:87], v[174:177], v[208:211], v[84:87]
	v_mfma_f32_16x16x32_bf16 v[80:83], v[182:185], v[208:211], v[80:83]
	v_mfma_f32_16x16x32_bf16 v[68:71], v[174:177], v[216:219], v[68:71]
	v_mfma_f32_16x16x32_bf16 v[64:67], v[182:185], v[216:219], v[64:67]
	v_mfma_f32_16x16x32_bf16 v[116:119], v[178:181], v[194:197], v[116:119]
	v_mfma_f32_16x16x32_bf16 v[112:115], v[186:189], v[194:197], v[112:115]
	v_mfma_f32_16x16x32_bf16 v[100:103], v[178:181], v[204:207], v[100:103]
	v_mfma_f32_16x16x32_bf16 v[96:99], v[186:189], v[204:207], v[96:99]
	v_mfma_f32_16x16x32_bf16 v[84:87], v[178:181], v[212:215], v[84:87]
	v_mfma_f32_16x16x32_bf16 v[80:83], v[186:189], v[212:215], v[80:83]
	v_mfma_f32_16x16x32_bf16 v[68:71], v[178:181], v[220:223], v[68:71]
	v_mfma_f32_16x16x32_bf16 v[64:67], v[186:189], v[220:223], v[64:67]
	s_setprio 0
	s_barrier
	s_add_u32 s98, s62, s8
	s_addc_u32 s99, s63, s9
	s_add_u32 s100, s64, s8
	s_addc_u32 s101, s65, s9
	s_add_i32 s88, s78, s66

; #define PG8_STAGE(bufoff, gbase, voff) do { _Pragma("unroll") for (int _i = 0; _i < 2; ++_i) \
;         __builtin_amdgcn_global_load_lds((const unsigned*)((const char*)(gbase) + (voff)[_i]), (PG8_LAS unsigned*)(lds + (bufoff) + ldsw + _i * 8192), 16, 0, 0); } while (0)
; #define PG8_LDA(dst, b, h) do { _Pragma("unroll") for (int m = 0; m < 4; ++m) _Pragma("unroll") for (int k = 0; k < 2; ++k) dst[m][k] = *(const PG8_LAS bf16x8*)(lds + PG8_SA(b, h) + aoff + m * 2048 + k * 1024); } while (0)
; template <class Epi, class Sched, bool ALIGN_EPI = false, bool SP2 = false, bool ATILED = false>
; __device__ __forceinline__ void gemm_phase(PG8_LAS unsigned char* lds, const Gemm g, const Sched& S, const Epi& E) {
;     ...
;             PG8_LDA(At, 0, 1); PG8_STAGE(PG8_SB(0, 0), b2, voffB); PG8_STAGE(PG8_SB(0, 1), b2 + hstep, voffB); PG8_STAGE(PG8_SA(0, 0), a2, voffA);
	s_mov_b32 m0, s88
	ds_read_b128 v[190:193], v158 offset:16384
	ds_read_b128 v[194:197], v158 offset:17408
	ds_read_b128 v[200:203], v158 offset:18432
	ds_read_b128 v[204:207], v158 offset:19456
	ds_read_b128 v[208:211], v158 offset:20480
	ds_read_b128 v[212:215], v158 offset:21504
	ds_read_b128 v[216:219], v158 offset:22528
	ds_read_b128 v[220:223], v158 offset:23552
	global_load_lds_dwordx4 v130, s[62:63]
	s_add_i32 m0, s88, 0x2000
	s_add_u32 s88, s62, 0x40000

; #define PG8_STAGE(bufoff, gbase, voff) do { _Pragma("unroll") for (int _i = 0; _i < 2; ++_i) \
;         __builtin_amdgcn_global_load_lds((const unsigned*)((const char*)(gbase) + (voff)[_i]), (PG8_LAS unsigned*)(lds + (bufoff) + ldsw + _i * 8192), 16, 0, 0); } while (0)
; #define PG8_LDA(dst, b, h) do { _Pragma("unroll") for (int m = 0; m < 4; ++m) _Pragma("unroll") for (int k = 0; k < 2; ++k) dst[m][k] = *(const PG8_LAS bf16x8*)(lds + PG8_SA(b, h) + aoff + m * 2048 + k * 1024); } while (0)
; template <class Epi, class Sched, bool ALIGN_EPI = false, bool SP2 = false, bool ATILED = false>
; __device__ __forceinline__ void gemm_phase(PG8_LAS unsigned char* lds, const Gemm g, const Sched& S, const Epi& E) {
;     ...
;             PG8_LDA(At, 0, 1); PG8_STAGE(PG8_SB(0, 0), b2, voffB); PG8_STAGE(PG8_SB(0, 1), b2 + hstep, voffB); PG8_STAGE(PG8_SA(0, 0), a2, voffA);
	s_addc_u32 s89, s63, 0
	s_add_i32 s90, s79, s66
	global_load_lds_dwordx4 v134, s[62:63]

; #define PG8_STAGE(bufoff, gbase, voff) do { _Pragma("unroll") for (int _i = 0; _i < 2; ++_i) \
;         __builtin_amdgcn_global_load_lds((const unsigned*)((const char*)(gbase) + (voff)[_i]), (PG8_LAS unsigned*)(lds + (bufoff) + ldsw + _i * 8192), 16, 0, 0); } while (0)
; #define PG8_LDA(dst, b, h) do { _Pragma("unroll") for (int m = 0; m < 4; ++m) _Pragma("unroll") for (int k = 0; k < 2; ++k) dst[m][k] = *(const PG8_LAS bf16x8*)(lds + PG8_SA(b, h) + aoff + m * 2048 + k * 1024); } while (0)
; template <class Epi, class Sched, bool ALIGN_EPI = false, bool SP2 = false, bool ATILED = false>
; __device__ __forceinline__ void gemm_phase(PG8_LAS unsigned char* lds, const Gemm g, const Sched& S, const Epi& E) {
;     ...
;             PG8_LDA(At, 0, 1); PG8_STAGE(PG8_SB(0, 0), b2, voffB); PG8_STAGE(PG8_SB(0, 1), b2 + hstep, voffB); PG8_STAGE(PG8_SA(0, 0), a2, voffA);
	s_mov_b32 m0, s90

; #define PG8_STAGE(bufoff, gbase, voff) do { _Pragma("unroll") for (int _i = 0; _i < 2; ++_i) \
;         __builtin_amdgcn_global_load_lds((const unsigned*)((const char*)(gbase) + (voff)[_i]), (PG8_LAS unsigned*)(lds + (bufoff) + ldsw + _i * 8192), 16, 0, 0); } while (0)
; #define PG8_LDA(dst, b, h) do { _Pragma("unroll") for (int m = 0; m < 4; ++m) _Pragma("unroll") for (int k = 0; k < 2; ++k) dst[m][k] = *(const PG8_LAS bf16x8*)(lds + PG8_SA(b, h) + aoff + m * 2048 + k * 1024); } while (0)
; template <class Epi, class Sched, bool ALIGN_EPI = false, bool SP2 = false, bool ATILED = false>
; __device__ __forceinline__ void gemm_phase(PG8_LAS unsigned char* lds, const Gemm g, const Sched& S, const Epi& E) {
;     ...
;             PG8_LDA(At, 0, 1); PG8_STAGE(PG8_SB(0, 0), b2, voffB); PG8_STAGE(PG8_SB(0, 1), b2 + hstep, voffB); PG8_STAGE(PG8_SA(0, 0), a2, voffA);
	s_nop 0
	global_load_lds_dwordx4 v130, s[88:89]

; #define PG8_STAGE(bufoff, gbase, voff) do { _Pragma("unroll") for (int _i = 0; _i < 2; ++_i) \
;         __builtin_amdgcn_global_load_lds((const unsigned*)((const char*)(gbase) + (voff)[_i]), (PG8_LAS unsigned*)(lds + (bufoff) + ldsw + _i * 8192), 16, 0, 0); } while (0)
; #define PG8_LDA(dst, b, h) do { _Pragma("unroll") for (int m = 0; m < 4; ++m) _Pragma("unroll") for (int k = 0; k < 2; ++k) dst[m][k] = *(const PG8_LAS bf16x8*)(lds + PG8_SA(b, h) + aoff + m * 2048 + k * 1024); } while (0)
; template <class Epi, class Sched, bool ALIGN_EPI = false, bool SP2 = false, bool ATILED = false>
; __device__ __forceinline__ void gemm_phase(PG8_LAS unsigned char* lds, const Gemm g, const Sched& S, const Epi& E) {
;     ...
;             PG8_LDA(At, 0, 1); PG8_STAGE(PG8_SB(0, 0), b2, voffB); PG8_STAGE(PG8_SB(0, 1), b2 + hstep, voffB); PG8_STAGE(PG8_SA(0, 0), a2, voffA);
	s_add_i32 m0, s90, 0x2000
	s_nop 0
	global_load_lds_dwordx4 v134, s[88:89]

; #define PG8_STAGE(bufoff, gbase, voff) do { _Pragma("unroll") for (int _i = 0; _i < 2; ++_i) \
;         __builtin_amdgcn_global_load_lds((const unsigned*)((const char*)(gbase) + (voff)[_i]), (PG8_LAS unsigned*)(lds + (bufoff) + ldsw + _i * 8192), 16, 0, 0); } while (0)
; #define PG8_LDA(dst, b, h) do { _Pragma("unroll") for (int m = 0; m < 4; ++m) _Pragma("unroll") for (int k = 0; k < 2; ++k) dst[m][k] = *(const PG8_LAS bf16x8*)(lds + PG8_SA(b, h) + aoff + m * 2048 + k * 1024); } while (0)
; #define PG8_LDB(dst, b, h) do { _Pragma("unroll") for (int n = 0; n < 2; ++n) _Pragma("unroll") for (int k = 0; k < 2; ++k) dst[n][k] = *(const PG8_LAS bf16x8*)(lds + PG8_SB(b, h) + boff + n * 2048 + k * 1024); } while (0)
; #define PG8_MMA(ai, bj, At, Bt) do { __builtin_amdgcn_s_setprio(1); _Pragma("unroll") for (int m = 0; m < 4; ++m) _Pragma("unroll") for (int n = 0; n < 2; ++n) _Pragma("unroll") for (int k = 0; k < 2; ++k) \
;         acc[ai][bj][m][n] = __builtin_amdgcn_mfma_f32_16x16x32_bf16(Bt[n][k], At[m][k], acc[ai][bj][m][n], 0, 0, 0); __builtin_amdgcn_s_setprio(0); } while (0)
; #define PG8_WAIT_V(n) asm volatile("s_waitcnt vmcnt(" #n ")" ::: "memory")
; #define PG8_WAIT_L(n) asm volatile("s_waitcnt lgkmcnt(" #n ")" ::: "memory")
; #define PG8_BAR __builtin_amdgcn_s_barrier()
; #define PG8_SCHED __builtin_amdgcn_sched_barrier(0)
; template <class Epi, class Sched, bool ALIGN_EPI = false, bool SP2 = false, bool ATILED = false>
; __device__ __forceinline__ void gemm_phase(PG8_LAS unsigned char* lds, const Gemm g, const Sched& S, const Epi& E) {
;     ...
;             PG8_LDA(At, 0, 1); PG8_STAGE(PG8_SB(0, 0), b2, voffB); PG8_STAGE(PG8_SB(0, 1), b2 + hstep, voffB); PG8_STAGE(PG8_SA(0, 0), a2, voffA);
;             PG8_WAIT_V(8); PG8_WAIT_L(0); PG8_BAR; PG8_MMA(1, 0, At, B0); PG8_MMA(1, 1, At, B1); PG8_BAR; PG8_SCHED;
;             PG8_LDB(B0, 1, 0); PG8_LDB(B1, 1, 1); PG8_SCHED; PG8_LDA(At, 1, 0); PG8_STAGE(PG8_SA(0, 1), a2 + hstepA, voffA);
	s_mov_b32 m0, s49
	s_nop 0
	global_load_lds_dwordx4 v128, s[64:65]
	s_mov_b32 m0, s68
	s_nop 0
	global_load_lds_dwordx4 v132, s[64:65]
	s_waitcnt vmcnt(8)
	s_waitcnt lgkmcnt(0)
	s_barrier
	s_setprio 1
	s_waitcnt lgkmcnt(0)
	v_mfma_f32_16x16x32_bf16 v[60:63], v[150:153], v[190:193], v[60:63]
	v_mfma_f32_16x16x32_bf16 v[56:59], v[166:169], v[190:193], v[56:59]
	v_mfma_f32_16x16x32_bf16 v[44:47], v[150:153], v[200:203], v[44:47]
	v_mfma_f32_16x16x32_bf16 v[40:43], v[166:169], v[200:203], v[40:43]
	v_mfma_f32_16x16x32_bf16 v[28:31], v[150:153], v[208:211], v[28:31]
	v_mfma_f32_16x16x32_bf16 v[24:27], v[166:169], v[208:211], v[24:27]
	v_mfma_f32_16x16x32_bf16 v[12:15], v[150:153], v[216:219], v[12:15]
	v_mfma_f32_16x16x32_bf16 v[8:11], v[166:169], v[216:219], v[8:11]
	v_mfma_f32_16x16x32_bf16 v[60:63], v[162:165], v[194:197], v[60:63]
	v_mfma_f32_16x16x32_bf16 v[56:59], v[170:173], v[194:197], v[56:59]
	v_mfma_f32_16x16x32_bf16 v[44:47], v[162:165], v[204:207], v[44:47]
	v_mfma_f32_16x16x32_bf16 v[40:43], v[170:173], v[204:207], v[40:43]
	v_mfma_f32_16x16x32_bf16 v[28:31], v[162:165], v[212:215], v[28:31]
	v_mfma_f32_16x16x32_bf16 v[24:27], v[170:173], v[212:215], v[24:27]
	v_mfma_f32_16x16x32_bf16 v[12:15], v[162:165], v[220:223], v[12:15]
	v_mfma_f32_16x16x32_bf16 v[8:11], v[170:173], v[220:223], v[8:11]
	s_setprio 0
	s_setprio 1
	v_mfma_f32_16x16x32_bf16 v[52:55], v[174:177], v[190:193], v[52:55]
	v_mfma_f32_16x16x32_bf16 v[48:51], v[182:185], v[190:193], v[48:51]
	v_mfma_f32_16x16x32_bf16 v[36:39], v[174:177], v[200:203], v[36:39]
	v_mfma_f32_16x16x32_bf16 v[32:35], v[182:185], v[200:203], v[32:35]
	v_mfma_f32_16x16x32_bf16 v[20:23], v[174:177], v[208:211], v[20:23]
	v_mfma_f32_16x16x32_bf16 v[16:19], v[182:185], v[208:211], v[16:19]
	v_mfma_f32_16x16x32_bf16 v[4:7], v[174:177], v[216:219], v[4:7]
	v_mfma_f32_16x16x32_bf16 v[0:3], v[182:185], v[216:219], v[0:3]
	v_mfma_f32_16x16x32_bf16 v[52:55], v[178:181], v[194:197], v[52:55]
	v_mfma_f32_16x16x32_bf16 v[48:51], v[186:189], v[194:197], v[48:51]
	v_mfma_f32_16x16x32_bf16 v[36:39], v[178:181], v[204:207], v[36:39]
	v_mfma_f32_16x16x32_bf16 v[32:35], v[186:189], v[204:207], v[32:35]
	v_mfma_f32_16x16x32_bf16 v[20:23], v[178:181], v[212:215], v[20:23]
	v_mfma_f32_16x16x32_bf16 v[16:19], v[186:189], v[212:215], v[16:19]
	v_mfma_f32_16x16x32_bf16 v[4:7], v[178:181], v[220:223], v[4:7]
	v_mfma_f32_16x16x32_bf16 v[0:3], v[186:189], v[220:223], v[0:3]
	s_setprio 0
	s_barrier
	s_add_i32 s88, 0, 0x18000
	v_add_u32_e32 v136, s88, v155
	s_add_i32 s89, 0, 0x1c000
	ds_read_b128 v[150:153], v136
	ds_read_b128 v[162:165], v136 offset:1024
	ds_read_b128 v[166:169], v136 offset:2048
	ds_read_b128 v[170:173], v136 offset:3072
	v_add_u32_e32 v136, s89, v155
	ds_read_b128 v[174:177], v136
	ds_read_b128 v[178:181], v136 offset:1024
	ds_read_b128 v[182:185], v136 offset:2048
	ds_read_b128 v[186:189], v136 offset:3072
	s_add_u32 s64, s64, 0x40000
	s_addc_u32 s65, s65, 0
	s_mov_b32 m0, s69

; #define PG8_STAGE(bufoff, gbase, voff) do { _Pragma("unroll") for (int _i = 0; _i < 2; ++_i) \
;         __builtin_amdgcn_global_load_lds((const unsigned*)((const char*)(gbase) + (voff)[_i]), (PG8_LAS unsigned*)(lds + (bufoff) + ldsw + _i * 8192), 16, 0, 0); } while (0)
; #define PG8_LDA(dst, b, h) do { _Pragma("unroll") for (int m = 0; m < 4; ++m) _Pragma("unroll") for (int k = 0; k < 2; ++k) dst[m][k] = *(const PG8_LAS bf16x8*)(lds + PG8_SA(b, h) + aoff + m * 2048 + k * 1024); } while (0)
; #define PG8_LDB(dst, b, h) do { _Pragma("unroll") for (int n = 0; n < 2; ++n) _Pragma("unroll") for (int k = 0; k < 2; ++k) dst[n][k] = *(const PG8_LAS bf16x8*)(lds + PG8_SB(b, h) + boff + n * 2048 + k * 1024); } while (0)
; #define PG8_SCHED __builtin_amdgcn_sched_barrier(0)
; template <class Epi, class Sched, bool ALIGN_EPI = false, bool SP2 = false, bool ATILED = false>
; __device__ __forceinline__ void gemm_phase(PG8_LAS unsigned char* lds, const Gemm g, const Sched& S, const Epi& E) {
;     ...
;             PG8_LDB(B0, 1, 0); PG8_LDB(B1, 1, 1); PG8_SCHED; PG8_LDA(At, 1, 0); PG8_STAGE(PG8_SA(0, 1), a2 + hstepA, voffA);
	ds_read_b128 v[190:193], v158 offset:32768
	ds_read_b128 v[194:197], v158 offset:33792
	ds_read_b128 v[200:203], v158 offset:34816
	ds_read_b128 v[204:207], v158 offset:35840
	ds_read_b128 v[208:211], v158 offset:36864
	ds_read_b128 v[212:215], v158 offset:37888
	ds_read_b128 v[216:219], v158 offset:38912
	ds_read_b128 v[220:223], v158 offset:39936
	global_load_lds_dwordx4 v128, s[64:65]

; #define PG8_STAGE(bufoff, gbase, voff) do { _Pragma("unroll") for (int _i = 0; _i < 2; ++_i) \
;         __builtin_amdgcn_global_load_lds((const unsigned*)((const char*)(gbase) + (voff)[_i]), (PG8_LAS unsigned*)(lds + (bufoff) + ldsw + _i * 8192), 16, 0, 0); } while (0)
; #define PG8_LDA(dst, b, h) do { _Pragma("unroll") for (int m = 0; m < 4; ++m) _Pragma("unroll") for (int k = 0; k < 2; ++k) dst[m][k] = *(const PG8_LAS bf16x8*)(lds + PG8_SA(b, h) + aoff + m * 2048 + k * 1024); } while (0)
; #define PG8_LDB(dst, b, h) do { _Pragma("unroll") for (int n = 0; n < 2; ++n) _Pragma("unroll") for (int k = 0; k < 2; ++k) dst[n][k] = *(const PG8_LAS bf16x8*)(lds + PG8_SB(b, h) + boff + n * 2048 + k * 1024); } while (0)
; #define PG8_MMA(ai, bj, At, Bt) do { __builtin_amdgcn_s_setprio(1); _Pragma("unroll") for (int m = 0; m < 4; ++m) _Pragma("unroll") for (int n = 0; n < 2; ++n) _Pragma("unroll") for (int k = 0; k < 2; ++k) \
;         acc[ai][bj][m][n] = __builtin_amdgcn_mfma_f32_16x16x32_bf16(Bt[n][k], At[m][k], acc[ai][bj][m][n], 0, 0, 0); __builtin_amdgcn_s_setprio(0); } while (0)
; #define PG8_WAIT_V(n) asm volatile("s_waitcnt vmcnt(" #n ")" ::: "memory")
; #define PG8_WAIT_L(n) asm volatile("s_waitcnt lgkmcnt(" #n ")" ::: "memory")
; #define PG8_BAR __builtin_amdgcn_s_barrier()
; #define PG8_SCHED __builtin_amdgcn_sched_barrier(0)
; template <class Epi, class Sched, bool ALIGN_EPI = false, bool SP2 = false, bool ATILED = false>
; __device__ __forceinline__ void gemm_phase(PG8_LAS unsigned char* lds, const Gemm g, const Sched& S, const Epi& E) {
;     ...
;             PG8_LDB(B0, 1, 0); PG8_LDB(B1, 1, 1); PG8_SCHED; PG8_LDA(At, 1, 0); PG8_STAGE(PG8_SA(0, 1), a2 + hstepA, voffA);
;             PG8_WAIT_V(8); PG8_WAIT_L(0); PG8_BAR; PG8_MMA(0, 0, At, B0); PG8_MMA(0, 1, At, B1); PG8_BAR; PG8_SCHED;
	s_mov_b32 m0, s70
	s_nop 0
	global_load_lds_dwordx4 v132, s[64:65]
	s_waitcnt vmcnt(8)
	s_waitcnt lgkmcnt(0)
	s_barrier
	s_setprio 1
	s_waitcnt lgkmcnt(0)
	v_mfma_f32_16x16x32_bf16 v[124:127], v[150:153], v[190:193], v[124:127]
	v_mfma_f32_16x16x32_bf16 v[120:123], v[166:169], v[190:193], v[120:123]
	v_mfma_f32_16x16x32_bf16 v[108:111], v[150:153], v[200:203], v[108:111]
	v_mfma_f32_16x16x32_bf16 v[104:107], v[166:169], v[200:203], v[104:107]
	v_mfma_f32_16x16x32_bf16 v[92:95], v[150:153], v[208:211], v[92:95]
	v_mfma_f32_16x16x32_bf16 v[88:91], v[166:169], v[208:211], v[88:91]
	v_mfma_f32_16x16x32_bf16 v[76:79], v[150:153], v[216:219], v[76:79]
	v_mfma_f32_16x16x32_bf16 v[72:75], v[166:169], v[216:219], v[72:75]
	v_mfma_f32_16x16x32_bf16 v[124:127], v[162:165], v[194:197], v[124:127]
	v_mfma_f32_16x16x32_bf16 v[120:123], v[170:173], v[194:197], v[120:123]
	v_mfma_f32_16x16x32_bf16 v[108:111], v[162:165], v[204:207], v[108:111]
	v_mfma_f32_16x16x32_bf16 v[104:107], v[170:173], v[204:207], v[104:107]
	v_mfma_f32_16x16x32_bf16 v[92:95], v[162:165], v[212:215], v[92:95]
	v_mfma_f32_16x16x32_bf16 v[88:91], v[170:173], v[212:215], v[88:91]
	v_mfma_f32_16x16x32_bf16 v[76:79], v[162:165], v[220:223], v[76:79]
	v_mfma_f32_16x16x32_bf16 v[72:75], v[170:173], v[220:223], v[72:75]
	s_setprio 0
	s_setprio 1
	v_mfma_f32_16x16x32_bf16 v[116:119], v[174:177], v[190:193], v[116:119]
	v_mfma_f32_16x16x32_bf16 v[112:115], v[182:185], v[190:193], v[112:115]
	v_mfma_f32_16x16x32_bf16 v[100:103], v[174:177], v[200:203], v[100:103]
	v_mfma_f32_16x16x32_bf16 v[96:99], v[182:185], v[200:203], v[96:99]
	v_mfma_f32_16x16x32_bf16 v[84:87], v[174:177], v[208:211], v[84:87]
	v_mfma_f32_16x16x32_bf16 v[80:83], v[182:185], v[208:211], v[80:83]
	v_mfma_f32_16x16x32_bf16 v[68:71], v[174:177], v[216:219], v[68:71]
	v_mfma_f32_16x16x32_bf16 v[64:67], v[182:185], v[216:219], v[64:67]
	v_mfma_f32_16x16x32_bf16 v[116:119], v[178:181], v[194:197], v[116:119]
	v_mfma_f32_16x16x32_bf16 v[112:115], v[186:189], v[194:197], v[112:115]
	v_mfma_f32_16x16x32_bf16 v[100:103], v[178:181], v[204:207], v[100:103]
	v_mfma_f32_16x16x32_bf16 v[96:99], v[186:189], v[204:207], v[96:99]
	v_mfma_f32_16x16x32_bf16 v[84:87], v[178:181], v[212:215], v[84:87]
	v_mfma_f32_16x16x32_bf16 v[80:83], v[186:189], v[212:215], v[80:83]
	v_mfma_f32_16x16x32_bf16 v[68:71], v[178:181], v[220:223], v[68:71]
	v_mfma_f32_16x16x32_bf16 v[64:67], v[186:189], v[220:223], v[64:67]
	s_setprio 0
	s_barrier
	s_add_i32 s64, s88, s66

; #define PG8_STAGE(bufoff, gbase, voff) do { _Pragma("unroll") for (int _i = 0; _i < 2; ++_i) \
;         __builtin_amdgcn_global_load_lds((const unsigned*)((const char*)(gbase) + (voff)[_i]), (PG8_LAS unsigned*)(lds + (bufoff) + ldsw + _i * 8192), 16, 0, 0); } while (0)
; #define PG8_LDA(dst, b, h) do { _Pragma("unroll") for (int m = 0; m < 4; ++m) _Pragma("unroll") for (int k = 0; k < 2; ++k) dst[m][k] = *(const PG8_LAS bf16x8*)(lds + PG8_SA(b, h) + aoff + m * 2048 + k * 1024); } while (0)
; template <class Epi, class Sched, bool ALIGN_EPI = false, bool SP2 = false, bool ATILED = false>
; __device__ __forceinline__ void gemm_phase(PG8_LAS unsigned char* lds, const Gemm g, const Sched& S, const Epi& E) {
;     ...
;             PG8_LDA(At, 1, 1); PG8_STAGE(PG8_SB(1, 0), b3, voffB); PG8_STAGE(PG8_SB(1, 1), b3 + hstep, voffB); PG8_STAGE(PG8_SA(1, 0), a3, voffA);
	s_mov_b32 m0, s64
	ds_read_b128 v[190:193], v158 offset:49152
	ds_read_b128 v[194:197], v158 offset:50176
	ds_read_b128 v[200:203], v158 offset:51200
	ds_read_b128 v[204:207], v158 offset:52224
	ds_read_b128 v[208:211], v158 offset:53248
	ds_read_b128 v[212:215], v158 offset:54272
	ds_read_b128 v[216:219], v158 offset:55296
	ds_read_b128 v[220:223], v158 offset:56320
	global_load_lds_dwordx4 v130, s[98:99]
	s_add_i32 m0, s64, 0x2000
	s_add_u32 s62, s62, 0x40080

; #define PG8_STAGE(bufoff, gbase, voff) do { _Pragma("unroll") for (int _i = 0; _i < 2; ++_i) \
;         __builtin_amdgcn_global_load_lds((const unsigned*)((const char*)(gbase) + (voff)[_i]), (PG8_LAS unsigned*)(lds + (bufoff) + ldsw + _i * 8192), 16, 0, 0); } while (0)
; #define PG8_LDA(dst, b, h) do { _Pragma("unroll") for (int m = 0; m < 4; ++m) _Pragma("unroll") for (int k = 0; k < 2; ++k) dst[m][k] = *(const PG8_LAS bf16x8*)(lds + PG8_SA(b, h) + aoff + m * 2048 + k * 1024); } while (0)
; template <class Epi, class Sched, bool ALIGN_EPI = false, bool SP2 = false, bool ATILED = false>
; __device__ __forceinline__ void gemm_phase(PG8_LAS unsigned char* lds, const Gemm g, const Sched& S, const Epi& E) {
;     ...
;             PG8_LDA(At, 1, 1); PG8_STAGE(PG8_SB(1, 0), b3, voffB); PG8_STAGE(PG8_SB(1, 1), b3 + hstep, voffB); PG8_STAGE(PG8_SA(1, 0), a3, voffA);
	s_addc_u32 s63, s63, 0
	s_add_i32 s64, s89, s66
	global_load_lds_dwordx4 v134, s[98:99]

; #define PG8_STAGE(bufoff, gbase, voff) do { _Pragma("unroll") for (int _i = 0; _i < 2; ++_i) \
;         __builtin_amdgcn_global_load_lds((const unsigned*)((const char*)(gbase) + (voff)[_i]), (PG8_LAS unsigned*)(lds + (bufoff) + ldsw + _i * 8192), 16, 0, 0); } while (0)
; #define PG8_LDA(dst, b, h) do { _Pragma("unroll") for (int m = 0; m < 4; ++m) _Pragma("unroll") for (int k = 0; k < 2; ++k) dst[m][k] = *(const PG8_LAS bf16x8*)(lds + PG8_SA(b, h) + aoff + m * 2048 + k * 1024); } while (0)
; template <class Epi, class Sched, bool ALIGN_EPI = false, bool SP2 = false, bool ATILED = false>
; __device__ __forceinline__ void gemm_phase(PG8_LAS unsigned char* lds, const Gemm g, const Sched& S, const Epi& E) {
;     ...
;             PG8_LDA(At, 1, 1); PG8_STAGE(PG8_SB(1, 0), b3, voffB); PG8_STAGE(PG8_SB(1, 1), b3 + hstep, voffB); PG8_STAGE(PG8_SA(1, 0), a3, voffA);
	s_mov_b32 m0, s64
	s_nop 0
	global_load_lds_dwordx4 v130, s[62:63]

; #define PG8_STAGE(bufoff, gbase, voff) do { _Pragma("unroll") for (int _i = 0; _i < 2; ++_i) \
;         __builtin_amdgcn_global_load_lds((const unsigned*)((const char*)(gbase) + (voff)[_i]), (PG8_LAS unsigned*)(lds + (bufoff) + ldsw + _i * 8192), 16, 0, 0); } while (0)
; #define PG8_LDA(dst, b, h) do { _Pragma("unroll") for (int m = 0; m < 4; ++m) _Pragma("unroll") for (int k = 0; k < 2; ++k) dst[m][k] = *(const PG8_LAS bf16x8*)(lds + PG8_SA(b, h) + aoff + m * 2048 + k * 1024); } while (0)
; template <class Epi, class Sched, bool ALIGN_EPI = false, bool SP2 = false, bool ATILED = false>
; __device__ __forceinline__ void gemm_phase(PG8_LAS unsigned char* lds, const Gemm g, const Sched& S, const Epi& E) {
;     ...
;             PG8_LDA(At, 1, 1); PG8_STAGE(PG8_SB(1, 0), b3, voffB); PG8_STAGE(PG8_SB(1, 1), b3 + hstep, voffB); PG8_STAGE(PG8_SA(1, 0), a3, voffA);
	s_add_i32 m0, s64, 0x2000
	s_nop 0
	global_load_lds_dwordx4 v134, s[62:63]

; #define PG8_STAGE(bufoff, gbase, voff) do { _Pragma("unroll") for (int _i = 0; _i < 2; ++_i) \
;         __builtin_amdgcn_global_load_lds((const unsigned*)((const char*)(gbase) + (voff)[_i]), (PG8_LAS unsigned*)(lds + (bufoff) + ldsw + _i * 8192), 16, 0, 0); } while (0)
; #define PG8_LDA(dst, b, h) do { _Pragma("unroll") for (int m = 0; m < 4; ++m) _Pragma("unroll") for (int k = 0; k < 2; ++k) dst[m][k] = *(const PG8_LAS bf16x8*)(lds + PG8_SA(b, h) + aoff + m * 2048 + k * 1024); } while (0)
; template <class Epi, class Sched, bool ALIGN_EPI = false, bool SP2 = false, bool ATILED = false>
; __device__ __forceinline__ void gemm_phase(PG8_LAS unsigned char* lds, const Gemm g, const Sched& S, const Epi& E) {
;     ...
;             PG8_LDA(At, 1, 1); PG8_STAGE(PG8_SB(1, 0), b3, voffB); PG8_STAGE(PG8_SB(1, 1), b3 + hstep, voffB); PG8_STAGE(PG8_SA(1, 0), a3, voffA);
	s_mov_b32 m0, s76
	s_nop 0
	global_load_lds_dwordx4 v128, s[100:101]

; #define PG8_STAGE(bufoff, gbase, voff) do { _Pragma("unroll") for (int _i = 0; _i < 2; ++_i) \
;         __builtin_amdgcn_global_load_lds((const unsigned*)((const char*)(gbase) + (voff)[_i]), (PG8_LAS unsigned*)(lds + (bufoff) + ldsw + _i * 8192), 16, 0, 0); } while (0)
; #define PG8_LDA(dst, b, h) do { _Pragma("unroll") for (int m = 0; m < 4; ++m) _Pragma("unroll") for (int k = 0; k < 2; ++k) dst[m][k] = *(const PG8_LAS bf16x8*)(lds + PG8_SA(b, h) + aoff + m * 2048 + k * 1024); } while (0)
; #define PG8_WAIT_V(n) asm volatile("s_waitcnt vmcnt(" #n ")" ::: "memory")
; #define PG8_WAIT_L(n) asm volatile("s_waitcnt lgkmcnt(" #n ")" ::: "memory")
; #define PG8_BAR __builtin_amdgcn_s_barrier()
; template <class Epi, class Sched, bool ALIGN_EPI = false, bool SP2 = false, bool ATILED = false>
; __device__ __forceinline__ void gemm_phase(PG8_LAS unsigned char* lds, const Gemm g, const Sched& S, const Epi& E) {
;     ...
;         for (int t = 0; t < nt; t += 2) {
;             const bool last = (t == nt - 2);
;             const char* a1 = cA + (size_t)(t + 1) * kstepA;
;             const char* a2 = last ? nA : cA + (size_t)(t + 2) * kstepA; const char* b2 = last ? nB : cB + (size_t)(t + 2) * kstep;
;             const char* a3 = a2 + kstepA; const char* b3 = b2 + kstep;
;             if (last && has_next) S.a_ready(nxt);
;             if constexpr (SP2) {
;             PG8_LDB(B0, 0, 0); PG8_LDB(B1, 0, 1); PG8_SCHED; PG8_LDA(At, 0, 0); PG8_STAGE(PG8_SA(1, 1), a1 + hstepA, voffA);
;             PG8_WAIT_V(8); PG8_WAIT_L(0); PG8_BAR; PG8_MMA(0, 0, At, B0); PG8_MMA(0, 1, At, B1); PG8_BAR; PG8_SCHED;
;             PG8_LDA(At, 0, 1); PG8_STAGE(PG8_SB(0, 0), b2, voffB); PG8_STAGE(PG8_SB(0, 1), b2 + hstep, voffB); PG8_STAGE(PG8_SA(0, 0), a2, voffA);
;             PG8_WAIT_V(8); PG8_WAIT_L(0); PG8_BAR; PG8_MMA(1, 0, At, B0); PG8_MMA(1, 1, At, B1); PG8_BAR; PG8_SCHED;
;             PG8_LDB(B0, 1, 0); PG8_LDB(B1, 1, 1); PG8_SCHED; PG8_LDA(At, 1, 0); PG8_STAGE(PG8_SA(0, 1), a2 + hstepA, voffA);
;             PG8_WAIT_V(8); PG8_WAIT_L(0); PG8_BAR; PG8_MMA(0, 0, At, B0); PG8_MMA(0, 1, At, B1); PG8_BAR; PG8_SCHED;
;             PG8_LDA(At, 1, 1); PG8_STAGE(PG8_SB(1, 0), b3, voffB); PG8_STAGE(PG8_SB(1, 1), b3 + hstep, voffB); PG8_STAGE(PG8_SA(1, 0), a3, voffA);
;             PG8_WAIT_V(8); PG8_WAIT_L(0); PG8_BAR; PG8_MMA(1, 0, At, B0); PG8_MMA(1, 1, At, B1); PG8_BAR; PG8_SCHED;
	s_mov_b32 m0, s77
	s_nop 0
	global_load_lds_dwordx4 v132, s[100:101]
	s_waitcnt vmcnt(8)
	s_waitcnt lgkmcnt(0)
	s_barrier
	s_setprio 1
	s_waitcnt lgkmcnt(0)
	v_mfma_f32_16x16x32_bf16 v[60:63], v[150:153], v[190:193], v[60:63]
	v_mfma_f32_16x16x32_bf16 v[56:59], v[166:169], v[190:193], v[56:59]
	v_mfma_f32_16x16x32_bf16 v[44:47], v[150:153], v[200:203], v[44:47]
	v_mfma_f32_16x16x32_bf16 v[40:43], v[166:169], v[200:203], v[40:43]
	v_mfma_f32_16x16x32_bf16 v[28:31], v[150:153], v[208:211], v[28:31]
	v_mfma_f32_16x16x32_bf16 v[24:27], v[166:169], v[208:211], v[24:27]
	v_mfma_f32_16x16x32_bf16 v[12:15], v[150:153], v[216:219], v[12:15]
	v_mfma_f32_16x16x32_bf16 v[8:11], v[166:169], v[216:219], v[8:11]
	v_mfma_f32_16x16x32_bf16 v[60:63], v[162:165], v[194:197], v[60:63]
	v_mfma_f32_16x16x32_bf16 v[56:59], v[170:173], v[194:197], v[56:59]
	v_mfma_f32_16x16x32_bf16 v[44:47], v[162:165], v[204:207], v[44:47]
	v_mfma_f32_16x16x32_bf16 v[40:43], v[170:173], v[204:207], v[40:43]
	v_mfma_f32_16x16x32_bf16 v[28:31], v[162:165], v[212:215], v[28:31]
	v_mfma_f32_16x16x32_bf16 v[24:27], v[170:173], v[212:215], v[24:27]
	v_mfma_f32_16x16x32_bf16 v[12:15], v[162:165], v[220:223], v[12:15]
	v_mfma_f32_16x16x32_bf16 v[8:11], v[170:173], v[220:223], v[8:11]
	s_setprio 0
	s_setprio 1
	v_mfma_f32_16x16x32_bf16 v[52:55], v[174:177], v[190:193], v[52:55]
	v_mfma_f32_16x16x32_bf16 v[48:51], v[182:185], v[190:193], v[48:51]
	v_mfma_f32_16x16x32_bf16 v[36:39], v[174:177], v[200:203], v[36:39]
	v_mfma_f32_16x16x32_bf16 v[32:35], v[182:185], v[200:203], v[32:35]
	v_mfma_f32_16x16x32_bf16 v[20:23], v[174:177], v[208:211], v[20:23]
	v_mfma_f32_16x16x32_bf16 v[16:19], v[182:185], v[208:211], v[16:19]
	v_mfma_f32_16x16x32_bf16 v[4:7], v[174:177], v[216:219], v[4:7]
	v_mfma_f32_16x16x32_bf16 v[0:3], v[182:185], v[216:219], v[0:3]
	v_mfma_f32_16x16x32_bf16 v[52:55], v[178:181], v[194:197], v[52:55]
	v_mfma_f32_16x16x32_bf16 v[48:51], v[186:189], v[194:197], v[48:51]
	v_mfma_f32_16x16x32_bf16 v[36:39], v[178:181], v[204:207], v[36:39]
	v_mfma_f32_16x16x32_bf16 v[32:35], v[186:189], v[204:207], v[32:35]
	v_mfma_f32_16x16x32_bf16 v[20:23], v[178:181], v[212:215], v[20:23]
	v_mfma_f32_16x16x32_bf16 v[16:19], v[186:189], v[212:215], v[16:19]
	v_mfma_f32_16x16x32_bf16 v[4:7], v[178:181], v[220:223], v[4:7]
	v_mfma_f32_16x16x32_bf16 v[0:3], v[186:189], v[220:223], v[0:3]
	s_setprio 0
	s_barrier
	s_add_i32 s87, s87, 2
	s_add_u32 s60, s60, 0x100
	s_addc_u32 s61, s61, 0
	s_add_u32 s85, s85, 0x100
	s_addc_u32 s86, s86, 0
	s_cmp_gt_u32 s87, 13
	s_cbranch_scc0 .LBB0_133
	s_and_b64 vcc, exec, s[38:39]
	s_cbranch_vccz .LBB0_136
	s_barrier

; #define PG8_STAGE(bufoff, gbase, voff) do { _Pragma("unroll") for (int _i = 0; _i < 2; ++_i) \
;         __builtin_amdgcn_global_load_lds((const unsigned*)((const char*)(gbase) + (voff)[_i]), (PG8_LAS unsigned*)(lds + (bufoff) + ldsw + _i * 8192), 16, 0, 0); } while (0)
; #define PG8_LDA(dst, b, h) do { _Pragma("unroll") for (int m = 0; m < 4; ++m) _Pragma("unroll") for (int k = 0; k < 2; ++k) dst[m][k] = *(const PG8_LAS bf16x8*)(lds + PG8_SA(b, h) + aoff + m * 2048 + k * 1024); } while (0)
; #define PG8_LDB(dst, b, h) do { _Pragma("unroll") for (int n = 0; n < 2; ++n) _Pragma("unroll") for (int k = 0; k < 2; ++k) dst[n][k] = *(const PG8_LAS bf16x8*)(lds + PG8_SB(b, h) + boff + n * 2048 + k * 1024); } while (0)
; #define PG8_SCHED __builtin_amdgcn_sched_barrier(0)
; template <class Epi, class Sched, bool ALIGN_EPI = false, bool SP2 = false, bool ATILED = false>
; __device__ __forceinline__ void gemm_phase(PG8_LAS unsigned char* lds, const Gemm g, const Sched& S, const Epi& E) {
;     ...
;             const char* a1 = cA + (size_t)(t + 1) * kstepA;
;             const char* a2 = last ? nA : cA + (size_t)(t + 2) * kstepA; const char* b2 = last ? nB : cB + (size_t)(t + 2) * kstep;
;             const char* a3 = a2 + kstepA; const char* b3 = b2 + kstep;
;             if (last && has_next) S.a_ready(nxt);
;             if constexpr (SP2) {
;             PG8_LDB(B0, 0, 0); PG8_LDB(B1, 0, 1); PG8_SCHED; PG8_LDA(At, 0, 0); PG8_STAGE(PG8_SA(1, 1), a1 + hstepA, voffA);
.LBB0_210:
	s_add_u32 s79, s46, 0x100
	s_addc_u32 s80, s47, 0
	s_add_u32 s46, s48, 0xc000
	s_addc_u32 s47, s49, 0
	s_mov_b32 s81, -2
	s_waitcnt lgkmcnt(0)
	ds_read_b128 v[128:131], v189
	ds_read_b128 v[132:135], v189 offset:1024
	ds_read_b128 v[136:139], v189 offset:2048
	ds_read_b128 v[140:143], v189 offset:3072
	ds_read_b128 v[144:147], v190
	ds_read_b128 v[148:151], v190 offset:1024
	ds_read_b128 v[168:171], v190 offset:2048
	ds_read_b128 v[172:175], v190 offset:3072
	s_add_u32 s48, s46, 0x4000
	s_addc_u32 s49, s47, 0
	s_cmp_eq_u32 s81, 40
	s_cselect_b32 s62, s4, s48
	s_cselect_b32 s63, s5, s49
	s_cselect_b32 s60, s44, s79
	s_cselect_b32 s61, s45, s80
	s_add_u32 s48, s62, 0x8000
	s_addc_u32 s49, s63, 0

; #define PG8_STAGE(bufoff, gbase, voff) do { _Pragma("unroll") for (int _i = 0; _i < 2; ++_i) \
;         __builtin_amdgcn_global_load_lds((const unsigned*)((const char*)(gbase) + (voff)[_i]), (PG8_LAS unsigned*)(lds + (bufoff) + ldsw + _i * 8192), 16, 0, 0); } while (0)
; #define PG8_LDA(dst, b, h) do { _Pragma("unroll") for (int m = 0; m < 4; ++m) _Pragma("unroll") for (int k = 0; k < 2; ++k) dst[m][k] = *(const PG8_LAS bf16x8*)(lds + PG8_SA(b, h) + aoff + m * 2048 + k * 1024); } while (0)
; #define PG8_LDB(dst, b, h) do { _Pragma("unroll") for (int n = 0; n < 2; ++n) _Pragma("unroll") for (int k = 0; k < 2; ++k) dst[n][k] = *(const PG8_LAS bf16x8*)(lds + PG8_SB(b, h) + boff + n * 2048 + k * 1024); } while (0)
; #define PG8_SCHED __builtin_amdgcn_sched_barrier(0)
; template <class Epi, class Sched, bool ALIGN_EPI = false, bool SP2 = false, bool ATILED = false>
; __device__ __forceinline__ void gemm_phase(PG8_LAS unsigned char* lds, const Gemm g, const Sched& S, const Epi& E) {
;     ...
;             PG8_LDB(B0, 0, 0); PG8_LDB(B1, 0, 1); PG8_SCHED; PG8_LDA(At, 0, 0); PG8_STAGE(PG8_SA(1, 1), a1 + hstepA, voffA);
	s_add_i32 m0, s65, 0xc000
	ds_read_b128 v[176:179], v191
	ds_read_b128 v[180:183], v191 offset:1024
	ds_read_b128 v[194:197], v191 offset:2048
	ds_read_b128 v[200:203], v191 offset:3072
	ds_read_b128 v[204:207], v191 offset:4096
	ds_read_b128 v[208:211], v191 offset:5120
	ds_read_b128 v[212:215], v191 offset:6144
	ds_read_b128 v[216:219], v191 offset:7168
	global_load_lds_dwordx4 v160, s[46:47]

; #define PG8_STAGE(bufoff, gbase, voff) do { _Pragma("unroll") for (int _i = 0; _i < 2; ++_i) \
;         __builtin_amdgcn_global_load_lds((const unsigned*)((const char*)(gbase) + (voff)[_i]), (PG8_LAS unsigned*)(lds + (bufoff) + ldsw + _i * 8192), 16, 0, 0); } while (0)
; #define PG8_LDA(dst, b, h) do { _Pragma("unroll") for (int m = 0; m < 4; ++m) _Pragma("unroll") for (int k = 0; k < 2; ++k) dst[m][k] = *(const PG8_LAS bf16x8*)(lds + PG8_SA(b, h) + aoff + m * 2048 + k * 1024); } while (0)
; #define PG8_LDB(dst, b, h) do { _Pragma("unroll") for (int n = 0; n < 2; ++n) _Pragma("unroll") for (int k = 0; k < 2; ++k) dst[n][k] = *(const PG8_LAS bf16x8*)(lds + PG8_SB(b, h) + boff + n * 2048 + k * 1024); } while (0)
; #define PG8_MMA(ai, bj, At, Bt) do { __builtin_amdgcn_s_setprio(1); _Pragma("unroll") for (int m = 0; m < 4; ++m) _Pragma("unroll") for (int n = 0; n < 2; ++n) _Pragma("unroll") for (int k = 0; k < 2; ++k) \
;         acc[ai][bj][m][n] = __builtin_amdgcn_mfma_f32_16x16x32_bf16(Bt[n][k], At[m][k], acc[ai][bj][m][n], 0, 0, 0); __builtin_amdgcn_s_setprio(0); } while (0)
; #define PG8_WAIT_V(n) asm volatile("s_waitcnt vmcnt(" #n ")" ::: "memory")
; #define PG8_WAIT_L(n) asm volatile("s_waitcnt lgkmcnt(" #n ")" ::: "memory")
; #define PG8_BAR __builtin_amdgcn_s_barrier()
; #define PG8_SCHED __builtin_amdgcn_sched_barrier(0)
; template <class Epi, class Sched, bool ALIGN_EPI = false, bool SP2 = false, bool ATILED = false>
; __device__ __forceinline__ void gemm_phase(PG8_LAS unsigned char* lds, const Gemm g, const Sched& S, const Epi& E) {
;     ...
;             PG8_LDB(B0, 0, 0); PG8_LDB(B1, 0, 1); PG8_SCHED; PG8_LDA(At, 0, 0); PG8_STAGE(PG8_SA(1, 1), a1 + hstepA, voffA);
;             PG8_WAIT_V(8); PG8_WAIT_L(0); PG8_BAR; PG8_MMA(0, 0, At, B0); PG8_MMA(0, 1, At, B1); PG8_BAR; PG8_SCHED;
	s_add_i32 m0, s65, 0xe000
	s_nop 0
	global_load_lds_dwordx4 v162, s[46:47]
	s_waitcnt vmcnt(8)
	s_waitcnt lgkmcnt(0)
	s_barrier
	s_setprio 1
	s_waitcnt lgkmcnt(0)
	v_mfma_f32_16x16x32_bf16 v[124:127], v[128:131], v[176:179], 0
	v_mfma_f32_16x16x32_bf16 v[120:123], v[136:139], v[176:179], 0
	v_mfma_f32_16x16x32_bf16 v[108:111], v[128:131], v[194:197], 0
	v_mfma_f32_16x16x32_bf16 v[104:107], v[136:139], v[194:197], 0
	v_mfma_f32_16x16x32_bf16 v[92:95], v[128:131], v[204:207], 0
	v_mfma_f32_16x16x32_bf16 v[88:91], v[136:139], v[204:207], 0
	v_mfma_f32_16x16x32_bf16 v[76:79], v[128:131], v[212:215], 0
	v_mfma_f32_16x16x32_bf16 v[72:75], v[136:139], v[212:215], 0
	v_mfma_f32_16x16x32_bf16 v[124:127], v[132:135], v[180:183], v[124:127]
	v_mfma_f32_16x16x32_bf16 v[120:123], v[140:143], v[180:183], v[120:123]
	v_mfma_f32_16x16x32_bf16 v[108:111], v[132:135], v[200:203], v[108:111]
	v_mfma_f32_16x16x32_bf16 v[104:107], v[140:143], v[200:203], v[104:107]
	v_mfma_f32_16x16x32_bf16 v[92:95], v[132:135], v[208:211], v[92:95]
	v_mfma_f32_16x16x32_bf16 v[88:91], v[140:143], v[208:211], v[88:91]
	v_mfma_f32_16x16x32_bf16 v[76:79], v[132:135], v[216:219], v[76:79]
	v_mfma_f32_16x16x32_bf16 v[72:75], v[140:143], v[216:219], v[72:75]
	s_setprio 0
	s_setprio 1
	v_mfma_f32_16x16x32_bf16 v[116:119], v[144:147], v[176:179], 0
	v_mfma_f32_16x16x32_bf16 v[112:115], v[168:171], v[176:179], 0
	v_mfma_f32_16x16x32_bf16 v[100:103], v[144:147], v[194:197], 0
	v_mfma_f32_16x16x32_bf16 v[96:99], v[168:171], v[194:197], 0
	v_mfma_f32_16x16x32_bf16 v[84:87], v[144:147], v[204:207], 0
	v_mfma_f32_16x16x32_bf16 v[80:83], v[168:171], v[204:207], 0
	v_mfma_f32_16x16x32_bf16 v[68:71], v[144:147], v[212:215], 0
	v_mfma_f32_16x16x32_bf16 v[64:67], v[168:171], v[212:215], 0
	v_mfma_f32_16x16x32_bf16 v[116:119], v[148:151], v[180:183], v[116:119]
	v_mfma_f32_16x16x32_bf16 v[112:115], v[172:175], v[180:183], v[112:115]
	v_mfma_f32_16x16x32_bf16 v[100:103], v[148:151], v[200:203], v[100:103]
	v_mfma_f32_16x16x32_bf16 v[96:99], v[172:175], v[200:203], v[96:99]
	v_mfma_f32_16x16x32_bf16 v[84:87], v[148:151], v[208:211], v[84:87]
	v_mfma_f32_16x16x32_bf16 v[80:83], v[172:175], v[208:211], v[80:83]
	v_mfma_f32_16x16x32_bf16 v[68:71], v[148:151], v[216:219], v[68:71]
	v_mfma_f32_16x16x32_bf16 v[64:67], v[172:175], v[216:219], v[64:67]
	s_setprio 0
	s_barrier
	s_add_u32 s98, s60, s40
	s_addc_u32 s99, s61, s41
	s_add_i32 s83, s73, s64

; #define PG8_STAGE(bufoff, gbase, voff) do { _Pragma("unroll") for (int _i = 0; _i < 2; ++_i) \
;         __builtin_amdgcn_global_load_lds((const unsigned*)((const char*)(gbase) + (voff)[_i]), (PG8_LAS unsigned*)(lds + (bufoff) + ldsw + _i * 8192), 16, 0, 0); } while (0)
; #define PG8_LDA(dst, b, h) do { _Pragma("unroll") for (int m = 0; m < 4; ++m) _Pragma("unroll") for (int k = 0; k < 2; ++k) dst[m][k] = *(const PG8_LAS bf16x8*)(lds + PG8_SA(b, h) + aoff + m * 2048 + k * 1024); } while (0)
; template <class Epi, class Sched, bool ALIGN_EPI = false, bool SP2 = false, bool ATILED = false>
; __device__ __forceinline__ void gemm_phase(PG8_LAS unsigned char* lds, const Gemm g, const Sched& S, const Epi& E) {
;     ...
;             PG8_LDA(At, 0, 1); PG8_STAGE(PG8_SB(0, 0), b2, voffB); PG8_STAGE(PG8_SB(0, 1), b2 + hstep, voffB); PG8_STAGE(PG8_SA(0, 0), a2, voffA);
	s_mov_b32 m0, s83
	ds_read_b128 v[176:179], v191 offset:16384
	ds_read_b128 v[180:183], v191 offset:17408
	ds_read_b128 v[194:197], v191 offset:18432
	ds_read_b128 v[200:203], v191 offset:19456
	ds_read_b128 v[204:207], v191 offset:20480
	ds_read_b128 v[208:211], v191 offset:21504
	ds_read_b128 v[212:215], v191 offset:22528
	ds_read_b128 v[216:219], v191 offset:23552
	global_load_lds_dwordx4 v154, s[60:61]
	s_add_i32 m0, s83, 0x2000
	s_add_u32 s84, s60, 0xb0000

; #define PG8_STAGE(bufoff, gbase, voff) do { _Pragma("unroll") for (int _i = 0; _i < 2; ++_i) \
;         __builtin_amdgcn_global_load_lds((const unsigned*)((const char*)(gbase) + (voff)[_i]), (PG8_LAS unsigned*)(lds + (bufoff) + ldsw + _i * 8192), 16, 0, 0); } while (0)
; #define PG8_LDA(dst, b, h) do { _Pragma("unroll") for (int m = 0; m < 4; ++m) _Pragma("unroll") for (int k = 0; k < 2; ++k) dst[m][k] = *(const PG8_LAS bf16x8*)(lds + PG8_SA(b, h) + aoff + m * 2048 + k * 1024); } while (0)
; template <class Epi, class Sched, bool ALIGN_EPI = false, bool SP2 = false, bool ATILED = false>
; __device__ __forceinline__ void gemm_phase(PG8_LAS unsigned char* lds, const Gemm g, const Sched& S, const Epi& E) {
;     ...
;             PG8_LDA(At, 0, 1); PG8_STAGE(PG8_SB(0, 0), b2, voffB); PG8_STAGE(PG8_SB(0, 1), b2 + hstep, voffB); PG8_STAGE(PG8_SA(0, 0), a2, voffA);
	s_addc_u32 s85, s61, 0
	s_add_i32 s83, s74, s64
	global_load_lds_dwordx4 v158, s[60:61]

; #define PG8_STAGE(bufoff, gbase, voff) do { _Pragma("unroll") for (int _i = 0; _i < 2; ++_i) \
;         __builtin_amdgcn_global_load_lds((const unsigned*)((const char*)(gbase) + (voff)[_i]), (PG8_LAS unsigned*)(lds + (bufoff) + ldsw + _i * 8192), 16, 0, 0); } while (0)
; #define PG8_LDA(dst, b, h) do { _Pragma("unroll") for (int m = 0; m < 4; ++m) _Pragma("unroll") for (int k = 0; k < 2; ++k) dst[m][k] = *(const PG8_LAS bf16x8*)(lds + PG8_SA(b, h) + aoff + m * 2048 + k * 1024); } while (0)
; template <class Epi, class Sched, bool ALIGN_EPI = false, bool SP2 = false, bool ATILED = false>
; __device__ __forceinline__ void gemm_phase(PG8_LAS unsigned char* lds, const Gemm g, const Sched& S, const Epi& E) {
;     ...
;             PG8_LDA(At, 0, 1); PG8_STAGE(PG8_SB(0, 0), b2, voffB); PG8_STAGE(PG8_SB(0, 1), b2 + hstep, voffB); PG8_STAGE(PG8_SA(0, 0), a2, voffA);
	s_mov_b32 m0, s83
	s_nop 0
	global_load_lds_dwordx4 v154, s[84:85]

; #define PG8_STAGE(bufoff, gbase, voff) do { _Pragma("unroll") for (int _i = 0; _i < 2; ++_i) \
;         __builtin_amdgcn_global_load_lds((const unsigned*)((const char*)(gbase) + (voff)[_i]), (PG8_LAS unsigned*)(lds + (bufoff) + ldsw + _i * 8192), 16, 0, 0); } while (0)
; #define PG8_LDA(dst, b, h) do { _Pragma("unroll") for (int m = 0; m < 4; ++m) _Pragma("unroll") for (int k = 0; k < 2; ++k) dst[m][k] = *(const PG8_LAS bf16x8*)(lds + PG8_SA(b, h) + aoff + m * 2048 + k * 1024); } while (0)
; template <class Epi, class Sched, bool ALIGN_EPI = false, bool SP2 = false, bool ATILED = false>
; __device__ __forceinline__ void gemm_phase(PG8_LAS unsigned char* lds, const Gemm g, const Sched& S, const Epi& E) {
;     ...
;             PG8_LDA(At, 0, 1); PG8_STAGE(PG8_SB(0, 0), b2, voffB); PG8_STAGE(PG8_SB(0, 1), b2 + hstep, voffB); PG8_STAGE(PG8_SA(0, 0), a2, voffA);
	s_add_i32 m0, s83, 0x2000
	s_nop 0
	global_load_lds_dwordx4 v158, s[84:85]

; #define PG8_STAGE(bufoff, gbase, voff) do { _Pragma("unroll") for (int _i = 0; _i < 2; ++_i) \
;         __builtin_amdgcn_global_load_lds((const unsigned*)((const char*)(gbase) + (voff)[_i]), (PG8_LAS unsigned*)(lds + (bufoff) + ldsw + _i * 8192), 16, 0, 0); } while (0)
; #define PG8_LDA(dst, b, h) do { _Pragma("unroll") for (int m = 0; m < 4; ++m) _Pragma("unroll") for (int k = 0; k < 2; ++k) dst[m][k] = *(const PG8_LAS bf16x8*)(lds + PG8_SA(b, h) + aoff + m * 2048 + k * 1024); } while (0)
; template <class Epi, class Sched, bool ALIGN_EPI = false, bool SP2 = false, bool ATILED = false>
; __device__ __forceinline__ void gemm_phase(PG8_LAS unsigned char* lds, const Gemm g, const Sched& S, const Epi& E) {
;     ...
;             PG8_LDA(At, 0, 1); PG8_STAGE(PG8_SB(0, 0), b2, voffB); PG8_STAGE(PG8_SB(0, 1), b2 + hstep, voffB); PG8_STAGE(PG8_SA(0, 0), a2, voffA);
	s_mov_b32 m0, s65
	s_nop 0
	global_load_lds_dwordx4 v152, s[62:63]

; #define PG8_STAGE(bufoff, gbase, voff) do { _Pragma("unroll") for (int _i = 0; _i < 2; ++_i) \
;         __builtin_amdgcn_global_load_lds((const unsigned*)((const char*)(gbase) + (voff)[_i]), (PG8_LAS unsigned*)(lds + (bufoff) + ldsw + _i * 8192), 16, 0, 0); } while (0)
; #define PG8_LDA(dst, b, h) do { _Pragma("unroll") for (int m = 0; m < 4; ++m) _Pragma("unroll") for (int k = 0; k < 2; ++k) dst[m][k] = *(const PG8_LAS bf16x8*)(lds + PG8_SA(b, h) + aoff + m * 2048 + k * 1024); } while (0)
; #define PG8_LDB(dst, b, h) do { _Pragma("unroll") for (int n = 0; n < 2; ++n) _Pragma("unroll") for (int k = 0; k < 2; ++k) dst[n][k] = *(const PG8_LAS bf16x8*)(lds + PG8_SB(b, h) + boff + n * 2048 + k * 1024); } while (0)
; #define PG8_MMA(ai, bj, At, Bt) do { __builtin_amdgcn_s_setprio(1); _Pragma("unroll") for (int m = 0; m < 4; ++m) _Pragma("unroll") for (int n = 0; n < 2; ++n) _Pragma("unroll") for (int k = 0; k < 2; ++k) \
;         acc[ai][bj][m][n] = __builtin_amdgcn_mfma_f32_16x16x32_bf16(Bt[n][k], At[m][k], acc[ai][bj][m][n], 0, 0, 0); __builtin_amdgcn_s_setprio(0); } while (0)
; #define PG8_WAIT_V(n) asm volatile("s_waitcnt vmcnt(" #n ")" ::: "memory")
; #define PG8_WAIT_L(n) asm volatile("s_waitcnt lgkmcnt(" #n ")" ::: "memory")
; #define PG8_BAR __builtin_amdgcn_s_barrier()
; #define PG8_SCHED __builtin_amdgcn_sched_barrier(0)
; template <class Epi, class Sched, bool ALIGN_EPI = false, bool SP2 = false, bool ATILED = false>
; __device__ __forceinline__ void gemm_phase(PG8_LAS unsigned char* lds, const Gemm g, const Sched& S, const Epi& E) {
;     ...
;             PG8_LDA(At, 0, 1); PG8_STAGE(PG8_SB(0, 0), b2, voffB); PG8_STAGE(PG8_SB(0, 1), b2 + hstep, voffB); PG8_STAGE(PG8_SA(0, 0), a2, voffA);
;             PG8_WAIT_V(8); PG8_WAIT_L(0); PG8_BAR; PG8_MMA(1, 0, At, B0); PG8_MMA(1, 1, At, B1); PG8_BAR; PG8_SCHED;
;             PG8_LDB(B0, 1, 0); PG8_LDB(B1, 1, 1); PG8_SCHED; PG8_LDA(At, 1, 0); PG8_STAGE(PG8_SA(0, 1), a2 + hstepA, voffA);
	s_mov_b32 m0, s66
	s_nop 0
	global_load_lds_dwordx4 v156, s[62:63]
	s_waitcnt vmcnt(8)
	s_waitcnt lgkmcnt(0)
	s_barrier
	s_setprio 1
	s_waitcnt lgkmcnt(0)
	v_mfma_f32_16x16x32_bf16 v[60:63], v[128:131], v[176:179], 0
	v_mfma_f32_16x16x32_bf16 v[56:59], v[136:139], v[176:179], 0
	v_mfma_f32_16x16x32_bf16 v[44:47], v[128:131], v[194:197], 0
	v_mfma_f32_16x16x32_bf16 v[40:43], v[136:139], v[194:197], 0
	v_mfma_f32_16x16x32_bf16 v[28:31], v[128:131], v[204:207], 0
	v_mfma_f32_16x16x32_bf16 v[24:27], v[136:139], v[204:207], 0
	v_mfma_f32_16x16x32_bf16 v[12:15], v[128:131], v[212:215], 0
	v_mfma_f32_16x16x32_bf16 v[8:11], v[136:139], v[212:215], 0
	v_mfma_f32_16x16x32_bf16 v[60:63], v[132:135], v[180:183], v[60:63]
	v_mfma_f32_16x16x32_bf16 v[56:59], v[140:143], v[180:183], v[56:59]
	v_mfma_f32_16x16x32_bf16 v[44:47], v[132:135], v[200:203], v[44:47]
	v_mfma_f32_16x16x32_bf16 v[40:43], v[140:143], v[200:203], v[40:43]
	v_mfma_f32_16x16x32_bf16 v[28:31], v[132:135], v[208:211], v[28:31]
	v_mfma_f32_16x16x32_bf16 v[24:27], v[140:143], v[208:211], v[24:27]
	v_mfma_f32_16x16x32_bf16 v[12:15], v[132:135], v[216:219], v[12:15]
	v_mfma_f32_16x16x32_bf16 v[8:11], v[140:143], v[216:219], v[8:11]
	s_setprio 0
	s_setprio 1
	v_mfma_f32_16x16x32_bf16 v[52:55], v[144:147], v[176:179], 0
	v_mfma_f32_16x16x32_bf16 v[48:51], v[168:171], v[176:179], 0
	v_mfma_f32_16x16x32_bf16 v[36:39], v[144:147], v[194:197], 0
	v_mfma_f32_16x16x32_bf16 v[32:35], v[168:171], v[194:197], 0
	v_mfma_f32_16x16x32_bf16 v[20:23], v[144:147], v[204:207], 0
	v_mfma_f32_16x16x32_bf16 v[16:19], v[168:171], v[204:207], 0
	v_mfma_f32_16x16x32_bf16 v[4:7], v[144:147], v[212:215], 0
	v_mfma_f32_16x16x32_bf16 v[0:3], v[168:171], v[212:215], 0
	v_mfma_f32_16x16x32_bf16 v[52:55], v[148:151], v[180:183], v[52:55]
	v_mfma_f32_16x16x32_bf16 v[48:51], v[172:175], v[180:183], v[48:51]
	v_mfma_f32_16x16x32_bf16 v[36:39], v[148:151], v[200:203], v[36:39]
	v_mfma_f32_16x16x32_bf16 v[32:35], v[172:175], v[200:203], v[32:35]
	v_mfma_f32_16x16x32_bf16 v[20:23], v[148:151], v[208:211], v[20:23]
	v_mfma_f32_16x16x32_bf16 v[16:19], v[172:175], v[208:211], v[16:19]
	v_mfma_f32_16x16x32_bf16 v[4:7], v[148:151], v[216:219], v[4:7]
	v_mfma_f32_16x16x32_bf16 v[0:3], v[172:175], v[216:219], v[0:3]
	s_setprio 0
	s_barrier
	s_add_i32 s83, 0, 0x18000
	s_add_i32 s84, 0, 0x1c000
	v_add_u32_e32 v140, s83, v187
	v_add_u32_e32 v172, s84, v187
	ds_read_b128 v[128:131], v140
	ds_read_b128 v[132:135], v140 offset:1024
	ds_read_b128 v[136:139], v140 offset:2048
	ds_read_b128 v[140:143], v140 offset:3072
	ds_read_b128 v[144:147], v172
	ds_read_b128 v[148:151], v172 offset:1024
	ds_read_b128 v[168:171], v172 offset:2048
	ds_read_b128 v[172:175], v172 offset:3072
	s_add_u32 s62, s62, 0x4000
	s_addc_u32 s63, s63, 0
	s_mov_b32 m0, s67

; #define PG8_STAGE(bufoff, gbase, voff) do { _Pragma("unroll") for (int _i = 0; _i < 2; ++_i) \
;         __builtin_amdgcn_global_load_lds((const unsigned*)((const char*)(gbase) + (voff)[_i]), (PG8_LAS unsigned*)(lds + (bufoff) + ldsw + _i * 8192), 16, 0, 0); } while (0)
; #define PG8_LDA(dst, b, h) do { _Pragma("unroll") for (int m = 0; m < 4; ++m) _Pragma("unroll") for (int k = 0; k < 2; ++k) dst[m][k] = *(const PG8_LAS bf16x8*)(lds + PG8_SA(b, h) + aoff + m * 2048 + k * 1024); } while (0)
; #define PG8_LDB(dst, b, h) do { _Pragma("unroll") for (int n = 0; n < 2; ++n) _Pragma("unroll") for (int k = 0; k < 2; ++k) dst[n][k] = *(const PG8_LAS bf16x8*)(lds + PG8_SB(b, h) + boff + n * 2048 + k * 1024); } while (0)
; #define PG8_SCHED __builtin_amdgcn_sched_barrier(0)
; template <class Epi, class Sched, bool ALIGN_EPI = false, bool SP2 = false, bool ATILED = false>
; __device__ __forceinline__ void gemm_phase(PG8_LAS unsigned char* lds, const Gemm g, const Sched& S, const Epi& E) {
;     ...
;             PG8_LDB(B0, 1, 0); PG8_LDB(B1, 1, 1); PG8_SCHED; PG8_LDA(At, 1, 0); PG8_STAGE(PG8_SA(0, 1), a2 + hstepA, voffA);
	ds_read_b128 v[176:179], v191 offset:32768
	ds_read_b128 v[180:183], v191 offset:33792
	ds_read_b128 v[194:197], v191 offset:34816
	ds_read_b128 v[200:203], v191 offset:35840
	ds_read_b128 v[204:207], v191 offset:36864
	ds_read_b128 v[208:211], v191 offset:37888
	ds_read_b128 v[212:215], v191 offset:38912
	ds_read_b128 v[216:219], v191 offset:39936
	global_load_lds_dwordx4 v152, s[62:63]

; #define PG8_STAGE(bufoff, gbase, voff) do { _Pragma("unroll") for (int _i = 0; _i < 2; ++_i) \
;         __builtin_amdgcn_global_load_lds((const unsigned*)((const char*)(gbase) + (voff)[_i]), (PG8_LAS unsigned*)(lds + (bufoff) + ldsw + _i * 8192), 16, 0, 0); } while (0)
; #define PG8_LDA(dst, b, h) do { _Pragma("unroll") for (int m = 0; m < 4; ++m) _Pragma("unroll") for (int k = 0; k < 2; ++k) dst[m][k] = *(const PG8_LAS bf16x8*)(lds + PG8_SA(b, h) + aoff + m * 2048 + k * 1024); } while (0)
; #define PG8_LDB(dst, b, h) do { _Pragma("unroll") for (int n = 0; n < 2; ++n) _Pragma("unroll") for (int k = 0; k < 2; ++k) dst[n][k] = *(const PG8_LAS bf16x8*)(lds + PG8_SB(b, h) + boff + n * 2048 + k * 1024); } while (0)
; #define PG8_MMA(ai, bj, At, Bt) do { __builtin_amdgcn_s_setprio(1); _Pragma("unroll") for (int m = 0; m < 4; ++m) _Pragma("unroll") for (int n = 0; n < 2; ++n) _Pragma("unroll") for (int k = 0; k < 2; ++k) \
;         acc[ai][bj][m][n] = __builtin_amdgcn_mfma_f32_16x16x32_bf16(Bt[n][k], At[m][k], acc[ai][bj][m][n], 0, 0, 0); __builtin_amdgcn_s_setprio(0); } while (0)
; #define PG8_WAIT_V(n) asm volatile("s_waitcnt vmcnt(" #n ")" ::: "memory")
; #define PG8_WAIT_L(n) asm volatile("s_waitcnt lgkmcnt(" #n ")" ::: "memory")
; #define PG8_BAR __builtin_amdgcn_s_barrier()
; #define PG8_SCHED __builtin_amdgcn_sched_barrier(0)
; template <class Epi, class Sched, bool ALIGN_EPI = false, bool SP2 = false, bool ATILED = false>
; __device__ __forceinline__ void gemm_phase(PG8_LAS unsigned char* lds, const Gemm g, const Sched& S, const Epi& E) {
;     ...
;             PG8_LDB(B0, 1, 0); PG8_LDB(B1, 1, 1); PG8_SCHED; PG8_LDA(At, 1, 0); PG8_STAGE(PG8_SA(0, 1), a2 + hstepA, voffA);
;             PG8_WAIT_V(8); PG8_WAIT_L(0); PG8_BAR; PG8_MMA(0, 0, At, B0); PG8_MMA(0, 1, At, B1); PG8_BAR; PG8_SCHED;
	s_mov_b32 m0, s68
	s_nop 0
	global_load_lds_dwordx4 v156, s[62:63]
	s_waitcnt vmcnt(8)
	s_waitcnt lgkmcnt(0)
	s_barrier
	s_setprio 1
	s_waitcnt lgkmcnt(0)
	v_mfma_f32_16x16x32_bf16 v[124:127], v[128:131], v[176:179], v[124:127]
	v_mfma_f32_16x16x32_bf16 v[120:123], v[136:139], v[176:179], v[120:123]
	v_mfma_f32_16x16x32_bf16 v[108:111], v[128:131], v[194:197], v[108:111]
	v_mfma_f32_16x16x32_bf16 v[104:107], v[136:139], v[194:197], v[104:107]
	v_mfma_f32_16x16x32_bf16 v[92:95], v[128:131], v[204:207], v[92:95]
	v_mfma_f32_16x16x32_bf16 v[88:91], v[136:139], v[204:207], v[88:91]
	v_mfma_f32_16x16x32_bf16 v[76:79], v[128:131], v[212:215], v[76:79]
	v_mfma_f32_16x16x32_bf16 v[72:75], v[136:139], v[212:215], v[72:75]
	v_mfma_f32_16x16x32_bf16 v[124:127], v[132:135], v[180:183], v[124:127]
	v_mfma_f32_16x16x32_bf16 v[120:123], v[140:143], v[180:183], v[120:123]
	v_mfma_f32_16x16x32_bf16 v[108:111], v[132:135], v[200:203], v[108:111]
	v_mfma_f32_16x16x32_bf16 v[104:107], v[140:143], v[200:203], v[104:107]
	v_mfma_f32_16x16x32_bf16 v[92:95], v[132:135], v[208:211], v[92:95]
	v_mfma_f32_16x16x32_bf16 v[88:91], v[140:143], v[208:211], v[88:91]
	v_mfma_f32_16x16x32_bf16 v[76:79], v[132:135], v[216:219], v[76:79]
	v_mfma_f32_16x16x32_bf16 v[72:75], v[140:143], v[216:219], v[72:75]
	s_setprio 0
	s_setprio 1
	v_mfma_f32_16x16x32_bf16 v[116:119], v[144:147], v[176:179], v[116:119]
	v_mfma_f32_16x16x32_bf16 v[112:115], v[168:171], v[176:179], v[112:115]
	v_mfma_f32_16x16x32_bf16 v[100:103], v[144:147], v[194:197], v[100:103]
	v_mfma_f32_16x16x32_bf16 v[96:99], v[168:171], v[194:197], v[96:99]
	v_mfma_f32_16x16x32_bf16 v[84:87], v[144:147], v[204:207], v[84:87]
	v_mfma_f32_16x16x32_bf16 v[80:83], v[168:171], v[204:207], v[80:83]
	v_mfma_f32_16x16x32_bf16 v[68:71], v[144:147], v[212:215], v[68:71]
	v_mfma_f32_16x16x32_bf16 v[64:67], v[168:171], v[212:215], v[64:67]
	v_mfma_f32_16x16x32_bf16 v[116:119], v[148:151], v[180:183], v[116:119]
	v_mfma_f32_16x16x32_bf16 v[112:115], v[172:175], v[180:183], v[112:115]
	v_mfma_f32_16x16x32_bf16 v[100:103], v[148:151], v[200:203], v[100:103]
	v_mfma_f32_16x16x32_bf16 v[96:99], v[172:175], v[200:203], v[96:99]
	v_mfma_f32_16x16x32_bf16 v[84:87], v[148:151], v[208:211], v[84:87]
	v_mfma_f32_16x16x32_bf16 v[80:83], v[172:175], v[208:211], v[80:83]
	v_mfma_f32_16x16x32_bf16 v[68:71], v[148:151], v[216:219], v[68:71]
	v_mfma_f32_16x16x32_bf16 v[64:67], v[172:175], v[216:219], v[64:67]
	s_setprio 0
	s_barrier
	s_add_i32 s62, s83, s64

; #define PG8_STAGE(bufoff, gbase, voff) do { _Pragma("unroll") for (int _i = 0; _i < 2; ++_i) \
;         __builtin_amdgcn_global_load_lds((const unsigned*)((const char*)(gbase) + (voff)[_i]), (PG8_LAS unsigned*)(lds + (bufoff) + ldsw + _i * 8192), 16, 0, 0); } while (0)
; #define PG8_LDA(dst, b, h) do { _Pragma("unroll") for (int m = 0; m < 4; ++m) _Pragma("unroll") for (int k = 0; k < 2; ++k) dst[m][k] = *(const PG8_LAS bf16x8*)(lds + PG8_SA(b, h) + aoff + m * 2048 + k * 1024); } while (0)
; template <class Epi, class Sched, bool ALIGN_EPI = false, bool SP2 = false, bool ATILED = false>
; __device__ __forceinline__ void gemm_phase(PG8_LAS unsigned char* lds, const Gemm g, const Sched& S, const Epi& E) {
;     ...
;             PG8_LDA(At, 1, 1); PG8_STAGE(PG8_SB(1, 0), b3, voffB); PG8_STAGE(PG8_SB(1, 1), b3 + hstep, voffB); PG8_STAGE(PG8_SA(1, 0), a3, voffA);
	s_mov_b32 m0, s62
	ds_read_b128 v[176:179], v191 offset:49152
	ds_read_b128 v[180:183], v191 offset:50176
	ds_read_b128 v[194:197], v191 offset:51200
	ds_read_b128 v[200:203], v191 offset:52224
	ds_read_b128 v[204:207], v191 offset:53248
	ds_read_b128 v[208:211], v191 offset:54272
	ds_read_b128 v[212:215], v191 offset:55296
	ds_read_b128 v[216:219], v191 offset:56320
	global_load_lds_dwordx4 v154, s[98:99]
	s_add_i32 m0, s62, 0x2000
	s_add_u32 s60, s60, 0xb0080

; #define PG8_STAGE(bufoff, gbase, voff) do { _Pragma("unroll") for (int _i = 0; _i < 2; ++_i) \
;         __builtin_amdgcn_global_load_lds((const unsigned*)((const char*)(gbase) + (voff)[_i]), (PG8_LAS unsigned*)(lds + (bufoff) + ldsw + _i * 8192), 16, 0, 0); } while (0)
; #define PG8_LDA(dst, b, h) do { _Pragma("unroll") for (int m = 0; m < 4; ++m) _Pragma("unroll") for (int k = 0; k < 2; ++k) dst[m][k] = *(const PG8_LAS bf16x8*)(lds + PG8_SA(b, h) + aoff + m * 2048 + k * 1024); } while (0)
; template <class Epi, class Sched, bool ALIGN_EPI = false, bool SP2 = false, bool ATILED = false>
; __device__ __forceinline__ void gemm_phase(PG8_LAS unsigned char* lds, const Gemm g, const Sched& S, const Epi& E) {
;     ...
;             PG8_LDA(At, 1, 1); PG8_STAGE(PG8_SB(1, 0), b3, voffB); PG8_STAGE(PG8_SB(1, 1), b3 + hstep, voffB); PG8_STAGE(PG8_SA(1, 0), a3, voffA);
	s_addc_u32 s61, s61, 0
	s_add_i32 s62, s84, s64
	global_load_lds_dwordx4 v158, s[98:99]

; #define PG8_STAGE(bufoff, gbase, voff) do { _Pragma("unroll") for (int _i = 0; _i < 2; ++_i) \
;         __builtin_amdgcn_global_load_lds((const unsigned*)((const char*)(gbase) + (voff)[_i]), (PG8_LAS unsigned*)(lds + (bufoff) + ldsw + _i * 8192), 16, 0, 0); } while (0)
; #define PG8_LDA(dst, b, h) do { _Pragma("unroll") for (int m = 0; m < 4; ++m) _Pragma("unroll") for (int k = 0; k < 2; ++k) dst[m][k] = *(const PG8_LAS bf16x8*)(lds + PG8_SA(b, h) + aoff + m * 2048 + k * 1024); } while (0)
; template <class Epi, class Sched, bool ALIGN_EPI = false, bool SP2 = false, bool ATILED = false>
; __device__ __forceinline__ void gemm_phase(PG8_LAS unsigned char* lds, const Gemm g, const Sched& S, const Epi& E) {
;     ...
;             PG8_LDA(At, 1, 1); PG8_STAGE(PG8_SB(1, 0), b3, voffB); PG8_STAGE(PG8_SB(1, 1), b3 + hstep, voffB); PG8_STAGE(PG8_SA(1, 0), a3, voffA);
	s_mov_b32 m0, s62
	s_nop 0
	global_load_lds_dwordx4 v154, s[60:61]

; #define PG8_STAGE(bufoff, gbase, voff) do { _Pragma("unroll") for (int _i = 0; _i < 2; ++_i) \
;         __builtin_amdgcn_global_load_lds((const unsigned*)((const char*)(gbase) + (voff)[_i]), (PG8_LAS unsigned*)(lds + (bufoff) + ldsw + _i * 8192), 16, 0, 0); } while (0)
; #define PG8_LDA(dst, b, h) do { _Pragma("unroll") for (int m = 0; m < 4; ++m) _Pragma("unroll") for (int k = 0; k < 2; ++k) dst[m][k] = *(const PG8_LAS bf16x8*)(lds + PG8_SA(b, h) + aoff + m * 2048 + k * 1024); } while (0)
; template <class Epi, class Sched, bool ALIGN_EPI = false, bool SP2 = false, bool ATILED = false>
; __device__ __forceinline__ void gemm_phase(PG8_LAS unsigned char* lds, const Gemm g, const Sched& S, const Epi& E) {
;     ...
;             PG8_LDA(At, 1, 1); PG8_STAGE(PG8_SB(1, 0), b3, voffB); PG8_STAGE(PG8_SB(1, 1), b3 + hstep, voffB); PG8_STAGE(PG8_SA(1, 0), a3, voffA);
	s_add_i32 m0, s62, 0x2000
	s_nop 0
	global_load_lds_dwordx4 v158, s[60:61]

; #define PG8_STAGE(bufoff, gbase, voff) do { _Pragma("unroll") for (int _i = 0; _i < 2; ++_i) \
;         __builtin_amdgcn_global_load_lds((const unsigned*)((const char*)(gbase) + (voff)[_i]), (PG8_LAS unsigned*)(lds + (bufoff) + ldsw + _i * 8192), 16, 0, 0); } while (0)
; #define PG8_LDA(dst, b, h) do { _Pragma("unroll") for (int m = 0; m < 4; ++m) _Pragma("unroll") for (int k = 0; k < 2; ++k) dst[m][k] = *(const PG8_LAS bf16x8*)(lds + PG8_SA(b, h) + aoff + m * 2048 + k * 1024); } while (0)
; template <class Epi, class Sched, bool ALIGN_EPI = false, bool SP2 = false, bool ATILED = false>
; __device__ __forceinline__ void gemm_phase(PG8_LAS unsigned char* lds, const Gemm g, const Sched& S, const Epi& E) {
;     ...
;             PG8_LDA(At, 1, 1); PG8_STAGE(PG8_SB(1, 0), b3, voffB); PG8_STAGE(PG8_SB(1, 1), b3 + hstep, voffB); PG8_STAGE(PG8_SA(1, 0), a3, voffA);
	s_mov_b32 m0, s71
	s_nop 0
	global_load_lds_dwordx4 v152, s[48:49]

; #define PG8_STAGE(bufoff, gbase, voff) do { _Pragma("unroll") for (int _i = 0; _i < 2; ++_i) \
;         __builtin_amdgcn_global_load_lds((const unsigned*)((const char*)(gbase) + (voff)[_i]), (PG8_LAS unsigned*)(lds + (bufoff) + ldsw + _i * 8192), 16, 0, 0); } while (0)
; #define PG8_LDA(dst, b, h) do { _Pragma("unroll") for (int m = 0; m < 4; ++m) _Pragma("unroll") for (int k = 0; k < 2; ++k) dst[m][k] = *(const PG8_LAS bf16x8*)(lds + PG8_SA(b, h) + aoff + m * 2048 + k * 1024); } while (0)
; #define PG8_LDB(dst, b, h) do { _Pragma("unroll") for (int n = 0; n < 2; ++n) _Pragma("unroll") for (int k = 0; k < 2; ++k) dst[n][k] = *(const PG8_LAS bf16x8*)(lds + PG8_SB(b, h) + boff + n * 2048 + k * 1024); } while (0)
; #define PG8_BAR __builtin_amdgcn_s_barrier()
; template <class Epi, class Sched, bool ALIGN_EPI = false, bool SP2 = false, bool ATILED = false>
; __device__ __forceinline__ void gemm_phase(PG8_LAS unsigned char* lds, const Gemm g, const Sched& S, const Epi& E) {
;     ...
;             const char* a1 = cA + (size_t)(t + 1) * kstepA;
;             const char* a2 = last ? nA : cA + (size_t)(t + 2) * kstepA; const char* b2 = last ? nB : cB + (size_t)(t + 2) * kstep;
;             const char* a3 = a2 + kstepA; const char* b3 = b2 + kstep;
;             if (last && has_next) S.a_ready(nxt);
;             if constexpr (SP2) {
;             PG8_LDB(B0, 0, 0); PG8_LDB(B1, 0, 1); PG8_SCHED; PG8_LDA(At, 0, 0); PG8_STAGE(PG8_SA(1, 1), a1 + hstepA, voffA);
;             PG8_WAIT_V(8); PG8_WAIT_L(0); PG8_BAR; PG8_MMA(0, 0, At, B0); PG8_MMA(0, 1, At, B1); PG8_BAR; PG8_SCHED;
;             PG8_LDA(At, 0, 1); PG8_STAGE(PG8_SB(0, 0), b2, voffB); PG8_STAGE(PG8_SB(0, 1), b2 + hstep, voffB); PG8_STAGE(PG8_SA(0, 0), a2, voffA);
;             PG8_WAIT_V(8); PG8_WAIT_L(0); PG8_BAR; PG8_MMA(1, 0, At, B0); PG8_MMA(1, 1, At, B1); PG8_BAR; PG8_SCHED;
;             PG8_LDB(B0, 1, 0); PG8_LDB(B1, 1, 1); PG8_SCHED; PG8_LDA(At, 1, 0); PG8_STAGE(PG8_SA(0, 1), a2 + hstepA, voffA);
;             PG8_WAIT_V(8); PG8_WAIT_L(0); PG8_BAR; PG8_MMA(0, 0, At, B0); PG8_MMA(0, 1, At, B1); PG8_BAR; PG8_SCHED;
;             PG8_LDA(At, 1, 1); PG8_STAGE(PG8_SB(1, 0), b3, voffB); PG8_STAGE(PG8_SB(1, 1), b3 + hstep, voffB); PG8_STAGE(PG8_SA(1, 0), a3, voffA);
;             PG8_WAIT_V(8); PG8_WAIT_L(0); PG8_BAR; PG8_MMA(1, 0, At, B0); PG8_MMA(1, 1, At, B1); PG8_BAR; PG8_SCHED;
	s_mov_b32 m0, s72
	s_nop 0
	global_load_lds_dwordx4 v156, s[48:49]
	s_waitcnt vmcnt(8)
	s_waitcnt lgkmcnt(0)
	s_barrier
	s_setprio 1
	s_waitcnt lgkmcnt(0)
	v_mfma_f32_16x16x32_bf16 v[60:63], v[128:131], v[176:179], v[60:63]
	v_mfma_f32_16x16x32_bf16 v[56:59], v[136:139], v[176:179], v[56:59]
	v_mfma_f32_16x16x32_bf16 v[44:47], v[128:131], v[194:197], v[44:47]
	v_mfma_f32_16x16x32_bf16 v[40:43], v[136:139], v[194:197], v[40:43]
	v_mfma_f32_16x16x32_bf16 v[28:31], v[128:131], v[204:207], v[28:31]
	v_mfma_f32_16x16x32_bf16 v[24:27], v[136:139], v[204:207], v[24:27]
	v_mfma_f32_16x16x32_bf16 v[12:15], v[128:131], v[212:215], v[12:15]
	v_mfma_f32_16x16x32_bf16 v[8:11], v[136:139], v[212:215], v[8:11]
	v_mfma_f32_16x16x32_bf16 v[60:63], v[132:135], v[180:183], v[60:63]
	v_mfma_f32_16x16x32_bf16 v[56:59], v[140:143], v[180:183], v[56:59]
	v_mfma_f32_16x16x32_bf16 v[44:47], v[132:135], v[200:203], v[44:47]
	v_mfma_f32_16x16x32_bf16 v[40:43], v[140:143], v[200:203], v[40:43]
	v_mfma_f32_16x16x32_bf16 v[28:31], v[132:135], v[208:211], v[28:31]
	v_mfma_f32_16x16x32_bf16 v[24:27], v[140:143], v[208:211], v[24:27]
	v_mfma_f32_16x16x32_bf16 v[12:15], v[132:135], v[216:219], v[12:15]
	v_mfma_f32_16x16x32_bf16 v[8:11], v[140:143], v[216:219], v[8:11]
	s_setprio 0
	s_setprio 1
	v_mfma_f32_16x16x32_bf16 v[52:55], v[144:147], v[176:179], v[52:55]
	v_mfma_f32_16x16x32_bf16 v[48:51], v[168:171], v[176:179], v[48:51]
	v_mfma_f32_16x16x32_bf16 v[36:39], v[144:147], v[194:197], v[36:39]
	v_mfma_f32_16x16x32_bf16 v[32:35], v[168:171], v[194:197], v[32:35]
	v_mfma_f32_16x16x32_bf16 v[20:23], v[144:147], v[204:207], v[20:23]
	v_mfma_f32_16x16x32_bf16 v[16:19], v[168:171], v[204:207], v[16:19]
	v_mfma_f32_16x16x32_bf16 v[4:7], v[144:147], v[212:215], v[4:7]
	v_mfma_f32_16x16x32_bf16 v[0:3], v[168:171], v[212:215], v[0:3]
	v_mfma_f32_16x16x32_bf16 v[52:55], v[148:151], v[180:183], v[52:55]
	v_mfma_f32_16x16x32_bf16 v[48:51], v[172:175], v[180:183], v[48:51]
	v_mfma_f32_16x16x32_bf16 v[36:39], v[148:151], v[200:203], v[36:39]
	v_mfma_f32_16x16x32_bf16 v[32:35], v[172:175], v[200:203], v[32:35]
	v_mfma_f32_16x16x32_bf16 v[20:23], v[148:151], v[208:211], v[20:23]
	v_mfma_f32_16x16x32_bf16 v[16:19], v[172:175], v[208:211], v[16:19]
	v_mfma_f32_16x16x32_bf16 v[4:7], v[148:151], v[216:219], v[4:7]
	v_mfma_f32_16x16x32_bf16 v[0:3], v[172:175], v[216:219], v[0:3]
	s_setprio 0
	s_barrier
	s_add_i32 s81, s81, 2
	s_add_u32 s79, s79, 0x100
	s_addc_u32 s80, s80, 0
	s_add_u32 s46, s46, 0x10000
	s_addc_u32 s47, s47, 0
	s_cmp_gt_u32 s81, 41
.LBB0_211:
	ds_read_b128 v[128:131], v189
	ds_read_b128 v[132:135], v189 offset:1024
	ds_read_b128 v[136:139], v189 offset:2048
	ds_read_b128 v[140:143], v189 offset:3072
	ds_read_b128 v[144:147], v190
	ds_read_b128 v[148:151], v190 offset:1024
	ds_read_b128 v[168:171], v190 offset:2048
	ds_read_b128 v[172:175], v190 offset:3072
	s_add_u32 s48, s46, 0x4000
	s_addc_u32 s49, s47, 0
	s_cmp_eq_u32 s81, 40
	s_cselect_b32 s62, s4, s48
	s_cselect_b32 s63, s5, s49
	s_cselect_b32 s60, s44, s79
	s_cselect_b32 s61, s45, s80
	s_add_u32 s48, s62, 0x8000
	s_addc_u32 s49, s63, 0

; #define PG8_STAGE(bufoff, gbase, voff) do { _Pragma("unroll") for (int _i = 0; _i < 2; ++_i) \
;         __builtin_amdgcn_global_load_lds((const unsigned*)((const char*)(gbase) + (voff)[_i]), (PG8_LAS unsigned*)(lds + (bufoff) + ldsw + _i * 8192), 16, 0, 0); } while (0)
; #define PG8_LDA(dst, b, h) do { _Pragma("unroll") for (int m = 0; m < 4; ++m) _Pragma("unroll") for (int k = 0; k < 2; ++k) dst[m][k] = *(const PG8_LAS bf16x8*)(lds + PG8_SA(b, h) + aoff + m * 2048 + k * 1024); } while (0)
; #define PG8_LDB(dst, b, h) do { _Pragma("unroll") for (int n = 0; n < 2; ++n) _Pragma("unroll") for (int k = 0; k < 2; ++k) dst[n][k] = *(const PG8_LAS bf16x8*)(lds + PG8_SB(b, h) + boff + n * 2048 + k * 1024); } while (0)
; #define PG8_SCHED __builtin_amdgcn_sched_barrier(0)
; template <class Epi, class Sched, bool ALIGN_EPI = false, bool SP2 = false, bool ATILED = false>
; __device__ __forceinline__ void gemm_phase(PG8_LAS unsigned char* lds, const Gemm g, const Sched& S, const Epi& E) {
;     ...
;             PG8_LDB(B0, 0, 0); PG8_LDB(B1, 0, 1); PG8_SCHED; PG8_LDA(At, 0, 0); PG8_STAGE(PG8_SA(1, 1), a1 + hstepA, voffA);
	s_add_i32 m0, s65, 0xc000
	ds_read_b128 v[176:179], v191
	ds_read_b128 v[180:183], v191 offset:1024
	ds_read_b128 v[194:197], v191 offset:2048
	ds_read_b128 v[200:203], v191 offset:3072
	ds_read_b128 v[204:207], v191 offset:4096
	ds_read_b128 v[208:211], v191 offset:5120
	ds_read_b128 v[212:215], v191 offset:6144
	ds_read_b128 v[216:219], v191 offset:7168
	global_load_lds_dwordx4 v160, s[46:47]

; #define PG8_STAGE(bufoff, gbase, voff) do { _Pragma("unroll") for (int _i = 0; _i < 2; ++_i) \
;         __builtin_amdgcn_global_load_lds((const unsigned*)((const char*)(gbase) + (voff)[_i]), (PG8_LAS unsigned*)(lds + (bufoff) + ldsw + _i * 8192), 16, 0, 0); } while (0)
; #define PG8_LDA(dst, b, h) do { _Pragma("unroll") for (int m = 0; m < 4; ++m) _Pragma("unroll") for (int k = 0; k < 2; ++k) dst[m][k] = *(const PG8_LAS bf16x8*)(lds + PG8_SA(b, h) + aoff + m * 2048 + k * 1024); } while (0)
; #define PG8_LDB(dst, b, h) do { _Pragma("unroll") for (int n = 0; n < 2; ++n) _Pragma("unroll") for (int k = 0; k < 2; ++k) dst[n][k] = *(const PG8_LAS bf16x8*)(lds + PG8_SB(b, h) + boff + n * 2048 + k * 1024); } while (0)
; #define PG8_MMA(ai, bj, At, Bt) do { __builtin_amdgcn_s_setprio(1); _Pragma("unroll") for (int m = 0; m < 4; ++m) _Pragma("unroll") for (int n = 0; n < 2; ++n) _Pragma("unroll") for (int k = 0; k < 2; ++k) \
;         acc[ai][bj][m][n] = __builtin_amdgcn_mfma_f32_16x16x32_bf16(Bt[n][k], At[m][k], acc[ai][bj][m][n], 0, 0, 0); __builtin_amdgcn_s_setprio(0); } while (0)
; #define PG8_WAIT_V(n) asm volatile("s_waitcnt vmcnt(" #n ")" ::: "memory")
; #define PG8_WAIT_L(n) asm volatile("s_waitcnt lgkmcnt(" #n ")" ::: "memory")
; #define PG8_BAR __builtin_amdgcn_s_barrier()
; #define PG8_SCHED __builtin_amdgcn_sched_barrier(0)
; template <class Epi, class Sched, bool ALIGN_EPI = false, bool SP2 = false, bool ATILED = false>
; __device__ __forceinline__ void gemm_phase(PG8_LAS unsigned char* lds, const Gemm g, const Sched& S, const Epi& E) {
;     ...
;             PG8_LDB(B0, 0, 0); PG8_LDB(B1, 0, 1); PG8_SCHED; PG8_LDA(At, 0, 0); PG8_STAGE(PG8_SA(1, 1), a1 + hstepA, voffA);
;             PG8_WAIT_V(8); PG8_WAIT_L(0); PG8_BAR; PG8_MMA(0, 0, At, B0); PG8_MMA(0, 1, At, B1); PG8_BAR; PG8_SCHED;
	s_add_i32 m0, s65, 0xe000
	s_nop 0
	global_load_lds_dwordx4 v162, s[46:47]
	s_waitcnt vmcnt(8)
	s_waitcnt lgkmcnt(0)
	s_barrier
	s_setprio 1
	s_waitcnt lgkmcnt(0)
	v_mfma_f32_16x16x32_bf16 v[124:127], v[128:131], v[176:179], v[124:127]
	v_mfma_f32_16x16x32_bf16 v[120:123], v[136:139], v[176:179], v[120:123]
	v_mfma_f32_16x16x32_bf16 v[108:111], v[128:131], v[194:197], v[108:111]
	v_mfma_f32_16x16x32_bf16 v[104:107], v[136:139], v[194:197], v[104:107]
	v_mfma_f32_16x16x32_bf16 v[92:95], v[128:131], v[204:207], v[92:95]
	v_mfma_f32_16x16x32_bf16 v[88:91], v[136:139], v[204:207], v[88:91]
	v_mfma_f32_16x16x32_bf16 v[76:79], v[128:131], v[212:215], v[76:79]
	v_mfma_f32_16x16x32_bf16 v[72:75], v[136:139], v[212:215], v[72:75]
	v_mfma_f32_16x16x32_bf16 v[124:127], v[132:135], v[180:183], v[124:127]
	v_mfma_f32_16x16x32_bf16 v[120:123], v[140:143], v[180:183], v[120:123]
	v_mfma_f32_16x16x32_bf16 v[108:111], v[132:135], v[200:203], v[108:111]
	v_mfma_f32_16x16x32_bf16 v[104:107], v[140:143], v[200:203], v[104:107]
	v_mfma_f32_16x16x32_bf16 v[92:95], v[132:135], v[208:211], v[92:95]
	v_mfma_f32_16x16x32_bf16 v[88:91], v[140:143], v[208:211], v[88:91]
	v_mfma_f32_16x16x32_bf16 v[76:79], v[132:135], v[216:219], v[76:79]
	v_mfma_f32_16x16x32_bf16 v[72:75], v[140:143], v[216:219], v[72:75]
	s_setprio 0
	s_setprio 1
	v_mfma_f32_16x16x32_bf16 v[116:119], v[144:147], v[176:179], v[116:119]
	v_mfma_f32_16x16x32_bf16 v[112:115], v[168:171], v[176:179], v[112:115]
	v_mfma_f32_16x16x32_bf16 v[100:103], v[144:147], v[194:197], v[100:103]
	v_mfma_f32_16x16x32_bf16 v[96:99], v[168:171], v[194:197], v[96:99]
	v_mfma_f32_16x16x32_bf16 v[84:87], v[144:147], v[204:207], v[84:87]
	v_mfma_f32_16x16x32_bf16 v[80:83], v[168:171], v[204:207], v[80:83]
	v_mfma_f32_16x16x32_bf16 v[68:71], v[144:147], v[212:215], v[68:71]
	v_mfma_f32_16x16x32_bf16 v[64:67], v[168:171], v[212:215], v[64:67]
	v_mfma_f32_16x16x32_bf16 v[116:119], v[148:151], v[180:183], v[116:119]
	v_mfma_f32_16x16x32_bf16 v[112:115], v[172:175], v[180:183], v[112:115]
	v_mfma_f32_16x16x32_bf16 v[100:103], v[148:151], v[200:203], v[100:103]
	v_mfma_f32_16x16x32_bf16 v[96:99], v[172:175], v[200:203], v[96:99]
	v_mfma_f32_16x16x32_bf16 v[84:87], v[148:151], v[208:211], v[84:87]
	v_mfma_f32_16x16x32_bf16 v[80:83], v[172:175], v[208:211], v[80:83]
	v_mfma_f32_16x16x32_bf16 v[68:71], v[148:151], v[216:219], v[68:71]
	v_mfma_f32_16x16x32_bf16 v[64:67], v[172:175], v[216:219], v[64:67]
	s_setprio 0
	s_barrier
	s_add_u32 s98, s60, s40
	s_addc_u32 s99, s61, s41
	s_add_i32 s83, s73, s64

; #define PG8_STAGE(bufoff, gbase, voff) do { _Pragma("unroll") for (int _i = 0; _i < 2; ++_i) \
;         __builtin_amdgcn_global_load_lds((const unsigned*)((const char*)(gbase) + (voff)[_i]), (PG8_LAS unsigned*)(lds + (bufoff) + ldsw + _i * 8192), 16, 0, 0); } while (0)
; #define PG8_LDA(dst, b, h) do { _Pragma("unroll") for (int m = 0; m < 4; ++m) _Pragma("unroll") for (int k = 0; k < 2; ++k) dst[m][k] = *(const PG8_LAS bf16x8*)(lds + PG8_SA(b, h) + aoff + m * 2048 + k * 1024); } while (0)
; template <class Epi, class Sched, bool ALIGN_EPI = false, bool SP2 = false, bool ATILED = false>
; __device__ __forceinline__ void gemm_phase(PG8_LAS unsigned char* lds, const Gemm g, const Sched& S, const Epi& E) {
;     ...
;             PG8_LDA(At, 0, 1); PG8_STAGE(PG8_SB(0, 0), b2, voffB); PG8_STAGE(PG8_SB(0, 1), b2 + hstep, voffB); PG8_STAGE(PG8_SA(0, 0), a2, voffA);
	s_mov_b32 m0, s83
	ds_read_b128 v[176:179], v191 offset:16384
	ds_read_b128 v[180:183], v191 offset:17408
	ds_read_b128 v[194:197], v191 offset:18432
	ds_read_b128 v[200:203], v191 offset:19456
	ds_read_b128 v[204:207], v191 offset:20480
	ds_read_b128 v[208:211], v191 offset:21504
	ds_read_b128 v[212:215], v191 offset:22528
	ds_read_b128 v[216:219], v191 offset:23552
	global_load_lds_dwordx4 v154, s[60:61]
	s_add_i32 m0, s83, 0x2000
	s_add_u32 s84, s60, 0xb0000

; #define PG8_STAGE(bufoff, gbase, voff) do { _Pragma("unroll") for (int _i = 0; _i < 2; ++_i) \
;         __builtin_amdgcn_global_load_lds((const unsigned*)((const char*)(gbase) + (voff)[_i]), (PG8_LAS unsigned*)(lds + (bufoff) + ldsw + _i * 8192), 16, 0, 0); } while (0)
; #define PG8_LDA(dst, b, h) do { _Pragma("unroll") for (int m = 0; m < 4; ++m) _Pragma("unroll") for (int k = 0; k < 2; ++k) dst[m][k] = *(const PG8_LAS bf16x8*)(lds + PG8_SA(b, h) + aoff + m * 2048 + k * 1024); } while (0)
; template <class Epi, class Sched, bool ALIGN_EPI = false, bool SP2 = false, bool ATILED = false>
; __device__ __forceinline__ void gemm_phase(PG8_LAS unsigned char* lds, const Gemm g, const Sched& S, const Epi& E) {
;     ...
;             PG8_LDA(At, 0, 1); PG8_STAGE(PG8_SB(0, 0), b2, voffB); PG8_STAGE(PG8_SB(0, 1), b2 + hstep, voffB); PG8_STAGE(PG8_SA(0, 0), a2, voffA);
	s_addc_u32 s85, s61, 0
	s_add_i32 s83, s74, s64
	global_load_lds_dwordx4 v158, s[60:61]

; #define PG8_STAGE(bufoff, gbase, voff) do { _Pragma("unroll") for (int _i = 0; _i < 2; ++_i) \
;         __builtin_amdgcn_global_load_lds((const unsigned*)((const char*)(gbase) + (voff)[_i]), (PG8_LAS unsigned*)(lds + (bufoff) + ldsw + _i * 8192), 16, 0, 0); } while (0)
; #define PG8_LDA(dst, b, h) do { _Pragma("unroll") for (int m = 0; m < 4; ++m) _Pragma("unroll") for (int k = 0; k < 2; ++k) dst[m][k] = *(const PG8_LAS bf16x8*)(lds + PG8_SA(b, h) + aoff + m * 2048 + k * 1024); } while (0)
; template <class Epi, class Sched, bool ALIGN_EPI = false, bool SP2 = false, bool ATILED = false>
; __device__ __forceinline__ void gemm_phase(PG8_LAS unsigned char* lds, const Gemm g, const Sched& S, const Epi& E) {
;     ...
;             PG8_LDA(At, 0, 1); PG8_STAGE(PG8_SB(0, 0), b2, voffB); PG8_STAGE(PG8_SB(0, 1), b2 + hstep, voffB); PG8_STAGE(PG8_SA(0, 0), a2, voffA);
	s_mov_b32 m0, s83
	s_nop 0
	global_load_lds_dwordx4 v154, s[84:85]

; #define PG8_STAGE(bufoff, gbase, voff) do { _Pragma("unroll") for (int _i = 0; _i < 2; ++_i) \
;         __builtin_amdgcn_global_load_lds((const unsigned*)((const char*)(gbase) + (voff)[_i]), (PG8_LAS unsigned*)(lds + (bufoff) + ldsw + _i * 8192), 16, 0, 0); } while (0)
; #define PG8_LDA(dst, b, h) do { _Pragma("unroll") for (int m = 0; m < 4; ++m) _Pragma("unroll") for (int k = 0; k < 2; ++k) dst[m][k] = *(const PG8_LAS bf16x8*)(lds + PG8_SA(b, h) + aoff + m * 2048 + k * 1024); } while (0)
; template <class Epi, class Sched, bool ALIGN_EPI = false, bool SP2 = false, bool ATILED = false>
; __device__ __forceinline__ void gemm_phase(PG8_LAS unsigned char* lds, const Gemm g, const Sched& S, const Epi& E) {
;     ...
;             PG8_LDA(At, 0, 1); PG8_STAGE(PG8_SB(0, 0), b2, voffB); PG8_STAGE(PG8_SB(0, 1), b2 + hstep, voffB); PG8_STAGE(PG8_SA(0, 0), a2, voffA);
	s_add_i32 m0, s83, 0x2000
	s_nop 0
	global_load_lds_dwordx4 v158, s[84:85]

; #define PG8_STAGE(bufoff, gbase, voff) do { _Pragma("unroll") for (int _i = 0; _i < 2; ++_i) \
;         __builtin_amdgcn_global_load_lds((const unsigned*)((const char*)(gbase) + (voff)[_i]), (PG8_LAS unsigned*)(lds + (bufoff) + ldsw + _i * 8192), 16, 0, 0); } while (0)
; #define PG8_LDA(dst, b, h) do { _Pragma("unroll") for (int m = 0; m < 4; ++m) _Pragma("unroll") for (int k = 0; k < 2; ++k) dst[m][k] = *(const PG8_LAS bf16x8*)(lds + PG8_SA(b, h) + aoff + m * 2048 + k * 1024); } while (0)
; template <class Epi, class Sched, bool ALIGN_EPI = false, bool SP2 = false, bool ATILED = false>
; __device__ __forceinline__ void gemm_phase(PG8_LAS unsigned char* lds, const Gemm g, const Sched& S, const Epi& E) {
;     ...
;             PG8_LDA(At, 0, 1); PG8_STAGE(PG8_SB(0, 0), b2, voffB); PG8_STAGE(PG8_SB(0, 1), b2 + hstep, voffB); PG8_STAGE(PG8_SA(0, 0), a2, voffA);
	s_mov_b32 m0, s65
	s_nop 0
	global_load_lds_dwordx4 v152, s[62:63]

; #define PG8_STAGE(bufoff, gbase, voff) do { _Pragma("unroll") for (int _i = 0; _i < 2; ++_i) \
;         __builtin_amdgcn_global_load_lds((const unsigned*)((const char*)(gbase) + (voff)[_i]), (PG8_LAS unsigned*)(lds + (bufoff) + ldsw + _i * 8192), 16, 0, 0); } while (0)
; #define PG8_LDA(dst, b, h) do { _Pragma("unroll") for (int m = 0; m < 4; ++m) _Pragma("unroll") for (int k = 0; k < 2; ++k) dst[m][k] = *(const PG8_LAS bf16x8*)(lds + PG8_SA(b, h) + aoff + m * 2048 + k * 1024); } while (0)
; #define PG8_LDB(dst, b, h) do { _Pragma("unroll") for (int n = 0; n < 2; ++n) _Pragma("unroll") for (int k = 0; k < 2; ++k) dst[n][k] = *(const PG8_LAS bf16x8*)(lds + PG8_SB(b, h) + boff + n * 2048 + k * 1024); } while (0)
; #define PG8_MMA(ai, bj, At, Bt) do { __builtin_amdgcn_s_setprio(1); _Pragma("unroll") for (int m = 0; m < 4; ++m) _Pragma("unroll") for (int n = 0; n < 2; ++n) _Pragma("unroll") for (int k = 0; k < 2; ++k) \
;         acc[ai][bj][m][n] = __builtin_amdgcn_mfma_f32_16x16x32_bf16(Bt[n][k], At[m][k], acc[ai][bj][m][n], 0, 0, 0); __builtin_amdgcn_s_setprio(0); } while (0)
; #define PG8_WAIT_V(n) asm volatile("s_waitcnt vmcnt(" #n ")" ::: "memory")
; #define PG8_WAIT_L(n) asm volatile("s_waitcnt lgkmcnt(" #n ")" ::: "memory")
; #define PG8_BAR __builtin_amdgcn_s_barrier()
; #define PG8_SCHED __builtin_amdgcn_sched_barrier(0)
; template <class Epi, class Sched, bool ALIGN_EPI = false, bool SP2 = false, bool ATILED = false>
; __device__ __forceinline__ void gemm_phase(PG8_LAS unsigned char* lds, const Gemm g, const Sched& S, const Epi& E) {
;     ...
;             PG8_LDA(At, 0, 1); PG8_STAGE(PG8_SB(0, 0), b2, voffB); PG8_STAGE(PG8_SB(0, 1), b2 + hstep, voffB); PG8_STAGE(PG8_SA(0, 0), a2, voffA);
;             PG8_WAIT_V(8); PG8_WAIT_L(0); PG8_BAR; PG8_MMA(1, 0, At, B0); PG8_MMA(1, 1, At, B1); PG8_BAR; PG8_SCHED;
;             PG8_LDB(B0, 1, 0); PG8_LDB(B1, 1, 1); PG8_SCHED; PG8_LDA(At, 1, 0); PG8_STAGE(PG8_SA(0, 1), a2 + hstepA, voffA);
	s_mov_b32 m0, s66
	s_nop 0
	global_load_lds_dwordx4 v156, s[62:63]
	s_waitcnt vmcnt(8)
	s_waitcnt lgkmcnt(0)
	s_barrier
	s_setprio 1
	s_waitcnt lgkmcnt(0)
	v_mfma_f32_16x16x32_bf16 v[60:63], v[128:131], v[176:179], v[60:63]
	v_mfma_f32_16x16x32_bf16 v[56:59], v[136:139], v[176:179], v[56:59]
	v_mfma_f32_16x16x32_bf16 v[44:47], v[128:131], v[194:197], v[44:47]
	v_mfma_f32_16x16x32_bf16 v[40:43], v[136:139], v[194:197], v[40:43]
	v_mfma_f32_16x16x32_bf16 v[28:31], v[128:131], v[204:207], v[28:31]
	v_mfma_f32_16x16x32_bf16 v[24:27], v[136:139], v[204:207], v[24:27]
	v_mfma_f32_16x16x32_bf16 v[12:15], v[128:131], v[212:215], v[12:15]
	v_mfma_f32_16x16x32_bf16 v[8:11], v[136:139], v[212:215], v[8:11]
	v_mfma_f32_16x16x32_bf16 v[60:63], v[132:135], v[180:183], v[60:63]
	v_mfma_f32_16x16x32_bf16 v[56:59], v[140:143], v[180:183], v[56:59]
	v_mfma_f32_16x16x32_bf16 v[44:47], v[132:135], v[200:203], v[44:47]
	v_mfma_f32_16x16x32_bf16 v[40:43], v[140:143], v[200:203], v[40:43]
	v_mfma_f32_16x16x32_bf16 v[28:31], v[132:135], v[208:211], v[28:31]
	v_mfma_f32_16x16x32_bf16 v[24:27], v[140:143], v[208:211], v[24:27]
	v_mfma_f32_16x16x32_bf16 v[12:15], v[132:135], v[216:219], v[12:15]
	v_mfma_f32_16x16x32_bf16 v[8:11], v[140:143], v[216:219], v[8:11]
	s_setprio 0
	s_setprio 1
	v_mfma_f32_16x16x32_bf16 v[52:55], v[144:147], v[176:179], v[52:55]
	v_mfma_f32_16x16x32_bf16 v[48:51], v[168:171], v[176:179], v[48:51]
	v_mfma_f32_16x16x32_bf16 v[36:39], v[144:147], v[194:197], v[36:39]
	v_mfma_f32_16x16x32_bf16 v[32:35], v[168:171], v[194:197], v[32:35]
	v_mfma_f32_16x16x32_bf16 v[20:23], v[144:147], v[204:207], v[20:23]
	v_mfma_f32_16x16x32_bf16 v[16:19], v[168:171], v[204:207], v[16:19]
	v_mfma_f32_16x16x32_bf16 v[4:7], v[144:147], v[212:215], v[4:7]
	v_mfma_f32_16x16x32_bf16 v[0:3], v[168:171], v[212:215], v[0:3]
	v_mfma_f32_16x16x32_bf16 v[52:55], v[148:151], v[180:183], v[52:55]
	v_mfma_f32_16x16x32_bf16 v[48:51], v[172:175], v[180:183], v[48:51]
	v_mfma_f32_16x16x32_bf16 v[36:39], v[148:151], v[200:203], v[36:39]
	v_mfma_f32_16x16x32_bf16 v[32:35], v[172:175], v[200:203], v[32:35]
	v_mfma_f32_16x16x32_bf16 v[20:23], v[148:151], v[208:211], v[20:23]
	v_mfma_f32_16x16x32_bf16 v[16:19], v[172:175], v[208:211], v[16:19]
	v_mfma_f32_16x16x32_bf16 v[4:7], v[148:151], v[216:219], v[4:7]
	v_mfma_f32_16x16x32_bf16 v[0:3], v[172:175], v[216:219], v[0:3]
	s_setprio 0
	s_barrier
	s_add_i32 s83, 0, 0x18000
	s_add_i32 s84, 0, 0x1c000
	v_add_u32_e32 v140, s83, v187
	v_add_u32_e32 v172, s84, v187
	ds_read_b128 v[128:131], v140
	ds_read_b128 v[132:135], v140 offset:1024
	ds_read_b128 v[136:139], v140 offset:2048
	ds_read_b128 v[140:143], v140 offset:3072
	ds_read_b128 v[144:147], v172
	ds_read_b128 v[148:151], v172 offset:1024
	ds_read_b128 v[168:171], v172 offset:2048
	ds_read_b128 v[172:175], v172 offset:3072
	s_add_u32 s62, s62, 0x4000
	s_addc_u32 s63, s63, 0
	s_mov_b32 m0, s67

; #define PG8_STAGE(bufoff, gbase, voff) do { _Pragma("unroll") for (int _i = 0; _i < 2; ++_i) \
;         __builtin_amdgcn_global_load_lds((const unsigned*)((const char*)(gbase) + (voff)[_i]), (PG8_LAS unsigned*)(lds + (bufoff) + ldsw + _i * 8192), 16, 0, 0); } while (0)
; #define PG8_LDA(dst, b, h) do { _Pragma("unroll") for (int m = 0; m < 4; ++m) _Pragma("unroll") for (int k = 0; k < 2; ++k) dst[m][k] = *(const PG8_LAS bf16x8*)(lds + PG8_SA(b, h) + aoff + m * 2048 + k * 1024); } while (0)
; #define PG8_LDB(dst, b, h) do { _Pragma("unroll") for (int n = 0; n < 2; ++n) _Pragma("unroll") for (int k = 0; k < 2; ++k) dst[n][k] = *(const PG8_LAS bf16x8*)(lds + PG8_SB(b, h) + boff + n * 2048 + k * 1024); } while (0)
; #define PG8_SCHED __builtin_amdgcn_sched_barrier(0)
; template <class Epi, class Sched, bool ALIGN_EPI = false, bool SP2 = false, bool ATILED = false>
; __device__ __forceinline__ void gemm_phase(PG8_LAS unsigned char* lds, const Gemm g, const Sched& S, const Epi& E) {
;     ...
;             PG8_LDB(B0, 1, 0); PG8_LDB(B1, 1, 1); PG8_SCHED; PG8_LDA(At, 1, 0); PG8_STAGE(PG8_SA(0, 1), a2 + hstepA, voffA);
	ds_read_b128 v[176:179], v191 offset:32768
	ds_read_b128 v[180:183], v191 offset:33792
	ds_read_b128 v[194:197], v191 offset:34816
	ds_read_b128 v[200:203], v191 offset:35840
	ds_read_b128 v[204:207], v191 offset:36864
	ds_read_b128 v[208:211], v191 offset:37888
	ds_read_b128 v[212:215], v191 offset:38912
	ds_read_b128 v[216:219], v191 offset:39936
	global_load_lds_dwordx4 v152, s[62:63]

; #define PG8_STAGE(bufoff, gbase, voff) do { _Pragma("unroll") for (int _i = 0; _i < 2; ++_i) \
;         __builtin_amdgcn_global_load_lds((const unsigned*)((const char*)(gbase) + (voff)[_i]), (PG8_LAS unsigned*)(lds + (bufoff) + ldsw + _i * 8192), 16, 0, 0); } while (0)
; #define PG8_LDA(dst, b, h) do { _Pragma("unroll") for (int m = 0; m < 4; ++m) _Pragma("unroll") for (int k = 0; k < 2; ++k) dst[m][k] = *(const PG8_LAS bf16x8*)(lds + PG8_SA(b, h) + aoff + m * 2048 + k * 1024); } while (0)
; #define PG8_LDB(dst, b, h) do { _Pragma("unroll") for (int n = 0; n < 2; ++n) _Pragma("unroll") for (int k = 0; k < 2; ++k) dst[n][k] = *(const PG8_LAS bf16x8*)(lds + PG8_SB(b, h) + boff + n * 2048 + k * 1024); } while (0)
; #define PG8_MMA(ai, bj, At, Bt) do { __builtin_amdgcn_s_setprio(1); _Pragma("unroll") for (int m = 0; m < 4; ++m) _Pragma("unroll") for (int n = 0; n < 2; ++n) _Pragma("unroll") for (int k = 0; k < 2; ++k) \
;         acc[ai][bj][m][n] = __builtin_amdgcn_mfma_f32_16x16x32_bf16(Bt[n][k], At[m][k], acc[ai][bj][m][n], 0, 0, 0); __builtin_amdgcn_s_setprio(0); } while (0)
; #define PG8_WAIT_V(n) asm volatile("s_waitcnt vmcnt(" #n ")" ::: "memory")
; #define PG8_WAIT_L(n) asm volatile("s_waitcnt lgkmcnt(" #n ")" ::: "memory")
; #define PG8_BAR __builtin_amdgcn_s_barrier()
; #define PG8_SCHED __builtin_amdgcn_sched_barrier(0)
; template <class Epi, class Sched, bool ALIGN_EPI = false, bool SP2 = false, bool ATILED = false>
; __device__ __forceinline__ void gemm_phase(PG8_LAS unsigned char* lds, const Gemm g, const Sched& S, const Epi& E) {
;     ...
;             PG8_LDB(B0, 1, 0); PG8_LDB(B1, 1, 1); PG8_SCHED; PG8_LDA(At, 1, 0); PG8_STAGE(PG8_SA(0, 1), a2 + hstepA, voffA);
;             PG8_WAIT_V(8); PG8_WAIT_L(0); PG8_BAR; PG8_MMA(0, 0, At, B0); PG8_MMA(0, 1, At, B1); PG8_BAR; PG8_SCHED;
	s_mov_b32 m0, s68
	s_nop 0
	global_load_lds_dwordx4 v156, s[62:63]
	s_waitcnt vmcnt(8)
	s_waitcnt lgkmcnt(0)
	s_barrier
	s_setprio 1
	s_waitcnt lgkmcnt(0)
	v_mfma_f32_16x16x32_bf16 v[124:127], v[128:131], v[176:179], v[124:127]
	v_mfma_f32_16x16x32_bf16 v[120:123], v[136:139], v[176:179], v[120:123]
	v_mfma_f32_16x16x32_bf16 v[108:111], v[128:131], v[194:197], v[108:111]
	v_mfma_f32_16x16x32_bf16 v[104:107], v[136:139], v[194:197], v[104:107]
	v_mfma_f32_16x16x32_bf16 v[92:95], v[128:131], v[204:207], v[92:95]
	v_mfma_f32_16x16x32_bf16 v[88:91], v[136:139], v[204:207], v[88:91]
	v_mfma_f32_16x16x32_bf16 v[76:79], v[128:131], v[212:215], v[76:79]
	v_mfma_f32_16x16x32_bf16 v[72:75], v[136:139], v[212:215], v[72:75]
	v_mfma_f32_16x16x32_bf16 v[124:127], v[132:135], v[180:183], v[124:127]
	v_mfma_f32_16x16x32_bf16 v[120:123], v[140:143], v[180:183], v[120:123]
	v_mfma_f32_16x16x32_bf16 v[108:111], v[132:135], v[200:203], v[108:111]
	v_mfma_f32_16x16x32_bf16 v[104:107], v[140:143], v[200:203], v[104:107]
	v_mfma_f32_16x16x32_bf16 v[92:95], v[132:135], v[208:211], v[92:95]
	v_mfma_f32_16x16x32_bf16 v[88:91], v[140:143], v[208:211], v[88:91]
	v_mfma_f32_16x16x32_bf16 v[76:79], v[132:135], v[216:219], v[76:79]
	v_mfma_f32_16x16x32_bf16 v[72:75], v[140:143], v[216:219], v[72:75]
	s_setprio 0
	s_setprio 1
	v_mfma_f32_16x16x32_bf16 v[116:119], v[144:147], v[176:179], v[116:119]
	v_mfma_f32_16x16x32_bf16 v[112:115], v[168:171], v[176:179], v[112:115]
	v_mfma_f32_16x16x32_bf16 v[100:103], v[144:147], v[194:197], v[100:103]
	v_mfma_f32_16x16x32_bf16 v[96:99], v[168:171], v[194:197], v[96:99]
	v_mfma_f32_16x16x32_bf16 v[84:87], v[144:147], v[204:207], v[84:87]
	v_mfma_f32_16x16x32_bf16 v[80:83], v[168:171], v[204:207], v[80:83]
	v_mfma_f32_16x16x32_bf16 v[68:71], v[144:147], v[212:215], v[68:71]
	v_mfma_f32_16x16x32_bf16 v[64:67], v[168:171], v[212:215], v[64:67]
	v_mfma_f32_16x16x32_bf16 v[116:119], v[148:151], v[180:183], v[116:119]
	v_mfma_f32_16x16x32_bf16 v[112:115], v[172:175], v[180:183], v[112:115]
	v_mfma_f32_16x16x32_bf16 v[100:103], v[148:151], v[200:203], v[100:103]
	v_mfma_f32_16x16x32_bf16 v[96:99], v[172:175], v[200:203], v[96:99]
	v_mfma_f32_16x16x32_bf16 v[84:87], v[148:151], v[208:211], v[84:87]
	v_mfma_f32_16x16x32_bf16 v[80:83], v[172:175], v[208:211], v[80:83]
	v_mfma_f32_16x16x32_bf16 v[68:71], v[148:151], v[216:219], v[68:71]
	v_mfma_f32_16x16x32_bf16 v[64:67], v[172:175], v[216:219], v[64:67]
	s_setprio 0
	s_barrier
	s_add_i32 s62, s83, s64

; #define PG8_STAGE(bufoff, gbase, voff) do { _Pragma("unroll") for (int _i = 0; _i < 2; ++_i) \
;         __builtin_amdgcn_global_load_lds((const unsigned*)((const char*)(gbase) + (voff)[_i]), (PG8_LAS unsigned*)(lds + (bufoff) + ldsw + _i * 8192), 16, 0, 0); } while (0)
; #define PG8_LDA(dst, b, h) do { _Pragma("unroll") for (int m = 0; m < 4; ++m) _Pragma("unroll") for (int k = 0; k < 2; ++k) dst[m][k] = *(const PG8_LAS bf16x8*)(lds + PG8_SA(b, h) + aoff + m * 2048 + k * 1024); } while (0)
; template <class Epi, class Sched, bool ALIGN_EPI = false, bool SP2 = false, bool ATILED = false>
; __device__ __forceinline__ void gemm_phase(PG8_LAS unsigned char* lds, const Gemm g, const Sched& S, const Epi& E) {
;     ...
;             PG8_LDA(At, 1, 1); PG8_STAGE(PG8_SB(1, 0), b3, voffB); PG8_STAGE(PG8_SB(1, 1), b3 + hstep, voffB); PG8_STAGE(PG8_SA(1, 0), a3, voffA);
	s_mov_b32 m0, s62
	ds_read_b128 v[176:179], v191 offset:49152
	ds_read_b128 v[180:183], v191 offset:50176
	ds_read_b128 v[194:197], v191 offset:51200
	ds_read_b128 v[200:203], v191 offset:52224
	ds_read_b128 v[204:207], v191 offset:53248
	ds_read_b128 v[208:211], v191 offset:54272
	ds_read_b128 v[212:215], v191 offset:55296
	ds_read_b128 v[216:219], v191 offset:56320
	global_load_lds_dwordx4 v154, s[98:99]
	s_add_i32 m0, s62, 0x2000
	s_add_u32 s60, s60, 0xb0080

; #define PG8_STAGE(bufoff, gbase, voff) do { _Pragma("unroll") for (int _i = 0; _i < 2; ++_i) \
;         __builtin_amdgcn_global_load_lds((const unsigned*)((const char*)(gbase) + (voff)[_i]), (PG8_LAS unsigned*)(lds + (bufoff) + ldsw + _i * 8192), 16, 0, 0); } while (0)
; #define PG8_LDA(dst, b, h) do { _Pragma("unroll") for (int m = 0; m < 4; ++m) _Pragma("unroll") for (int k = 0; k < 2; ++k) dst[m][k] = *(const PG8_LAS bf16x8*)(lds + PG8_SA(b, h) + aoff + m * 2048 + k * 1024); } while (0)
; template <class Epi, class Sched, bool ALIGN_EPI = false, bool SP2 = false, bool ATILED = false>
; __device__ __forceinline__ void gemm_phase(PG8_LAS unsigned char* lds, const Gemm g, const Sched& S, const Epi& E) {
;     ...
;             PG8_LDA(At, 1, 1); PG8_STAGE(PG8_SB(1, 0), b3, voffB); PG8_STAGE(PG8_SB(1, 1), b3 + hstep, voffB); PG8_STAGE(PG8_SA(1, 0), a3, voffA);
	s_addc_u32 s61, s61, 0
	s_add_i32 s62, s84, s64
	global_load_lds_dwordx4 v158, s[98:99]

; #define PG8_STAGE(bufoff, gbase, voff) do { _Pragma("unroll") for (int _i = 0; _i < 2; ++_i) \
;         __builtin_amdgcn_global_load_lds((const unsigned*)((const char*)(gbase) + (voff)[_i]), (PG8_LAS unsigned*)(lds + (bufoff) + ldsw + _i * 8192), 16, 0, 0); } while (0)
; #define PG8_LDA(dst, b, h) do { _Pragma("unroll") for (int m = 0; m < 4; ++m) _Pragma("unroll") for (int k = 0; k < 2; ++k) dst[m][k] = *(const PG8_LAS bf16x8*)(lds + PG8_SA(b, h) + aoff + m * 2048 + k * 1024); } while (0)
; template <class Epi, class Sched, bool ALIGN_EPI = false, bool SP2 = false, bool ATILED = false>
; __device__ __forceinline__ void gemm_phase(PG8_LAS unsigned char* lds, const Gemm g, const Sched& S, const Epi& E) {
;     ...
;             PG8_LDA(At, 1, 1); PG8_STAGE(PG8_SB(1, 0), b3, voffB); PG8_STAGE(PG8_SB(1, 1), b3 + hstep, voffB); PG8_STAGE(PG8_SA(1, 0), a3, voffA);
	s_mov_b32 m0, s62
	s_nop 0
	global_load_lds_dwordx4 v154, s[60:61]

; #define PG8_STAGE(bufoff, gbase, voff) do { _Pragma("unroll") for (int _i = 0; _i < 2; ++_i) \
;         __builtin_amdgcn_global_load_lds((const unsigned*)((const char*)(gbase) + (voff)[_i]), (PG8_LAS unsigned*)(lds + (bufoff) + ldsw + _i * 8192), 16, 0, 0); } while (0)
; #define PG8_LDA(dst, b, h) do { _Pragma("unroll") for (int m = 0; m < 4; ++m) _Pragma("unroll") for (int k = 0; k < 2; ++k) dst[m][k] = *(const PG8_LAS bf16x8*)(lds + PG8_SA(b, h) + aoff + m * 2048 + k * 1024); } while (0)
; template <class Epi, class Sched, bool ALIGN_EPI = false, bool SP2 = false, bool ATILED = false>
; __device__ __forceinline__ void gemm_phase(PG8_LAS unsigned char* lds, const Gemm g, const Sched& S, const Epi& E) {
;     ...
;             PG8_LDA(At, 1, 1); PG8_STAGE(PG8_SB(1, 0), b3, voffB); PG8_STAGE(PG8_SB(1, 1), b3 + hstep, voffB); PG8_STAGE(PG8_SA(1, 0), a3, voffA);
	s_add_i32 m0, s62, 0x2000
	s_nop 0
	global_load_lds_dwordx4 v158, s[60:61]

; #define PG8_STAGE(bufoff, gbase, voff) do { _Pragma("unroll") for (int _i = 0; _i < 2; ++_i) \
;         __builtin_amdgcn_global_load_lds((const unsigned*)((const char*)(gbase) + (voff)[_i]), (PG8_LAS unsigned*)(lds + (bufoff) + ldsw + _i * 8192), 16, 0, 0); } while (0)
; #define PG8_LDA(dst, b, h) do { _Pragma("unroll") for (int m = 0; m < 4; ++m) _Pragma("unroll") for (int k = 0; k < 2; ++k) dst[m][k] = *(const PG8_LAS bf16x8*)(lds + PG8_SA(b, h) + aoff + m * 2048 + k * 1024); } while (0)
; template <class Epi, class Sched, bool ALIGN_EPI = false, bool SP2 = false, bool ATILED = false>
; __device__ __forceinline__ void gemm_phase(PG8_LAS unsigned char* lds, const Gemm g, const Sched& S, const Epi& E) {
;     ...
;             PG8_LDA(At, 1, 1); PG8_STAGE(PG8_SB(1, 0), b3, voffB); PG8_STAGE(PG8_SB(1, 1), b3 + hstep, voffB); PG8_STAGE(PG8_SA(1, 0), a3, voffA);
	s_mov_b32 m0, s71
	s_nop 0
	global_load_lds_dwordx4 v152, s[48:49]

; #define PG8_STAGE(bufoff, gbase, voff) do { _Pragma("unroll") for (int _i = 0; _i < 2; ++_i) \
;         __builtin_amdgcn_global_load_lds((const unsigned*)((const char*)(gbase) + (voff)[_i]), (PG8_LAS unsigned*)(lds + (bufoff) + ldsw + _i * 8192), 16, 0, 0); } while (0)
; #define PG8_LDA(dst, b, h) do { _Pragma("unroll") for (int m = 0; m < 4; ++m) _Pragma("unroll") for (int k = 0; k < 2; ++k) dst[m][k] = *(const PG8_LAS bf16x8*)(lds + PG8_SA(b, h) + aoff + m * 2048 + k * 1024); } while (0)
; #define PG8_WAIT_V(n) asm volatile("s_waitcnt vmcnt(" #n ")" ::: "memory")
; #define PG8_WAIT_L(n) asm volatile("s_waitcnt lgkmcnt(" #n ")" ::: "memory")
; #define PG8_BAR __builtin_amdgcn_s_barrier()
; template <class Epi, class Sched, bool ALIGN_EPI = false, bool SP2 = false, bool ATILED = false>
; __device__ __forceinline__ void gemm_phase(PG8_LAS unsigned char* lds, const Gemm g, const Sched& S, const Epi& E) {
;     ...
;         for (int t = 0; t < nt; t += 2) {
;             const bool last = (t == nt - 2);
;             const char* a1 = cA + (size_t)(t + 1) * kstepA;
;             const char* a2 = last ? nA : cA + (size_t)(t + 2) * kstepA; const char* b2 = last ? nB : cB + (size_t)(t + 2) * kstep;
;             const char* a3 = a2 + kstepA; const char* b3 = b2 + kstep;
;             if (last && has_next) S.a_ready(nxt);
;             if constexpr (SP2) {
;             PG8_LDB(B0, 0, 0); PG8_LDB(B1, 0, 1); PG8_SCHED; PG8_LDA(At, 0, 0); PG8_STAGE(PG8_SA(1, 1), a1 + hstepA, voffA);
;             PG8_WAIT_V(8); PG8_WAIT_L(0); PG8_BAR; PG8_MMA(0, 0, At, B0); PG8_MMA(0, 1, At, B1); PG8_BAR; PG8_SCHED;
;             PG8_LDA(At, 0, 1); PG8_STAGE(PG8_SB(0, 0), b2, voffB); PG8_STAGE(PG8_SB(0, 1), b2 + hstep, voffB); PG8_STAGE(PG8_SA(0, 0), a2, voffA);
;             PG8_WAIT_V(8); PG8_WAIT_L(0); PG8_BAR; PG8_MMA(1, 0, At, B0); PG8_MMA(1, 1, At, B1); PG8_BAR; PG8_SCHED;
;             PG8_LDB(B0, 1, 0); PG8_LDB(B1, 1, 1); PG8_SCHED; PG8_LDA(At, 1, 0); PG8_STAGE(PG8_SA(0, 1), a2 + hstepA, voffA);
;             PG8_WAIT_V(8); PG8_WAIT_L(0); PG8_BAR; PG8_MMA(0, 0, At, B0); PG8_MMA(0, 1, At, B1); PG8_BAR; PG8_SCHED;
;             PG8_LDA(At, 1, 1); PG8_STAGE(PG8_SB(1, 0), b3, voffB); PG8_STAGE(PG8_SB(1, 1), b3 + hstep, voffB); PG8_STAGE(PG8_SA(1, 0), a3, voffA);
;             PG8_WAIT_V(8); PG8_WAIT_L(0); PG8_BAR; PG8_MMA(1, 0, At, B0); PG8_MMA(1, 1, At, B1); PG8_BAR; PG8_SCHED;
	s_mov_b32 m0, s72
	s_nop 0
	global_load_lds_dwordx4 v156, s[48:49]
	s_waitcnt vmcnt(8)
	s_waitcnt lgkmcnt(0)
	s_barrier
	s_setprio 1
	s_waitcnt lgkmcnt(0)
	v_mfma_f32_16x16x32_bf16 v[60:63], v[128:131], v[176:179], v[60:63]
	v_mfma_f32_16x16x32_bf16 v[56:59], v[136:139], v[176:179], v[56:59]
	v_mfma_f32_16x16x32_bf16 v[44:47], v[128:131], v[194:197], v[44:47]
	v_mfma_f32_16x16x32_bf16 v[40:43], v[136:139], v[194:197], v[40:43]
	v_mfma_f32_16x16x32_bf16 v[28:31], v[128:131], v[204:207], v[28:31]
	v_mfma_f32_16x16x32_bf16 v[24:27], v[136:139], v[204:207], v[24:27]
	v_mfma_f32_16x16x32_bf16 v[12:15], v[128:131], v[212:215], v[12:15]
	v_mfma_f32_16x16x32_bf16 v[8:11], v[136:139], v[212:215], v[8:11]
	v_mfma_f32_16x16x32_bf16 v[60:63], v[132:135], v[180:183], v[60:63]
	v_mfma_f32_16x16x32_bf16 v[56:59], v[140:143], v[180:183], v[56:59]
	v_mfma_f32_16x16x32_bf16 v[44:47], v[132:135], v[200:203], v[44:47]
	v_mfma_f32_16x16x32_bf16 v[40:43], v[140:143], v[200:203], v[40:43]
	v_mfma_f32_16x16x32_bf16 v[28:31], v[132:135], v[208:211], v[28:31]
	v_mfma_f32_16x16x32_bf16 v[24:27], v[140:143], v[208:211], v[24:27]
	v_mfma_f32_16x16x32_bf16 v[12:15], v[132:135], v[216:219], v[12:15]
	v_mfma_f32_16x16x32_bf16 v[8:11], v[140:143], v[216:219], v[8:11]
	s_setprio 0
	s_setprio 1
	v_mfma_f32_16x16x32_bf16 v[52:55], v[144:147], v[176:179], v[52:55]
	v_mfma_f32_16x16x32_bf16 v[48:51], v[168:171], v[176:179], v[48:51]
	v_mfma_f32_16x16x32_bf16 v[36:39], v[144:147], v[194:197], v[36:39]
	v_mfma_f32_16x16x32_bf16 v[32:35], v[168:171], v[194:197], v[32:35]
	v_mfma_f32_16x16x32_bf16 v[20:23], v[144:147], v[204:207], v[20:23]
	v_mfma_f32_16x16x32_bf16 v[16:19], v[168:171], v[204:207], v[16:19]
	v_mfma_f32_16x16x32_bf16 v[4:7], v[144:147], v[212:215], v[4:7]
	v_mfma_f32_16x16x32_bf16 v[0:3], v[168:171], v[212:215], v[0:3]
	v_mfma_f32_16x16x32_bf16 v[52:55], v[148:151], v[180:183], v[52:55]
	v_mfma_f32_16x16x32_bf16 v[48:51], v[172:175], v[180:183], v[48:51]
	v_mfma_f32_16x16x32_bf16 v[36:39], v[148:151], v[200:203], v[36:39]
	v_mfma_f32_16x16x32_bf16 v[32:35], v[172:175], v[200:203], v[32:35]
	v_mfma_f32_16x16x32_bf16 v[20:23], v[148:151], v[208:211], v[20:23]
	v_mfma_f32_16x16x32_bf16 v[16:19], v[172:175], v[208:211], v[16:19]
	v_mfma_f32_16x16x32_bf16 v[4:7], v[148:151], v[216:219], v[4:7]
	v_mfma_f32_16x16x32_bf16 v[0:3], v[172:175], v[216:219], v[0:3]
	s_setprio 0
	s_barrier
	s_add_i32 s81, s81, 2
	s_add_u32 s79, s79, 0x100
	s_addc_u32 s80, s80, 0
	s_add_u32 s46, s46, 0x10000
	s_addc_u32 s47, s47, 0
	s_cmp_gt_u32 s81, 41
	s_cbranch_scc0 .LBB0_211
	s_and_b64 vcc, exec, s[42:43]
	s_cbranch_vccz .LBB0_214
	s_barrier

; #define PG8_STAGE(bufoff, gbase, voff) do { _Pragma("unroll") for (int _i = 0; _i < 2; ++_i) \
;         __builtin_amdgcn_global_load_lds((const unsigned*)((const char*)(gbase) + (voff)[_i]), (PG8_LAS unsigned*)(lds + (bufoff) + ldsw + _i * 8192), 16, 0, 0); } while (0)
; #define PG8_LDA(dst, b, h) do { _Pragma("unroll") for (int m = 0; m < 4; ++m) _Pragma("unroll") for (int k = 0; k < 2; ++k) dst[m][k] = *(const PG8_LAS bf16x8*)(lds + PG8_SA(b, h) + aoff + m * 2048 + k * 1024); } while (0)
; #define PG8_LDB(dst, b, h) do { _Pragma("unroll") for (int n = 0; n < 2; ++n) _Pragma("unroll") for (int k = 0; k < 2; ++k) dst[n][k] = *(const PG8_LAS bf16x8*)(lds + PG8_SB(b, h) + boff + n * 2048 + k * 1024); } while (0)
; #define PG8_SCHED __builtin_amdgcn_sched_barrier(0)
; template <class Epi, class Sched, bool ALIGN_EPI = false, bool SP2 = false, bool ATILED = false>
; __device__ __forceinline__ void gemm_phase(PG8_LAS unsigned char* lds, const Gemm g, const Sched& S, const Epi& E) {
;     ...
;             const char* a1 = cA + (size_t)(t + 1) * kstepA;
;             const char* a2 = last ? nA : cA + (size_t)(t + 2) * kstepA; const char* b2 = last ? nB : cB + (size_t)(t + 2) * kstep;
;             const char* a3 = a2 + kstepA; const char* b3 = b2 + kstep;
;             if (last && has_next) S.a_ready(nxt);
;             if constexpr (SP2) {
;             PG8_LDB(B0, 0, 0); PG8_LDB(B1, 0, 1); PG8_SCHED; PG8_LDA(At, 0, 0); PG8_STAGE(PG8_SA(1, 1), a1 + hstepA, voffA);
.LBB0_299:
	s_ashr_i32 s49, s48, 31
	s_lshl_b64 s[58:59], s[48:49], 19
	s_add_u32 s58, s26, s58
	s_addc_u32 s59, s27, s59
	s_and_b64 s[60:61], s[0:1], exec
	s_cselect_b32 s5, s59, s65
	s_cselect_b32 s6, s58, s64
	s_ashr_i32 s47, s46, 31
	s_lshl_b64 s[60:61], s[46:47], 19
	s_add_u32 s60, s54, s60
	s_addc_u32 s61, s55, s61
	s_and_b64 s[68:69], s[0:1], exec
	s_cselect_b32 s45, s61, s67
	s_cselect_b32 s47, s60, s66
	s_add_u32 s64, s64, 0x40080
	s_addc_u32 s65, s65, 0
	s_add_u32 s49, s66, 0x100
	s_addc_u32 s63, s67, 0
	s_mov_b32 s83, -2
	ds_read_b128 v[156:159], v201
	ds_read_b128 v[160:163], v201 offset:1024
	ds_read_b128 v[164:167], v201 offset:2048
	ds_read_b128 v[168:171], v201 offset:3072
	ds_read_b128 v[172:175], v202
	ds_read_b128 v[176:179], v202 offset:1024
	ds_read_b128 v[180:183], v202 offset:2048
	ds_read_b128 v[184:187], v202 offset:3072
	s_add_u32 s66, s64, 0xfffc0080
	s_addc_u32 s67, s65, -1
	s_cmp_eq_u32 s83, 12
	s_cselect_b32 s69, s5, s67
	s_cselect_b32 s68, s6, s66
	s_cselect_b32 s67, s45, s63
	s_cselect_b32 s66, s47, s49

; #define PG8_STAGE(bufoff, gbase, voff) do { _Pragma("unroll") for (int _i = 0; _i < 2; ++_i) \
;         __builtin_amdgcn_global_load_lds((const unsigned*)((const char*)(gbase) + (voff)[_i]), (PG8_LAS unsigned*)(lds + (bufoff) + ldsw + _i * 8192), 16, 0, 0); } while (0)
; #define PG8_LDA(dst, b, h) do { _Pragma("unroll") for (int m = 0; m < 4; ++m) _Pragma("unroll") for (int k = 0; k < 2; ++k) dst[m][k] = *(const PG8_LAS bf16x8*)(lds + PG8_SA(b, h) + aoff + m * 2048 + k * 1024); } while (0)
; #define PG8_LDB(dst, b, h) do { _Pragma("unroll") for (int n = 0; n < 2; ++n) _Pragma("unroll") for (int k = 0; k < 2; ++k) dst[n][k] = *(const PG8_LAS bf16x8*)(lds + PG8_SB(b, h) + boff + n * 2048 + k * 1024); } while (0)
; #define PG8_SCHED __builtin_amdgcn_sched_barrier(0)
; template <class Epi, class Sched, bool ALIGN_EPI = false, bool SP2 = false, bool ATILED = false>
; __device__ __forceinline__ void gemm_phase(PG8_LAS unsigned char* lds, const Gemm g, const Sched& S, const Epi& E) {
;     ...
;             PG8_LDB(B0, 0, 0); PG8_LDB(B1, 0, 1); PG8_SCHED; PG8_LDA(At, 0, 0); PG8_STAGE(PG8_SA(1, 1), a1 + hstepA, voffA);
	s_add_i32 m0, s71, 0xc000
	ds_read_b128 v[188:191], v203
	ds_read_b128 v[192:195], v203 offset:1024
	ds_read_b128 v[208:211], v203 offset:2048
	ds_read_b128 v[212:215], v203 offset:3072
	ds_read_b128 v[216:219], v203 offset:4096
	ds_read_b128 v[220:223], v203 offset:5120
	ds_read_b128 v[224:227], v203 offset:6144
	ds_read_b128 v[228:231], v203 offset:7168
	global_load_lds_dwordx4 v146, s[64:65]

; #define PG8_STAGE(bufoff, gbase, voff) do { _Pragma("unroll") for (int _i = 0; _i < 2; ++_i) \
;         __builtin_amdgcn_global_load_lds((const unsigned*)((const char*)(gbase) + (voff)[_i]), (PG8_LAS unsigned*)(lds + (bufoff) + ldsw + _i * 8192), 16, 0, 0); } while (0)
; #define PG8_LDA(dst, b, h) do { _Pragma("unroll") for (int m = 0; m < 4; ++m) _Pragma("unroll") for (int k = 0; k < 2; ++k) dst[m][k] = *(const PG8_LAS bf16x8*)(lds + PG8_SA(b, h) + aoff + m * 2048 + k * 1024); } while (0)
; #define PG8_LDB(dst, b, h) do { _Pragma("unroll") for (int n = 0; n < 2; ++n) _Pragma("unroll") for (int k = 0; k < 2; ++k) dst[n][k] = *(const PG8_LAS bf16x8*)(lds + PG8_SB(b, h) + boff + n * 2048 + k * 1024); } while (0)
; #define PG8_MMA(ai, bj, At, Bt) do { __builtin_amdgcn_s_setprio(1); _Pragma("unroll") for (int m = 0; m < 4; ++m) _Pragma("unroll") for (int n = 0; n < 2; ++n) _Pragma("unroll") for (int k = 0; k < 2; ++k) \
;         acc[ai][bj][m][n] = __builtin_amdgcn_mfma_f32_16x16x32_bf16(Bt[n][k], At[m][k], acc[ai][bj][m][n], 0, 0, 0); __builtin_amdgcn_s_setprio(0); } while (0)
; #define PG8_WAIT_V(n) asm volatile("s_waitcnt vmcnt(" #n ")" ::: "memory")
; #define PG8_WAIT_L(n) asm volatile("s_waitcnt lgkmcnt(" #n ")" ::: "memory")
; #define PG8_BAR __builtin_amdgcn_s_barrier()
; #define PG8_SCHED __builtin_amdgcn_sched_barrier(0)
; template <class Epi, class Sched, bool ALIGN_EPI = false, bool SP2 = false, bool ATILED = false>
; __device__ __forceinline__ void gemm_phase(PG8_LAS unsigned char* lds, const Gemm g, const Sched& S, const Epi& E) {
;     ...
;             PG8_LDB(B0, 0, 0); PG8_LDB(B1, 0, 1); PG8_SCHED; PG8_LDA(At, 0, 0); PG8_STAGE(PG8_SA(1, 1), a1 + hstepA, voffA);
;             PG8_WAIT_V(8); PG8_WAIT_L(0); PG8_BAR; PG8_MMA(0, 0, At, B0); PG8_MMA(0, 1, At, B1); PG8_BAR; PG8_SCHED;
	s_add_i32 m0, s71, 0xe000
	s_nop 0
	global_load_lds_dwordx4 v148, s[64:65]
	s_waitcnt vmcnt(8)
	s_waitcnt lgkmcnt(0)
	s_barrier
	s_setprio 1
	s_waitcnt lgkmcnt(0)
	v_mfma_f32_16x16x32_bf16 v[124:127], v[156:159], v[188:191], 0
	v_mfma_f32_16x16x32_bf16 v[120:123], v[164:167], v[188:191], 0
	v_mfma_f32_16x16x32_bf16 v[116:119], v[156:159], v[208:211], 0
	v_mfma_f32_16x16x32_bf16 v[112:115], v[164:167], v[208:211], 0
	v_mfma_f32_16x16x32_bf16 v[96:99], v[156:159], v[216:219], 0
	v_mfma_f32_16x16x32_bf16 v[88:91], v[164:167], v[216:219], 0
	v_mfma_f32_16x16x32_bf16 v[80:83], v[156:159], v[224:227], 0
	v_mfma_f32_16x16x32_bf16 v[72:75], v[164:167], v[224:227], 0
	v_mfma_f32_16x16x32_bf16 v[124:127], v[160:163], v[192:195], v[124:127]
	v_mfma_f32_16x16x32_bf16 v[120:123], v[168:171], v[192:195], v[120:123]
	v_mfma_f32_16x16x32_bf16 v[116:119], v[160:163], v[212:215], v[116:119]
	v_mfma_f32_16x16x32_bf16 v[112:115], v[168:171], v[212:215], v[112:115]
	v_mfma_f32_16x16x32_bf16 v[96:99], v[160:163], v[220:223], v[96:99]
	v_mfma_f32_16x16x32_bf16 v[88:91], v[168:171], v[220:223], v[88:91]
	v_mfma_f32_16x16x32_bf16 v[80:83], v[160:163], v[228:231], v[80:83]
	v_mfma_f32_16x16x32_bf16 v[72:75], v[168:171], v[228:231], v[72:75]
	s_setprio 0
	s_setprio 1
	v_mfma_f32_16x16x32_bf16 v[108:111], v[172:175], v[188:191], 0
	v_mfma_f32_16x16x32_bf16 v[104:107], v[180:183], v[188:191], 0
	v_mfma_f32_16x16x32_bf16 v[100:103], v[172:175], v[208:211], 0
	v_mfma_f32_16x16x32_bf16 v[92:95], v[180:183], v[208:211], 0
	v_mfma_f32_16x16x32_bf16 v[84:87], v[172:175], v[216:219], 0
	v_mfma_f32_16x16x32_bf16 v[76:79], v[180:183], v[216:219], 0
	v_mfma_f32_16x16x32_bf16 v[68:71], v[172:175], v[224:227], 0
	v_mfma_f32_16x16x32_bf16 v[64:67], v[180:183], v[224:227], 0
	v_mfma_f32_16x16x32_bf16 v[108:111], v[176:179], v[192:195], v[108:111]
	v_mfma_f32_16x16x32_bf16 v[104:107], v[184:187], v[192:195], v[104:107]
	v_mfma_f32_16x16x32_bf16 v[100:103], v[176:179], v[212:215], v[100:103]
	v_mfma_f32_16x16x32_bf16 v[92:95], v[184:187], v[212:215], v[92:95]
	v_mfma_f32_16x16x32_bf16 v[84:87], v[176:179], v[220:223], v[84:87]
	v_mfma_f32_16x16x32_bf16 v[76:79], v[184:187], v[220:223], v[76:79]
	v_mfma_f32_16x16x32_bf16 v[68:71], v[176:179], v[228:231], v[68:71]
	v_mfma_f32_16x16x32_bf16 v[64:67], v[184:187], v[228:231], v[64:67]
	s_setprio 0
	s_barrier
	s_add_u32 s98, s66, s38
	s_addc_u32 s99, s67, s39
	s_add_u32 s100, s68, s38
	s_addc_u32 s101, s69, s39
	s_add_i32 s84, s79, s70

; #define PG8_STAGE(bufoff, gbase, voff) do { _Pragma("unroll") for (int _i = 0; _i < 2; ++_i) \
;         __builtin_amdgcn_global_load_lds((const unsigned*)((const char*)(gbase) + (voff)[_i]), (PG8_LAS unsigned*)(lds + (bufoff) + ldsw + _i * 8192), 16, 0, 0); } while (0)
; #define PG8_LDA(dst, b, h) do { _Pragma("unroll") for (int m = 0; m < 4; ++m) _Pragma("unroll") for (int k = 0; k < 2; ++k) dst[m][k] = *(const PG8_LAS bf16x8*)(lds + PG8_SA(b, h) + aoff + m * 2048 + k * 1024); } while (0)
; template <class Epi, class Sched, bool ALIGN_EPI = false, bool SP2 = false, bool ATILED = false>
; __device__ __forceinline__ void gemm_phase(PG8_LAS unsigned char* lds, const Gemm g, const Sched& S, const Epi& E) {
;     ...
;             PG8_LDA(At, 0, 1); PG8_STAGE(PG8_SB(0, 0), b2, voffB); PG8_STAGE(PG8_SB(0, 1), b2 + hstep, voffB); PG8_STAGE(PG8_SA(0, 0), a2, voffA);
	s_mov_b32 m0, s84
	ds_read_b128 v[188:191], v203 offset:16384
	ds_read_b128 v[192:195], v203 offset:17408
	ds_read_b128 v[208:211], v203 offset:18432
	ds_read_b128 v[212:215], v203 offset:19456
	ds_read_b128 v[216:219], v203 offset:20480
	ds_read_b128 v[220:223], v203 offset:21504
	ds_read_b128 v[224:227], v203 offset:22528
	ds_read_b128 v[228:231], v203 offset:23552
	global_load_lds_dwordx4 v130, s[66:67]
	s_add_i32 m0, s84, 0x2000
	s_add_u32 s84, s66, 0x40000

; #define PG8_STAGE(bufoff, gbase, voff) do { _Pragma("unroll") for (int _i = 0; _i < 2; ++_i) \
;         __builtin_amdgcn_global_load_lds((const unsigned*)((const char*)(gbase) + (voff)[_i]), (PG8_LAS unsigned*)(lds + (bufoff) + ldsw + _i * 8192), 16, 0, 0); } while (0)
; #define PG8_LDA(dst, b, h) do { _Pragma("unroll") for (int m = 0; m < 4; ++m) _Pragma("unroll") for (int k = 0; k < 2; ++k) dst[m][k] = *(const PG8_LAS bf16x8*)(lds + PG8_SA(b, h) + aoff + m * 2048 + k * 1024); } while (0)
; template <class Epi, class Sched, bool ALIGN_EPI = false, bool SP2 = false, bool ATILED = false>
; __device__ __forceinline__ void gemm_phase(PG8_LAS unsigned char* lds, const Gemm g, const Sched& S, const Epi& E) {
;     ...
;             PG8_LDA(At, 0, 1); PG8_STAGE(PG8_SB(0, 0), b2, voffB); PG8_STAGE(PG8_SB(0, 1), b2 + hstep, voffB); PG8_STAGE(PG8_SA(0, 0), a2, voffA);
	s_addc_u32 s85, s67, 0
	s_add_i32 s86, s80, s70
	global_load_lds_dwordx4 v134, s[66:67]

; #define PG8_STAGE(bufoff, gbase, voff) do { _Pragma("unroll") for (int _i = 0; _i < 2; ++_i) \
;         __builtin_amdgcn_global_load_lds((const unsigned*)((const char*)(gbase) + (voff)[_i]), (PG8_LAS unsigned*)(lds + (bufoff) + ldsw + _i * 8192), 16, 0, 0); } while (0)
; #define PG8_LDA(dst, b, h) do { _Pragma("unroll") for (int m = 0; m < 4; ++m) _Pragma("unroll") for (int k = 0; k < 2; ++k) dst[m][k] = *(const PG8_LAS bf16x8*)(lds + PG8_SA(b, h) + aoff + m * 2048 + k * 1024); } while (0)
; template <class Epi, class Sched, bool ALIGN_EPI = false, bool SP2 = false, bool ATILED = false>
; __device__ __forceinline__ void gemm_phase(PG8_LAS unsigned char* lds, const Gemm g, const Sched& S, const Epi& E) {
;     ...
;             PG8_LDA(At, 0, 1); PG8_STAGE(PG8_SB(0, 0), b2, voffB); PG8_STAGE(PG8_SB(0, 1), b2 + hstep, voffB); PG8_STAGE(PG8_SA(0, 0), a2, voffA);
	s_mov_b32 m0, s86

; #define PG8_STAGE(bufoff, gbase, voff) do { _Pragma("unroll") for (int _i = 0; _i < 2; ++_i) \
;         __builtin_amdgcn_global_load_lds((const unsigned*)((const char*)(gbase) + (voff)[_i]), (PG8_LAS unsigned*)(lds + (bufoff) + ldsw + _i * 8192), 16, 0, 0); } while (0)
; #define PG8_LDA(dst, b, h) do { _Pragma("unroll") for (int m = 0; m < 4; ++m) _Pragma("unroll") for (int k = 0; k < 2; ++k) dst[m][k] = *(const PG8_LAS bf16x8*)(lds + PG8_SA(b, h) + aoff + m * 2048 + k * 1024); } while (0)
; template <class Epi, class Sched, bool ALIGN_EPI = false, bool SP2 = false, bool ATILED = false>
; __device__ __forceinline__ void gemm_phase(PG8_LAS unsigned char* lds, const Gemm g, const Sched& S, const Epi& E) {
;     ...
;             PG8_LDA(At, 0, 1); PG8_STAGE(PG8_SB(0, 0), b2, voffB); PG8_STAGE(PG8_SB(0, 1), b2 + hstep, voffB); PG8_STAGE(PG8_SA(0, 0), a2, voffA);
	s_nop 0
	global_load_lds_dwordx4 v130, s[84:85]

; #define PG8_STAGE(bufoff, gbase, voff) do { _Pragma("unroll") for (int _i = 0; _i < 2; ++_i) \
;         __builtin_amdgcn_global_load_lds((const unsigned*)((const char*)(gbase) + (voff)[_i]), (PG8_LAS unsigned*)(lds + (bufoff) + ldsw + _i * 8192), 16, 0, 0); } while (0)
; #define PG8_LDA(dst, b, h) do { _Pragma("unroll") for (int m = 0; m < 4; ++m) _Pragma("unroll") for (int k = 0; k < 2; ++k) dst[m][k] = *(const PG8_LAS bf16x8*)(lds + PG8_SA(b, h) + aoff + m * 2048 + k * 1024); } while (0)
; template <class Epi, class Sched, bool ALIGN_EPI = false, bool SP2 = false, bool ATILED = false>
; __device__ __forceinline__ void gemm_phase(PG8_LAS unsigned char* lds, const Gemm g, const Sched& S, const Epi& E) {
;     ...
;             PG8_LDA(At, 0, 1); PG8_STAGE(PG8_SB(0, 0), b2, voffB); PG8_STAGE(PG8_SB(0, 1), b2 + hstep, voffB); PG8_STAGE(PG8_SA(0, 0), a2, voffA);
	s_add_i32 m0, s86, 0x2000
	s_nop 0
	global_load_lds_dwordx4 v134, s[84:85]

; #define PG8_STAGE(bufoff, gbase, voff) do { _Pragma("unroll") for (int _i = 0; _i < 2; ++_i) \
;         __builtin_amdgcn_global_load_lds((const unsigned*)((const char*)(gbase) + (voff)[_i]), (PG8_LAS unsigned*)(lds + (bufoff) + ldsw + _i * 8192), 16, 0, 0); } while (0)
; #define PG8_LDA(dst, b, h) do { _Pragma("unroll") for (int m = 0; m < 4; ++m) _Pragma("unroll") for (int k = 0; k < 2; ++k) dst[m][k] = *(const PG8_LAS bf16x8*)(lds + PG8_SA(b, h) + aoff + m * 2048 + k * 1024); } while (0)
; #define PG8_LDB(dst, b, h) do { _Pragma("unroll") for (int n = 0; n < 2; ++n) _Pragma("unroll") for (int k = 0; k < 2; ++k) dst[n][k] = *(const PG8_LAS bf16x8*)(lds + PG8_SB(b, h) + boff + n * 2048 + k * 1024); } while (0)
; #define PG8_MMA(ai, bj, At, Bt) do { __builtin_amdgcn_s_setprio(1); _Pragma("unroll") for (int m = 0; m < 4; ++m) _Pragma("unroll") for (int n = 0; n < 2; ++n) _Pragma("unroll") for (int k = 0; k < 2; ++k) \
;         acc[ai][bj][m][n] = __builtin_amdgcn_mfma_f32_16x16x32_bf16(Bt[n][k], At[m][k], acc[ai][bj][m][n], 0, 0, 0); __builtin_amdgcn_s_setprio(0); } while (0)
; #define PG8_WAIT_V(n) asm volatile("s_waitcnt vmcnt(" #n ")" ::: "memory")
; #define PG8_WAIT_L(n) asm volatile("s_waitcnt lgkmcnt(" #n ")" ::: "memory")
; #define PG8_BAR __builtin_amdgcn_s_barrier()
; #define PG8_SCHED __builtin_amdgcn_sched_barrier(0)
; template <class Epi, class Sched, bool ALIGN_EPI = false, bool SP2 = false, bool ATILED = false>
; __device__ __forceinline__ void gemm_phase(PG8_LAS unsigned char* lds, const Gemm g, const Sched& S, const Epi& E) {
;     ...
;             PG8_LDA(At, 0, 1); PG8_STAGE(PG8_SB(0, 0), b2, voffB); PG8_STAGE(PG8_SB(0, 1), b2 + hstep, voffB); PG8_STAGE(PG8_SA(0, 0), a2, voffA);
;             PG8_WAIT_V(8); PG8_WAIT_L(0); PG8_BAR; PG8_MMA(1, 0, At, B0); PG8_MMA(1, 1, At, B1); PG8_BAR; PG8_SCHED;
;             PG8_LDB(B0, 1, 0); PG8_LDB(B1, 1, 1); PG8_SCHED; PG8_LDA(At, 1, 0); PG8_STAGE(PG8_SA(0, 1), a2 + hstepA, voffA);
	s_mov_b32 m0, s71
	s_nop 0
	global_load_lds_dwordx4 v128, s[68:69]
	s_mov_b32 m0, s72
	s_nop 0
	global_load_lds_dwordx4 v132, s[68:69]
	s_waitcnt vmcnt(8)
	s_waitcnt lgkmcnt(0)
	s_barrier
	s_setprio 1
	s_waitcnt lgkmcnt(0)
	v_mfma_f32_16x16x32_bf16 v[60:63], v[156:159], v[188:191], 0
	v_mfma_f32_16x16x32_bf16 v[56:59], v[164:167], v[188:191], 0
	v_mfma_f32_16x16x32_bf16 v[48:51], v[156:159], v[208:211], 0
	v_mfma_f32_16x16x32_bf16 v[40:43], v[164:167], v[208:211], 0
	v_mfma_f32_16x16x32_bf16 v[32:35], v[156:159], v[216:219], 0
	v_mfma_f32_16x16x32_bf16 v[24:27], v[164:167], v[216:219], 0
	v_mfma_f32_16x16x32_bf16 v[16:19], v[156:159], v[224:227], 0
	v_mfma_f32_16x16x32_bf16 v[8:11], v[164:167], v[224:227], 0
	v_mfma_f32_16x16x32_bf16 v[60:63], v[160:163], v[192:195], v[60:63]
	v_mfma_f32_16x16x32_bf16 v[56:59], v[168:171], v[192:195], v[56:59]
	v_mfma_f32_16x16x32_bf16 v[48:51], v[160:163], v[212:215], v[48:51]
	v_mfma_f32_16x16x32_bf16 v[40:43], v[168:171], v[212:215], v[40:43]
	v_mfma_f32_16x16x32_bf16 v[32:35], v[160:163], v[220:223], v[32:35]
	v_mfma_f32_16x16x32_bf16 v[24:27], v[168:171], v[220:223], v[24:27]
	v_mfma_f32_16x16x32_bf16 v[16:19], v[160:163], v[228:231], v[16:19]
	v_mfma_f32_16x16x32_bf16 v[8:11], v[168:171], v[228:231], v[8:11]
	s_setprio 0
	s_setprio 1
	v_mfma_f32_16x16x32_bf16 v[52:55], v[172:175], v[188:191], 0
	v_mfma_f32_16x16x32_bf16 v[44:47], v[180:183], v[188:191], 0
	v_mfma_f32_16x16x32_bf16 v[36:39], v[172:175], v[208:211], 0
	v_mfma_f32_16x16x32_bf16 v[28:31], v[180:183], v[208:211], 0
	v_mfma_f32_16x16x32_bf16 v[20:23], v[172:175], v[216:219], 0
	v_mfma_f32_16x16x32_bf16 v[12:15], v[180:183], v[216:219], 0
	v_mfma_f32_16x16x32_bf16 v[4:7], v[172:175], v[224:227], 0
	v_mfma_f32_16x16x32_bf16 v[0:3], v[180:183], v[224:227], 0
	v_mfma_f32_16x16x32_bf16 v[52:55], v[176:179], v[192:195], v[52:55]
	v_mfma_f32_16x16x32_bf16 v[44:47], v[184:187], v[192:195], v[44:47]
	v_mfma_f32_16x16x32_bf16 v[36:39], v[176:179], v[212:215], v[36:39]
	v_mfma_f32_16x16x32_bf16 v[28:31], v[184:187], v[212:215], v[28:31]
	v_mfma_f32_16x16x32_bf16 v[20:23], v[176:179], v[220:223], v[20:23]
	v_mfma_f32_16x16x32_bf16 v[12:15], v[184:187], v[220:223], v[12:15]
	v_mfma_f32_16x16x32_bf16 v[4:7], v[176:179], v[228:231], v[4:7]
	v_mfma_f32_16x16x32_bf16 v[0:3], v[184:187], v[228:231], v[0:3]
	s_setprio 0
	s_barrier
	s_add_i32 s84, 0, 0x18000
	v_add_u32_e32 v136, s84, v200
	s_add_i32 s85, 0, 0x1c000
	ds_read_b128 v[156:159], v136
	ds_read_b128 v[160:163], v136 offset:1024
	ds_read_b128 v[164:167], v136 offset:2048
	ds_read_b128 v[168:171], v136 offset:3072
	v_add_u32_e32 v136, s85, v200
	ds_read_b128 v[172:175], v136
	ds_read_b128 v[176:179], v136 offset:1024
	ds_read_b128 v[180:183], v136 offset:2048
	ds_read_b128 v[184:187], v136 offset:3072
	s_add_u32 s68, s68, 0x40000
	s_addc_u32 s69, s69, 0
	s_mov_b32 m0, s73

; #define PG8_STAGE(bufoff, gbase, voff) do { _Pragma("unroll") for (int _i = 0; _i < 2; ++_i) \
;         __builtin_amdgcn_global_load_lds((const unsigned*)((const char*)(gbase) + (voff)[_i]), (PG8_LAS unsigned*)(lds + (bufoff) + ldsw + _i * 8192), 16, 0, 0); } while (0)
; #define PG8_LDA(dst, b, h) do { _Pragma("unroll") for (int m = 0; m < 4; ++m) _Pragma("unroll") for (int k = 0; k < 2; ++k) dst[m][k] = *(const PG8_LAS bf16x8*)(lds + PG8_SA(b, h) + aoff + m * 2048 + k * 1024); } while (0)
; #define PG8_LDB(dst, b, h) do { _Pragma("unroll") for (int n = 0; n < 2; ++n) _Pragma("unroll") for (int k = 0; k < 2; ++k) dst[n][k] = *(const PG8_LAS bf16x8*)(lds + PG8_SB(b, h) + boff + n * 2048 + k * 1024); } while (0)
; #define PG8_SCHED __builtin_amdgcn_sched_barrier(0)
; template <class Epi, class Sched, bool ALIGN_EPI = false, bool SP2 = false, bool ATILED = false>
; __device__ __forceinline__ void gemm_phase(PG8_LAS unsigned char* lds, const Gemm g, const Sched& S, const Epi& E) {
;     ...
;             PG8_LDB(B0, 1, 0); PG8_LDB(B1, 1, 1); PG8_SCHED; PG8_LDA(At, 1, 0); PG8_STAGE(PG8_SA(0, 1), a2 + hstepA, voffA);
	ds_read_b128 v[188:191], v203 offset:32768
	ds_read_b128 v[192:195], v203 offset:33792
	ds_read_b128 v[208:211], v203 offset:34816
	ds_read_b128 v[212:215], v203 offset:35840
	ds_read_b128 v[216:219], v203 offset:36864
	ds_read_b128 v[220:223], v203 offset:37888
	ds_read_b128 v[224:227], v203 offset:38912
	ds_read_b128 v[228:231], v203 offset:39936
	global_load_lds_dwordx4 v128, s[68:69]

; #define PG8_STAGE(bufoff, gbase, voff) do { _Pragma("unroll") for (int _i = 0; _i < 2; ++_i) \
;         __builtin_amdgcn_global_load_lds((const unsigned*)((const char*)(gbase) + (voff)[_i]), (PG8_LAS unsigned*)(lds + (bufoff) + ldsw + _i * 8192), 16, 0, 0); } while (0)
; #define PG8_LDA(dst, b, h) do { _Pragma("unroll") for (int m = 0; m < 4; ++m) _Pragma("unroll") for (int k = 0; k < 2; ++k) dst[m][k] = *(const PG8_LAS bf16x8*)(lds + PG8_SA(b, h) + aoff + m * 2048 + k * 1024); } while (0)
; #define PG8_LDB(dst, b, h) do { _Pragma("unroll") for (int n = 0; n < 2; ++n) _Pragma("unroll") for (int k = 0; k < 2; ++k) dst[n][k] = *(const PG8_LAS bf16x8*)(lds + PG8_SB(b, h) + boff + n * 2048 + k * 1024); } while (0)
; #define PG8_MMA(ai, bj, At, Bt) do { __builtin_amdgcn_s_setprio(1); _Pragma("unroll") for (int m = 0; m < 4; ++m) _Pragma("unroll") for (int n = 0; n < 2; ++n) _Pragma("unroll") for (int k = 0; k < 2; ++k) \
;         acc[ai][bj][m][n] = __builtin_amdgcn_mfma_f32_16x16x32_bf16(Bt[n][k], At[m][k], acc[ai][bj][m][n], 0, 0, 0); __builtin_amdgcn_s_setprio(0); } while (0)
; #define PG8_WAIT_V(n) asm volatile("s_waitcnt vmcnt(" #n ")" ::: "memory")
; #define PG8_WAIT_L(n) asm volatile("s_waitcnt lgkmcnt(" #n ")" ::: "memory")
; #define PG8_BAR __builtin_amdgcn_s_barrier()
; #define PG8_SCHED __builtin_amdgcn_sched_barrier(0)
; template <class Epi, class Sched, bool ALIGN_EPI = false, bool SP2 = false, bool ATILED = false>
; __device__ __forceinline__ void gemm_phase(PG8_LAS unsigned char* lds, const Gemm g, const Sched& S, const Epi& E) {
;     ...
;             PG8_LDB(B0, 1, 0); PG8_LDB(B1, 1, 1); PG8_SCHED; PG8_LDA(At, 1, 0); PG8_STAGE(PG8_SA(0, 1), a2 + hstepA, voffA);
;             PG8_WAIT_V(8); PG8_WAIT_L(0); PG8_BAR; PG8_MMA(0, 0, At, B0); PG8_MMA(0, 1, At, B1); PG8_BAR; PG8_SCHED;
	s_mov_b32 m0, s74
	s_nop 0
	global_load_lds_dwordx4 v132, s[68:69]
	s_waitcnt vmcnt(8)
	s_waitcnt lgkmcnt(0)
	s_barrier
	s_setprio 1
	s_waitcnt lgkmcnt(0)
	v_mfma_f32_16x16x32_bf16 v[124:127], v[156:159], v[188:191], v[124:127]
	v_mfma_f32_16x16x32_bf16 v[120:123], v[164:167], v[188:191], v[120:123]
	v_mfma_f32_16x16x32_bf16 v[116:119], v[156:159], v[208:211], v[116:119]
	v_mfma_f32_16x16x32_bf16 v[112:115], v[164:167], v[208:211], v[112:115]
	v_mfma_f32_16x16x32_bf16 v[96:99], v[156:159], v[216:219], v[96:99]
	v_mfma_f32_16x16x32_bf16 v[88:91], v[164:167], v[216:219], v[88:91]
	v_mfma_f32_16x16x32_bf16 v[80:83], v[156:159], v[224:227], v[80:83]
	v_mfma_f32_16x16x32_bf16 v[72:75], v[164:167], v[224:227], v[72:75]
	v_mfma_f32_16x16x32_bf16 v[124:127], v[160:163], v[192:195], v[124:127]
	v_mfma_f32_16x16x32_bf16 v[120:123], v[168:171], v[192:195], v[120:123]
	v_mfma_f32_16x16x32_bf16 v[116:119], v[160:163], v[212:215], v[116:119]
	v_mfma_f32_16x16x32_bf16 v[112:115], v[168:171], v[212:215], v[112:115]
	v_mfma_f32_16x16x32_bf16 v[96:99], v[160:163], v[220:223], v[96:99]
	v_mfma_f32_16x16x32_bf16 v[88:91], v[168:171], v[220:223], v[88:91]
	v_mfma_f32_16x16x32_bf16 v[80:83], v[160:163], v[228:231], v[80:83]
	v_mfma_f32_16x16x32_bf16 v[72:75], v[168:171], v[228:231], v[72:75]
	s_setprio 0
	s_setprio 1
	v_mfma_f32_16x16x32_bf16 v[108:111], v[172:175], v[188:191], v[108:111]
	v_mfma_f32_16x16x32_bf16 v[104:107], v[180:183], v[188:191], v[104:107]
	v_mfma_f32_16x16x32_bf16 v[100:103], v[172:175], v[208:211], v[100:103]
	v_mfma_f32_16x16x32_bf16 v[92:95], v[180:183], v[208:211], v[92:95]
	v_mfma_f32_16x16x32_bf16 v[84:87], v[172:175], v[216:219], v[84:87]
	v_mfma_f32_16x16x32_bf16 v[76:79], v[180:183], v[216:219], v[76:79]
	v_mfma_f32_16x16x32_bf16 v[68:71], v[172:175], v[224:227], v[68:71]
	v_mfma_f32_16x16x32_bf16 v[64:67], v[180:183], v[224:227], v[64:67]
	v_mfma_f32_16x16x32_bf16 v[108:111], v[176:179], v[192:195], v[108:111]
	v_mfma_f32_16x16x32_bf16 v[104:107], v[184:187], v[192:195], v[104:107]
	v_mfma_f32_16x16x32_bf16 v[100:103], v[176:179], v[212:215], v[100:103]
	v_mfma_f32_16x16x32_bf16 v[92:95], v[184:187], v[212:215], v[92:95]
	v_mfma_f32_16x16x32_bf16 v[84:87], v[176:179], v[220:223], v[84:87]
	v_mfma_f32_16x16x32_bf16 v[76:79], v[184:187], v[220:223], v[76:79]
	v_mfma_f32_16x16x32_bf16 v[68:71], v[176:179], v[228:231], v[68:71]
	v_mfma_f32_16x16x32_bf16 v[64:67], v[184:187], v[228:231], v[64:67]
	s_setprio 0
	s_barrier
	s_add_i32 s68, s84, s70

; #define PG8_STAGE(bufoff, gbase, voff) do { _Pragma("unroll") for (int _i = 0; _i < 2; ++_i) \
;         __builtin_amdgcn_global_load_lds((const unsigned*)((const char*)(gbase) + (voff)[_i]), (PG8_LAS unsigned*)(lds + (bufoff) + ldsw + _i * 8192), 16, 0, 0); } while (0)
; #define PG8_LDA(dst, b, h) do { _Pragma("unroll") for (int m = 0; m < 4; ++m) _Pragma("unroll") for (int k = 0; k < 2; ++k) dst[m][k] = *(const PG8_LAS bf16x8*)(lds + PG8_SA(b, h) + aoff + m * 2048 + k * 1024); } while (0)
; template <class Epi, class Sched, bool ALIGN_EPI = false, bool SP2 = false, bool ATILED = false>
; __device__ __forceinline__ void gemm_phase(PG8_LAS unsigned char* lds, const Gemm g, const Sched& S, const Epi& E) {
;     ...
;             PG8_LDA(At, 1, 1); PG8_STAGE(PG8_SB(1, 0), b3, voffB); PG8_STAGE(PG8_SB(1, 1), b3 + hstep, voffB); PG8_STAGE(PG8_SA(1, 0), a3, voffA);
	s_mov_b32 m0, s68
	ds_read_b128 v[188:191], v203 offset:49152
	ds_read_b128 v[192:195], v203 offset:50176
	ds_read_b128 v[208:211], v203 offset:51200
	ds_read_b128 v[212:215], v203 offset:52224
	ds_read_b128 v[216:219], v203 offset:53248
	ds_read_b128 v[220:223], v203 offset:54272
	ds_read_b128 v[224:227], v203 offset:55296
	ds_read_b128 v[228:231], v203 offset:56320
	global_load_lds_dwordx4 v130, s[98:99]
	s_add_i32 m0, s68, 0x2000
	s_add_u32 s66, s66, 0x40080

; #define PG8_STAGE(bufoff, gbase, voff) do { _Pragma("unroll") for (int _i = 0; _i < 2; ++_i) \
;         __builtin_amdgcn_global_load_lds((const unsigned*)((const char*)(gbase) + (voff)[_i]), (PG8_LAS unsigned*)(lds + (bufoff) + ldsw + _i * 8192), 16, 0, 0); } while (0)
; #define PG8_LDA(dst, b, h) do { _Pragma("unroll") for (int m = 0; m < 4; ++m) _Pragma("unroll") for (int k = 0; k < 2; ++k) dst[m][k] = *(const PG8_LAS bf16x8*)(lds + PG8_SA(b, h) + aoff + m * 2048 + k * 1024); } while (0)
; template <class Epi, class Sched, bool ALIGN_EPI = false, bool SP2 = false, bool ATILED = false>
; __device__ __forceinline__ void gemm_phase(PG8_LAS unsigned char* lds, const Gemm g, const Sched& S, const Epi& E) {
;     ...
;             PG8_LDA(At, 1, 1); PG8_STAGE(PG8_SB(1, 0), b3, voffB); PG8_STAGE(PG8_SB(1, 1), b3 + hstep, voffB); PG8_STAGE(PG8_SA(1, 0), a3, voffA);
	s_addc_u32 s67, s67, 0
	s_add_i32 s68, s85, s70
	global_load_lds_dwordx4 v134, s[98:99]

; #define PG8_STAGE(bufoff, gbase, voff) do { _Pragma("unroll") for (int _i = 0; _i < 2; ++_i) \
;         __builtin_amdgcn_global_load_lds((const unsigned*)((const char*)(gbase) + (voff)[_i]), (PG8_LAS unsigned*)(lds + (bufoff) + ldsw + _i * 8192), 16, 0, 0); } while (0)
; #define PG8_LDA(dst, b, h) do { _Pragma("unroll") for (int m = 0; m < 4; ++m) _Pragma("unroll") for (int k = 0; k < 2; ++k) dst[m][k] = *(const PG8_LAS bf16x8*)(lds + PG8_SA(b, h) + aoff + m * 2048 + k * 1024); } while (0)
; template <class Epi, class Sched, bool ALIGN_EPI = false, bool SP2 = false, bool ATILED = false>
; __device__ __forceinline__ void gemm_phase(PG8_LAS unsigned char* lds, const Gemm g, const Sched& S, const Epi& E) {
;     ...
;             PG8_LDA(At, 1, 1); PG8_STAGE(PG8_SB(1, 0), b3, voffB); PG8_STAGE(PG8_SB(1, 1), b3 + hstep, voffB); PG8_STAGE(PG8_SA(1, 0), a3, voffA);
	s_mov_b32 m0, s68
	s_nop 0
	global_load_lds_dwordx4 v130, s[66:67]

; #define PG8_STAGE(bufoff, gbase, voff) do { _Pragma("unroll") for (int _i = 0; _i < 2; ++_i) \
;         __builtin_amdgcn_global_load_lds((const unsigned*)((const char*)(gbase) + (voff)[_i]), (PG8_LAS unsigned*)(lds + (bufoff) + ldsw + _i * 8192), 16, 0, 0); } while (0)
; #define PG8_LDA(dst, b, h) do { _Pragma("unroll") for (int m = 0; m < 4; ++m) _Pragma("unroll") for (int k = 0; k < 2; ++k) dst[m][k] = *(const PG8_LAS bf16x8*)(lds + PG8_SA(b, h) + aoff + m * 2048 + k * 1024); } while (0)
; template <class Epi, class Sched, bool ALIGN_EPI = false, bool SP2 = false, bool ATILED = false>
; __device__ __forceinline__ void gemm_phase(PG8_LAS unsigned char* lds, const Gemm g, const Sched& S, const Epi& E) {
;     ...
;             PG8_LDA(At, 1, 1); PG8_STAGE(PG8_SB(1, 0), b3, voffB); PG8_STAGE(PG8_SB(1, 1), b3 + hstep, voffB); PG8_STAGE(PG8_SA(1, 0), a3, voffA);
	s_add_i32 m0, s68, 0x2000
	s_nop 0
	global_load_lds_dwordx4 v134, s[66:67]

; #define PG8_STAGE(bufoff, gbase, voff) do { _Pragma("unroll") for (int _i = 0; _i < 2; ++_i) \
;         __builtin_amdgcn_global_load_lds((const unsigned*)((const char*)(gbase) + (voff)[_i]), (PG8_LAS unsigned*)(lds + (bufoff) + ldsw + _i * 8192), 16, 0, 0); } while (0)
; #define PG8_LDA(dst, b, h) do { _Pragma("unroll") for (int m = 0; m < 4; ++m) _Pragma("unroll") for (int k = 0; k < 2; ++k) dst[m][k] = *(const PG8_LAS bf16x8*)(lds + PG8_SA(b, h) + aoff + m * 2048 + k * 1024); } while (0)
; template <class Epi, class Sched, bool ALIGN_EPI = false, bool SP2 = false, bool ATILED = false>
; __device__ __forceinline__ void gemm_phase(PG8_LAS unsigned char* lds, const Gemm g, const Sched& S, const Epi& E) {
;     ...
;             PG8_LDA(At, 1, 1); PG8_STAGE(PG8_SB(1, 0), b3, voffB); PG8_STAGE(PG8_SB(1, 1), b3 + hstep, voffB); PG8_STAGE(PG8_SA(1, 0), a3, voffA);
	s_mov_b32 m0, s77
	s_nop 0
	global_load_lds_dwordx4 v128, s[100:101]

; #define PG8_STAGE(bufoff, gbase, voff) do { _Pragma("unroll") for (int _i = 0; _i < 2; ++_i) \
;         __builtin_amdgcn_global_load_lds((const unsigned*)((const char*)(gbase) + (voff)[_i]), (PG8_LAS unsigned*)(lds + (bufoff) + ldsw + _i * 8192), 16, 0, 0); } while (0)
; #define PG8_LDA(dst, b, h) do { _Pragma("unroll") for (int m = 0; m < 4; ++m) _Pragma("unroll") for (int k = 0; k < 2; ++k) dst[m][k] = *(const PG8_LAS bf16x8*)(lds + PG8_SA(b, h) + aoff + m * 2048 + k * 1024); } while (0)
; #define PG8_WAIT_V(n) asm volatile("s_waitcnt vmcnt(" #n ")" ::: "memory")
; #define PG8_WAIT_L(n) asm volatile("s_waitcnt lgkmcnt(" #n ")" ::: "memory")
; #define PG8_BAR __builtin_amdgcn_s_barrier()
; template <class Epi, class Sched, bool ALIGN_EPI = false, bool SP2 = false, bool ATILED = false>
; __device__ __forceinline__ void gemm_phase(PG8_LAS unsigned char* lds, const Gemm g, const Sched& S, const Epi& E) {
;     ...
;         for (int t = 0; t < nt; t += 2) {
;             const bool last = (t == nt - 2);
;             const char* a1 = cA + (size_t)(t + 1) * kstepA;
;             const char* a2 = last ? nA : cA + (size_t)(t + 2) * kstepA; const char* b2 = last ? nB : cB + (size_t)(t + 2) * kstep;
;             const char* a3 = a2 + kstepA; const char* b3 = b2 + kstep;
;             if (last && has_next) S.a_ready(nxt);
;             if constexpr (SP2) {
;             PG8_LDB(B0, 0, 0); PG8_LDB(B1, 0, 1); PG8_SCHED; PG8_LDA(At, 0, 0); PG8_STAGE(PG8_SA(1, 1), a1 + hstepA, voffA);
;             PG8_WAIT_V(8); PG8_WAIT_L(0); PG8_BAR; PG8_MMA(0, 0, At, B0); PG8_MMA(0, 1, At, B1); PG8_BAR; PG8_SCHED;
;             PG8_LDA(At, 0, 1); PG8_STAGE(PG8_SB(0, 0), b2, voffB); PG8_STAGE(PG8_SB(0, 1), b2 + hstep, voffB); PG8_STAGE(PG8_SA(0, 0), a2, voffA);
;             PG8_WAIT_V(8); PG8_WAIT_L(0); PG8_BAR; PG8_MMA(1, 0, At, B0); PG8_MMA(1, 1, At, B1); PG8_BAR; PG8_SCHED;
;             PG8_LDB(B0, 1, 0); PG8_LDB(B1, 1, 1); PG8_SCHED; PG8_LDA(At, 1, 0); PG8_STAGE(PG8_SA(0, 1), a2 + hstepA, voffA);
;             PG8_WAIT_V(8); PG8_WAIT_L(0); PG8_BAR; PG8_MMA(0, 0, At, B0); PG8_MMA(0, 1, At, B1); PG8_BAR; PG8_SCHED;
;             PG8_LDA(At, 1, 1); PG8_STAGE(PG8_SB(1, 0), b3, voffB); PG8_STAGE(PG8_SB(1, 1), b3 + hstep, voffB); PG8_STAGE(PG8_SA(1, 0), a3, voffA);
;             PG8_WAIT_V(8); PG8_WAIT_L(0); PG8_BAR; PG8_MMA(1, 0, At, B0); PG8_MMA(1, 1, At, B1); PG8_BAR; PG8_SCHED;
	s_mov_b32 m0, s78
	s_nop 0
	global_load_lds_dwordx4 v132, s[100:101]
	s_waitcnt vmcnt(8)
	s_waitcnt lgkmcnt(0)
	s_barrier
	s_setprio 1
	s_waitcnt lgkmcnt(0)
	v_mfma_f32_16x16x32_bf16 v[60:63], v[156:159], v[188:191], v[60:63]
	v_mfma_f32_16x16x32_bf16 v[56:59], v[164:167], v[188:191], v[56:59]
	v_mfma_f32_16x16x32_bf16 v[48:51], v[156:159], v[208:211], v[48:51]
	v_mfma_f32_16x16x32_bf16 v[40:43], v[164:167], v[208:211], v[40:43]
	v_mfma_f32_16x16x32_bf16 v[32:35], v[156:159], v[216:219], v[32:35]
	v_mfma_f32_16x16x32_bf16 v[24:27], v[164:167], v[216:219], v[24:27]
	v_mfma_f32_16x16x32_bf16 v[16:19], v[156:159], v[224:227], v[16:19]
	v_mfma_f32_16x16x32_bf16 v[8:11], v[164:167], v[224:227], v[8:11]
	v_mfma_f32_16x16x32_bf16 v[60:63], v[160:163], v[192:195], v[60:63]
	v_mfma_f32_16x16x32_bf16 v[56:59], v[168:171], v[192:195], v[56:59]
	v_mfma_f32_16x16x32_bf16 v[48:51], v[160:163], v[212:215], v[48:51]
	v_mfma_f32_16x16x32_bf16 v[40:43], v[168:171], v[212:215], v[40:43]
	v_mfma_f32_16x16x32_bf16 v[32:35], v[160:163], v[220:223], v[32:35]
	v_mfma_f32_16x16x32_bf16 v[24:27], v[168:171], v[220:223], v[24:27]
	v_mfma_f32_16x16x32_bf16 v[16:19], v[160:163], v[228:231], v[16:19]
	v_mfma_f32_16x16x32_bf16 v[8:11], v[168:171], v[228:231], v[8:11]
	s_setprio 0
	s_setprio 1
	v_mfma_f32_16x16x32_bf16 v[52:55], v[172:175], v[188:191], v[52:55]
	v_mfma_f32_16x16x32_bf16 v[44:47], v[180:183], v[188:191], v[44:47]
	v_mfma_f32_16x16x32_bf16 v[36:39], v[172:175], v[208:211], v[36:39]
	v_mfma_f32_16x16x32_bf16 v[28:31], v[180:183], v[208:211], v[28:31]
	v_mfma_f32_16x16x32_bf16 v[20:23], v[172:175], v[216:219], v[20:23]
	v_mfma_f32_16x16x32_bf16 v[12:15], v[180:183], v[216:219], v[12:15]
	v_mfma_f32_16x16x32_bf16 v[4:7], v[172:175], v[224:227], v[4:7]
	v_mfma_f32_16x16x32_bf16 v[0:3], v[180:183], v[224:227], v[0:3]
	v_mfma_f32_16x16x32_bf16 v[52:55], v[176:179], v[192:195], v[52:55]
	v_mfma_f32_16x16x32_bf16 v[44:47], v[184:187], v[192:195], v[44:47]
	v_mfma_f32_16x16x32_bf16 v[36:39], v[176:179], v[212:215], v[36:39]
	v_mfma_f32_16x16x32_bf16 v[28:31], v[184:187], v[212:215], v[28:31]
	v_mfma_f32_16x16x32_bf16 v[20:23], v[176:179], v[220:223], v[20:23]
	v_mfma_f32_16x16x32_bf16 v[12:15], v[184:187], v[220:223], v[12:15]
	v_mfma_f32_16x16x32_bf16 v[4:7], v[176:179], v[228:231], v[4:7]
	v_mfma_f32_16x16x32_bf16 v[0:3], v[184:187], v[228:231], v[0:3]
	s_setprio 0
	s_barrier
	s_add_i32 s83, s83, 2
	s_add_u32 s64, s64, 0x100
	s_addc_u32 s65, s65, 0
	s_add_u32 s49, s49, 0x100
	s_addc_u32 s63, s63, 0
	s_cmp_gt_u32 s83, 13
.LBB0_300:
	ds_read_b128 v[156:159], v201
	ds_read_b128 v[160:163], v201 offset:1024
	ds_read_b128 v[164:167], v201 offset:2048
	ds_read_b128 v[168:171], v201 offset:3072
	ds_read_b128 v[172:175], v202
	ds_read_b128 v[176:179], v202 offset:1024
	ds_read_b128 v[180:183], v202 offset:2048
	ds_read_b128 v[184:187], v202 offset:3072
	s_add_u32 s66, s64, 0xfffc0080
	s_addc_u32 s67, s65, -1
	s_cmp_eq_u32 s83, 12
	s_cselect_b32 s69, s5, s67
	s_cselect_b32 s68, s6, s66
	s_cselect_b32 s67, s45, s63
	s_cselect_b32 s66, s47, s49

; #define PG8_STAGE(bufoff, gbase, voff) do { _Pragma("unroll") for (int _i = 0; _i < 2; ++_i) \
;         __builtin_amdgcn_global_load_lds((const unsigned*)((const char*)(gbase) + (voff)[_i]), (PG8_LAS unsigned*)(lds + (bufoff) + ldsw + _i * 8192), 16, 0, 0); } while (0)
; #define PG8_LDA(dst, b, h) do { _Pragma("unroll") for (int m = 0; m < 4; ++m) _Pragma("unroll") for (int k = 0; k < 2; ++k) dst[m][k] = *(const PG8_LAS bf16x8*)(lds + PG8_SA(b, h) + aoff + m * 2048 + k * 1024); } while (0)
; #define PG8_LDB(dst, b, h) do { _Pragma("unroll") for (int n = 0; n < 2; ++n) _Pragma("unroll") for (int k = 0; k < 2; ++k) dst[n][k] = *(const PG8_LAS bf16x8*)(lds + PG8_SB(b, h) + boff + n * 2048 + k * 1024); } while (0)
; #define PG8_SCHED __builtin_amdgcn_sched_barrier(0)
; template <class Epi, class Sched, bool ALIGN_EPI = false, bool SP2 = false, bool ATILED = false>
; __device__ __forceinline__ void gemm_phase(PG8_LAS unsigned char* lds, const Gemm g, const Sched& S, const Epi& E) {
;     ...
;             PG8_LDB(B0, 0, 0); PG8_LDB(B1, 0, 1); PG8_SCHED; PG8_LDA(At, 0, 0); PG8_STAGE(PG8_SA(1, 1), a1 + hstepA, voffA);
	s_add_i32 m0, s71, 0xc000
	ds_read_b128 v[188:191], v203
	ds_read_b128 v[192:195], v203 offset:1024
	ds_read_b128 v[208:211], v203 offset:2048
	ds_read_b128 v[212:215], v203 offset:3072
	ds_read_b128 v[216:219], v203 offset:4096
	ds_read_b128 v[220:223], v203 offset:5120
	ds_read_b128 v[224:227], v203 offset:6144
	ds_read_b128 v[228:231], v203 offset:7168
	global_load_lds_dwordx4 v146, s[64:65]

; #define PG8_STAGE(bufoff, gbase, voff) do { _Pragma("unroll") for (int _i = 0; _i < 2; ++_i) \
;         __builtin_amdgcn_global_load_lds((const unsigned*)((const char*)(gbase) + (voff)[_i]), (PG8_LAS unsigned*)(lds + (bufoff) + ldsw + _i * 8192), 16, 0, 0); } while (0)
; #define PG8_LDA(dst, b, h) do { _Pragma("unroll") for (int m = 0; m < 4; ++m) _Pragma("unroll") for (int k = 0; k < 2; ++k) dst[m][k] = *(const PG8_LAS bf16x8*)(lds + PG8_SA(b, h) + aoff + m * 2048 + k * 1024); } while (0)
; #define PG8_LDB(dst, b, h) do { _Pragma("unroll") for (int n = 0; n < 2; ++n) _Pragma("unroll") for (int k = 0; k < 2; ++k) dst[n][k] = *(const PG8_LAS bf16x8*)(lds + PG8_SB(b, h) + boff + n * 2048 + k * 1024); } while (0)
; #define PG8_MMA(ai, bj, At, Bt) do { __builtin_amdgcn_s_setprio(1); _Pragma("unroll") for (int m = 0; m < 4; ++m) _Pragma("unroll") for (int n = 0; n < 2; ++n) _Pragma("unroll") for (int k = 0; k < 2; ++k) \
;         acc[ai][bj][m][n] = __builtin_amdgcn_mfma_f32_16x16x32_bf16(Bt[n][k], At[m][k], acc[ai][bj][m][n], 0, 0, 0); __builtin_amdgcn_s_setprio(0); } while (0)
; #define PG8_WAIT_V(n) asm volatile("s_waitcnt vmcnt(" #n ")" ::: "memory")
; #define PG8_WAIT_L(n) asm volatile("s_waitcnt lgkmcnt(" #n ")" ::: "memory")
; #define PG8_BAR __builtin_amdgcn_s_barrier()
; #define PG8_SCHED __builtin_amdgcn_sched_barrier(0)
; template <class Epi, class Sched, bool ALIGN_EPI = false, bool SP2 = false, bool ATILED = false>
; __device__ __forceinline__ void gemm_phase(PG8_LAS unsigned char* lds, const Gemm g, const Sched& S, const Epi& E) {
;     ...
;             PG8_LDB(B0, 0, 0); PG8_LDB(B1, 0, 1); PG8_SCHED; PG8_LDA(At, 0, 0); PG8_STAGE(PG8_SA(1, 1), a1 + hstepA, voffA);
;             PG8_WAIT_V(8); PG8_WAIT_L(0); PG8_BAR; PG8_MMA(0, 0, At, B0); PG8_MMA(0, 1, At, B1); PG8_BAR; PG8_SCHED;
;     ...
;             PG8_LDA(At, 1, 1); PG8_STAGE(PG8_SB(1, 0), b3, voffB); PG8_STAGE(PG8_SB(1, 1), b3 + hstep, voffB); PG8_STAGE(PG8_SA(1, 0), a3, voffA);
	s_add_i32 m0, s71, 0xe000
	s_nop 0
	global_load_lds_dwordx4 v148, s[64:65]
	s_waitcnt vmcnt(8)
	s_waitcnt lgkmcnt(0)
	s_barrier
	s_setprio 1
	s_waitcnt lgkmcnt(0)
	v_mfma_f32_16x16x32_bf16 v[124:127], v[156:159], v[188:191], v[124:127]
	v_mfma_f32_16x16x32_bf16 v[120:123], v[164:167], v[188:191], v[120:123]
	v_mfma_f32_16x16x32_bf16 v[116:119], v[156:159], v[208:211], v[116:119]
	v_mfma_f32_16x16x32_bf16 v[112:115], v[164:167], v[208:211], v[112:115]
	v_mfma_f32_16x16x32_bf16 v[96:99], v[156:159], v[216:219], v[96:99]
	v_mfma_f32_16x16x32_bf16 v[88:91], v[164:167], v[216:219], v[88:91]
	v_mfma_f32_16x16x32_bf16 v[80:83], v[156:159], v[224:227], v[80:83]
	v_mfma_f32_16x16x32_bf16 v[72:75], v[164:167], v[224:227], v[72:75]
	v_mfma_f32_16x16x32_bf16 v[124:127], v[160:163], v[192:195], v[124:127]
	v_mfma_f32_16x16x32_bf16 v[120:123], v[168:171], v[192:195], v[120:123]
	v_mfma_f32_16x16x32_bf16 v[116:119], v[160:163], v[212:215], v[116:119]
	v_mfma_f32_16x16x32_bf16 v[112:115], v[168:171], v[212:215], v[112:115]
	v_mfma_f32_16x16x32_bf16 v[96:99], v[160:163], v[220:223], v[96:99]
	v_mfma_f32_16x16x32_bf16 v[88:91], v[168:171], v[220:223], v[88:91]
	v_mfma_f32_16x16x32_bf16 v[80:83], v[160:163], v[228:231], v[80:83]
	v_mfma_f32_16x16x32_bf16 v[72:75], v[168:171], v[228:231], v[72:75]
	s_setprio 0
	s_setprio 1
	v_mfma_f32_16x16x32_bf16 v[108:111], v[172:175], v[188:191], v[108:111]
	v_mfma_f32_16x16x32_bf16 v[104:107], v[180:183], v[188:191], v[104:107]
	v_mfma_f32_16x16x32_bf16 v[100:103], v[172:175], v[208:211], v[100:103]
	v_mfma_f32_16x16x32_bf16 v[92:95], v[180:183], v[208:211], v[92:95]
	v_mfma_f32_16x16x32_bf16 v[84:87], v[172:175], v[216:219], v[84:87]
	v_mfma_f32_16x16x32_bf16 v[76:79], v[180:183], v[216:219], v[76:79]
	v_mfma_f32_16x16x32_bf16 v[68:71], v[172:175], v[224:227], v[68:71]
	v_mfma_f32_16x16x32_bf16 v[64:67], v[180:183], v[224:227], v[64:67]
	v_mfma_f32_16x16x32_bf16 v[108:111], v[176:179], v[192:195], v[108:111]
	v_mfma_f32_16x16x32_bf16 v[104:107], v[184:187], v[192:195], v[104:107]
	v_mfma_f32_16x16x32_bf16 v[100:103], v[176:179], v[212:215], v[100:103]
	v_mfma_f32_16x16x32_bf16 v[92:95], v[184:187], v[212:215], v[92:95]
	v_mfma_f32_16x16x32_bf16 v[84:87], v[176:179], v[220:223], v[84:87]
	v_mfma_f32_16x16x32_bf16 v[76:79], v[184:187], v[220:223], v[76:79]
	v_mfma_f32_16x16x32_bf16 v[68:71], v[176:179], v[228:231], v[68:71]
	v_mfma_f32_16x16x32_bf16 v[64:67], v[184:187], v[228:231], v[64:67]
	s_setprio 0
	s_barrier
	s_add_u32 s98, s66, s38
	s_addc_u32 s99, s67, s39
	s_add_u32 s100, s68, s38
	s_addc_u32 s101, s69, s39
	s_add_i32 s84, s79, s70

; #define PG8_STAGE(bufoff, gbase, voff) do { _Pragma("unroll") for (int _i = 0; _i < 2; ++_i) \
;         __builtin_amdgcn_global_load_lds((const unsigned*)((const char*)(gbase) + (voff)[_i]), (PG8_LAS unsigned*)(lds + (bufoff) + ldsw + _i * 8192), 16, 0, 0); } while (0)
; #define PG8_LDA(dst, b, h) do { _Pragma("unroll") for (int m = 0; m < 4; ++m) _Pragma("unroll") for (int k = 0; k < 2; ++k) dst[m][k] = *(const PG8_LAS bf16x8*)(lds + PG8_SA(b, h) + aoff + m * 2048 + k * 1024); } while (0)
; template <class Epi, class Sched, bool ALIGN_EPI = false, bool SP2 = false, bool ATILED = false>
; __device__ __forceinline__ void gemm_phase(PG8_LAS unsigned char* lds, const Gemm g, const Sched& S, const Epi& E) {
;     ...
;             PG8_LDA(At, 0, 1); PG8_STAGE(PG8_SB(0, 0), b2, voffB); PG8_STAGE(PG8_SB(0, 1), b2 + hstep, voffB); PG8_STAGE(PG8_SA(0, 0), a2, voffA);
	s_mov_b32 m0, s84
	ds_read_b128 v[188:191], v203 offset:16384
	ds_read_b128 v[192:195], v203 offset:17408
	ds_read_b128 v[208:211], v203 offset:18432
	ds_read_b128 v[212:215], v203 offset:19456
	ds_read_b128 v[216:219], v203 offset:20480
	ds_read_b128 v[220:223], v203 offset:21504
	ds_read_b128 v[224:227], v203 offset:22528
	ds_read_b128 v[228:231], v203 offset:23552
	global_load_lds_dwordx4 v130, s[66:67]
	s_add_i32 m0, s84, 0x2000
	s_add_u32 s84, s66, 0x40000

; #define PG8_STAGE(bufoff, gbase, voff) do { _Pragma("unroll") for (int _i = 0; _i < 2; ++_i) \
;         __builtin_amdgcn_global_load_lds((const unsigned*)((const char*)(gbase) + (voff)[_i]), (PG8_LAS unsigned*)(lds + (bufoff) + ldsw + _i * 8192), 16, 0, 0); } while (0)
; #define PG8_LDA(dst, b, h) do { _Pragma("unroll") for (int m = 0; m < 4; ++m) _Pragma("unroll") for (int k = 0; k < 2; ++k) dst[m][k] = *(const PG8_LAS bf16x8*)(lds + PG8_SA(b, h) + aoff + m * 2048 + k * 1024); } while (0)
; template <class Epi, class Sched, bool ALIGN_EPI = false, bool SP2 = false, bool ATILED = false>
; __device__ __forceinline__ void gemm_phase(PG8_LAS unsigned char* lds, const Gemm g, const Sched& S, const Epi& E) {
;     ...
;             PG8_LDA(At, 0, 1); PG8_STAGE(PG8_SB(0, 0), b2, voffB); PG8_STAGE(PG8_SB(0, 1), b2 + hstep, voffB); PG8_STAGE(PG8_SA(0, 0), a2, voffA);
	s_addc_u32 s85, s67, 0
	s_add_i32 s86, s80, s70
	global_load_lds_dwordx4 v134, s[66:67]

; #define PG8_STAGE(bufoff, gbase, voff) do { _Pragma("unroll") for (int _i = 0; _i < 2; ++_i) \
;         __builtin_amdgcn_global_load_lds((const unsigned*)((const char*)(gbase) + (voff)[_i]), (PG8_LAS unsigned*)(lds + (bufoff) + ldsw + _i * 8192), 16, 0, 0); } while (0)
; #define PG8_LDA(dst, b, h) do { _Pragma("unroll") for (int m = 0; m < 4; ++m) _Pragma("unroll") for (int k = 0; k < 2; ++k) dst[m][k] = *(const PG8_LAS bf16x8*)(lds + PG8_SA(b, h) + aoff + m * 2048 + k * 1024); } while (0)
; template <class Epi, class Sched, bool ALIGN_EPI = false, bool SP2 = false, bool ATILED = false>
; __device__ __forceinline__ void gemm_phase(PG8_LAS unsigned char* lds, const Gemm g, const Sched& S, const Epi& E) {
;     ...
;             PG8_LDA(At, 0, 1); PG8_STAGE(PG8_SB(0, 0), b2, voffB); PG8_STAGE(PG8_SB(0, 1), b2 + hstep, voffB); PG8_STAGE(PG8_SA(0, 0), a2, voffA);
	s_mov_b32 m0, s86

; #define PG8_STAGE(bufoff, gbase, voff) do { _Pragma("unroll") for (int _i = 0; _i < 2; ++_i) \
;         __builtin_amdgcn_global_load_lds((const unsigned*)((const char*)(gbase) + (voff)[_i]), (PG8_LAS unsigned*)(lds + (bufoff) + ldsw + _i * 8192), 16, 0, 0); } while (0)
; #define PG8_LDA(dst, b, h) do { _Pragma("unroll") for (int m = 0; m < 4; ++m) _Pragma("unroll") for (int k = 0; k < 2; ++k) dst[m][k] = *(const PG8_LAS bf16x8*)(lds + PG8_SA(b, h) + aoff + m * 2048 + k * 1024); } while (0)
; template <class Epi, class Sched, bool ALIGN_EPI = false, bool SP2 = false, bool ATILED = false>
; __device__ __forceinline__ void gemm_phase(PG8_LAS unsigned char* lds, const Gemm g, const Sched& S, const Epi& E) {
;     ...
;             PG8_LDA(At, 0, 1); PG8_STAGE(PG8_SB(0, 0), b2, voffB); PG8_STAGE(PG8_SB(0, 1), b2 + hstep, voffB); PG8_STAGE(PG8_SA(0, 0), a2, voffA);
	s_nop 0
	global_load_lds_dwordx4 v130, s[84:85]

; #define PG8_STAGE(bufoff, gbase, voff) do { _Pragma("unroll") for (int _i = 0; _i < 2; ++_i) \
;         __builtin_amdgcn_global_load_lds((const unsigned*)((const char*)(gbase) + (voff)[_i]), (PG8_LAS unsigned*)(lds + (bufoff) + ldsw + _i * 8192), 16, 0, 0); } while (0)
; #define PG8_LDA(dst, b, h) do { _Pragma("unroll") for (int m = 0; m < 4; ++m) _Pragma("unroll") for (int k = 0; k < 2; ++k) dst[m][k] = *(const PG8_LAS bf16x8*)(lds + PG8_SA(b, h) + aoff + m * 2048 + k * 1024); } while (0)
; template <class Epi, class Sched, bool ALIGN_EPI = false, bool SP2 = false, bool ATILED = false>
; __device__ __forceinline__ void gemm_phase(PG8_LAS unsigned char* lds, const Gemm g, const Sched& S, const Epi& E) {
;     ...
;             PG8_LDA(At, 0, 1); PG8_STAGE(PG8_SB(0, 0), b2, voffB); PG8_STAGE(PG8_SB(0, 1), b2 + hstep, voffB); PG8_STAGE(PG8_SA(0, 0), a2, voffA);
	s_add_i32 m0, s86, 0x2000
	s_nop 0
	global_load_lds_dwordx4 v134, s[84:85]

; #define PG8_STAGE(bufoff, gbase, voff) do { _Pragma("unroll") for (int _i = 0; _i < 2; ++_i) \
;         __builtin_amdgcn_global_load_lds((const unsigned*)((const char*)(gbase) + (voff)[_i]), (PG8_LAS unsigned*)(lds + (bufoff) + ldsw + _i * 8192), 16, 0, 0); } while (0)
; #define PG8_LDA(dst, b, h) do { _Pragma("unroll") for (int m = 0; m < 4; ++m) _Pragma("unroll") for (int k = 0; k < 2; ++k) dst[m][k] = *(const PG8_LAS bf16x8*)(lds + PG8_SA(b, h) + aoff + m * 2048 + k * 1024); } while (0)
; #define PG8_LDB(dst, b, h) do { _Pragma("unroll") for (int n = 0; n < 2; ++n) _Pragma("unroll") for (int k = 0; k < 2; ++k) dst[n][k] = *(const PG8_LAS bf16x8*)(lds + PG8_SB(b, h) + boff + n * 2048 + k * 1024); } while (0)
; #define PG8_MMA(ai, bj, At, Bt) do { __builtin_amdgcn_s_setprio(1); _Pragma("unroll") for (int m = 0; m < 4; ++m) _Pragma("unroll") for (int n = 0; n < 2; ++n) _Pragma("unroll") for (int k = 0; k < 2; ++k) \
;         acc[ai][bj][m][n] = __builtin_amdgcn_mfma_f32_16x16x32_bf16(Bt[n][k], At[m][k], acc[ai][bj][m][n], 0, 0, 0); __builtin_amdgcn_s_setprio(0); } while (0)
; #define PG8_WAIT_V(n) asm volatile("s_waitcnt vmcnt(" #n ")" ::: "memory")
; #define PG8_WAIT_L(n) asm volatile("s_waitcnt lgkmcnt(" #n ")" ::: "memory")
; #define PG8_BAR __builtin_amdgcn_s_barrier()
; #define PG8_SCHED __builtin_amdgcn_sched_barrier(0)
; template <class Epi, class Sched, bool ALIGN_EPI = false, bool SP2 = false, bool ATILED = false>
; __device__ __forceinline__ void gemm_phase(PG8_LAS unsigned char* lds, const Gemm g, const Sched& S, const Epi& E) {
;     ...
;             PG8_LDA(At, 0, 1); PG8_STAGE(PG8_SB(0, 0), b2, voffB); PG8_STAGE(PG8_SB(0, 1), b2 + hstep, voffB); PG8_STAGE(PG8_SA(0, 0), a2, voffA);
;             PG8_WAIT_V(8); PG8_WAIT_L(0); PG8_BAR; PG8_MMA(1, 0, At, B0); PG8_MMA(1, 1, At, B1); PG8_BAR; PG8_SCHED;
;             PG8_LDB(B0, 1, 0); PG8_LDB(B1, 1, 1); PG8_SCHED; PG8_LDA(At, 1, 0); PG8_STAGE(PG8_SA(0, 1), a2 + hstepA, voffA);
	s_mov_b32 m0, s71
	s_nop 0
	global_load_lds_dwordx4 v128, s[68:69]
	s_mov_b32 m0, s72
	s_nop 0
	global_load_lds_dwordx4 v132, s[68:69]
	s_waitcnt vmcnt(8)
	s_waitcnt lgkmcnt(0)
	s_barrier
	s_setprio 1
	s_waitcnt lgkmcnt(0)
	v_mfma_f32_16x16x32_bf16 v[60:63], v[156:159], v[188:191], v[60:63]
	v_mfma_f32_16x16x32_bf16 v[56:59], v[164:167], v[188:191], v[56:59]
	v_mfma_f32_16x16x32_bf16 v[48:51], v[156:159], v[208:211], v[48:51]
	v_mfma_f32_16x16x32_bf16 v[40:43], v[164:167], v[208:211], v[40:43]
	v_mfma_f32_16x16x32_bf16 v[32:35], v[156:159], v[216:219], v[32:35]
	v_mfma_f32_16x16x32_bf16 v[24:27], v[164:167], v[216:219], v[24:27]
	v_mfma_f32_16x16x32_bf16 v[16:19], v[156:159], v[224:227], v[16:19]
	v_mfma_f32_16x16x32_bf16 v[8:11], v[164:167], v[224:227], v[8:11]
	v_mfma_f32_16x16x32_bf16 v[60:63], v[160:163], v[192:195], v[60:63]
	v_mfma_f32_16x16x32_bf16 v[56:59], v[168:171], v[192:195], v[56:59]
	v_mfma_f32_16x16x32_bf16 v[48:51], v[160:163], v[212:215], v[48:51]
	v_mfma_f32_16x16x32_bf16 v[40:43], v[168:171], v[212:215], v[40:43]
	v_mfma_f32_16x16x32_bf16 v[32:35], v[160:163], v[220:223], v[32:35]
	v_mfma_f32_16x16x32_bf16 v[24:27], v[168:171], v[220:223], v[24:27]
	v_mfma_f32_16x16x32_bf16 v[16:19], v[160:163], v[228:231], v[16:19]
	v_mfma_f32_16x16x32_bf16 v[8:11], v[168:171], v[228:231], v[8:11]
	s_setprio 0
	s_setprio 1
	v_mfma_f32_16x16x32_bf16 v[52:55], v[172:175], v[188:191], v[52:55]
	v_mfma_f32_16x16x32_bf16 v[44:47], v[180:183], v[188:191], v[44:47]
	v_mfma_f32_16x16x32_bf16 v[36:39], v[172:175], v[208:211], v[36:39]
	v_mfma_f32_16x16x32_bf16 v[28:31], v[180:183], v[208:211], v[28:31]
	v_mfma_f32_16x16x32_bf16 v[20:23], v[172:175], v[216:219], v[20:23]
	v_mfma_f32_16x16x32_bf16 v[12:15], v[180:183], v[216:219], v[12:15]
	v_mfma_f32_16x16x32_bf16 v[4:7], v[172:175], v[224:227], v[4:7]
	v_mfma_f32_16x16x32_bf16 v[0:3], v[180:183], v[224:227], v[0:3]
	v_mfma_f32_16x16x32_bf16 v[52:55], v[176:179], v[192:195], v[52:55]
	v_mfma_f32_16x16x32_bf16 v[44:47], v[184:187], v[192:195], v[44:47]
	v_mfma_f32_16x16x32_bf16 v[36:39], v[176:179], v[212:215], v[36:39]
	v_mfma_f32_16x16x32_bf16 v[28:31], v[184:187], v[212:215], v[28:31]
	v_mfma_f32_16x16x32_bf16 v[20:23], v[176:179], v[220:223], v[20:23]
	v_mfma_f32_16x16x32_bf16 v[12:15], v[184:187], v[220:223], v[12:15]
	v_mfma_f32_16x16x32_bf16 v[4:7], v[176:179], v[228:231], v[4:7]
	v_mfma_f32_16x16x32_bf16 v[0:3], v[184:187], v[228:231], v[0:3]
	s_setprio 0
	s_barrier
	s_add_i32 s84, 0, 0x18000
	v_add_u32_e32 v136, s84, v200
	s_add_i32 s85, 0, 0x1c000
	ds_read_b128 v[156:159], v136
	ds_read_b128 v[160:163], v136 offset:1024
	ds_read_b128 v[164:167], v136 offset:2048
	ds_read_b128 v[168:171], v136 offset:3072
	v_add_u32_e32 v136, s85, v200
	ds_read_b128 v[172:175], v136
	ds_read_b128 v[176:179], v136 offset:1024
	ds_read_b128 v[180:183], v136 offset:2048
	ds_read_b128 v[184:187], v136 offset:3072
	s_add_u32 s68, s68, 0x40000
	s_addc_u32 s69, s69, 0
	s_mov_b32 m0, s73

; #define PG8_STAGE(bufoff, gbase, voff) do { _Pragma("unroll") for (int _i = 0; _i < 2; ++_i) \
;         __builtin_amdgcn_global_load_lds((const unsigned*)((const char*)(gbase) + (voff)[_i]), (PG8_LAS unsigned*)(lds + (bufoff) + ldsw + _i * 8192), 16, 0, 0); } while (0)
; #define PG8_LDA(dst, b, h) do { _Pragma("unroll") for (int m = 0; m < 4; ++m) _Pragma("unroll") for (int k = 0; k < 2; ++k) dst[m][k] = *(const PG8_LAS bf16x8*)(lds + PG8_SA(b, h) + aoff + m * 2048 + k * 1024); } while (0)
; #define PG8_LDB(dst, b, h) do { _Pragma("unroll") for (int n = 0; n < 2; ++n) _Pragma("unroll") for (int k = 0; k < 2; ++k) dst[n][k] = *(const PG8_LAS bf16x8*)(lds + PG8_SB(b, h) + boff + n * 2048 + k * 1024); } while (0)
; #define PG8_SCHED __builtin_amdgcn_sched_barrier(0)
; template <class Epi, class Sched, bool ALIGN_EPI = false, bool SP2 = false, bool ATILED = false>
; __device__ __forceinline__ void gemm_phase(PG8_LAS unsigned char* lds, const Gemm g, const Sched& S, const Epi& E) {
;     ...
;             PG8_LDB(B0, 1, 0); PG8_LDB(B1, 1, 1); PG8_SCHED; PG8_LDA(At, 1, 0); PG8_STAGE(PG8_SA(0, 1), a2 + hstepA, voffA);
	ds_read_b128 v[188:191], v203 offset:32768
	ds_read_b128 v[192:195], v203 offset:33792
	ds_read_b128 v[208:211], v203 offset:34816
	ds_read_b128 v[212:215], v203 offset:35840
	ds_read_b128 v[216:219], v203 offset:36864
	ds_read_b128 v[220:223], v203 offset:37888
	ds_read_b128 v[224:227], v203 offset:38912
	ds_read_b128 v[228:231], v203 offset:39936
	global_load_lds_dwordx4 v128, s[68:69]

; #define PG8_STAGE(bufoff, gbase, voff) do { _Pragma("unroll") for (int _i = 0; _i < 2; ++_i) \
;         __builtin_amdgcn_global_load_lds((const unsigned*)((const char*)(gbase) + (voff)[_i]), (PG8_LAS unsigned*)(lds + (bufoff) + ldsw + _i * 8192), 16, 0, 0); } while (0)
; #define PG8_LDA(dst, b, h) do { _Pragma("unroll") for (int m = 0; m < 4; ++m) _Pragma("unroll") for (int k = 0; k < 2; ++k) dst[m][k] = *(const PG8_LAS bf16x8*)(lds + PG8_SA(b, h) + aoff + m * 2048 + k * 1024); } while (0)
; #define PG8_LDB(dst, b, h) do { _Pragma("unroll") for (int n = 0; n < 2; ++n) _Pragma("unroll") for (int k = 0; k < 2; ++k) dst[n][k] = *(const PG8_LAS bf16x8*)(lds + PG8_SB(b, h) + boff + n * 2048 + k * 1024); } while (0)
; #define PG8_MMA(ai, bj, At, Bt) do { __builtin_amdgcn_s_setprio(1); _Pragma("unroll") for (int m = 0; m < 4; ++m) _Pragma("unroll") for (int n = 0; n < 2; ++n) _Pragma("unroll") for (int k = 0; k < 2; ++k) \
;         acc[ai][bj][m][n] = __builtin_amdgcn_mfma_f32_16x16x32_bf16(Bt[n][k], At[m][k], acc[ai][bj][m][n], 0, 0, 0); __builtin_amdgcn_s_setprio(0); } while (0)
; #define PG8_WAIT_V(n) asm volatile("s_waitcnt vmcnt(" #n ")" ::: "memory")
; #define PG8_WAIT_L(n) asm volatile("s_waitcnt lgkmcnt(" #n ")" ::: "memory")
; #define PG8_BAR __builtin_amdgcn_s_barrier()
; #define PG8_SCHED __builtin_amdgcn_sched_barrier(0)
; template <class Epi, class Sched, bool ALIGN_EPI = false, bool SP2 = false, bool ATILED = false>
; __device__ __forceinline__ void gemm_phase(PG8_LAS unsigned char* lds, const Gemm g, const Sched& S, const Epi& E) {
;     ...
;             PG8_LDB(B0, 1, 0); PG8_LDB(B1, 1, 1); PG8_SCHED; PG8_LDA(At, 1, 0); PG8_STAGE(PG8_SA(0, 1), a2 + hstepA, voffA);
;             PG8_WAIT_V(8); PG8_WAIT_L(0); PG8_BAR; PG8_MMA(0, 0, At, B0); PG8_MMA(0, 1, At, B1); PG8_BAR; PG8_SCHED;
	s_mov_b32 m0, s74
	s_nop 0
	global_load_lds_dwordx4 v132, s[68:69]
	s_waitcnt vmcnt(8)
	s_waitcnt lgkmcnt(0)
	s_barrier
	s_setprio 1
	s_waitcnt lgkmcnt(0)
	v_mfma_f32_16x16x32_bf16 v[124:127], v[156:159], v[188:191], v[124:127]
	v_mfma_f32_16x16x32_bf16 v[120:123], v[164:167], v[188:191], v[120:123]
	v_mfma_f32_16x16x32_bf16 v[116:119], v[156:159], v[208:211], v[116:119]
	v_mfma_f32_16x16x32_bf16 v[112:115], v[164:167], v[208:211], v[112:115]
	v_mfma_f32_16x16x32_bf16 v[96:99], v[156:159], v[216:219], v[96:99]
	v_mfma_f32_16x16x32_bf16 v[88:91], v[164:167], v[216:219], v[88:91]
	v_mfma_f32_16x16x32_bf16 v[80:83], v[156:159], v[224:227], v[80:83]
	v_mfma_f32_16x16x32_bf16 v[72:75], v[164:167], v[224:227], v[72:75]
	v_mfma_f32_16x16x32_bf16 v[124:127], v[160:163], v[192:195], v[124:127]
	v_mfma_f32_16x16x32_bf16 v[120:123], v[168:171], v[192:195], v[120:123]
	v_mfma_f32_16x16x32_bf16 v[116:119], v[160:163], v[212:215], v[116:119]
	v_mfma_f32_16x16x32_bf16 v[112:115], v[168:171], v[212:215], v[112:115]
	v_mfma_f32_16x16x32_bf16 v[96:99], v[160:163], v[220:223], v[96:99]
	v_mfma_f32_16x16x32_bf16 v[88:91], v[168:171], v[220:223], v[88:91]
	v_mfma_f32_16x16x32_bf16 v[80:83], v[160:163], v[228:231], v[80:83]
	v_mfma_f32_16x16x32_bf16 v[72:75], v[168:171], v[228:231], v[72:75]
	s_setprio 0
	s_setprio 1
	v_mfma_f32_16x16x32_bf16 v[108:111], v[172:175], v[188:191], v[108:111]
	v_mfma_f32_16x16x32_bf16 v[104:107], v[180:183], v[188:191], v[104:107]
	v_mfma_f32_16x16x32_bf16 v[100:103], v[172:175], v[208:211], v[100:103]
	v_mfma_f32_16x16x32_bf16 v[92:95], v[180:183], v[208:211], v[92:95]
	v_mfma_f32_16x16x32_bf16 v[84:87], v[172:175], v[216:219], v[84:87]
	v_mfma_f32_16x16x32_bf16 v[76:79], v[180:183], v[216:219], v[76:79]
	v_mfma_f32_16x16x32_bf16 v[68:71], v[172:175], v[224:227], v[68:71]
	v_mfma_f32_16x16x32_bf16 v[64:67], v[180:183], v[224:227], v[64:67]
	v_mfma_f32_16x16x32_bf16 v[108:111], v[176:179], v[192:195], v[108:111]
	v_mfma_f32_16x16x32_bf16 v[104:107], v[184:187], v[192:195], v[104:107]
	v_mfma_f32_16x16x32_bf16 v[100:103], v[176:179], v[212:215], v[100:103]
	v_mfma_f32_16x16x32_bf16 v[92:95], v[184:187], v[212:215], v[92:95]
	v_mfma_f32_16x16x32_bf16 v[84:87], v[176:179], v[220:223], v[84:87]
	v_mfma_f32_16x16x32_bf16 v[76:79], v[184:187], v[220:223], v[76:79]
	v_mfma_f32_16x16x32_bf16 v[68:71], v[176:179], v[228:231], v[68:71]
	v_mfma_f32_16x16x32_bf16 v[64:67], v[184:187], v[228:231], v[64:67]
	s_setprio 0
	s_barrier
	s_add_i32 s68, s84, s70

; #define PG8_STAGE(bufoff, gbase, voff) do { _Pragma("unroll") for (int _i = 0; _i < 2; ++_i) \
;         __builtin_amdgcn_global_load_lds((const unsigned*)((const char*)(gbase) + (voff)[_i]), (PG8_LAS unsigned*)(lds + (bufoff) + ldsw + _i * 8192), 16, 0, 0); } while (0)
; #define PG8_LDA(dst, b, h) do { _Pragma("unroll") for (int m = 0; m < 4; ++m) _Pragma("unroll") for (int k = 0; k < 2; ++k) dst[m][k] = *(const PG8_LAS bf16x8*)(lds + PG8_SA(b, h) + aoff + m * 2048 + k * 1024); } while (0)
; template <class Epi, class Sched, bool ALIGN_EPI = false, bool SP2 = false, bool ATILED = false>
; __device__ __forceinline__ void gemm_phase(PG8_LAS unsigned char* lds, const Gemm g, const Sched& S, const Epi& E) {
;     ...
;             PG8_LDA(At, 1, 1); PG8_STAGE(PG8_SB(1, 0), b3, voffB); PG8_STAGE(PG8_SB(1, 1), b3 + hstep, voffB); PG8_STAGE(PG8_SA(1, 0), a3, voffA);
	s_mov_b32 m0, s68
	ds_read_b128 v[188:191], v203 offset:49152
	ds_read_b128 v[192:195], v203 offset:50176
	ds_read_b128 v[208:211], v203 offset:51200
	ds_read_b128 v[212:215], v203 offset:52224
	ds_read_b128 v[216:219], v203 offset:53248
	ds_read_b128 v[220:223], v203 offset:54272
	ds_read_b128 v[224:227], v203 offset:55296
	ds_read_b128 v[228:231], v203 offset:56320
	global_load_lds_dwordx4 v130, s[98:99]
	s_add_i32 m0, s68, 0x2000
	s_add_u32 s66, s66, 0x40080

; #define PG8_STAGE(bufoff, gbase, voff) do { _Pragma("unroll") for (int _i = 0; _i < 2; ++_i) \
;         __builtin_amdgcn_global_load_lds((const unsigned*)((const char*)(gbase) + (voff)[_i]), (PG8_LAS unsigned*)(lds + (bufoff) + ldsw + _i * 8192), 16, 0, 0); } while (0)
; #define PG8_LDA(dst, b, h) do { _Pragma("unroll") for (int m = 0; m < 4; ++m) _Pragma("unroll") for (int k = 0; k < 2; ++k) dst[m][k] = *(const PG8_LAS bf16x8*)(lds + PG8_SA(b, h) + aoff + m * 2048 + k * 1024); } while (0)
; template <class Epi, class Sched, bool ALIGN_EPI = false, bool SP2 = false, bool ATILED = false>
; __device__ __forceinline__ void gemm_phase(PG8_LAS unsigned char* lds, const Gemm g, const Sched& S, const Epi& E) {
;     ...
;             PG8_LDA(At, 1, 1); PG8_STAGE(PG8_SB(1, 0), b3, voffB); PG8_STAGE(PG8_SB(1, 1), b3 + hstep, voffB); PG8_STAGE(PG8_SA(1, 0), a3, voffA);
	s_addc_u32 s67, s67, 0
	s_add_i32 s68, s85, s70
	global_load_lds_dwordx4 v134, s[98:99]

; #define PG8_STAGE(bufoff, gbase, voff) do { _Pragma("unroll") for (int _i = 0; _i < 2; ++_i) \
;         __builtin_amdgcn_global_load_lds((const unsigned*)((const char*)(gbase) + (voff)[_i]), (PG8_LAS unsigned*)(lds + (bufoff) + ldsw + _i * 8192), 16, 0, 0); } while (0)
; #define PG8_LDA(dst, b, h) do { _Pragma("unroll") for (int m = 0; m < 4; ++m) _Pragma("unroll") for (int k = 0; k < 2; ++k) dst[m][k] = *(const PG8_LAS bf16x8*)(lds + PG8_SA(b, h) + aoff + m * 2048 + k * 1024); } while (0)
; template <class Epi, class Sched, bool ALIGN_EPI = false, bool SP2 = false, bool ATILED = false>
; __device__ __forceinline__ void gemm_phase(PG8_LAS unsigned char* lds, const Gemm g, const Sched& S, const Epi& E) {
;     ...
;             PG8_LDA(At, 1, 1); PG8_STAGE(PG8_SB(1, 0), b3, voffB); PG8_STAGE(PG8_SB(1, 1), b3 + hstep, voffB); PG8_STAGE(PG8_SA(1, 0), a3, voffA);
	s_mov_b32 m0, s68
	s_nop 0
	global_load_lds_dwordx4 v130, s[66:67]

; #define PG8_STAGE(bufoff, gbase, voff) do { _Pragma("unroll") for (int _i = 0; _i < 2; ++_i) \
;         __builtin_amdgcn_global_load_lds((const unsigned*)((const char*)(gbase) + (voff)[_i]), (PG8_LAS unsigned*)(lds + (bufoff) + ldsw + _i * 8192), 16, 0, 0); } while (0)
; #define PG8_LDA(dst, b, h) do { _Pragma("unroll") for (int m = 0; m < 4; ++m) _Pragma("unroll") for (int k = 0; k < 2; ++k) dst[m][k] = *(const PG8_LAS bf16x8*)(lds + PG8_SA(b, h) + aoff + m * 2048 + k * 1024); } while (0)
; template <class Epi, class Sched, bool ALIGN_EPI = false, bool SP2 = false, bool ATILED = false>
; __device__ __forceinline__ void gemm_phase(PG8_LAS unsigned char* lds, const Gemm g, const Sched& S, const Epi& E) {
;     ...
;             PG8_LDA(At, 1, 1); PG8_STAGE(PG8_SB(1, 0), b3, voffB); PG8_STAGE(PG8_SB(1, 1), b3 + hstep, voffB); PG8_STAGE(PG8_SA(1, 0), a3, voffA);
	s_add_i32 m0, s68, 0x2000
	s_nop 0
	global_load_lds_dwordx4 v134, s[66:67]

; #define PG8_STAGE(bufoff, gbase, voff) do { _Pragma("unroll") for (int _i = 0; _i < 2; ++_i) \
;         __builtin_amdgcn_global_load_lds((const unsigned*)((const char*)(gbase) + (voff)[_i]), (PG8_LAS unsigned*)(lds + (bufoff) + ldsw + _i * 8192), 16, 0, 0); } while (0)
; #define PG8_LDA(dst, b, h) do { _Pragma("unroll") for (int m = 0; m < 4; ++m) _Pragma("unroll") for (int k = 0; k < 2; ++k) dst[m][k] = *(const PG8_LAS bf16x8*)(lds + PG8_SA(b, h) + aoff + m * 2048 + k * 1024); } while (0)
; template <class Epi, class Sched, bool ALIGN_EPI = false, bool SP2 = false, bool ATILED = false>
; __device__ __forceinline__ void gemm_phase(PG8_LAS unsigned char* lds, const Gemm g, const Sched& S, const Epi& E) {
;     ...
;             PG8_LDA(At, 1, 1); PG8_STAGE(PG8_SB(1, 0), b3, voffB); PG8_STAGE(PG8_SB(1, 1), b3 + hstep, voffB); PG8_STAGE(PG8_SA(1, 0), a3, voffA);
	s_mov_b32 m0, s77
	s_nop 0
	global_load_lds_dwordx4 v128, s[100:101]

; #define PG8_STAGE(bufoff, gbase, voff) do { _Pragma("unroll") for (int _i = 0; _i < 2; ++_i) \
;         __builtin_amdgcn_global_load_lds((const unsigned*)((const char*)(gbase) + (voff)[_i]), (PG8_LAS unsigned*)(lds + (bufoff) + ldsw + _i * 8192), 16, 0, 0); } while (0)
; #define PG8_LDA(dst, b, h) do { _Pragma("unroll") for (int m = 0; m < 4; ++m) _Pragma("unroll") for (int k = 0; k < 2; ++k) dst[m][k] = *(const PG8_LAS bf16x8*)(lds + PG8_SA(b, h) + aoff + m * 2048 + k * 1024); } while (0)
; #define PG8_MMA(ai, bj, At, Bt) do { __builtin_amdgcn_s_setprio(1); _Pragma("unroll") for (int m = 0; m < 4; ++m) _Pragma("unroll") for (int n = 0; n < 2; ++n) _Pragma("unroll") for (int k = 0; k < 2; ++k) \
;         acc[ai][bj][m][n] = __builtin_amdgcn_mfma_f32_16x16x32_bf16(Bt[n][k], At[m][k], acc[ai][bj][m][n], 0, 0, 0); __builtin_amdgcn_s_setprio(0); } while (0)
; #define PG8_WAIT_V(n) asm volatile("s_waitcnt vmcnt(" #n ")" ::: "memory")
; #define PG8_WAIT_L(n) asm volatile("s_waitcnt lgkmcnt(" #n ")" ::: "memory")
; #define PG8_BAR __builtin_amdgcn_s_barrier()
; #define PG8_SCHED __builtin_amdgcn_sched_barrier(0)
; template <class Epi, class Sched, bool ALIGN_EPI = false, bool SP2 = false, bool ATILED = false>
; __device__ __forceinline__ void gemm_phase(PG8_LAS unsigned char* lds, const Gemm g, const Sched& S, const Epi& E) {
;     ...
;             PG8_LDA(At, 1, 1); PG8_STAGE(PG8_SB(1, 0), b3, voffB); PG8_STAGE(PG8_SB(1, 1), b3 + hstep, voffB); PG8_STAGE(PG8_SA(1, 0), a3, voffA);
;             PG8_WAIT_V(8); PG8_WAIT_L(0); PG8_BAR; PG8_MMA(1, 0, At, B0); PG8_MMA(1, 1, At, B1); PG8_BAR; PG8_SCHED;
;     ...
;         if constexpr (ALIGN_EPI) { if (wr == 0) PG8_BAR; }
	s_mov_b32 m0, s78
	s_nop 0
	global_load_lds_dwordx4 v132, s[100:101]
	s_waitcnt vmcnt(8)
	s_waitcnt lgkmcnt(0)
	s_barrier
	s_setprio 1
	s_waitcnt lgkmcnt(0)
	v_mfma_f32_16x16x32_bf16 v[60:63], v[156:159], v[188:191], v[60:63]
	v_mfma_f32_16x16x32_bf16 v[56:59], v[164:167], v[188:191], v[56:59]
	v_mfma_f32_16x16x32_bf16 v[48:51], v[156:159], v[208:211], v[48:51]
	v_mfma_f32_16x16x32_bf16 v[40:43], v[164:167], v[208:211], v[40:43]
	v_mfma_f32_16x16x32_bf16 v[32:35], v[156:159], v[216:219], v[32:35]
	v_mfma_f32_16x16x32_bf16 v[24:27], v[164:167], v[216:219], v[24:27]
	v_mfma_f32_16x16x32_bf16 v[16:19], v[156:159], v[224:227], v[16:19]
	v_mfma_f32_16x16x32_bf16 v[8:11], v[164:167], v[224:227], v[8:11]
	v_mfma_f32_16x16x32_bf16 v[60:63], v[160:163], v[192:195], v[60:63]
	v_mfma_f32_16x16x32_bf16 v[56:59], v[168:171], v[192:195], v[56:59]
	v_mfma_f32_16x16x32_bf16 v[48:51], v[160:163], v[212:215], v[48:51]
	v_mfma_f32_16x16x32_bf16 v[40:43], v[168:171], v[212:215], v[40:43]
	v_mfma_f32_16x16x32_bf16 v[32:35], v[160:163], v[220:223], v[32:35]
	v_mfma_f32_16x16x32_bf16 v[24:27], v[168:171], v[220:223], v[24:27]
	v_mfma_f32_16x16x32_bf16 v[16:19], v[160:163], v[228:231], v[16:19]
	v_mfma_f32_16x16x32_bf16 v[8:11], v[168:171], v[228:231], v[8:11]
	s_setprio 0
	s_setprio 1
	v_mfma_f32_16x16x32_bf16 v[52:55], v[172:175], v[188:191], v[52:55]
	v_mfma_f32_16x16x32_bf16 v[44:47], v[180:183], v[188:191], v[44:47]
	v_mfma_f32_16x16x32_bf16 v[36:39], v[172:175], v[208:211], v[36:39]
	v_mfma_f32_16x16x32_bf16 v[28:31], v[180:183], v[208:211], v[28:31]
	v_mfma_f32_16x16x32_bf16 v[20:23], v[172:175], v[216:219], v[20:23]
	v_mfma_f32_16x16x32_bf16 v[12:15], v[180:183], v[216:219], v[12:15]
	v_mfma_f32_16x16x32_bf16 v[4:7], v[172:175], v[224:227], v[4:7]
	v_mfma_f32_16x16x32_bf16 v[0:3], v[180:183], v[224:227], v[0:3]
	v_mfma_f32_16x16x32_bf16 v[52:55], v[176:179], v[192:195], v[52:55]
	v_mfma_f32_16x16x32_bf16 v[44:47], v[184:187], v[192:195], v[44:47]
	v_mfma_f32_16x16x32_bf16 v[36:39], v[176:179], v[212:215], v[36:39]
	v_mfma_f32_16x16x32_bf16 v[28:31], v[184:187], v[212:215], v[28:31]
	v_mfma_f32_16x16x32_bf16 v[20:23], v[176:179], v[220:223], v[20:23]
	v_mfma_f32_16x16x32_bf16 v[12:15], v[184:187], v[220:223], v[12:15]
	v_mfma_f32_16x16x32_bf16 v[4:7], v[176:179], v[228:231], v[4:7]
	v_mfma_f32_16x16x32_bf16 v[0:3], v[184:187], v[228:231], v[0:3]
	s_setprio 0
	s_barrier
	s_add_i32 s83, s83, 2
	s_add_u32 s64, s64, 0x100
	s_addc_u32 s65, s65, 0
	s_add_u32 s49, s49, 0x100
	s_addc_u32 s63, s63, 0
	s_cmp_gt_u32 s83, 13
	s_cbranch_scc0 .LBB0_300
	s_and_b64 vcc, exec, s[40:41]
	s_cbranch_vccz .LBB0_303
	s_barrier

; #define PG8_STAGE(bufoff, gbase, voff) do { _Pragma("unroll") for (int _i = 0; _i < 2; ++_i) \
;         __builtin_amdgcn_global_load_lds((const unsigned*)((const char*)(gbase) + (voff)[_i]), (PG8_LAS unsigned*)(lds + (bufoff) + ldsw + _i * 8192), 16, 0, 0); } while (0)
; #define PG8_LDA(dst, b, h) do { _Pragma("unroll") for (int m = 0; m < 4; ++m) _Pragma("unroll") for (int k = 0; k < 2; ++k) dst[m][k] = *(const PG8_LAS bf16x8*)(lds + PG8_SA(b, h) + aoff + m * 2048 + k * 1024); } while (0)
; #define PG8_LDB(dst, b, h) do { _Pragma("unroll") for (int n = 0; n < 2; ++n) _Pragma("unroll") for (int k = 0; k < 2; ++k) dst[n][k] = *(const PG8_LAS bf16x8*)(lds + PG8_SB(b, h) + boff + n * 2048 + k * 1024); } while (0)
; #define PG8_SCHED __builtin_amdgcn_sched_barrier(0)
; template <class Epi, class Sched, bool ALIGN_EPI = false, bool SP2 = false, bool ATILED = false>
; __device__ __forceinline__ void gemm_phase(PG8_LAS unsigned char* lds, const Gemm g, const Sched& S, const Epi& E) {
;     ...
;         const bool has_next = S.next(ui + 1, nxt);
;         const char* nA = has_next ? (const char*)g.A + (size_t)nxt.pm * tstepA : cA; const char* nB = has_next ? (const char*)g.Bt + (size_t)nxt.pn * tstep : cB;
;         for (int t = 0; t < nt; t += 2) {
;             const bool last = (t == nt - 2);
;             const char* a1 = cA + (size_t)(t + 1) * kstepA;
;             const char* a2 = last ? nA : cA + (size_t)(t + 2) * kstepA; const char* b2 = last ? nB : cB + (size_t)(t + 2) * kstep;
;             const char* a3 = a2 + kstepA; const char* b3 = b2 + kstep;
;             if (last && has_next) S.a_ready(nxt);
;             if constexpr (SP2) {
;             PG8_LDB(B0, 0, 0); PG8_LDB(B1, 0, 1); PG8_SCHED; PG8_LDA(At, 0, 0); PG8_STAGE(PG8_SA(1, 1), a1 + hstepA, voffA);
.LBB0_734:
	s_ashr_i32 s19, s18, 31
	s_lshl_b64 s[20:21], s[18:19], 19
	s_add_u32 s20, s44, s20
	s_addc_u32 s21, s45, s21
	s_and_b64 s[42:43], s[4:5], exec
	s_cselect_b32 s19, s21, s51
	s_cselect_b32 s49, s20, s50
	s_ashr_i32 s17, s16, 31
	s_lshl_b64 s[42:43], s[16:17], 19
	s_add_u32 s42, s46, s42
	s_addc_u32 s43, s47, s43
	s_and_b64 s[56:57], s[4:5], exec
	s_cselect_b32 s17, s43, s55
	s_cselect_b32 s70, s42, s54
	s_add_u32 s50, s50, 0x40080
	s_addc_u32 s51, s51, 0
	s_add_u32 s71, s54, 0x100
	s_addc_u32 s72, s55, 0
	s_mov_b32 s73, -2
	s_waitcnt lgkmcnt(0)
	s_waitcnt vmcnt(0)
	ds_read_b128 v[128:131], v189
	ds_read_b128 v[132:135], v189 offset:1024
	ds_read_b128 v[136:139], v189 offset:2048
	ds_read_b128 v[140:143], v189 offset:3072
	ds_read_b128 v[144:147], v190
	ds_read_b128 v[148:151], v190 offset:1024
	ds_read_b128 v[168:171], v190 offset:2048
	ds_read_b128 v[172:175], v190 offset:3072
	s_add_u32 s54, s50, 0xfffc0080
	s_addc_u32 s55, s51, -1
	s_cmp_eq_u32 s73, 12
	s_cselect_b32 s57, s19, s55
	s_cselect_b32 s56, s49, s54
	s_cselect_b32 s55, s17, s72
	s_cselect_b32 s54, s70, s71

; #define PG8_STAGE(bufoff, gbase, voff) do { _Pragma("unroll") for (int _i = 0; _i < 2; ++_i) \
;         __builtin_amdgcn_global_load_lds((const unsigned*)((const char*)(gbase) + (voff)[_i]), (PG8_LAS unsigned*)(lds + (bufoff) + ldsw + _i * 8192), 16, 0, 0); } while (0)
; #define PG8_LDA(dst, b, h) do { _Pragma("unroll") for (int m = 0; m < 4; ++m) _Pragma("unroll") for (int k = 0; k < 2; ++k) dst[m][k] = *(const PG8_LAS bf16x8*)(lds + PG8_SA(b, h) + aoff + m * 2048 + k * 1024); } while (0)
; #define PG8_LDB(dst, b, h) do { _Pragma("unroll") for (int n = 0; n < 2; ++n) _Pragma("unroll") for (int k = 0; k < 2; ++k) dst[n][k] = *(const PG8_LAS bf16x8*)(lds + PG8_SB(b, h) + boff + n * 2048 + k * 1024); } while (0)
; #define PG8_SCHED __builtin_amdgcn_sched_barrier(0)
; template <class Epi, class Sched, bool ALIGN_EPI = false, bool SP2 = false, bool ATILED = false>
; __device__ __forceinline__ void gemm_phase(PG8_LAS unsigned char* lds, const Gemm g, const Sched& S, const Epi& E) {
;     ...
;             PG8_LDB(B0, 0, 0); PG8_LDB(B1, 0, 1); PG8_SCHED; PG8_LDA(At, 0, 0); PG8_STAGE(PG8_SA(1, 1), a1 + hstepA, voffA);
	s_add_i32 m0, s58, 0xc000
	ds_read_b128 v[176:179], v191
	ds_read_b128 v[180:183], v191 offset:1024
	ds_read_b128 v[194:197], v191 offset:2048
	ds_read_b128 v[200:203], v191 offset:3072
	ds_read_b128 v[204:207], v191 offset:4096
	ds_read_b128 v[208:211], v191 offset:5120
	ds_read_b128 v[212:215], v191 offset:6144
	ds_read_b128 v[216:219], v191 offset:7168
	global_load_lds_dwordx4 v160, s[50:51]

; #define PG8_STAGE(bufoff, gbase, voff) do { _Pragma("unroll") for (int _i = 0; _i < 2; ++_i) \
;         __builtin_amdgcn_global_load_lds((const unsigned*)((const char*)(gbase) + (voff)[_i]), (PG8_LAS unsigned*)(lds + (bufoff) + ldsw + _i * 8192), 16, 0, 0); } while (0)
; #define PG8_LDA(dst, b, h) do { _Pragma("unroll") for (int m = 0; m < 4; ++m) _Pragma("unroll") for (int k = 0; k < 2; ++k) dst[m][k] = *(const PG8_LAS bf16x8*)(lds + PG8_SA(b, h) + aoff + m * 2048 + k * 1024); } while (0)
; #define PG8_LDB(dst, b, h) do { _Pragma("unroll") for (int n = 0; n < 2; ++n) _Pragma("unroll") for (int k = 0; k < 2; ++k) dst[n][k] = *(const PG8_LAS bf16x8*)(lds + PG8_SB(b, h) + boff + n * 2048 + k * 1024); } while (0)
; #define PG8_MMA(ai, bj, At, Bt) do { __builtin_amdgcn_s_setprio(1); _Pragma("unroll") for (int m = 0; m < 4; ++m) _Pragma("unroll") for (int n = 0; n < 2; ++n) _Pragma("unroll") for (int k = 0; k < 2; ++k) \
;         acc[ai][bj][m][n] = __builtin_amdgcn_mfma_f32_16x16x32_bf16(Bt[n][k], At[m][k], acc[ai][bj][m][n], 0, 0, 0); __builtin_amdgcn_s_setprio(0); } while (0)
; #define PG8_WAIT_V(n) asm volatile("s_waitcnt vmcnt(" #n ")" ::: "memory")
; #define PG8_WAIT_L(n) asm volatile("s_waitcnt lgkmcnt(" #n ")" ::: "memory")
; #define PG8_BAR __builtin_amdgcn_s_barrier()
; #define PG8_SCHED __builtin_amdgcn_sched_barrier(0)
; template <class Epi, class Sched, bool ALIGN_EPI = false, bool SP2 = false, bool ATILED = false>
; __device__ __forceinline__ void gemm_phase(PG8_LAS unsigned char* lds, const Gemm g, const Sched& S, const Epi& E) {
;     ...
;             PG8_LDB(B0, 0, 0); PG8_LDB(B1, 0, 1); PG8_SCHED; PG8_LDA(At, 0, 0); PG8_STAGE(PG8_SA(1, 1), a1 + hstepA, voffA);
;             PG8_WAIT_V(8); PG8_WAIT_L(0); PG8_BAR; PG8_MMA(0, 0, At, B0); PG8_MMA(0, 1, At, B1); PG8_BAR; PG8_SCHED;
	s_add_i32 m0, s58, 0xe000
	s_nop 0
	global_load_lds_dwordx4 v162, s[50:51]
	s_waitcnt vmcnt(8)
	s_waitcnt lgkmcnt(0)
	s_barrier
	s_setprio 1
	s_waitcnt lgkmcnt(0)
	v_mfma_f32_16x16x32_bf16 v[124:127], v[128:131], v[176:179], 0
	v_mfma_f32_16x16x32_bf16 v[120:123], v[136:139], v[176:179], 0
	v_mfma_f32_16x16x32_bf16 v[108:111], v[128:131], v[194:197], 0
	v_mfma_f32_16x16x32_bf16 v[104:107], v[136:139], v[194:197], 0
	v_mfma_f32_16x16x32_bf16 v[92:95], v[128:131], v[204:207], 0
	v_mfma_f32_16x16x32_bf16 v[88:91], v[136:139], v[204:207], 0
	v_mfma_f32_16x16x32_bf16 v[76:79], v[128:131], v[212:215], 0
	v_mfma_f32_16x16x32_bf16 v[72:75], v[136:139], v[212:215], 0
	v_mfma_f32_16x16x32_bf16 v[124:127], v[132:135], v[180:183], v[124:127]
	v_mfma_f32_16x16x32_bf16 v[120:123], v[140:143], v[180:183], v[120:123]
	v_mfma_f32_16x16x32_bf16 v[108:111], v[132:135], v[200:203], v[108:111]
	v_mfma_f32_16x16x32_bf16 v[104:107], v[140:143], v[200:203], v[104:107]
	v_mfma_f32_16x16x32_bf16 v[92:95], v[132:135], v[208:211], v[92:95]
	v_mfma_f32_16x16x32_bf16 v[88:91], v[140:143], v[208:211], v[88:91]
	v_mfma_f32_16x16x32_bf16 v[76:79], v[132:135], v[216:219], v[76:79]
	v_mfma_f32_16x16x32_bf16 v[72:75], v[140:143], v[216:219], v[72:75]
	s_setprio 0
	s_setprio 1
	v_mfma_f32_16x16x32_bf16 v[116:119], v[144:147], v[176:179], 0
	v_mfma_f32_16x16x32_bf16 v[112:115], v[168:171], v[176:179], 0
	v_mfma_f32_16x16x32_bf16 v[100:103], v[144:147], v[194:197], 0
	v_mfma_f32_16x16x32_bf16 v[96:99], v[168:171], v[194:197], 0
	v_mfma_f32_16x16x32_bf16 v[84:87], v[144:147], v[204:207], 0
	v_mfma_f32_16x16x32_bf16 v[80:83], v[168:171], v[204:207], 0
	v_mfma_f32_16x16x32_bf16 v[68:71], v[144:147], v[212:215], 0
	v_mfma_f32_16x16x32_bf16 v[64:67], v[168:171], v[212:215], 0
	v_mfma_f32_16x16x32_bf16 v[116:119], v[148:151], v[180:183], v[116:119]
	v_mfma_f32_16x16x32_bf16 v[112:115], v[172:175], v[180:183], v[112:115]
	v_mfma_f32_16x16x32_bf16 v[100:103], v[148:151], v[200:203], v[100:103]
	v_mfma_f32_16x16x32_bf16 v[96:99], v[172:175], v[200:203], v[96:99]
	v_mfma_f32_16x16x32_bf16 v[84:87], v[148:151], v[208:211], v[84:87]
	v_mfma_f32_16x16x32_bf16 v[80:83], v[172:175], v[208:211], v[80:83]
	v_mfma_f32_16x16x32_bf16 v[68:71], v[148:151], v[216:219], v[68:71]
	v_mfma_f32_16x16x32_bf16 v[64:67], v[172:175], v[216:219], v[64:67]
	s_setprio 0
	s_barrier
	s_add_u32 s98, s54, s12
	s_addc_u32 s99, s55, s13
	s_add_u32 s100, s56, s12
	s_addc_u32 s101, s57, s13
	s_add_i32 s74, s67, s29

; #define PG8_STAGE(bufoff, gbase, voff) do { _Pragma("unroll") for (int _i = 0; _i < 2; ++_i) \
;         __builtin_amdgcn_global_load_lds((const unsigned*)((const char*)(gbase) + (voff)[_i]), (PG8_LAS unsigned*)(lds + (bufoff) + ldsw + _i * 8192), 16, 0, 0); } while (0)
; #define PG8_LDA(dst, b, h) do { _Pragma("unroll") for (int m = 0; m < 4; ++m) _Pragma("unroll") for (int k = 0; k < 2; ++k) dst[m][k] = *(const PG8_LAS bf16x8*)(lds + PG8_SA(b, h) + aoff + m * 2048 + k * 1024); } while (0)
; template <class Epi, class Sched, bool ALIGN_EPI = false, bool SP2 = false, bool ATILED = false>
; __device__ __forceinline__ void gemm_phase(PG8_LAS unsigned char* lds, const Gemm g, const Sched& S, const Epi& E) {
;     ...
;             PG8_LDA(At, 0, 1); PG8_STAGE(PG8_SB(0, 0), b2, voffB); PG8_STAGE(PG8_SB(0, 1), b2 + hstep, voffB); PG8_STAGE(PG8_SA(0, 0), a2, voffA);
	s_mov_b32 m0, s74
	ds_read_b128 v[176:179], v191 offset:16384
	ds_read_b128 v[180:183], v191 offset:17408
	ds_read_b128 v[194:197], v191 offset:18432
	ds_read_b128 v[200:203], v191 offset:19456
	ds_read_b128 v[204:207], v191 offset:20480
	ds_read_b128 v[208:211], v191 offset:21504
	ds_read_b128 v[212:215], v191 offset:22528
	ds_read_b128 v[216:219], v191 offset:23552
	global_load_lds_dwordx4 v154, s[54:55]
	s_add_i32 m0, s74, 0x2000
	s_add_u32 s74, s54, 0x40000

; #define PG8_STAGE(bufoff, gbase, voff) do { _Pragma("unroll") for (int _i = 0; _i < 2; ++_i) \
;         __builtin_amdgcn_global_load_lds((const unsigned*)((const char*)(gbase) + (voff)[_i]), (PG8_LAS unsigned*)(lds + (bufoff) + ldsw + _i * 8192), 16, 0, 0); } while (0)
; #define PG8_LDA(dst, b, h) do { _Pragma("unroll") for (int m = 0; m < 4; ++m) _Pragma("unroll") for (int k = 0; k < 2; ++k) dst[m][k] = *(const PG8_LAS bf16x8*)(lds + PG8_SA(b, h) + aoff + m * 2048 + k * 1024); } while (0)
; template <class Epi, class Sched, bool ALIGN_EPI = false, bool SP2 = false, bool ATILED = false>
; __device__ __forceinline__ void gemm_phase(PG8_LAS unsigned char* lds, const Gemm g, const Sched& S, const Epi& E) {
;     ...
;             PG8_LDA(At, 0, 1); PG8_STAGE(PG8_SB(0, 0), b2, voffB); PG8_STAGE(PG8_SB(0, 1), b2 + hstep, voffB); PG8_STAGE(PG8_SA(0, 0), a2, voffA);
	s_addc_u32 s75, s55, 0
	s_add_i32 s76, s68, s29
	global_load_lds_dwordx4 v158, s[54:55]

; #define PG8_STAGE(bufoff, gbase, voff) do { _Pragma("unroll") for (int _i = 0; _i < 2; ++_i) \
;         __builtin_amdgcn_global_load_lds((const unsigned*)((const char*)(gbase) + (voff)[_i]), (PG8_LAS unsigned*)(lds + (bufoff) + ldsw + _i * 8192), 16, 0, 0); } while (0)
; #define PG8_LDA(dst, b, h) do { _Pragma("unroll") for (int m = 0; m < 4; ++m) _Pragma("unroll") for (int k = 0; k < 2; ++k) dst[m][k] = *(const PG8_LAS bf16x8*)(lds + PG8_SA(b, h) + aoff + m * 2048 + k * 1024); } while (0)
; template <class Epi, class Sched, bool ALIGN_EPI = false, bool SP2 = false, bool ATILED = false>
; __device__ __forceinline__ void gemm_phase(PG8_LAS unsigned char* lds, const Gemm g, const Sched& S, const Epi& E) {
;     ...
;             PG8_LDA(At, 0, 1); PG8_STAGE(PG8_SB(0, 0), b2, voffB); PG8_STAGE(PG8_SB(0, 1), b2 + hstep, voffB); PG8_STAGE(PG8_SA(0, 0), a2, voffA);
	s_mov_b32 m0, s76

; #define PG8_STAGE(bufoff, gbase, voff) do { _Pragma("unroll") for (int _i = 0; _i < 2; ++_i) \
;         __builtin_amdgcn_global_load_lds((const unsigned*)((const char*)(gbase) + (voff)[_i]), (PG8_LAS unsigned*)(lds + (bufoff) + ldsw + _i * 8192), 16, 0, 0); } while (0)
; #define PG8_LDA(dst, b, h) do { _Pragma("unroll") for (int m = 0; m < 4; ++m) _Pragma("unroll") for (int k = 0; k < 2; ++k) dst[m][k] = *(const PG8_LAS bf16x8*)(lds + PG8_SA(b, h) + aoff + m * 2048 + k * 1024); } while (0)
; template <class Epi, class Sched, bool ALIGN_EPI = false, bool SP2 = false, bool ATILED = false>
; __device__ __forceinline__ void gemm_phase(PG8_LAS unsigned char* lds, const Gemm g, const Sched& S, const Epi& E) {
;     ...
;             PG8_LDA(At, 0, 1); PG8_STAGE(PG8_SB(0, 0), b2, voffB); PG8_STAGE(PG8_SB(0, 1), b2 + hstep, voffB); PG8_STAGE(PG8_SA(0, 0), a2, voffA);
	s_nop 0
	global_load_lds_dwordx4 v154, s[74:75]

; #define PG8_STAGE(bufoff, gbase, voff) do { _Pragma("unroll") for (int _i = 0; _i < 2; ++_i) \
;         __builtin_amdgcn_global_load_lds((const unsigned*)((const char*)(gbase) + (voff)[_i]), (PG8_LAS unsigned*)(lds + (bufoff) + ldsw + _i * 8192), 16, 0, 0); } while (0)
; #define PG8_LDA(dst, b, h) do { _Pragma("unroll") for (int m = 0; m < 4; ++m) _Pragma("unroll") for (int k = 0; k < 2; ++k) dst[m][k] = *(const PG8_LAS bf16x8*)(lds + PG8_SA(b, h) + aoff + m * 2048 + k * 1024); } while (0)
; template <class Epi, class Sched, bool ALIGN_EPI = false, bool SP2 = false, bool ATILED = false>
; __device__ __forceinline__ void gemm_phase(PG8_LAS unsigned char* lds, const Gemm g, const Sched& S, const Epi& E) {
;     ...
;             PG8_LDA(At, 0, 1); PG8_STAGE(PG8_SB(0, 0), b2, voffB); PG8_STAGE(PG8_SB(0, 1), b2 + hstep, voffB); PG8_STAGE(PG8_SA(0, 0), a2, voffA);
	s_add_i32 m0, s76, 0x2000
	s_nop 0
	global_load_lds_dwordx4 v158, s[74:75]

; #define PG8_STAGE(bufoff, gbase, voff) do { _Pragma("unroll") for (int _i = 0; _i < 2; ++_i) \
;         __builtin_amdgcn_global_load_lds((const unsigned*)((const char*)(gbase) + (voff)[_i]), (PG8_LAS unsigned*)(lds + (bufoff) + ldsw + _i * 8192), 16, 0, 0); } while (0)
; #define PG8_LDA(dst, b, h) do { _Pragma("unroll") for (int m = 0; m < 4; ++m) _Pragma("unroll") for (int k = 0; k < 2; ++k) dst[m][k] = *(const PG8_LAS bf16x8*)(lds + PG8_SA(b, h) + aoff + m * 2048 + k * 1024); } while (0)
; #define PG8_LDB(dst, b, h) do { _Pragma("unroll") for (int n = 0; n < 2; ++n) _Pragma("unroll") for (int k = 0; k < 2; ++k) dst[n][k] = *(const PG8_LAS bf16x8*)(lds + PG8_SB(b, h) + boff + n * 2048 + k * 1024); } while (0)
; #define PG8_MMA(ai, bj, At, Bt) do { __builtin_amdgcn_s_setprio(1); _Pragma("unroll") for (int m = 0; m < 4; ++m) _Pragma("unroll") for (int n = 0; n < 2; ++n) _Pragma("unroll") for (int k = 0; k < 2; ++k) \
;         acc[ai][bj][m][n] = __builtin_amdgcn_mfma_f32_16x16x32_bf16(Bt[n][k], At[m][k], acc[ai][bj][m][n], 0, 0, 0); __builtin_amdgcn_s_setprio(0); } while (0)
; #define PG8_WAIT_V(n) asm volatile("s_waitcnt vmcnt(" #n ")" ::: "memory")
; #define PG8_WAIT_L(n) asm volatile("s_waitcnt lgkmcnt(" #n ")" ::: "memory")
; #define PG8_BAR __builtin_amdgcn_s_barrier()
; #define PG8_SCHED __builtin_amdgcn_sched_barrier(0)
; template <class Epi, class Sched, bool ALIGN_EPI = false, bool SP2 = false, bool ATILED = false>
; __device__ __forceinline__ void gemm_phase(PG8_LAS unsigned char* lds, const Gemm g, const Sched& S, const Epi& E) {
;     ...
;             PG8_LDA(At, 0, 1); PG8_STAGE(PG8_SB(0, 0), b2, voffB); PG8_STAGE(PG8_SB(0, 1), b2 + hstep, voffB); PG8_STAGE(PG8_SA(0, 0), a2, voffA);
;             PG8_WAIT_V(8); PG8_WAIT_L(0); PG8_BAR; PG8_MMA(1, 0, At, B0); PG8_MMA(1, 1, At, B1); PG8_BAR; PG8_SCHED;
;             PG8_LDB(B0, 1, 0); PG8_LDB(B1, 1, 1); PG8_SCHED; PG8_LDA(At, 1, 0); PG8_STAGE(PG8_SA(0, 1), a2 + hstepA, voffA);
	s_mov_b32 m0, s58
	s_nop 0
	global_load_lds_dwordx4 v152, s[56:57]
	s_mov_b32 m0, s59
	s_nop 0
	global_load_lds_dwordx4 v156, s[56:57]
	s_waitcnt vmcnt(8)
	s_waitcnt lgkmcnt(0)
	s_barrier
	s_setprio 1
	s_waitcnt lgkmcnt(0)
	v_mfma_f32_16x16x32_bf16 v[60:63], v[128:131], v[176:179], 0
	v_mfma_f32_16x16x32_bf16 v[56:59], v[136:139], v[176:179], 0
	v_mfma_f32_16x16x32_bf16 v[44:47], v[128:131], v[194:197], 0
	v_mfma_f32_16x16x32_bf16 v[40:43], v[136:139], v[194:197], 0
	v_mfma_f32_16x16x32_bf16 v[28:31], v[128:131], v[204:207], 0
	v_mfma_f32_16x16x32_bf16 v[24:27], v[136:139], v[204:207], 0
	v_mfma_f32_16x16x32_bf16 v[12:15], v[128:131], v[212:215], 0
	v_mfma_f32_16x16x32_bf16 v[8:11], v[136:139], v[212:215], 0
	v_mfma_f32_16x16x32_bf16 v[60:63], v[132:135], v[180:183], v[60:63]
	v_mfma_f32_16x16x32_bf16 v[56:59], v[140:143], v[180:183], v[56:59]
	v_mfma_f32_16x16x32_bf16 v[44:47], v[132:135], v[200:203], v[44:47]
	v_mfma_f32_16x16x32_bf16 v[40:43], v[140:143], v[200:203], v[40:43]
	v_mfma_f32_16x16x32_bf16 v[28:31], v[132:135], v[208:211], v[28:31]
	v_mfma_f32_16x16x32_bf16 v[24:27], v[140:143], v[208:211], v[24:27]
	v_mfma_f32_16x16x32_bf16 v[12:15], v[132:135], v[216:219], v[12:15]
	v_mfma_f32_16x16x32_bf16 v[8:11], v[140:143], v[216:219], v[8:11]
	s_setprio 0
	s_setprio 1
	v_mfma_f32_16x16x32_bf16 v[52:55], v[144:147], v[176:179], 0
	v_mfma_f32_16x16x32_bf16 v[48:51], v[168:171], v[176:179], 0
	v_mfma_f32_16x16x32_bf16 v[36:39], v[144:147], v[194:197], 0
	v_mfma_f32_16x16x32_bf16 v[32:35], v[168:171], v[194:197], 0
	v_mfma_f32_16x16x32_bf16 v[20:23], v[144:147], v[204:207], 0
	v_mfma_f32_16x16x32_bf16 v[16:19], v[168:171], v[204:207], 0
	v_mfma_f32_16x16x32_bf16 v[4:7], v[144:147], v[212:215], 0
	v_mfma_f32_16x16x32_bf16 v[0:3], v[168:171], v[212:215], 0
	v_mfma_f32_16x16x32_bf16 v[52:55], v[148:151], v[180:183], v[52:55]
	v_mfma_f32_16x16x32_bf16 v[48:51], v[172:175], v[180:183], v[48:51]
	v_mfma_f32_16x16x32_bf16 v[36:39], v[148:151], v[200:203], v[36:39]
	v_mfma_f32_16x16x32_bf16 v[32:35], v[172:175], v[200:203], v[32:35]
	v_mfma_f32_16x16x32_bf16 v[20:23], v[148:151], v[208:211], v[20:23]
	v_mfma_f32_16x16x32_bf16 v[16:19], v[172:175], v[208:211], v[16:19]
	v_mfma_f32_16x16x32_bf16 v[4:7], v[148:151], v[216:219], v[4:7]
	v_mfma_f32_16x16x32_bf16 v[0:3], v[172:175], v[216:219], v[0:3]
	s_setprio 0
	s_barrier
	s_add_i32 s74, 0, 0x18000
	s_add_i32 s75, 0, 0x1c000
	v_add_u32_e32 v140, s74, v187
	v_add_u32_e32 v172, s75, v187
	ds_read_b128 v[128:131], v140
	ds_read_b128 v[132:135], v140 offset:1024
	ds_read_b128 v[136:139], v140 offset:2048
	ds_read_b128 v[140:143], v140 offset:3072
	ds_read_b128 v[144:147], v172
	ds_read_b128 v[148:151], v172 offset:1024
	ds_read_b128 v[168:171], v172 offset:2048
	ds_read_b128 v[172:175], v172 offset:3072
	s_add_u32 s56, s56, 0x40000
	s_addc_u32 s57, s57, 0
	s_mov_b32 m0, s60

; #define PG8_STAGE(bufoff, gbase, voff) do { _Pragma("unroll") for (int _i = 0; _i < 2; ++_i) \
;         __builtin_amdgcn_global_load_lds((const unsigned*)((const char*)(gbase) + (voff)[_i]), (PG8_LAS unsigned*)(lds + (bufoff) + ldsw + _i * 8192), 16, 0, 0); } while (0)
; #define PG8_LDA(dst, b, h) do { _Pragma("unroll") for (int m = 0; m < 4; ++m) _Pragma("unroll") for (int k = 0; k < 2; ++k) dst[m][k] = *(const PG8_LAS bf16x8*)(lds + PG8_SA(b, h) + aoff + m * 2048 + k * 1024); } while (0)
; #define PG8_LDB(dst, b, h) do { _Pragma("unroll") for (int n = 0; n < 2; ++n) _Pragma("unroll") for (int k = 0; k < 2; ++k) dst[n][k] = *(const PG8_LAS bf16x8*)(lds + PG8_SB(b, h) + boff + n * 2048 + k * 1024); } while (0)
; #define PG8_SCHED __builtin_amdgcn_sched_barrier(0)
; template <class Epi, class Sched, bool ALIGN_EPI = false, bool SP2 = false, bool ATILED = false>
; __device__ __forceinline__ void gemm_phase(PG8_LAS unsigned char* lds, const Gemm g, const Sched& S, const Epi& E) {
;     ...
;             PG8_LDB(B0, 1, 0); PG8_LDB(B1, 1, 1); PG8_SCHED; PG8_LDA(At, 1, 0); PG8_STAGE(PG8_SA(0, 1), a2 + hstepA, voffA);
	ds_read_b128 v[176:179], v191 offset:32768
	ds_read_b128 v[180:183], v191 offset:33792
	ds_read_b128 v[194:197], v191 offset:34816
	ds_read_b128 v[200:203], v191 offset:35840
	ds_read_b128 v[204:207], v191 offset:36864
	ds_read_b128 v[208:211], v191 offset:37888
	ds_read_b128 v[212:215], v191 offset:38912
	ds_read_b128 v[216:219], v191 offset:39936
	global_load_lds_dwordx4 v152, s[56:57]

; #define PG8_STAGE(bufoff, gbase, voff) do { _Pragma("unroll") for (int _i = 0; _i < 2; ++_i) \
;         __builtin_amdgcn_global_load_lds((const unsigned*)((const char*)(gbase) + (voff)[_i]), (PG8_LAS unsigned*)(lds + (bufoff) + ldsw + _i * 8192), 16, 0, 0); } while (0)
; #define PG8_LDA(dst, b, h) do { _Pragma("unroll") for (int m = 0; m < 4; ++m) _Pragma("unroll") for (int k = 0; k < 2; ++k) dst[m][k] = *(const PG8_LAS bf16x8*)(lds + PG8_SA(b, h) + aoff + m * 2048 + k * 1024); } while (0)
; #define PG8_LDB(dst, b, h) do { _Pragma("unroll") for (int n = 0; n < 2; ++n) _Pragma("unroll") for (int k = 0; k < 2; ++k) dst[n][k] = *(const PG8_LAS bf16x8*)(lds + PG8_SB(b, h) + boff + n * 2048 + k * 1024); } while (0)
; #define PG8_MMA(ai, bj, At, Bt) do { __builtin_amdgcn_s_setprio(1); _Pragma("unroll") for (int m = 0; m < 4; ++m) _Pragma("unroll") for (int n = 0; n < 2; ++n) _Pragma("unroll") for (int k = 0; k < 2; ++k) \
;         acc[ai][bj][m][n] = __builtin_amdgcn_mfma_f32_16x16x32_bf16(Bt[n][k], At[m][k], acc[ai][bj][m][n], 0, 0, 0); __builtin_amdgcn_s_setprio(0); } while (0)
; #define PG8_WAIT_V(n) asm volatile("s_waitcnt vmcnt(" #n ")" ::: "memory")
; #define PG8_WAIT_L(n) asm volatile("s_waitcnt lgkmcnt(" #n ")" ::: "memory")
; #define PG8_BAR __builtin_amdgcn_s_barrier()
; #define PG8_SCHED __builtin_amdgcn_sched_barrier(0)
; template <class Epi, class Sched, bool ALIGN_EPI = false, bool SP2 = false, bool ATILED = false>
; __device__ __forceinline__ void gemm_phase(PG8_LAS unsigned char* lds, const Gemm g, const Sched& S, const Epi& E) {
;     ...
;             PG8_LDB(B0, 1, 0); PG8_LDB(B1, 1, 1); PG8_SCHED; PG8_LDA(At, 1, 0); PG8_STAGE(PG8_SA(0, 1), a2 + hstepA, voffA);
;             PG8_WAIT_V(8); PG8_WAIT_L(0); PG8_BAR; PG8_MMA(0, 0, At, B0); PG8_MMA(0, 1, At, B1); PG8_BAR; PG8_SCHED;
	s_mov_b32 m0, s61
	s_nop 0
	global_load_lds_dwordx4 v156, s[56:57]
	s_waitcnt vmcnt(8)
	s_waitcnt lgkmcnt(0)
	s_barrier
	s_setprio 1
	s_waitcnt lgkmcnt(0)
	v_mfma_f32_16x16x32_bf16 v[124:127], v[128:131], v[176:179], v[124:127]
	v_mfma_f32_16x16x32_bf16 v[120:123], v[136:139], v[176:179], v[120:123]
	v_mfma_f32_16x16x32_bf16 v[108:111], v[128:131], v[194:197], v[108:111]
	v_mfma_f32_16x16x32_bf16 v[104:107], v[136:139], v[194:197], v[104:107]
	v_mfma_f32_16x16x32_bf16 v[92:95], v[128:131], v[204:207], v[92:95]
	v_mfma_f32_16x16x32_bf16 v[88:91], v[136:139], v[204:207], v[88:91]
	v_mfma_f32_16x16x32_bf16 v[76:79], v[128:131], v[212:215], v[76:79]
	v_mfma_f32_16x16x32_bf16 v[72:75], v[136:139], v[212:215], v[72:75]
	v_mfma_f32_16x16x32_bf16 v[124:127], v[132:135], v[180:183], v[124:127]
	v_mfma_f32_16x16x32_bf16 v[120:123], v[140:143], v[180:183], v[120:123]
	v_mfma_f32_16x16x32_bf16 v[108:111], v[132:135], v[200:203], v[108:111]
	v_mfma_f32_16x16x32_bf16 v[104:107], v[140:143], v[200:203], v[104:107]
	v_mfma_f32_16x16x32_bf16 v[92:95], v[132:135], v[208:211], v[92:95]
	v_mfma_f32_16x16x32_bf16 v[88:91], v[140:143], v[208:211], v[88:91]
	v_mfma_f32_16x16x32_bf16 v[76:79], v[132:135], v[216:219], v[76:79]
	v_mfma_f32_16x16x32_bf16 v[72:75], v[140:143], v[216:219], v[72:75]
	s_setprio 0
	s_setprio 1
	v_mfma_f32_16x16x32_bf16 v[116:119], v[144:147], v[176:179], v[116:119]
	v_mfma_f32_16x16x32_bf16 v[112:115], v[168:171], v[176:179], v[112:115]
	v_mfma_f32_16x16x32_bf16 v[100:103], v[144:147], v[194:197], v[100:103]
	v_mfma_f32_16x16x32_bf16 v[96:99], v[168:171], v[194:197], v[96:99]
	v_mfma_f32_16x16x32_bf16 v[84:87], v[144:147], v[204:207], v[84:87]
	v_mfma_f32_16x16x32_bf16 v[80:83], v[168:171], v[204:207], v[80:83]
	v_mfma_f32_16x16x32_bf16 v[68:71], v[144:147], v[212:215], v[68:71]
	v_mfma_f32_16x16x32_bf16 v[64:67], v[168:171], v[212:215], v[64:67]
	v_mfma_f32_16x16x32_bf16 v[116:119], v[148:151], v[180:183], v[116:119]
	v_mfma_f32_16x16x32_bf16 v[112:115], v[172:175], v[180:183], v[112:115]
	v_mfma_f32_16x16x32_bf16 v[100:103], v[148:151], v[200:203], v[100:103]
	v_mfma_f32_16x16x32_bf16 v[96:99], v[172:175], v[200:203], v[96:99]
	v_mfma_f32_16x16x32_bf16 v[84:87], v[148:151], v[208:211], v[84:87]
	v_mfma_f32_16x16x32_bf16 v[80:83], v[172:175], v[208:211], v[80:83]
	v_mfma_f32_16x16x32_bf16 v[68:71], v[148:151], v[216:219], v[68:71]
	v_mfma_f32_16x16x32_bf16 v[64:67], v[172:175], v[216:219], v[64:67]
	s_setprio 0
	s_barrier
	s_add_i32 s56, s74, s29

; #define PG8_STAGE(bufoff, gbase, voff) do { _Pragma("unroll") for (int _i = 0; _i < 2; ++_i) \
;         __builtin_amdgcn_global_load_lds((const unsigned*)((const char*)(gbase) + (voff)[_i]), (PG8_LAS unsigned*)(lds + (bufoff) + ldsw + _i * 8192), 16, 0, 0); } while (0)
; #define PG8_LDA(dst, b, h) do { _Pragma("unroll") for (int m = 0; m < 4; ++m) _Pragma("unroll") for (int k = 0; k < 2; ++k) dst[m][k] = *(const PG8_LAS bf16x8*)(lds + PG8_SA(b, h) + aoff + m * 2048 + k * 1024); } while (0)
; template <class Epi, class Sched, bool ALIGN_EPI = false, bool SP2 = false, bool ATILED = false>
; __device__ __forceinline__ void gemm_phase(PG8_LAS unsigned char* lds, const Gemm g, const Sched& S, const Epi& E) {
;     ...
;             PG8_LDA(At, 1, 1); PG8_STAGE(PG8_SB(1, 0), b3, voffB); PG8_STAGE(PG8_SB(1, 1), b3 + hstep, voffB); PG8_STAGE(PG8_SA(1, 0), a3, voffA);
	s_mov_b32 m0, s56
	ds_read_b128 v[176:179], v191 offset:49152
	ds_read_b128 v[180:183], v191 offset:50176
	ds_read_b128 v[194:197], v191 offset:51200
	ds_read_b128 v[200:203], v191 offset:52224
	ds_read_b128 v[204:207], v191 offset:53248
	ds_read_b128 v[208:211], v191 offset:54272
	ds_read_b128 v[212:215], v191 offset:55296
	ds_read_b128 v[216:219], v191 offset:56320
	global_load_lds_dwordx4 v154, s[98:99]
	s_add_i32 m0, s56, 0x2000
	s_add_u32 s54, s54, 0x40080

; #define PG8_STAGE(bufoff, gbase, voff) do { _Pragma("unroll") for (int _i = 0; _i < 2; ++_i) \
;         __builtin_amdgcn_global_load_lds((const unsigned*)((const char*)(gbase) + (voff)[_i]), (PG8_LAS unsigned*)(lds + (bufoff) + ldsw + _i * 8192), 16, 0, 0); } while (0)
; #define PG8_LDA(dst, b, h) do { _Pragma("unroll") for (int m = 0; m < 4; ++m) _Pragma("unroll") for (int k = 0; k < 2; ++k) dst[m][k] = *(const PG8_LAS bf16x8*)(lds + PG8_SA(b, h) + aoff + m * 2048 + k * 1024); } while (0)
; template <class Epi, class Sched, bool ALIGN_EPI = false, bool SP2 = false, bool ATILED = false>
; __device__ __forceinline__ void gemm_phase(PG8_LAS unsigned char* lds, const Gemm g, const Sched& S, const Epi& E) {
;     ...
;             PG8_LDA(At, 1, 1); PG8_STAGE(PG8_SB(1, 0), b3, voffB); PG8_STAGE(PG8_SB(1, 1), b3 + hstep, voffB); PG8_STAGE(PG8_SA(1, 0), a3, voffA);
	s_addc_u32 s55, s55, 0
	s_add_i32 s56, s75, s29
	global_load_lds_dwordx4 v158, s[98:99]

; #define PG8_STAGE(bufoff, gbase, voff) do { _Pragma("unroll") for (int _i = 0; _i < 2; ++_i) \
;         __builtin_amdgcn_global_load_lds((const unsigned*)((const char*)(gbase) + (voff)[_i]), (PG8_LAS unsigned*)(lds + (bufoff) + ldsw + _i * 8192), 16, 0, 0); } while (0)
; #define PG8_LDA(dst, b, h) do { _Pragma("unroll") for (int m = 0; m < 4; ++m) _Pragma("unroll") for (int k = 0; k < 2; ++k) dst[m][k] = *(const PG8_LAS bf16x8*)(lds + PG8_SA(b, h) + aoff + m * 2048 + k * 1024); } while (0)
; template <class Epi, class Sched, bool ALIGN_EPI = false, bool SP2 = false, bool ATILED = false>
; __device__ __forceinline__ void gemm_phase(PG8_LAS unsigned char* lds, const Gemm g, const Sched& S, const Epi& E) {
;     ...
;             PG8_LDA(At, 1, 1); PG8_STAGE(PG8_SB(1, 0), b3, voffB); PG8_STAGE(PG8_SB(1, 1), b3 + hstep, voffB); PG8_STAGE(PG8_SA(1, 0), a3, voffA);
	s_mov_b32 m0, s56
	s_nop 0
	global_load_lds_dwordx4 v154, s[54:55]

; #define PG8_STAGE(bufoff, gbase, voff) do { _Pragma("unroll") for (int _i = 0; _i < 2; ++_i) \
;         __builtin_amdgcn_global_load_lds((const unsigned*)((const char*)(gbase) + (voff)[_i]), (PG8_LAS unsigned*)(lds + (bufoff) + ldsw + _i * 8192), 16, 0, 0); } while (0)
; #define PG8_LDA(dst, b, h) do { _Pragma("unroll") for (int m = 0; m < 4; ++m) _Pragma("unroll") for (int k = 0; k < 2; ++k) dst[m][k] = *(const PG8_LAS bf16x8*)(lds + PG8_SA(b, h) + aoff + m * 2048 + k * 1024); } while (0)
; template <class Epi, class Sched, bool ALIGN_EPI = false, bool SP2 = false, bool ATILED = false>
; __device__ __forceinline__ void gemm_phase(PG8_LAS unsigned char* lds, const Gemm g, const Sched& S, const Epi& E) {
;     ...
;             PG8_LDA(At, 1, 1); PG8_STAGE(PG8_SB(1, 0), b3, voffB); PG8_STAGE(PG8_SB(1, 1), b3 + hstep, voffB); PG8_STAGE(PG8_SA(1, 0), a3, voffA);
	s_add_i32 m0, s56, 0x2000
	s_nop 0
	global_load_lds_dwordx4 v158, s[54:55]

; #define PG8_STAGE(bufoff, gbase, voff) do { _Pragma("unroll") for (int _i = 0; _i < 2; ++_i) \
;         __builtin_amdgcn_global_load_lds((const unsigned*)((const char*)(gbase) + (voff)[_i]), (PG8_LAS unsigned*)(lds + (bufoff) + ldsw + _i * 8192), 16, 0, 0); } while (0)
; #define PG8_LDA(dst, b, h) do { _Pragma("unroll") for (int m = 0; m < 4; ++m) _Pragma("unroll") for (int k = 0; k < 2; ++k) dst[m][k] = *(const PG8_LAS bf16x8*)(lds + PG8_SA(b, h) + aoff + m * 2048 + k * 1024); } while (0)
; template <class Epi, class Sched, bool ALIGN_EPI = false, bool SP2 = false, bool ATILED = false>
; __device__ __forceinline__ void gemm_phase(PG8_LAS unsigned char* lds, const Gemm g, const Sched& S, const Epi& E) {
;     ...
;             PG8_LDA(At, 1, 1); PG8_STAGE(PG8_SB(1, 0), b3, voffB); PG8_STAGE(PG8_SB(1, 1), b3 + hstep, voffB); PG8_STAGE(PG8_SA(1, 0), a3, voffA);
	s_mov_b32 m0, s63
	s_nop 0
	global_load_lds_dwordx4 v152, s[100:101]

; #define PG8_STAGE(bufoff, gbase, voff) do { _Pragma("unroll") for (int _i = 0; _i < 2; ++_i) \
;         __builtin_amdgcn_global_load_lds((const unsigned*)((const char*)(gbase) + (voff)[_i]), (PG8_LAS unsigned*)(lds + (bufoff) + ldsw + _i * 8192), 16, 0, 0); } while (0)
; #define PG8_LDA(dst, b, h) do { _Pragma("unroll") for (int m = 0; m < 4; ++m) _Pragma("unroll") for (int k = 0; k < 2; ++k) dst[m][k] = *(const PG8_LAS bf16x8*)(lds + PG8_SA(b, h) + aoff + m * 2048 + k * 1024); } while (0)
; #define PG8_WAIT_V(n) asm volatile("s_waitcnt vmcnt(" #n ")" ::: "memory")
; #define PG8_WAIT_L(n) asm volatile("s_waitcnt lgkmcnt(" #n ")" ::: "memory")
; #define PG8_BAR __builtin_amdgcn_s_barrier()
; template <class Epi, class Sched, bool ALIGN_EPI = false, bool SP2 = false, bool ATILED = false>
; __device__ __forceinline__ void gemm_phase(PG8_LAS unsigned char* lds, const Gemm g, const Sched& S, const Epi& E) {
;     ...
;         for (int t = 0; t < nt; t += 2) {
;             const bool last = (t == nt - 2);
;             const char* a1 = cA + (size_t)(t + 1) * kstepA;
;             const char* a2 = last ? nA : cA + (size_t)(t + 2) * kstepA; const char* b2 = last ? nB : cB + (size_t)(t + 2) * kstep;
;             const char* a3 = a2 + kstepA; const char* b3 = b2 + kstep;
;             if (last && has_next) S.a_ready(nxt);
;             if constexpr (SP2) {
;             PG8_LDB(B0, 0, 0); PG8_LDB(B1, 0, 1); PG8_SCHED; PG8_LDA(At, 0, 0); PG8_STAGE(PG8_SA(1, 1), a1 + hstepA, voffA);
;             PG8_WAIT_V(8); PG8_WAIT_L(0); PG8_BAR; PG8_MMA(0, 0, At, B0); PG8_MMA(0, 1, At, B1); PG8_BAR; PG8_SCHED;
;             PG8_LDA(At, 0, 1); PG8_STAGE(PG8_SB(0, 0), b2, voffB); PG8_STAGE(PG8_SB(0, 1), b2 + hstep, voffB); PG8_STAGE(PG8_SA(0, 0), a2, voffA);
;             PG8_WAIT_V(8); PG8_WAIT_L(0); PG8_BAR; PG8_MMA(1, 0, At, B0); PG8_MMA(1, 1, At, B1); PG8_BAR; PG8_SCHED;
;             PG8_LDB(B0, 1, 0); PG8_LDB(B1, 1, 1); PG8_SCHED; PG8_LDA(At, 1, 0); PG8_STAGE(PG8_SA(0, 1), a2 + hstepA, voffA);
;             PG8_WAIT_V(8); PG8_WAIT_L(0); PG8_BAR; PG8_MMA(0, 0, At, B0); PG8_MMA(0, 1, At, B1); PG8_BAR; PG8_SCHED;
;             PG8_LDA(At, 1, 1); PG8_STAGE(PG8_SB(1, 0), b3, voffB); PG8_STAGE(PG8_SB(1, 1), b3 + hstep, voffB); PG8_STAGE(PG8_SA(1, 0), a3, voffA);
;             PG8_WAIT_V(8); PG8_WAIT_L(0); PG8_BAR; PG8_MMA(1, 0, At, B0); PG8_MMA(1, 1, At, B1); PG8_BAR; PG8_SCHED;
	s_mov_b32 m0, s64
	s_nop 0
	global_load_lds_dwordx4 v156, s[100:101]
	s_waitcnt vmcnt(8)
	s_waitcnt lgkmcnt(0)
	s_barrier
	s_setprio 1
	s_waitcnt lgkmcnt(0)
	v_mfma_f32_16x16x32_bf16 v[60:63], v[128:131], v[176:179], v[60:63]
	v_mfma_f32_16x16x32_bf16 v[56:59], v[136:139], v[176:179], v[56:59]
	v_mfma_f32_16x16x32_bf16 v[44:47], v[128:131], v[194:197], v[44:47]
	v_mfma_f32_16x16x32_bf16 v[40:43], v[136:139], v[194:197], v[40:43]
	v_mfma_f32_16x16x32_bf16 v[28:31], v[128:131], v[204:207], v[28:31]
	v_mfma_f32_16x16x32_bf16 v[24:27], v[136:139], v[204:207], v[24:27]
	v_mfma_f32_16x16x32_bf16 v[12:15], v[128:131], v[212:215], v[12:15]
	v_mfma_f32_16x16x32_bf16 v[8:11], v[136:139], v[212:215], v[8:11]
	v_mfma_f32_16x16x32_bf16 v[60:63], v[132:135], v[180:183], v[60:63]
	v_mfma_f32_16x16x32_bf16 v[56:59], v[140:143], v[180:183], v[56:59]
	v_mfma_f32_16x16x32_bf16 v[44:47], v[132:135], v[200:203], v[44:47]
	v_mfma_f32_16x16x32_bf16 v[40:43], v[140:143], v[200:203], v[40:43]
	v_mfma_f32_16x16x32_bf16 v[28:31], v[132:135], v[208:211], v[28:31]
	v_mfma_f32_16x16x32_bf16 v[24:27], v[140:143], v[208:211], v[24:27]
	v_mfma_f32_16x16x32_bf16 v[12:15], v[132:135], v[216:219], v[12:15]
	v_mfma_f32_16x16x32_bf16 v[8:11], v[140:143], v[216:219], v[8:11]
	s_setprio 0
	s_setprio 1
	v_mfma_f32_16x16x32_bf16 v[52:55], v[144:147], v[176:179], v[52:55]
	v_mfma_f32_16x16x32_bf16 v[48:51], v[168:171], v[176:179], v[48:51]
	v_mfma_f32_16x16x32_bf16 v[36:39], v[144:147], v[194:197], v[36:39]
	v_mfma_f32_16x16x32_bf16 v[32:35], v[168:171], v[194:197], v[32:35]
	v_mfma_f32_16x16x32_bf16 v[20:23], v[144:147], v[204:207], v[20:23]
	v_mfma_f32_16x16x32_bf16 v[16:19], v[168:171], v[204:207], v[16:19]
	v_mfma_f32_16x16x32_bf16 v[4:7], v[144:147], v[212:215], v[4:7]
	v_mfma_f32_16x16x32_bf16 v[0:3], v[168:171], v[212:215], v[0:3]
	v_mfma_f32_16x16x32_bf16 v[52:55], v[148:151], v[180:183], v[52:55]
	v_mfma_f32_16x16x32_bf16 v[48:51], v[172:175], v[180:183], v[48:51]
	v_mfma_f32_16x16x32_bf16 v[36:39], v[148:151], v[200:203], v[36:39]
	v_mfma_f32_16x16x32_bf16 v[32:35], v[172:175], v[200:203], v[32:35]
	v_mfma_f32_16x16x32_bf16 v[20:23], v[148:151], v[208:211], v[20:23]
	v_mfma_f32_16x16x32_bf16 v[16:19], v[172:175], v[208:211], v[16:19]
	v_mfma_f32_16x16x32_bf16 v[4:7], v[148:151], v[216:219], v[4:7]
	v_mfma_f32_16x16x32_bf16 v[0:3], v[172:175], v[216:219], v[0:3]
	s_setprio 0
	s_barrier
	s_add_i32 s73, s73, 2
	s_add_u32 s50, s50, 0x100
	s_addc_u32 s51, s51, 0
	s_add_u32 s71, s71, 0x100
	s_addc_u32 s72, s72, 0
	s_cmp_gt_u32 s73, 13
.LBB0_735:
	ds_read_b128 v[128:131], v189
	ds_read_b128 v[132:135], v189 offset:1024
	ds_read_b128 v[136:139], v189 offset:2048
	ds_read_b128 v[140:143], v189 offset:3072
	ds_read_b128 v[144:147], v190
	ds_read_b128 v[148:151], v190 offset:1024
	ds_read_b128 v[168:171], v190 offset:2048
	ds_read_b128 v[172:175], v190 offset:3072
	s_add_u32 s54, s50, 0xfffc0080
	s_addc_u32 s55, s51, -1
	s_cmp_eq_u32 s73, 12
	s_cselect_b32 s57, s19, s55
	s_cselect_b32 s56, s49, s54
	s_cselect_b32 s55, s17, s72
	s_cselect_b32 s54, s70, s71

; #define PG8_STAGE(bufoff, gbase, voff) do { _Pragma("unroll") for (int _i = 0; _i < 2; ++_i) \
;         __builtin_amdgcn_global_load_lds((const unsigned*)((const char*)(gbase) + (voff)[_i]), (PG8_LAS unsigned*)(lds + (bufoff) + ldsw + _i * 8192), 16, 0, 0); } while (0)
; #define PG8_LDA(dst, b, h) do { _Pragma("unroll") for (int m = 0; m < 4; ++m) _Pragma("unroll") for (int k = 0; k < 2; ++k) dst[m][k] = *(const PG8_LAS bf16x8*)(lds + PG8_SA(b, h) + aoff + m * 2048 + k * 1024); } while (0)
; #define PG8_LDB(dst, b, h) do { _Pragma("unroll") for (int n = 0; n < 2; ++n) _Pragma("unroll") for (int k = 0; k < 2; ++k) dst[n][k] = *(const PG8_LAS bf16x8*)(lds + PG8_SB(b, h) + boff + n * 2048 + k * 1024); } while (0)
; #define PG8_SCHED __builtin_amdgcn_sched_barrier(0)
; template <class Epi, class Sched, bool ALIGN_EPI = false, bool SP2 = false, bool ATILED = false>
; __device__ __forceinline__ void gemm_phase(PG8_LAS unsigned char* lds, const Gemm g, const Sched& S, const Epi& E) {
;     ...
;             PG8_LDB(B0, 0, 0); PG8_LDB(B1, 0, 1); PG8_SCHED; PG8_LDA(At, 0, 0); PG8_STAGE(PG8_SA(1, 1), a1 + hstepA, voffA);
	s_add_i32 m0, s58, 0xc000
	ds_read_b128 v[176:179], v191
	ds_read_b128 v[180:183], v191 offset:1024
	ds_read_b128 v[194:197], v191 offset:2048
	ds_read_b128 v[200:203], v191 offset:3072
	ds_read_b128 v[204:207], v191 offset:4096
	ds_read_b128 v[208:211], v191 offset:5120
	ds_read_b128 v[212:215], v191 offset:6144
	ds_read_b128 v[216:219], v191 offset:7168
	global_load_lds_dwordx4 v160, s[50:51]

; #define PG8_STAGE(bufoff, gbase, voff) do { _Pragma("unroll") for (int _i = 0; _i < 2; ++_i) \
;         __builtin_amdgcn_global_load_lds((const unsigned*)((const char*)(gbase) + (voff)[_i]), (PG8_LAS unsigned*)(lds + (bufoff) + ldsw + _i * 8192), 16, 0, 0); } while (0)
; #define PG8_LDA(dst, b, h) do { _Pragma("unroll") for (int m = 0; m < 4; ++m) _Pragma("unroll") for (int k = 0; k < 2; ++k) dst[m][k] = *(const PG8_LAS bf16x8*)(lds + PG8_SA(b, h) + aoff + m * 2048 + k * 1024); } while (0)
; #define PG8_LDB(dst, b, h) do { _Pragma("unroll") for (int n = 0; n < 2; ++n) _Pragma("unroll") for (int k = 0; k < 2; ++k) dst[n][k] = *(const PG8_LAS bf16x8*)(lds + PG8_SB(b, h) + boff + n * 2048 + k * 1024); } while (0)
; #define PG8_MMA(ai, bj, At, Bt) do { __builtin_amdgcn_s_setprio(1); _Pragma("unroll") for (int m = 0; m < 4; ++m) _Pragma("unroll") for (int n = 0; n < 2; ++n) _Pragma("unroll") for (int k = 0; k < 2; ++k) \
;         acc[ai][bj][m][n] = __builtin_amdgcn_mfma_f32_16x16x32_bf16(Bt[n][k], At[m][k], acc[ai][bj][m][n], 0, 0, 0); __builtin_amdgcn_s_setprio(0); } while (0)
; #define PG8_WAIT_V(n) asm volatile("s_waitcnt vmcnt(" #n ")" ::: "memory")
; #define PG8_WAIT_L(n) asm volatile("s_waitcnt lgkmcnt(" #n ")" ::: "memory")
; #define PG8_BAR __builtin_amdgcn_s_barrier()
; #define PG8_SCHED __builtin_amdgcn_sched_barrier(0)
; template <class Epi, class Sched, bool ALIGN_EPI = false, bool SP2 = false, bool ATILED = false>
; __device__ __forceinline__ void gemm_phase(PG8_LAS unsigned char* lds, const Gemm g, const Sched& S, const Epi& E) {
;     ...
;             PG8_LDB(B0, 0, 0); PG8_LDB(B1, 0, 1); PG8_SCHED; PG8_LDA(At, 0, 0); PG8_STAGE(PG8_SA(1, 1), a1 + hstepA, voffA);
;             PG8_WAIT_V(8); PG8_WAIT_L(0); PG8_BAR; PG8_MMA(0, 0, At, B0); PG8_MMA(0, 1, At, B1); PG8_BAR; PG8_SCHED;
;     ...
;             PG8_LDA(At, 1, 1); PG8_STAGE(PG8_SB(1, 0), b3, voffB); PG8_STAGE(PG8_SB(1, 1), b3 + hstep, voffB); PG8_STAGE(PG8_SA(1, 0), a3, voffA);
	s_add_i32 m0, s58, 0xe000
	s_nop 0
	global_load_lds_dwordx4 v162, s[50:51]
	s_waitcnt vmcnt(8)
	s_waitcnt lgkmcnt(0)
	s_barrier
	s_setprio 1
	s_waitcnt lgkmcnt(0)
	v_mfma_f32_16x16x32_bf16 v[124:127], v[128:131], v[176:179], v[124:127]
	v_mfma_f32_16x16x32_bf16 v[120:123], v[136:139], v[176:179], v[120:123]
	v_mfma_f32_16x16x32_bf16 v[108:111], v[128:131], v[194:197], v[108:111]
	v_mfma_f32_16x16x32_bf16 v[104:107], v[136:139], v[194:197], v[104:107]
	v_mfma_f32_16x16x32_bf16 v[92:95], v[128:131], v[204:207], v[92:95]
	v_mfma_f32_16x16x32_bf16 v[88:91], v[136:139], v[204:207], v[88:91]
	v_mfma_f32_16x16x32_bf16 v[76:79], v[128:131], v[212:215], v[76:79]
	v_mfma_f32_16x16x32_bf16 v[72:75], v[136:139], v[212:215], v[72:75]
	v_mfma_f32_16x16x32_bf16 v[124:127], v[132:135], v[180:183], v[124:127]
	v_mfma_f32_16x16x32_bf16 v[120:123], v[140:143], v[180:183], v[120:123]
	v_mfma_f32_16x16x32_bf16 v[108:111], v[132:135], v[200:203], v[108:111]
	v_mfma_f32_16x16x32_bf16 v[104:107], v[140:143], v[200:203], v[104:107]
	v_mfma_f32_16x16x32_bf16 v[92:95], v[132:135], v[208:211], v[92:95]
	v_mfma_f32_16x16x32_bf16 v[88:91], v[140:143], v[208:211], v[88:91]
	v_mfma_f32_16x16x32_bf16 v[76:79], v[132:135], v[216:219], v[76:79]
	v_mfma_f32_16x16x32_bf16 v[72:75], v[140:143], v[216:219], v[72:75]
	s_setprio 0
	s_setprio 1
	v_mfma_f32_16x16x32_bf16 v[116:119], v[144:147], v[176:179], v[116:119]
	v_mfma_f32_16x16x32_bf16 v[112:115], v[168:171], v[176:179], v[112:115]
	v_mfma_f32_16x16x32_bf16 v[100:103], v[144:147], v[194:197], v[100:103]
	v_mfma_f32_16x16x32_bf16 v[96:99], v[168:171], v[194:197], v[96:99]
	v_mfma_f32_16x16x32_bf16 v[84:87], v[144:147], v[204:207], v[84:87]
	v_mfma_f32_16x16x32_bf16 v[80:83], v[168:171], v[204:207], v[80:83]
	v_mfma_f32_16x16x32_bf16 v[68:71], v[144:147], v[212:215], v[68:71]
	v_mfma_f32_16x16x32_bf16 v[64:67], v[168:171], v[212:215], v[64:67]
	v_mfma_f32_16x16x32_bf16 v[116:119], v[148:151], v[180:183], v[116:119]
	v_mfma_f32_16x16x32_bf16 v[112:115], v[172:175], v[180:183], v[112:115]
	v_mfma_f32_16x16x32_bf16 v[100:103], v[148:151], v[200:203], v[100:103]
	v_mfma_f32_16x16x32_bf16 v[96:99], v[172:175], v[200:203], v[96:99]
	v_mfma_f32_16x16x32_bf16 v[84:87], v[148:151], v[208:211], v[84:87]
	v_mfma_f32_16x16x32_bf16 v[80:83], v[172:175], v[208:211], v[80:83]
	v_mfma_f32_16x16x32_bf16 v[68:71], v[148:151], v[216:219], v[68:71]
	v_mfma_f32_16x16x32_bf16 v[64:67], v[172:175], v[216:219], v[64:67]
	s_setprio 0
	s_barrier
	s_add_u32 s98, s54, s12
	s_addc_u32 s99, s55, s13
	s_add_u32 s100, s56, s12
	s_addc_u32 s101, s57, s13
	s_add_i32 s74, s67, s29

; #define PG8_STAGE(bufoff, gbase, voff) do { _Pragma("unroll") for (int _i = 0; _i < 2; ++_i) \
;         __builtin_amdgcn_global_load_lds((const unsigned*)((const char*)(gbase) + (voff)[_i]), (PG8_LAS unsigned*)(lds + (bufoff) + ldsw + _i * 8192), 16, 0, 0); } while (0)
; #define PG8_LDA(dst, b, h) do { _Pragma("unroll") for (int m = 0; m < 4; ++m) _Pragma("unroll") for (int k = 0; k < 2; ++k) dst[m][k] = *(const PG8_LAS bf16x8*)(lds + PG8_SA(b, h) + aoff + m * 2048 + k * 1024); } while (0)
; template <class Epi, class Sched, bool ALIGN_EPI = false, bool SP2 = false, bool ATILED = false>
; __device__ __forceinline__ void gemm_phase(PG8_LAS unsigned char* lds, const Gemm g, const Sched& S, const Epi& E) {
;     ...
;             PG8_LDA(At, 0, 1); PG8_STAGE(PG8_SB(0, 0), b2, voffB); PG8_STAGE(PG8_SB(0, 1), b2 + hstep, voffB); PG8_STAGE(PG8_SA(0, 0), a2, voffA);
	s_mov_b32 m0, s74
	ds_read_b128 v[176:179], v191 offset:16384
	ds_read_b128 v[180:183], v191 offset:17408
	ds_read_b128 v[194:197], v191 offset:18432
	ds_read_b128 v[200:203], v191 offset:19456
	ds_read_b128 v[204:207], v191 offset:20480
	ds_read_b128 v[208:211], v191 offset:21504
	ds_read_b128 v[212:215], v191 offset:22528
	ds_read_b128 v[216:219], v191 offset:23552
	global_load_lds_dwordx4 v154, s[54:55]
	s_add_i32 m0, s74, 0x2000
	s_add_u32 s74, s54, 0x40000

; #define PG8_STAGE(bufoff, gbase, voff) do { _Pragma("unroll") for (int _i = 0; _i < 2; ++_i) \
;         __builtin_amdgcn_global_load_lds((const unsigned*)((const char*)(gbase) + (voff)[_i]), (PG8_LAS unsigned*)(lds + (bufoff) + ldsw + _i * 8192), 16, 0, 0); } while (0)
; #define PG8_LDA(dst, b, h) do { _Pragma("unroll") for (int m = 0; m < 4; ++m) _Pragma("unroll") for (int k = 0; k < 2; ++k) dst[m][k] = *(const PG8_LAS bf16x8*)(lds + PG8_SA(b, h) + aoff + m * 2048 + k * 1024); } while (0)
; template <class Epi, class Sched, bool ALIGN_EPI = false, bool SP2 = false, bool ATILED = false>
; __device__ __forceinline__ void gemm_phase(PG8_LAS unsigned char* lds, const Gemm g, const Sched& S, const Epi& E) {
;     ...
;             PG8_LDA(At, 0, 1); PG8_STAGE(PG8_SB(0, 0), b2, voffB); PG8_STAGE(PG8_SB(0, 1), b2 + hstep, voffB); PG8_STAGE(PG8_SA(0, 0), a2, voffA);
	s_addc_u32 s75, s55, 0
	s_add_i32 s76, s68, s29
	global_load_lds_dwordx4 v158, s[54:55]

; #define PG8_STAGE(bufoff, gbase, voff) do { _Pragma("unroll") for (int _i = 0; _i < 2; ++_i) \
;         __builtin_amdgcn_global_load_lds((const unsigned*)((const char*)(gbase) + (voff)[_i]), (PG8_LAS unsigned*)(lds + (bufoff) + ldsw + _i * 8192), 16, 0, 0); } while (0)
; #define PG8_LDA(dst, b, h) do { _Pragma("unroll") for (int m = 0; m < 4; ++m) _Pragma("unroll") for (int k = 0; k < 2; ++k) dst[m][k] = *(const PG8_LAS bf16x8*)(lds + PG8_SA(b, h) + aoff + m * 2048 + k * 1024); } while (0)
; template <class Epi, class Sched, bool ALIGN_EPI = false, bool SP2 = false, bool ATILED = false>
; __device__ __forceinline__ void gemm_phase(PG8_LAS unsigned char* lds, const Gemm g, const Sched& S, const Epi& E) {
;     ...
;             PG8_LDA(At, 0, 1); PG8_STAGE(PG8_SB(0, 0), b2, voffB); PG8_STAGE(PG8_SB(0, 1), b2 + hstep, voffB); PG8_STAGE(PG8_SA(0, 0), a2, voffA);
	s_mov_b32 m0, s76

; #define PG8_STAGE(bufoff, gbase, voff) do { _Pragma("unroll") for (int _i = 0; _i < 2; ++_i) \
;         __builtin_amdgcn_global_load_lds((const unsigned*)((const char*)(gbase) + (voff)[_i]), (PG8_LAS unsigned*)(lds + (bufoff) + ldsw + _i * 8192), 16, 0, 0); } while (0)
; #define PG8_LDA(dst, b, h) do { _Pragma("unroll") for (int m = 0; m < 4; ++m) _Pragma("unroll") for (int k = 0; k < 2; ++k) dst[m][k] = *(const PG8_LAS bf16x8*)(lds + PG8_SA(b, h) + aoff + m * 2048 + k * 1024); } while (0)
; template <class Epi, class Sched, bool ALIGN_EPI = false, bool SP2 = false, bool ATILED = false>
; __device__ __forceinline__ void gemm_phase(PG8_LAS unsigned char* lds, const Gemm g, const Sched& S, const Epi& E) {
;     ...
;             PG8_LDA(At, 0, 1); PG8_STAGE(PG8_SB(0, 0), b2, voffB); PG8_STAGE(PG8_SB(0, 1), b2 + hstep, voffB); PG8_STAGE(PG8_SA(0, 0), a2, voffA);
	s_nop 0
	global_load_lds_dwordx4 v154, s[74:75]

; #define PG8_STAGE(bufoff, gbase, voff) do { _Pragma("unroll") for (int _i = 0; _i < 2; ++_i) \
;         __builtin_amdgcn_global_load_lds((const unsigned*)((const char*)(gbase) + (voff)[_i]), (PG8_LAS unsigned*)(lds + (bufoff) + ldsw + _i * 8192), 16, 0, 0); } while (0)
; #define PG8_LDA(dst, b, h) do { _Pragma("unroll") for (int m = 0; m < 4; ++m) _Pragma("unroll") for (int k = 0; k < 2; ++k) dst[m][k] = *(const PG8_LAS bf16x8*)(lds + PG8_SA(b, h) + aoff + m * 2048 + k * 1024); } while (0)
; template <class Epi, class Sched, bool ALIGN_EPI = false, bool SP2 = false, bool ATILED = false>
; __device__ __forceinline__ void gemm_phase(PG8_LAS unsigned char* lds, const Gemm g, const Sched& S, const Epi& E) {
;     ...
;             PG8_LDA(At, 0, 1); PG8_STAGE(PG8_SB(0, 0), b2, voffB); PG8_STAGE(PG8_SB(0, 1), b2 + hstep, voffB); PG8_STAGE(PG8_SA(0, 0), a2, voffA);
	s_add_i32 m0, s76, 0x2000
	s_nop 0
	global_load_lds_dwordx4 v158, s[74:75]

; #define PG8_STAGE(bufoff, gbase, voff) do { _Pragma("unroll") for (int _i = 0; _i < 2; ++_i) \
;         __builtin_amdgcn_global_load_lds((const unsigned*)((const char*)(gbase) + (voff)[_i]), (PG8_LAS unsigned*)(lds + (bufoff) + ldsw + _i * 8192), 16, 0, 0); } while (0)
; #define PG8_LDA(dst, b, h) do { _Pragma("unroll") for (int m = 0; m < 4; ++m) _Pragma("unroll") for (int k = 0; k < 2; ++k) dst[m][k] = *(const PG8_LAS bf16x8*)(lds + PG8_SA(b, h) + aoff + m * 2048 + k * 1024); } while (0)
; #define PG8_LDB(dst, b, h) do { _Pragma("unroll") for (int n = 0; n < 2; ++n) _Pragma("unroll") for (int k = 0; k < 2; ++k) dst[n][k] = *(const PG8_LAS bf16x8*)(lds + PG8_SB(b, h) + boff + n * 2048 + k * 1024); } while (0)
; #define PG8_MMA(ai, bj, At, Bt) do { __builtin_amdgcn_s_setprio(1); _Pragma("unroll") for (int m = 0; m < 4; ++m) _Pragma("unroll") for (int n = 0; n < 2; ++n) _Pragma("unroll") for (int k = 0; k < 2; ++k) \
;         acc[ai][bj][m][n] = __builtin_amdgcn_mfma_f32_16x16x32_bf16(Bt[n][k], At[m][k], acc[ai][bj][m][n], 0, 0, 0); __builtin_amdgcn_s_setprio(0); } while (0)
; #define PG8_WAIT_V(n) asm volatile("s_waitcnt vmcnt(" #n ")" ::: "memory")
; #define PG8_WAIT_L(n) asm volatile("s_waitcnt lgkmcnt(" #n ")" ::: "memory")
; #define PG8_BAR __builtin_amdgcn_s_barrier()
; #define PG8_SCHED __builtin_amdgcn_sched_barrier(0)
; template <class Epi, class Sched, bool ALIGN_EPI = false, bool SP2 = false, bool ATILED = false>
; __device__ __forceinline__ void gemm_phase(PG8_LAS unsigned char* lds, const Gemm g, const Sched& S, const Epi& E) {
;     ...
;             PG8_LDA(At, 0, 1); PG8_STAGE(PG8_SB(0, 0), b2, voffB); PG8_STAGE(PG8_SB(0, 1), b2 + hstep, voffB); PG8_STAGE(PG8_SA(0, 0), a2, voffA);
;             PG8_WAIT_V(8); PG8_WAIT_L(0); PG8_BAR; PG8_MMA(1, 0, At, B0); PG8_MMA(1, 1, At, B1); PG8_BAR; PG8_SCHED;
;             PG8_LDB(B0, 1, 0); PG8_LDB(B1, 1, 1); PG8_SCHED; PG8_LDA(At, 1, 0); PG8_STAGE(PG8_SA(0, 1), a2 + hstepA, voffA);
	s_mov_b32 m0, s58
	s_nop 0
	global_load_lds_dwordx4 v152, s[56:57]
	s_mov_b32 m0, s59
	s_nop 0
	global_load_lds_dwordx4 v156, s[56:57]
	s_waitcnt vmcnt(8)
	s_waitcnt lgkmcnt(0)
	s_barrier
	s_setprio 1
	s_waitcnt lgkmcnt(0)
	v_mfma_f32_16x16x32_bf16 v[60:63], v[128:131], v[176:179], v[60:63]
	v_mfma_f32_16x16x32_bf16 v[56:59], v[136:139], v[176:179], v[56:59]
	v_mfma_f32_16x16x32_bf16 v[44:47], v[128:131], v[194:197], v[44:47]
	v_mfma_f32_16x16x32_bf16 v[40:43], v[136:139], v[194:197], v[40:43]
	v_mfma_f32_16x16x32_bf16 v[28:31], v[128:131], v[204:207], v[28:31]
	v_mfma_f32_16x16x32_bf16 v[24:27], v[136:139], v[204:207], v[24:27]
	v_mfma_f32_16x16x32_bf16 v[12:15], v[128:131], v[212:215], v[12:15]
	v_mfma_f32_16x16x32_bf16 v[8:11], v[136:139], v[212:215], v[8:11]
	v_mfma_f32_16x16x32_bf16 v[60:63], v[132:135], v[180:183], v[60:63]
	v_mfma_f32_16x16x32_bf16 v[56:59], v[140:143], v[180:183], v[56:59]
	v_mfma_f32_16x16x32_bf16 v[44:47], v[132:135], v[200:203], v[44:47]
	v_mfma_f32_16x16x32_bf16 v[40:43], v[140:143], v[200:203], v[40:43]
	v_mfma_f32_16x16x32_bf16 v[28:31], v[132:135], v[208:211], v[28:31]
	v_mfma_f32_16x16x32_bf16 v[24:27], v[140:143], v[208:211], v[24:27]
	v_mfma_f32_16x16x32_bf16 v[12:15], v[132:135], v[216:219], v[12:15]
	v_mfma_f32_16x16x32_bf16 v[8:11], v[140:143], v[216:219], v[8:11]
	s_setprio 0
	s_setprio 1
	v_mfma_f32_16x16x32_bf16 v[52:55], v[144:147], v[176:179], v[52:55]
	v_mfma_f32_16x16x32_bf16 v[48:51], v[168:171], v[176:179], v[48:51]
	v_mfma_f32_16x16x32_bf16 v[36:39], v[144:147], v[194:197], v[36:39]
	v_mfma_f32_16x16x32_bf16 v[32:35], v[168:171], v[194:197], v[32:35]
	v_mfma_f32_16x16x32_bf16 v[20:23], v[144:147], v[204:207], v[20:23]
	v_mfma_f32_16x16x32_bf16 v[16:19], v[168:171], v[204:207], v[16:19]
	v_mfma_f32_16x16x32_bf16 v[4:7], v[144:147], v[212:215], v[4:7]
	v_mfma_f32_16x16x32_bf16 v[0:3], v[168:171], v[212:215], v[0:3]
	v_mfma_f32_16x16x32_bf16 v[52:55], v[148:151], v[180:183], v[52:55]
	v_mfma_f32_16x16x32_bf16 v[48:51], v[172:175], v[180:183], v[48:51]
	v_mfma_f32_16x16x32_bf16 v[36:39], v[148:151], v[200:203], v[36:39]
	v_mfma_f32_16x16x32_bf16 v[32:35], v[172:175], v[200:203], v[32:35]
	v_mfma_f32_16x16x32_bf16 v[20:23], v[148:151], v[208:211], v[20:23]
	v_mfma_f32_16x16x32_bf16 v[16:19], v[172:175], v[208:211], v[16:19]
	v_mfma_f32_16x16x32_bf16 v[4:7], v[148:151], v[216:219], v[4:7]
	v_mfma_f32_16x16x32_bf16 v[0:3], v[172:175], v[216:219], v[0:3]
	s_setprio 0
	s_barrier
	s_add_i32 s74, 0, 0x18000
	s_add_i32 s75, 0, 0x1c000
	v_add_u32_e32 v140, s74, v187
	v_add_u32_e32 v172, s75, v187
	ds_read_b128 v[128:131], v140
	ds_read_b128 v[132:135], v140 offset:1024
	ds_read_b128 v[136:139], v140 offset:2048
	ds_read_b128 v[140:143], v140 offset:3072
	ds_read_b128 v[144:147], v172
	ds_read_b128 v[148:151], v172 offset:1024
	ds_read_b128 v[168:171], v172 offset:2048
	ds_read_b128 v[172:175], v172 offset:3072
	s_add_u32 s56, s56, 0x40000
	s_addc_u32 s57, s57, 0
	s_mov_b32 m0, s60

; #define PG8_STAGE(bufoff, gbase, voff) do { _Pragma("unroll") for (int _i = 0; _i < 2; ++_i) \
;         __builtin_amdgcn_global_load_lds((const unsigned*)((const char*)(gbase) + (voff)[_i]), (PG8_LAS unsigned*)(lds + (bufoff) + ldsw + _i * 8192), 16, 0, 0); } while (0)
; #define PG8_LDA(dst, b, h) do { _Pragma("unroll") for (int m = 0; m < 4; ++m) _Pragma("unroll") for (int k = 0; k < 2; ++k) dst[m][k] = *(const PG8_LAS bf16x8*)(lds + PG8_SA(b, h) + aoff + m * 2048 + k * 1024); } while (0)
; #define PG8_LDB(dst, b, h) do { _Pragma("unroll") for (int n = 0; n < 2; ++n) _Pragma("unroll") for (int k = 0; k < 2; ++k) dst[n][k] = *(const PG8_LAS bf16x8*)(lds + PG8_SB(b, h) + boff + n * 2048 + k * 1024); } while (0)
; #define PG8_SCHED __builtin_amdgcn_sched_barrier(0)
; template <class Epi, class Sched, bool ALIGN_EPI = false, bool SP2 = false, bool ATILED = false>
; __device__ __forceinline__ void gemm_phase(PG8_LAS unsigned char* lds, const Gemm g, const Sched& S, const Epi& E) {
;     ...
;             PG8_LDB(B0, 1, 0); PG8_LDB(B1, 1, 1); PG8_SCHED; PG8_LDA(At, 1, 0); PG8_STAGE(PG8_SA(0, 1), a2 + hstepA, voffA);
	ds_read_b128 v[176:179], v191 offset:32768
	ds_read_b128 v[180:183], v191 offset:33792
	ds_read_b128 v[194:197], v191 offset:34816
	ds_read_b128 v[200:203], v191 offset:35840
	ds_read_b128 v[204:207], v191 offset:36864
	ds_read_b128 v[208:211], v191 offset:37888
	ds_read_b128 v[212:215], v191 offset:38912
	ds_read_b128 v[216:219], v191 offset:39936
	global_load_lds_dwordx4 v152, s[56:57]

; #define PG8_STAGE(bufoff, gbase, voff) do { _Pragma("unroll") for (int _i = 0; _i < 2; ++_i) \
;         __builtin_amdgcn_global_load_lds((const unsigned*)((const char*)(gbase) + (voff)[_i]), (PG8_LAS unsigned*)(lds + (bufoff) + ldsw + _i * 8192), 16, 0, 0); } while (0)
; #define PG8_LDA(dst, b, h) do { _Pragma("unroll") for (int m = 0; m < 4; ++m) _Pragma("unroll") for (int k = 0; k < 2; ++k) dst[m][k] = *(const PG8_LAS bf16x8*)(lds + PG8_SA(b, h) + aoff + m * 2048 + k * 1024); } while (0)
; #define PG8_LDB(dst, b, h) do { _Pragma("unroll") for (int n = 0; n < 2; ++n) _Pragma("unroll") for (int k = 0; k < 2; ++k) dst[n][k] = *(const PG8_LAS bf16x8*)(lds + PG8_SB(b, h) + boff + n * 2048 + k * 1024); } while (0)
; #define PG8_MMA(ai, bj, At, Bt) do { __builtin_amdgcn_s_setprio(1); _Pragma("unroll") for (int m = 0; m < 4; ++m) _Pragma("unroll") for (int n = 0; n < 2; ++n) _Pragma("unroll") for (int k = 0; k < 2; ++k) \
;         acc[ai][bj][m][n] = __builtin_amdgcn_mfma_f32_16x16x32_bf16(Bt[n][k], At[m][k], acc[ai][bj][m][n], 0, 0, 0); __builtin_amdgcn_s_setprio(0); } while (0)
; #define PG8_WAIT_V(n) asm volatile("s_waitcnt vmcnt(" #n ")" ::: "memory")
; #define PG8_WAIT_L(n) asm volatile("s_waitcnt lgkmcnt(" #n ")" ::: "memory")
; #define PG8_BAR __builtin_amdgcn_s_barrier()
; #define PG8_SCHED __builtin_amdgcn_sched_barrier(0)
; template <class Epi, class Sched, bool ALIGN_EPI = false, bool SP2 = false, bool ATILED = false>
; __device__ __forceinline__ void gemm_phase(PG8_LAS unsigned char* lds, const Gemm g, const Sched& S, const Epi& E) {
;     ...
;             PG8_LDB(B0, 1, 0); PG8_LDB(B1, 1, 1); PG8_SCHED; PG8_LDA(At, 1, 0); PG8_STAGE(PG8_SA(0, 1), a2 + hstepA, voffA);
;             PG8_WAIT_V(8); PG8_WAIT_L(0); PG8_BAR; PG8_MMA(0, 0, At, B0); PG8_MMA(0, 1, At, B1); PG8_BAR; PG8_SCHED;
	s_mov_b32 m0, s61
	s_nop 0
	global_load_lds_dwordx4 v156, s[56:57]
	s_waitcnt vmcnt(8)
	s_waitcnt lgkmcnt(0)
	s_barrier
	s_setprio 1
	s_waitcnt lgkmcnt(0)
	v_mfma_f32_16x16x32_bf16 v[124:127], v[128:131], v[176:179], v[124:127]
	v_mfma_f32_16x16x32_bf16 v[120:123], v[136:139], v[176:179], v[120:123]
	v_mfma_f32_16x16x32_bf16 v[108:111], v[128:131], v[194:197], v[108:111]
	v_mfma_f32_16x16x32_bf16 v[104:107], v[136:139], v[194:197], v[104:107]
	v_mfma_f32_16x16x32_bf16 v[92:95], v[128:131], v[204:207], v[92:95]
	v_mfma_f32_16x16x32_bf16 v[88:91], v[136:139], v[204:207], v[88:91]
	v_mfma_f32_16x16x32_bf16 v[76:79], v[128:131], v[212:215], v[76:79]
	v_mfma_f32_16x16x32_bf16 v[72:75], v[136:139], v[212:215], v[72:75]
	v_mfma_f32_16x16x32_bf16 v[124:127], v[132:135], v[180:183], v[124:127]
	v_mfma_f32_16x16x32_bf16 v[120:123], v[140:143], v[180:183], v[120:123]
	v_mfma_f32_16x16x32_bf16 v[108:111], v[132:135], v[200:203], v[108:111]
	v_mfma_f32_16x16x32_bf16 v[104:107], v[140:143], v[200:203], v[104:107]
	v_mfma_f32_16x16x32_bf16 v[92:95], v[132:135], v[208:211], v[92:95]
	v_mfma_f32_16x16x32_bf16 v[88:91], v[140:143], v[208:211], v[88:91]
	v_mfma_f32_16x16x32_bf16 v[76:79], v[132:135], v[216:219], v[76:79]
	v_mfma_f32_16x16x32_bf16 v[72:75], v[140:143], v[216:219], v[72:75]
	s_setprio 0
	s_setprio 1
	v_mfma_f32_16x16x32_bf16 v[116:119], v[144:147], v[176:179], v[116:119]
	v_mfma_f32_16x16x32_bf16 v[112:115], v[168:171], v[176:179], v[112:115]
	v_mfma_f32_16x16x32_bf16 v[100:103], v[144:147], v[194:197], v[100:103]
	v_mfma_f32_16x16x32_bf16 v[96:99], v[168:171], v[194:197], v[96:99]
	v_mfma_f32_16x16x32_bf16 v[84:87], v[144:147], v[204:207], v[84:87]
	v_mfma_f32_16x16x32_bf16 v[80:83], v[168:171], v[204:207], v[80:83]
	v_mfma_f32_16x16x32_bf16 v[68:71], v[144:147], v[212:215], v[68:71]
	v_mfma_f32_16x16x32_bf16 v[64:67], v[168:171], v[212:215], v[64:67]
	v_mfma_f32_16x16x32_bf16 v[116:119], v[148:151], v[180:183], v[116:119]
	v_mfma_f32_16x16x32_bf16 v[112:115], v[172:175], v[180:183], v[112:115]
	v_mfma_f32_16x16x32_bf16 v[100:103], v[148:151], v[200:203], v[100:103]
	v_mfma_f32_16x16x32_bf16 v[96:99], v[172:175], v[200:203], v[96:99]
	v_mfma_f32_16x16x32_bf16 v[84:87], v[148:151], v[208:211], v[84:87]
	v_mfma_f32_16x16x32_bf16 v[80:83], v[172:175], v[208:211], v[80:83]
	v_mfma_f32_16x16x32_bf16 v[68:71], v[148:151], v[216:219], v[68:71]
	v_mfma_f32_16x16x32_bf16 v[64:67], v[172:175], v[216:219], v[64:67]
	s_setprio 0
	s_barrier
	s_add_i32 s56, s74, s29

; #define PG8_STAGE(bufoff, gbase, voff) do { _Pragma("unroll") for (int _i = 0; _i < 2; ++_i) \
;         __builtin_amdgcn_global_load_lds((const unsigned*)((const char*)(gbase) + (voff)[_i]), (PG8_LAS unsigned*)(lds + (bufoff) + ldsw + _i * 8192), 16, 0, 0); } while (0)
; #define PG8_LDA(dst, b, h) do { _Pragma("unroll") for (int m = 0; m < 4; ++m) _Pragma("unroll") for (int k = 0; k < 2; ++k) dst[m][k] = *(const PG8_LAS bf16x8*)(lds + PG8_SA(b, h) + aoff + m * 2048 + k * 1024); } while (0)
; template <class Epi, class Sched, bool ALIGN_EPI = false, bool SP2 = false, bool ATILED = false>
; __device__ __forceinline__ void gemm_phase(PG8_LAS unsigned char* lds, const Gemm g, const Sched& S, const Epi& E) {
;     ...
;             PG8_LDA(At, 1, 1); PG8_STAGE(PG8_SB(1, 0), b3, voffB); PG8_STAGE(PG8_SB(1, 1), b3 + hstep, voffB); PG8_STAGE(PG8_SA(1, 0), a3, voffA);
	s_mov_b32 m0, s56
	ds_read_b128 v[176:179], v191 offset:49152
	ds_read_b128 v[180:183], v191 offset:50176
	ds_read_b128 v[194:197], v191 offset:51200
	ds_read_b128 v[200:203], v191 offset:52224
	ds_read_b128 v[204:207], v191 offset:53248
	ds_read_b128 v[208:211], v191 offset:54272
	ds_read_b128 v[212:215], v191 offset:55296
	ds_read_b128 v[216:219], v191 offset:56320
	global_load_lds_dwordx4 v154, s[98:99]
	s_add_i32 m0, s56, 0x2000
	s_add_u32 s54, s54, 0x40080

; #define PG8_STAGE(bufoff, gbase, voff) do { _Pragma("unroll") for (int _i = 0; _i < 2; ++_i) \
;         __builtin_amdgcn_global_load_lds((const unsigned*)((const char*)(gbase) + (voff)[_i]), (PG8_LAS unsigned*)(lds + (bufoff) + ldsw + _i * 8192), 16, 0, 0); } while (0)
; #define PG8_LDA(dst, b, h) do { _Pragma("unroll") for (int m = 0; m < 4; ++m) _Pragma("unroll") for (int k = 0; k < 2; ++k) dst[m][k] = *(const PG8_LAS bf16x8*)(lds + PG8_SA(b, h) + aoff + m * 2048 + k * 1024); } while (0)
; template <class Epi, class Sched, bool ALIGN_EPI = false, bool SP2 = false, bool ATILED = false>
; __device__ __forceinline__ void gemm_phase(PG8_LAS unsigned char* lds, const Gemm g, const Sched& S, const Epi& E) {
;     ...
;             PG8_LDA(At, 1, 1); PG8_STAGE(PG8_SB(1, 0), b3, voffB); PG8_STAGE(PG8_SB(1, 1), b3 + hstep, voffB); PG8_STAGE(PG8_SA(1, 0), a3, voffA);
	s_addc_u32 s55, s55, 0
	s_add_i32 s56, s75, s29
	global_load_lds_dwordx4 v158, s[98:99]

; #define PG8_STAGE(bufoff, gbase, voff) do { _Pragma("unroll") for (int _i = 0; _i < 2; ++_i) \
;         __builtin_amdgcn_global_load_lds((const unsigned*)((const char*)(gbase) + (voff)[_i]), (PG8_LAS unsigned*)(lds + (bufoff) + ldsw + _i * 8192), 16, 0, 0); } while (0)
; #define PG8_LDA(dst, b, h) do { _Pragma("unroll") for (int m = 0; m < 4; ++m) _Pragma("unroll") for (int k = 0; k < 2; ++k) dst[m][k] = *(const PG8_LAS bf16x8*)(lds + PG8_SA(b, h) + aoff + m * 2048 + k * 1024); } while (0)
; template <class Epi, class Sched, bool ALIGN_EPI = false, bool SP2 = false, bool ATILED = false>
; __device__ __forceinline__ void gemm_phase(PG8_LAS unsigned char* lds, const Gemm g, const Sched& S, const Epi& E) {
;     ...
;             PG8_LDA(At, 1, 1); PG8_STAGE(PG8_SB(1, 0), b3, voffB); PG8_STAGE(PG8_SB(1, 1), b3 + hstep, voffB); PG8_STAGE(PG8_SA(1, 0), a3, voffA);
	s_mov_b32 m0, s56
	s_nop 0
	global_load_lds_dwordx4 v154, s[54:55]

; #define PG8_STAGE(bufoff, gbase, voff) do { _Pragma("unroll") for (int _i = 0; _i < 2; ++_i) \
;         __builtin_amdgcn_global_load_lds((const unsigned*)((const char*)(gbase) + (voff)[_i]), (PG8_LAS unsigned*)(lds + (bufoff) + ldsw + _i * 8192), 16, 0, 0); } while (0)
; #define PG8_LDA(dst, b, h) do { _Pragma("unroll") for (int m = 0; m < 4; ++m) _Pragma("unroll") for (int k = 0; k < 2; ++k) dst[m][k] = *(const PG8_LAS bf16x8*)(lds + PG8_SA(b, h) + aoff + m * 2048 + k * 1024); } while (0)
; template <class Epi, class Sched, bool ALIGN_EPI = false, bool SP2 = false, bool ATILED = false>
; __device__ __forceinline__ void gemm_phase(PG8_LAS unsigned char* lds, const Gemm g, const Sched& S, const Epi& E) {
;     ...
;             PG8_LDA(At, 1, 1); PG8_STAGE(PG8_SB(1, 0), b3, voffB); PG8_STAGE(PG8_SB(1, 1), b3 + hstep, voffB); PG8_STAGE(PG8_SA(1, 0), a3, voffA);
	s_add_i32 m0, s56, 0x2000
	s_nop 0
	global_load_lds_dwordx4 v158, s[54:55]

; #define PG8_STAGE(bufoff, gbase, voff) do { _Pragma("unroll") for (int _i = 0; _i < 2; ++_i) \
;         __builtin_amdgcn_global_load_lds((const unsigned*)((const char*)(gbase) + (voff)[_i]), (PG8_LAS unsigned*)(lds + (bufoff) + ldsw + _i * 8192), 16, 0, 0); } while (0)
; #define PG8_LDA(dst, b, h) do { _Pragma("unroll") for (int m = 0; m < 4; ++m) _Pragma("unroll") for (int k = 0; k < 2; ++k) dst[m][k] = *(const PG8_LAS bf16x8*)(lds + PG8_SA(b, h) + aoff + m * 2048 + k * 1024); } while (0)
; template <class Epi, class Sched, bool ALIGN_EPI = false, bool SP2 = false, bool ATILED = false>
; __device__ __forceinline__ void gemm_phase(PG8_LAS unsigned char* lds, const Gemm g, const Sched& S, const Epi& E) {
;     ...
;             PG8_LDA(At, 1, 1); PG8_STAGE(PG8_SB(1, 0), b3, voffB); PG8_STAGE(PG8_SB(1, 1), b3 + hstep, voffB); PG8_STAGE(PG8_SA(1, 0), a3, voffA);
	s_mov_b32 m0, s63
	s_nop 0
	global_load_lds_dwordx4 v152, s[100:101]

; #define PG8_STAGE(bufoff, gbase, voff) do { _Pragma("unroll") for (int _i = 0; _i < 2; ++_i) \
;         __builtin_amdgcn_global_load_lds((const unsigned*)((const char*)(gbase) + (voff)[_i]), (PG8_LAS unsigned*)(lds + (bufoff) + ldsw + _i * 8192), 16, 0, 0); } while (0)
; #define PG8_LDA(dst, b, h) do { _Pragma("unroll") for (int m = 0; m < 4; ++m) _Pragma("unroll") for (int k = 0; k < 2; ++k) dst[m][k] = *(const PG8_LAS bf16x8*)(lds + PG8_SA(b, h) + aoff + m * 2048 + k * 1024); } while (0)
; #define PG8_MMA(ai, bj, At, Bt) do { __builtin_amdgcn_s_setprio(1); _Pragma("unroll") for (int m = 0; m < 4; ++m) _Pragma("unroll") for (int n = 0; n < 2; ++n) _Pragma("unroll") for (int k = 0; k < 2; ++k) \
;         acc[ai][bj][m][n] = __builtin_amdgcn_mfma_f32_16x16x32_bf16(Bt[n][k], At[m][k], acc[ai][bj][m][n], 0, 0, 0); __builtin_amdgcn_s_setprio(0); } while (0)
; #define PG8_WAIT_V(n) asm volatile("s_waitcnt vmcnt(" #n ")" ::: "memory")
; #define PG8_WAIT_L(n) asm volatile("s_waitcnt lgkmcnt(" #n ")" ::: "memory")
; #define PG8_BAR __builtin_amdgcn_s_barrier()
; #define PG8_SCHED __builtin_amdgcn_sched_barrier(0)
; template <class Epi, class Sched, bool ALIGN_EPI = false, bool SP2 = false, bool ATILED = false>
; __device__ __forceinline__ void gemm_phase(PG8_LAS unsigned char* lds, const Gemm g, const Sched& S, const Epi& E) {
;     ...
;             PG8_LDA(At, 1, 1); PG8_STAGE(PG8_SB(1, 0), b3, voffB); PG8_STAGE(PG8_SB(1, 1), b3 + hstep, voffB); PG8_STAGE(PG8_SA(1, 0), a3, voffA);
;             PG8_WAIT_V(8); PG8_WAIT_L(0); PG8_BAR; PG8_MMA(1, 0, At, B0); PG8_MMA(1, 1, At, B1); PG8_BAR; PG8_SCHED;
;     ...
;         if constexpr (ALIGN_EPI) { if (wr == 0) PG8_BAR; }
	s_mov_b32 m0, s64
	s_nop 0
	global_load_lds_dwordx4 v156, s[100:101]
	s_waitcnt vmcnt(8)
	s_waitcnt lgkmcnt(0)
	s_barrier
	s_setprio 1
	s_waitcnt lgkmcnt(0)
	v_mfma_f32_16x16x32_bf16 v[60:63], v[128:131], v[176:179], v[60:63]
	v_mfma_f32_16x16x32_bf16 v[56:59], v[136:139], v[176:179], v[56:59]
	v_mfma_f32_16x16x32_bf16 v[44:47], v[128:131], v[194:197], v[44:47]
	v_mfma_f32_16x16x32_bf16 v[40:43], v[136:139], v[194:197], v[40:43]
	v_mfma_f32_16x16x32_bf16 v[28:31], v[128:131], v[204:207], v[28:31]
	v_mfma_f32_16x16x32_bf16 v[24:27], v[136:139], v[204:207], v[24:27]
	v_mfma_f32_16x16x32_bf16 v[12:15], v[128:131], v[212:215], v[12:15]
	v_mfma_f32_16x16x32_bf16 v[8:11], v[136:139], v[212:215], v[8:11]
	v_mfma_f32_16x16x32_bf16 v[60:63], v[132:135], v[180:183], v[60:63]
	v_mfma_f32_16x16x32_bf16 v[56:59], v[140:143], v[180:183], v[56:59]
	v_mfma_f32_16x16x32_bf16 v[44:47], v[132:135], v[200:203], v[44:47]
	v_mfma_f32_16x16x32_bf16 v[40:43], v[140:143], v[200:203], v[40:43]
	v_mfma_f32_16x16x32_bf16 v[28:31], v[132:135], v[208:211], v[28:31]
	v_mfma_f32_16x16x32_bf16 v[24:27], v[140:143], v[208:211], v[24:27]
	v_mfma_f32_16x16x32_bf16 v[12:15], v[132:135], v[216:219], v[12:15]
	v_mfma_f32_16x16x32_bf16 v[8:11], v[140:143], v[216:219], v[8:11]
	s_setprio 0
	s_setprio 1
	v_mfma_f32_16x16x32_bf16 v[52:55], v[144:147], v[176:179], v[52:55]
	v_mfma_f32_16x16x32_bf16 v[48:51], v[168:171], v[176:179], v[48:51]
	v_mfma_f32_16x16x32_bf16 v[36:39], v[144:147], v[194:197], v[36:39]
	v_mfma_f32_16x16x32_bf16 v[32:35], v[168:171], v[194:197], v[32:35]
	v_mfma_f32_16x16x32_bf16 v[20:23], v[144:147], v[204:207], v[20:23]
	v_mfma_f32_16x16x32_bf16 v[16:19], v[168:171], v[204:207], v[16:19]
	v_mfma_f32_16x16x32_bf16 v[4:7], v[144:147], v[212:215], v[4:7]
	v_mfma_f32_16x16x32_bf16 v[0:3], v[168:171], v[212:215], v[0:3]
	v_mfma_f32_16x16x32_bf16 v[52:55], v[148:151], v[180:183], v[52:55]
	v_mfma_f32_16x16x32_bf16 v[48:51], v[172:175], v[180:183], v[48:51]
	v_mfma_f32_16x16x32_bf16 v[36:39], v[148:151], v[200:203], v[36:39]
	v_mfma_f32_16x16x32_bf16 v[32:35], v[172:175], v[200:203], v[32:35]
	v_mfma_f32_16x16x32_bf16 v[20:23], v[148:151], v[208:211], v[20:23]
	v_mfma_f32_16x16x32_bf16 v[16:19], v[172:175], v[208:211], v[16:19]
	v_mfma_f32_16x16x32_bf16 v[4:7], v[148:151], v[216:219], v[4:7]
	v_mfma_f32_16x16x32_bf16 v[0:3], v[172:175], v[216:219], v[0:3]
	s_setprio 0
	s_barrier
	s_add_i32 s73, s73, 2
	s_add_u32 s50, s50, 0x100
	s_addc_u32 s51, s51, 0
	s_add_u32 s71, s71, 0x100
	s_addc_u32 s72, s72, 0
	s_cmp_gt_u32 s73, 13
	s_cbranch_scc0 .LBB0_735
	s_and_b64 vcc, exec, s[14:15]
	s_cbranch_vccz .LBB0_738
	s_barrier

; #define PG8_STAGE(bufoff, gbase, voff) do { _Pragma("unroll") for (int _i = 0; _i < 2; ++_i) \
;         __builtin_amdgcn_global_load_lds((const unsigned*)((const char*)(gbase) + (voff)[_i]), (PG8_LAS unsigned*)(lds + (bufoff) + ldsw + _i * 8192), 16, 0, 0); } while (0)
; #define PG8_LDA(dst, b, h) do { _Pragma("unroll") for (int m = 0; m < 4; ++m) _Pragma("unroll") for (int k = 0; k < 2; ++k) dst[m][k] = *(const PG8_LAS bf16x8*)(lds + PG8_SA(b, h) + aoff + m * 2048 + k * 1024); } while (0)
; #define PG8_LDB(dst, b, h) do { _Pragma("unroll") for (int n = 0; n < 2; ++n) _Pragma("unroll") for (int k = 0; k < 2; ++k) dst[n][k] = *(const PG8_LAS bf16x8*)(lds + PG8_SB(b, h) + boff + n * 2048 + k * 1024); } while (0)
; #define PG8_SCHED __builtin_amdgcn_sched_barrier(0)
; template <class Epi, class Sched, bool ALIGN_EPI = false, bool SP2 = false, bool ATILED = false>
; __device__ __forceinline__ void gemm_phase(PG8_LAS unsigned char* lds, const Gemm g, const Sched& S, const Epi& E) {
;     ...
;         const bool has_next = S.next(ui + 1, nxt);
;         const char* nA = has_next ? (const char*)g.A + (size_t)nxt.pm * tstepA : cA; const char* nB = has_next ? (const char*)g.Bt + (size_t)nxt.pn * tstep : cB;
;         for (int t = 0; t < nt; t += 2) {
;             const bool last = (t == nt - 2);
;             const char* a1 = cA + (size_t)(t + 1) * kstepA;
;             const char* a2 = last ? nA : cA + (size_t)(t + 2) * kstepA; const char* b2 = last ? nB : cB + (size_t)(t + 2) * kstep;
;             const char* a3 = a2 + kstepA; const char* b3 = b2 + kstep;
;             if (last && has_next) S.a_ready(nxt);
;             if constexpr (SP2) {
;             PG8_LDB(B0, 0, 0); PG8_LDB(B1, 0, 1); PG8_SCHED; PG8_LDA(At, 0, 0); PG8_STAGE(PG8_SA(1, 1), a1 + hstepA, voffA);
.LBB0_816:
	s_ashr_i32 s13, s12, 31
	s_lshl_b64 s[14:15], s[12:13], 19
	s_add_u32 s14, s26, s14
	s_addc_u32 s15, s27, s15
	s_and_b64 s[16:17], s[0:1], exec
	s_cselect_b32 s13, s15, s21
	s_cselect_b32 s64, s14, s20
	s_ashr_i32 s11, s10, 31
	s_lshl_b64 s[16:17], s[10:11], 19
	s_add_u32 s16, s40, s16
	s_addc_u32 s17, s41, s17
	s_and_b64 s[44:45], s[0:1], exec
	s_cselect_b32 s11, s17, s43
	s_cselect_b32 s65, s16, s42
	s_add_u32 s20, s20, 0x40080
	s_addc_u32 s21, s21, 0
	s_add_u32 s66, s42, 0x100
	s_addc_u32 s67, s43, 0
	s_mov_b32 s68, -2
	s_waitcnt vmcnt(0)
	ds_read_b128 v[150:153], v156
	ds_read_b128 v[162:165], v156 offset:1024
	ds_read_b128 v[166:169], v156 offset:2048
	ds_read_b128 v[170:173], v156 offset:3072
	ds_read_b128 v[174:177], v157
	ds_read_b128 v[178:181], v157 offset:1024
	ds_read_b128 v[182:185], v157 offset:2048
	ds_read_b128 v[186:189], v157 offset:3072
	s_add_u32 s42, s20, 0xfffc0080
	s_addc_u32 s43, s21, -1
	s_cmp_eq_u32 s68, 12
	s_cselect_b32 s45, s13, s43
	s_cselect_b32 s44, s64, s42
	s_cselect_b32 s43, s11, s67
	s_cselect_b32 s42, s65, s66

; #define PG8_STAGE(bufoff, gbase, voff) do { _Pragma("unroll") for (int _i = 0; _i < 2; ++_i) \
;         __builtin_amdgcn_global_load_lds((const unsigned*)((const char*)(gbase) + (voff)[_i]), (PG8_LAS unsigned*)(lds + (bufoff) + ldsw + _i * 8192), 16, 0, 0); } while (0)
; #define PG8_LDA(dst, b, h) do { _Pragma("unroll") for (int m = 0; m < 4; ++m) _Pragma("unroll") for (int k = 0; k < 2; ++k) dst[m][k] = *(const PG8_LAS bf16x8*)(lds + PG8_SA(b, h) + aoff + m * 2048 + k * 1024); } while (0)
; #define PG8_LDB(dst, b, h) do { _Pragma("unroll") for (int n = 0; n < 2; ++n) _Pragma("unroll") for (int k = 0; k < 2; ++k) dst[n][k] = *(const PG8_LAS bf16x8*)(lds + PG8_SB(b, h) + boff + n * 2048 + k * 1024); } while (0)
; #define PG8_SCHED __builtin_amdgcn_sched_barrier(0)
; template <class Epi, class Sched, bool ALIGN_EPI = false, bool SP2 = false, bool ATILED = false>
; __device__ __forceinline__ void gemm_phase(PG8_LAS unsigned char* lds, const Gemm g, const Sched& S, const Epi& E) {
;     ...
;             PG8_LDB(B0, 0, 0); PG8_LDB(B1, 0, 1); PG8_SCHED; PG8_LDA(At, 0, 0); PG8_STAGE(PG8_SA(1, 1), a1 + hstepA, voffA);
	s_add_i32 m0, s19, 0xc000
	ds_read_b128 v[190:193], v158
	ds_read_b128 v[194:197], v158 offset:1024
	ds_read_b128 v[200:203], v158 offset:2048
	ds_read_b128 v[204:207], v158 offset:3072
	ds_read_b128 v[208:211], v158 offset:4096
	ds_read_b128 v[212:215], v158 offset:5120
	ds_read_b128 v[216:219], v158 offset:6144
	ds_read_b128 v[220:223], v158 offset:7168
	global_load_lds_dwordx4 v140, s[20:21]

; #define PG8_STAGE(bufoff, gbase, voff) do { _Pragma("unroll") for (int _i = 0; _i < 2; ++_i) \
;         __builtin_amdgcn_global_load_lds((const unsigned*)((const char*)(gbase) + (voff)[_i]), (PG8_LAS unsigned*)(lds + (bufoff) + ldsw + _i * 8192), 16, 0, 0); } while (0)
; #define PG8_LDA(dst, b, h) do { _Pragma("unroll") for (int m = 0; m < 4; ++m) _Pragma("unroll") for (int k = 0; k < 2; ++k) dst[m][k] = *(const PG8_LAS bf16x8*)(lds + PG8_SA(b, h) + aoff + m * 2048 + k * 1024); } while (0)
; #define PG8_LDB(dst, b, h) do { _Pragma("unroll") for (int n = 0; n < 2; ++n) _Pragma("unroll") for (int k = 0; k < 2; ++k) dst[n][k] = *(const PG8_LAS bf16x8*)(lds + PG8_SB(b, h) + boff + n * 2048 + k * 1024); } while (0)
; #define PG8_MMA(ai, bj, At, Bt) do { __builtin_amdgcn_s_setprio(1); _Pragma("unroll") for (int m = 0; m < 4; ++m) _Pragma("unroll") for (int n = 0; n < 2; ++n) _Pragma("unroll") for (int k = 0; k < 2; ++k) \
;         acc[ai][bj][m][n] = __builtin_amdgcn_mfma_f32_16x16x32_bf16(Bt[n][k], At[m][k], acc[ai][bj][m][n], 0, 0, 0); __builtin_amdgcn_s_setprio(0); } while (0)
; #define PG8_WAIT_V(n) asm volatile("s_waitcnt vmcnt(" #n ")" ::: "memory")
; #define PG8_WAIT_L(n) asm volatile("s_waitcnt lgkmcnt(" #n ")" ::: "memory")
; #define PG8_BAR __builtin_amdgcn_s_barrier()
; #define PG8_SCHED __builtin_amdgcn_sched_barrier(0)
; template <class Epi, class Sched, bool ALIGN_EPI = false, bool SP2 = false, bool ATILED = false>
; __device__ __forceinline__ void gemm_phase(PG8_LAS unsigned char* lds, const Gemm g, const Sched& S, const Epi& E) {
;     ...
;             PG8_LDB(B0, 0, 0); PG8_LDB(B1, 0, 1); PG8_SCHED; PG8_LDA(At, 0, 0); PG8_STAGE(PG8_SA(1, 1), a1 + hstepA, voffA);
;             PG8_WAIT_V(8); PG8_WAIT_L(0); PG8_BAR; PG8_MMA(0, 0, At, B0); PG8_MMA(0, 1, At, B1); PG8_BAR; PG8_SCHED;
	s_add_i32 m0, s19, 0xe000
	s_nop 0
	global_load_lds_dwordx4 v142, s[20:21]
	s_waitcnt vmcnt(8)
	s_waitcnt lgkmcnt(0)
	s_barrier
	s_setprio 1
	s_waitcnt lgkmcnt(0)
	v_mfma_f32_16x16x32_bf16 v[124:127], v[150:153], v[190:193], 0
	v_mfma_f32_16x16x32_bf16 v[120:123], v[166:169], v[190:193], 0
	v_mfma_f32_16x16x32_bf16 v[108:111], v[150:153], v[200:203], 0
	v_mfma_f32_16x16x32_bf16 v[104:107], v[166:169], v[200:203], 0
	v_mfma_f32_16x16x32_bf16 v[92:95], v[150:153], v[208:211], 0
	v_mfma_f32_16x16x32_bf16 v[88:91], v[166:169], v[208:211], 0
	v_mfma_f32_16x16x32_bf16 v[76:79], v[150:153], v[216:219], 0
	v_mfma_f32_16x16x32_bf16 v[72:75], v[166:169], v[216:219], 0
	v_mfma_f32_16x16x32_bf16 v[124:127], v[162:165], v[194:197], v[124:127]
	v_mfma_f32_16x16x32_bf16 v[120:123], v[170:173], v[194:197], v[120:123]
	v_mfma_f32_16x16x32_bf16 v[108:111], v[162:165], v[204:207], v[108:111]
	v_mfma_f32_16x16x32_bf16 v[104:107], v[170:173], v[204:207], v[104:107]
	v_mfma_f32_16x16x32_bf16 v[92:95], v[162:165], v[212:215], v[92:95]
	v_mfma_f32_16x16x32_bf16 v[88:91], v[170:173], v[212:215], v[88:91]
	v_mfma_f32_16x16x32_bf16 v[76:79], v[162:165], v[220:223], v[76:79]
	v_mfma_f32_16x16x32_bf16 v[72:75], v[170:173], v[220:223], v[72:75]
	s_setprio 0
	s_setprio 1
	v_mfma_f32_16x16x32_bf16 v[116:119], v[174:177], v[190:193], 0
	v_mfma_f32_16x16x32_bf16 v[112:115], v[182:185], v[190:193], 0
	v_mfma_f32_16x16x32_bf16 v[100:103], v[174:177], v[200:203], 0
	v_mfma_f32_16x16x32_bf16 v[96:99], v[182:185], v[200:203], 0
	v_mfma_f32_16x16x32_bf16 v[84:87], v[174:177], v[208:211], 0
	v_mfma_f32_16x16x32_bf16 v[80:83], v[182:185], v[208:211], 0
	v_mfma_f32_16x16x32_bf16 v[68:71], v[174:177], v[216:219], 0
	v_mfma_f32_16x16x32_bf16 v[64:67], v[182:185], v[216:219], 0
	v_mfma_f32_16x16x32_bf16 v[116:119], v[178:181], v[194:197], v[116:119]
	v_mfma_f32_16x16x32_bf16 v[112:115], v[186:189], v[194:197], v[112:115]
	v_mfma_f32_16x16x32_bf16 v[100:103], v[178:181], v[204:207], v[100:103]
	v_mfma_f32_16x16x32_bf16 v[96:99], v[186:189], v[204:207], v[96:99]
	v_mfma_f32_16x16x32_bf16 v[84:87], v[178:181], v[212:215], v[84:87]
	v_mfma_f32_16x16x32_bf16 v[80:83], v[186:189], v[212:215], v[80:83]
	v_mfma_f32_16x16x32_bf16 v[68:71], v[178:181], v[220:223], v[68:71]
	v_mfma_f32_16x16x32_bf16 v[64:67], v[186:189], v[220:223], v[64:67]
	s_setprio 0
	s_barrier
	s_add_u32 s98, s42, s6
	s_addc_u32 s99, s43, s7
	s_add_u32 s100, s44, s6
	s_addc_u32 s101, s45, s7
	s_add_i32 s69, s60, s46

; #define PG8_STAGE(bufoff, gbase, voff) do { _Pragma("unroll") for (int _i = 0; _i < 2; ++_i) \
;         __builtin_amdgcn_global_load_lds((const unsigned*)((const char*)(gbase) + (voff)[_i]), (PG8_LAS unsigned*)(lds + (bufoff) + ldsw + _i * 8192), 16, 0, 0); } while (0)
; #define PG8_LDA(dst, b, h) do { _Pragma("unroll") for (int m = 0; m < 4; ++m) _Pragma("unroll") for (int k = 0; k < 2; ++k) dst[m][k] = *(const PG8_LAS bf16x8*)(lds + PG8_SA(b, h) + aoff + m * 2048 + k * 1024); } while (0)
; template <class Epi, class Sched, bool ALIGN_EPI = false, bool SP2 = false, bool ATILED = false>
; __device__ __forceinline__ void gemm_phase(PG8_LAS unsigned char* lds, const Gemm g, const Sched& S, const Epi& E) {
;     ...
;             PG8_LDA(At, 0, 1); PG8_STAGE(PG8_SB(0, 0), b2, voffB); PG8_STAGE(PG8_SB(0, 1), b2 + hstep, voffB); PG8_STAGE(PG8_SA(0, 0), a2, voffA);
	s_mov_b32 m0, s69
	ds_read_b128 v[190:193], v158 offset:16384
	ds_read_b128 v[194:197], v158 offset:17408
	ds_read_b128 v[200:203], v158 offset:18432
	ds_read_b128 v[204:207], v158 offset:19456
	ds_read_b128 v[208:211], v158 offset:20480
	ds_read_b128 v[212:215], v158 offset:21504
	ds_read_b128 v[216:219], v158 offset:22528
	ds_read_b128 v[220:223], v158 offset:23552
	global_load_lds_dwordx4 v130, s[42:43]
	s_add_i32 m0, s69, 0x2000
	s_add_u32 s70, s42, 0x40000

; #define PG8_STAGE(bufoff, gbase, voff) do { _Pragma("unroll") for (int _i = 0; _i < 2; ++_i) \
;         __builtin_amdgcn_global_load_lds((const unsigned*)((const char*)(gbase) + (voff)[_i]), (PG8_LAS unsigned*)(lds + (bufoff) + ldsw + _i * 8192), 16, 0, 0); } while (0)
; #define PG8_LDA(dst, b, h) do { _Pragma("unroll") for (int m = 0; m < 4; ++m) _Pragma("unroll") for (int k = 0; k < 2; ++k) dst[m][k] = *(const PG8_LAS bf16x8*)(lds + PG8_SA(b, h) + aoff + m * 2048 + k * 1024); } while (0)
; template <class Epi, class Sched, bool ALIGN_EPI = false, bool SP2 = false, bool ATILED = false>
; __device__ __forceinline__ void gemm_phase(PG8_LAS unsigned char* lds, const Gemm g, const Sched& S, const Epi& E) {
;     ...
;             PG8_LDA(At, 0, 1); PG8_STAGE(PG8_SB(0, 0), b2, voffB); PG8_STAGE(PG8_SB(0, 1), b2 + hstep, voffB); PG8_STAGE(PG8_SA(0, 0), a2, voffA);
	s_addc_u32 s71, s43, 0
	s_add_i32 s69, s61, s46
	global_load_lds_dwordx4 v134, s[42:43]

; #define PG8_STAGE(bufoff, gbase, voff) do { _Pragma("unroll") for (int _i = 0; _i < 2; ++_i) \
;         __builtin_amdgcn_global_load_lds((const unsigned*)((const char*)(gbase) + (voff)[_i]), (PG8_LAS unsigned*)(lds + (bufoff) + ldsw + _i * 8192), 16, 0, 0); } while (0)
; #define PG8_LDA(dst, b, h) do { _Pragma("unroll") for (int m = 0; m < 4; ++m) _Pragma("unroll") for (int k = 0; k < 2; ++k) dst[m][k] = *(const PG8_LAS bf16x8*)(lds + PG8_SA(b, h) + aoff + m * 2048 + k * 1024); } while (0)
; template <class Epi, class Sched, bool ALIGN_EPI = false, bool SP2 = false, bool ATILED = false>
; __device__ __forceinline__ void gemm_phase(PG8_LAS unsigned char* lds, const Gemm g, const Sched& S, const Epi& E) {
;     ...
;             PG8_LDA(At, 0, 1); PG8_STAGE(PG8_SB(0, 0), b2, voffB); PG8_STAGE(PG8_SB(0, 1), b2 + hstep, voffB); PG8_STAGE(PG8_SA(0, 0), a2, voffA);
	s_mov_b32 m0, s69

; #define PG8_STAGE(bufoff, gbase, voff) do { _Pragma("unroll") for (int _i = 0; _i < 2; ++_i) \
;         __builtin_amdgcn_global_load_lds((const unsigned*)((const char*)(gbase) + (voff)[_i]), (PG8_LAS unsigned*)(lds + (bufoff) + ldsw + _i * 8192), 16, 0, 0); } while (0)
; #define PG8_LDA(dst, b, h) do { _Pragma("unroll") for (int m = 0; m < 4; ++m) _Pragma("unroll") for (int k = 0; k < 2; ++k) dst[m][k] = *(const PG8_LAS bf16x8*)(lds + PG8_SA(b, h) + aoff + m * 2048 + k * 1024); } while (0)
; template <class Epi, class Sched, bool ALIGN_EPI = false, bool SP2 = false, bool ATILED = false>
; __device__ __forceinline__ void gemm_phase(PG8_LAS unsigned char* lds, const Gemm g, const Sched& S, const Epi& E) {
;     ...
;             PG8_LDA(At, 0, 1); PG8_STAGE(PG8_SB(0, 0), b2, voffB); PG8_STAGE(PG8_SB(0, 1), b2 + hstep, voffB); PG8_STAGE(PG8_SA(0, 0), a2, voffA);
	s_nop 0
	global_load_lds_dwordx4 v130, s[70:71]

; #define PG8_STAGE(bufoff, gbase, voff) do { _Pragma("unroll") for (int _i = 0; _i < 2; ++_i) \
;         __builtin_amdgcn_global_load_lds((const unsigned*)((const char*)(gbase) + (voff)[_i]), (PG8_LAS unsigned*)(lds + (bufoff) + ldsw + _i * 8192), 16, 0, 0); } while (0)
; #define PG8_LDA(dst, b, h) do { _Pragma("unroll") for (int m = 0; m < 4; ++m) _Pragma("unroll") for (int k = 0; k < 2; ++k) dst[m][k] = *(const PG8_LAS bf16x8*)(lds + PG8_SA(b, h) + aoff + m * 2048 + k * 1024); } while (0)
; template <class Epi, class Sched, bool ALIGN_EPI = false, bool SP2 = false, bool ATILED = false>
; __device__ __forceinline__ void gemm_phase(PG8_LAS unsigned char* lds, const Gemm g, const Sched& S, const Epi& E) {
;     ...
;             PG8_LDA(At, 0, 1); PG8_STAGE(PG8_SB(0, 0), b2, voffB); PG8_STAGE(PG8_SB(0, 1), b2 + hstep, voffB); PG8_STAGE(PG8_SA(0, 0), a2, voffA);
	s_add_i32 m0, s69, 0x2000
	s_nop 0
	global_load_lds_dwordx4 v134, s[70:71]

; #define PG8_STAGE(bufoff, gbase, voff) do { _Pragma("unroll") for (int _i = 0; _i < 2; ++_i) \
;         __builtin_amdgcn_global_load_lds((const unsigned*)((const char*)(gbase) + (voff)[_i]), (PG8_LAS unsigned*)(lds + (bufoff) + ldsw + _i * 8192), 16, 0, 0); } while (0)
; #define PG8_LDA(dst, b, h) do { _Pragma("unroll") for (int m = 0; m < 4; ++m) _Pragma("unroll") for (int k = 0; k < 2; ++k) dst[m][k] = *(const PG8_LAS bf16x8*)(lds + PG8_SA(b, h) + aoff + m * 2048 + k * 1024); } while (0)
; #define PG8_LDB(dst, b, h) do { _Pragma("unroll") for (int n = 0; n < 2; ++n) _Pragma("unroll") for (int k = 0; k < 2; ++k) dst[n][k] = *(const PG8_LAS bf16x8*)(lds + PG8_SB(b, h) + boff + n * 2048 + k * 1024); } while (0)
; #define PG8_MMA(ai, bj, At, Bt) do { __builtin_amdgcn_s_setprio(1); _Pragma("unroll") for (int m = 0; m < 4; ++m) _Pragma("unroll") for (int n = 0; n < 2; ++n) _Pragma("unroll") for (int k = 0; k < 2; ++k) \
;         acc[ai][bj][m][n] = __builtin_amdgcn_mfma_f32_16x16x32_bf16(Bt[n][k], At[m][k], acc[ai][bj][m][n], 0, 0, 0); __builtin_amdgcn_s_setprio(0); } while (0)
; #define PG8_WAIT_V(n) asm volatile("s_waitcnt vmcnt(" #n ")" ::: "memory")
; #define PG8_WAIT_L(n) asm volatile("s_waitcnt lgkmcnt(" #n ")" ::: "memory")
; #define PG8_BAR __builtin_amdgcn_s_barrier()
; #define PG8_SCHED __builtin_amdgcn_sched_barrier(0)
; template <class Epi, class Sched, bool ALIGN_EPI = false, bool SP2 = false, bool ATILED = false>
; __device__ __forceinline__ void gemm_phase(PG8_LAS unsigned char* lds, const Gemm g, const Sched& S, const Epi& E) {
;     ...
;             PG8_LDA(At, 0, 1); PG8_STAGE(PG8_SB(0, 0), b2, voffB); PG8_STAGE(PG8_SB(0, 1), b2 + hstep, voffB); PG8_STAGE(PG8_SA(0, 0), a2, voffA);
;             PG8_WAIT_V(8); PG8_WAIT_L(0); PG8_BAR; PG8_MMA(1, 0, At, B0); PG8_MMA(1, 1, At, B1); PG8_BAR; PG8_SCHED;
;             PG8_LDB(B0, 1, 0); PG8_LDB(B1, 1, 1); PG8_SCHED; PG8_LDA(At, 1, 0); PG8_STAGE(PG8_SA(0, 1), a2 + hstepA, voffA);
	s_mov_b32 m0, s19
	s_nop 0
	global_load_lds_dwordx4 v128, s[44:45]
	s_mov_b32 m0, s48
	s_nop 0
	global_load_lds_dwordx4 v132, s[44:45]
	s_waitcnt vmcnt(8)
	s_waitcnt lgkmcnt(0)
	s_barrier
	s_setprio 1
	s_waitcnt lgkmcnt(0)
	v_mfma_f32_16x16x32_bf16 v[60:63], v[150:153], v[190:193], 0
	v_mfma_f32_16x16x32_bf16 v[56:59], v[166:169], v[190:193], 0
	v_mfma_f32_16x16x32_bf16 v[44:47], v[150:153], v[200:203], 0
	v_mfma_f32_16x16x32_bf16 v[40:43], v[166:169], v[200:203], 0
	v_mfma_f32_16x16x32_bf16 v[28:31], v[150:153], v[208:211], 0
	v_mfma_f32_16x16x32_bf16 v[24:27], v[166:169], v[208:211], 0
	v_mfma_f32_16x16x32_bf16 v[12:15], v[150:153], v[216:219], 0
	v_mfma_f32_16x16x32_bf16 v[8:11], v[166:169], v[216:219], 0
	v_mfma_f32_16x16x32_bf16 v[60:63], v[162:165], v[194:197], v[60:63]
	v_mfma_f32_16x16x32_bf16 v[56:59], v[170:173], v[194:197], v[56:59]
	v_mfma_f32_16x16x32_bf16 v[44:47], v[162:165], v[204:207], v[44:47]
	v_mfma_f32_16x16x32_bf16 v[40:43], v[170:173], v[204:207], v[40:43]
	v_mfma_f32_16x16x32_bf16 v[28:31], v[162:165], v[212:215], v[28:31]
	v_mfma_f32_16x16x32_bf16 v[24:27], v[170:173], v[212:215], v[24:27]
	v_mfma_f32_16x16x32_bf16 v[12:15], v[162:165], v[220:223], v[12:15]
	v_mfma_f32_16x16x32_bf16 v[8:11], v[170:173], v[220:223], v[8:11]
	s_setprio 0
	s_setprio 1
	v_mfma_f32_16x16x32_bf16 v[52:55], v[174:177], v[190:193], 0
	v_mfma_f32_16x16x32_bf16 v[48:51], v[182:185], v[190:193], 0
	v_mfma_f32_16x16x32_bf16 v[36:39], v[174:177], v[200:203], 0
	v_mfma_f32_16x16x32_bf16 v[32:35], v[182:185], v[200:203], 0
	v_mfma_f32_16x16x32_bf16 v[20:23], v[174:177], v[208:211], 0
	v_mfma_f32_16x16x32_bf16 v[16:19], v[182:185], v[208:211], 0
	v_mfma_f32_16x16x32_bf16 v[4:7], v[174:177], v[216:219], 0
	v_mfma_f32_16x16x32_bf16 v[0:3], v[182:185], v[216:219], 0
	v_mfma_f32_16x16x32_bf16 v[52:55], v[178:181], v[194:197], v[52:55]
	v_mfma_f32_16x16x32_bf16 v[48:51], v[186:189], v[194:197], v[48:51]
	v_mfma_f32_16x16x32_bf16 v[36:39], v[178:181], v[204:207], v[36:39]
	v_mfma_f32_16x16x32_bf16 v[32:35], v[186:189], v[204:207], v[32:35]
	v_mfma_f32_16x16x32_bf16 v[20:23], v[178:181], v[212:215], v[20:23]
	v_mfma_f32_16x16x32_bf16 v[16:19], v[186:189], v[212:215], v[16:19]
	v_mfma_f32_16x16x32_bf16 v[4:7], v[178:181], v[220:223], v[4:7]
	v_mfma_f32_16x16x32_bf16 v[0:3], v[186:189], v[220:223], v[0:3]
	s_setprio 0
	s_barrier
	s_add_i32 s69, 0, 0x18000
	v_add_u32_e32 v136, s69, v155
	s_add_i32 s70, 0, 0x1c000
	ds_read_b128 v[150:153], v136
	ds_read_b128 v[162:165], v136 offset:1024
	ds_read_b128 v[166:169], v136 offset:2048
	ds_read_b128 v[170:173], v136 offset:3072
	v_add_u32_e32 v136, s70, v155
	ds_read_b128 v[174:177], v136
	ds_read_b128 v[178:181], v136 offset:1024
	ds_read_b128 v[182:185], v136 offset:2048
	ds_read_b128 v[186:189], v136 offset:3072
	s_add_u32 s44, s44, 0x40000
	s_addc_u32 s45, s45, 0
	s_mov_b32 m0, s49

; #define PG8_STAGE(bufoff, gbase, voff) do { _Pragma("unroll") for (int _i = 0; _i < 2; ++_i) \
;         __builtin_amdgcn_global_load_lds((const unsigned*)((const char*)(gbase) + (voff)[_i]), (PG8_LAS unsigned*)(lds + (bufoff) + ldsw + _i * 8192), 16, 0, 0); } while (0)
; #define PG8_LDA(dst, b, h) do { _Pragma("unroll") for (int m = 0; m < 4; ++m) _Pragma("unroll") for (int k = 0; k < 2; ++k) dst[m][k] = *(const PG8_LAS bf16x8*)(lds + PG8_SA(b, h) + aoff + m * 2048 + k * 1024); } while (0)
; #define PG8_LDB(dst, b, h) do { _Pragma("unroll") for (int n = 0; n < 2; ++n) _Pragma("unroll") for (int k = 0; k < 2; ++k) dst[n][k] = *(const PG8_LAS bf16x8*)(lds + PG8_SB(b, h) + boff + n * 2048 + k * 1024); } while (0)
; #define PG8_SCHED __builtin_amdgcn_sched_barrier(0)
; template <class Epi, class Sched, bool ALIGN_EPI = false, bool SP2 = false, bool ATILED = false>
; __device__ __forceinline__ void gemm_phase(PG8_LAS unsigned char* lds, const Gemm g, const Sched& S, const Epi& E) {
;     ...
;             PG8_LDB(B0, 1, 0); PG8_LDB(B1, 1, 1); PG8_SCHED; PG8_LDA(At, 1, 0); PG8_STAGE(PG8_SA(0, 1), a2 + hstepA, voffA);
	ds_read_b128 v[190:193], v158 offset:32768
	ds_read_b128 v[194:197], v158 offset:33792
	ds_read_b128 v[200:203], v158 offset:34816
	ds_read_b128 v[204:207], v158 offset:35840
	ds_read_b128 v[208:211], v158 offset:36864
	ds_read_b128 v[212:215], v158 offset:37888
	ds_read_b128 v[216:219], v158 offset:38912
	ds_read_b128 v[220:223], v158 offset:39936
	global_load_lds_dwordx4 v128, s[44:45]

; #define PG8_STAGE(bufoff, gbase, voff) do { _Pragma("unroll") for (int _i = 0; _i < 2; ++_i) \
;         __builtin_amdgcn_global_load_lds((const unsigned*)((const char*)(gbase) + (voff)[_i]), (PG8_LAS unsigned*)(lds + (bufoff) + ldsw + _i * 8192), 16, 0, 0); } while (0)
; #define PG8_LDA(dst, b, h) do { _Pragma("unroll") for (int m = 0; m < 4; ++m) _Pragma("unroll") for (int k = 0; k < 2; ++k) dst[m][k] = *(const PG8_LAS bf16x8*)(lds + PG8_SA(b, h) + aoff + m * 2048 + k * 1024); } while (0)
; #define PG8_LDB(dst, b, h) do { _Pragma("unroll") for (int n = 0; n < 2; ++n) _Pragma("unroll") for (int k = 0; k < 2; ++k) dst[n][k] = *(const PG8_LAS bf16x8*)(lds + PG8_SB(b, h) + boff + n * 2048 + k * 1024); } while (0)
; #define PG8_MMA(ai, bj, At, Bt) do { __builtin_amdgcn_s_setprio(1); _Pragma("unroll") for (int m = 0; m < 4; ++m) _Pragma("unroll") for (int n = 0; n < 2; ++n) _Pragma("unroll") for (int k = 0; k < 2; ++k) \
;         acc[ai][bj][m][n] = __builtin_amdgcn_mfma_f32_16x16x32_bf16(Bt[n][k], At[m][k], acc[ai][bj][m][n], 0, 0, 0); __builtin_amdgcn_s_setprio(0); } while (0)
; #define PG8_WAIT_V(n) asm volatile("s_waitcnt vmcnt(" #n ")" ::: "memory")
; #define PG8_WAIT_L(n) asm volatile("s_waitcnt lgkmcnt(" #n ")" ::: "memory")
; #define PG8_BAR __builtin_amdgcn_s_barrier()
; #define PG8_SCHED __builtin_amdgcn_sched_barrier(0)
; template <class Epi, class Sched, bool ALIGN_EPI = false, bool SP2 = false, bool ATILED = false>
; __device__ __forceinline__ void gemm_phase(PG8_LAS unsigned char* lds, const Gemm g, const Sched& S, const Epi& E) {
;     ...
;             PG8_LDB(B0, 1, 0); PG8_LDB(B1, 1, 1); PG8_SCHED; PG8_LDA(At, 1, 0); PG8_STAGE(PG8_SA(0, 1), a2 + hstepA, voffA);
;             PG8_WAIT_V(8); PG8_WAIT_L(0); PG8_BAR; PG8_MMA(0, 0, At, B0); PG8_MMA(0, 1, At, B1); PG8_BAR; PG8_SCHED;
;             PG8_LDA(At, 1, 1); PG8_STAGE(PG8_SB(1, 0), b3, voffB); PG8_STAGE(PG8_SB(1, 1), b3 + hstep, voffB); PG8_STAGE(PG8_SA(1, 0), a3, voffA);
	s_mov_b32 m0, s50
	s_nop 0
	global_load_lds_dwordx4 v132, s[44:45]
	s_waitcnt vmcnt(8)
	s_waitcnt lgkmcnt(0)
	s_barrier
	s_setprio 1
	s_waitcnt lgkmcnt(0)
	v_mfma_f32_16x16x32_bf16 v[124:127], v[150:153], v[190:193], v[124:127]
	v_mfma_f32_16x16x32_bf16 v[120:123], v[166:169], v[190:193], v[120:123]
	v_mfma_f32_16x16x32_bf16 v[108:111], v[150:153], v[200:203], v[108:111]
	v_mfma_f32_16x16x32_bf16 v[104:107], v[166:169], v[200:203], v[104:107]
	v_mfma_f32_16x16x32_bf16 v[92:95], v[150:153], v[208:211], v[92:95]
	v_mfma_f32_16x16x32_bf16 v[88:91], v[166:169], v[208:211], v[88:91]
	v_mfma_f32_16x16x32_bf16 v[76:79], v[150:153], v[216:219], v[76:79]
	v_mfma_f32_16x16x32_bf16 v[72:75], v[166:169], v[216:219], v[72:75]
	v_mfma_f32_16x16x32_bf16 v[124:127], v[162:165], v[194:197], v[124:127]
	v_mfma_f32_16x16x32_bf16 v[120:123], v[170:173], v[194:197], v[120:123]
	v_mfma_f32_16x16x32_bf16 v[108:111], v[162:165], v[204:207], v[108:111]
	v_mfma_f32_16x16x32_bf16 v[104:107], v[170:173], v[204:207], v[104:107]
	v_mfma_f32_16x16x32_bf16 v[92:95], v[162:165], v[212:215], v[92:95]
	v_mfma_f32_16x16x32_bf16 v[88:91], v[170:173], v[212:215], v[88:91]
	v_mfma_f32_16x16x32_bf16 v[76:79], v[162:165], v[220:223], v[76:79]
	v_mfma_f32_16x16x32_bf16 v[72:75], v[170:173], v[220:223], v[72:75]
	s_setprio 0
	s_setprio 1
	v_mfma_f32_16x16x32_bf16 v[116:119], v[174:177], v[190:193], v[116:119]
	v_mfma_f32_16x16x32_bf16 v[112:115], v[182:185], v[190:193], v[112:115]
	v_mfma_f32_16x16x32_bf16 v[100:103], v[174:177], v[200:203], v[100:103]
	v_mfma_f32_16x16x32_bf16 v[96:99], v[182:185], v[200:203], v[96:99]
	v_mfma_f32_16x16x32_bf16 v[84:87], v[174:177], v[208:211], v[84:87]
	v_mfma_f32_16x16x32_bf16 v[80:83], v[182:185], v[208:211], v[80:83]
	v_mfma_f32_16x16x32_bf16 v[68:71], v[174:177], v[216:219], v[68:71]
	v_mfma_f32_16x16x32_bf16 v[64:67], v[182:185], v[216:219], v[64:67]
	v_mfma_f32_16x16x32_bf16 v[116:119], v[178:181], v[194:197], v[116:119]
	v_mfma_f32_16x16x32_bf16 v[112:115], v[186:189], v[194:197], v[112:115]
	v_mfma_f32_16x16x32_bf16 v[100:103], v[178:181], v[204:207], v[100:103]
	v_mfma_f32_16x16x32_bf16 v[96:99], v[186:189], v[204:207], v[96:99]
	v_mfma_f32_16x16x32_bf16 v[84:87], v[178:181], v[212:215], v[84:87]
	v_mfma_f32_16x16x32_bf16 v[80:83], v[186:189], v[212:215], v[80:83]
	v_mfma_f32_16x16x32_bf16 v[68:71], v[178:181], v[220:223], v[68:71]
	v_mfma_f32_16x16x32_bf16 v[64:67], v[186:189], v[220:223], v[64:67]
	s_setprio 0
	s_barrier
	s_add_i32 s44, s69, s46

; #define PG8_STAGE(bufoff, gbase, voff) do { _Pragma("unroll") for (int _i = 0; _i < 2; ++_i) \
;         __builtin_amdgcn_global_load_lds((const unsigned*)((const char*)(gbase) + (voff)[_i]), (PG8_LAS unsigned*)(lds + (bufoff) + ldsw + _i * 8192), 16, 0, 0); } while (0)
; #define PG8_LDA(dst, b, h) do { _Pragma("unroll") for (int m = 0; m < 4; ++m) _Pragma("unroll") for (int k = 0; k < 2; ++k) dst[m][k] = *(const PG8_LAS bf16x8*)(lds + PG8_SA(b, h) + aoff + m * 2048 + k * 1024); } while (0)
; template <class Epi, class Sched, bool ALIGN_EPI = false, bool SP2 = false, bool ATILED = false>
; __device__ __forceinline__ void gemm_phase(PG8_LAS unsigned char* lds, const Gemm g, const Sched& S, const Epi& E) {
;     ...
;             PG8_LDA(At, 1, 1); PG8_STAGE(PG8_SB(1, 0), b3, voffB); PG8_STAGE(PG8_SB(1, 1), b3 + hstep, voffB); PG8_STAGE(PG8_SA(1, 0), a3, voffA);
	s_mov_b32 m0, s44
	ds_read_b128 v[190:193], v158 offset:49152
	ds_read_b128 v[194:197], v158 offset:50176
	ds_read_b128 v[200:203], v158 offset:51200
	ds_read_b128 v[204:207], v158 offset:52224
	ds_read_b128 v[208:211], v158 offset:53248
	ds_read_b128 v[212:215], v158 offset:54272
	ds_read_b128 v[216:219], v158 offset:55296
	ds_read_b128 v[220:223], v158 offset:56320
	global_load_lds_dwordx4 v130, s[98:99]
	s_add_i32 m0, s44, 0x2000
	s_add_u32 s42, s42, 0x40080

; #define PG8_STAGE(bufoff, gbase, voff) do { _Pragma("unroll") for (int _i = 0; _i < 2; ++_i) \
;         __builtin_amdgcn_global_load_lds((const unsigned*)((const char*)(gbase) + (voff)[_i]), (PG8_LAS unsigned*)(lds + (bufoff) + ldsw + _i * 8192), 16, 0, 0); } while (0)
; #define PG8_LDA(dst, b, h) do { _Pragma("unroll") for (int m = 0; m < 4; ++m) _Pragma("unroll") for (int k = 0; k < 2; ++k) dst[m][k] = *(const PG8_LAS bf16x8*)(lds + PG8_SA(b, h) + aoff + m * 2048 + k * 1024); } while (0)
; template <class Epi, class Sched, bool ALIGN_EPI = false, bool SP2 = false, bool ATILED = false>
; __device__ __forceinline__ void gemm_phase(PG8_LAS unsigned char* lds, const Gemm g, const Sched& S, const Epi& E) {
;     ...
;             PG8_LDA(At, 1, 1); PG8_STAGE(PG8_SB(1, 0), b3, voffB); PG8_STAGE(PG8_SB(1, 1), b3 + hstep, voffB); PG8_STAGE(PG8_SA(1, 0), a3, voffA);
	s_addc_u32 s43, s43, 0
	s_add_i32 s44, s70, s46
	global_load_lds_dwordx4 v134, s[98:99]

; #define PG8_STAGE(bufoff, gbase, voff) do { _Pragma("unroll") for (int _i = 0; _i < 2; ++_i) \
;         __builtin_amdgcn_global_load_lds((const unsigned*)((const char*)(gbase) + (voff)[_i]), (PG8_LAS unsigned*)(lds + (bufoff) + ldsw + _i * 8192), 16, 0, 0); } while (0)
; #define PG8_LDA(dst, b, h) do { _Pragma("unroll") for (int m = 0; m < 4; ++m) _Pragma("unroll") for (int k = 0; k < 2; ++k) dst[m][k] = *(const PG8_LAS bf16x8*)(lds + PG8_SA(b, h) + aoff + m * 2048 + k * 1024); } while (0)
; template <class Epi, class Sched, bool ALIGN_EPI = false, bool SP2 = false, bool ATILED = false>
; __device__ __forceinline__ void gemm_phase(PG8_LAS unsigned char* lds, const Gemm g, const Sched& S, const Epi& E) {
;     ...
;             PG8_LDA(At, 1, 1); PG8_STAGE(PG8_SB(1, 0), b3, voffB); PG8_STAGE(PG8_SB(1, 1), b3 + hstep, voffB); PG8_STAGE(PG8_SA(1, 0), a3, voffA);
	s_mov_b32 m0, s44
	s_nop 0
	global_load_lds_dwordx4 v130, s[42:43]

; #define PG8_STAGE(bufoff, gbase, voff) do { _Pragma("unroll") for (int _i = 0; _i < 2; ++_i) \
;         __builtin_amdgcn_global_load_lds((const unsigned*)((const char*)(gbase) + (voff)[_i]), (PG8_LAS unsigned*)(lds + (bufoff) + ldsw + _i * 8192), 16, 0, 0); } while (0)
; #define PG8_LDA(dst, b, h) do { _Pragma("unroll") for (int m = 0; m < 4; ++m) _Pragma("unroll") for (int k = 0; k < 2; ++k) dst[m][k] = *(const PG8_LAS bf16x8*)(lds + PG8_SA(b, h) + aoff + m * 2048 + k * 1024); } while (0)
; template <class Epi, class Sched, bool ALIGN_EPI = false, bool SP2 = false, bool ATILED = false>
; __device__ __forceinline__ void gemm_phase(PG8_LAS unsigned char* lds, const Gemm g, const Sched& S, const Epi& E) {
;     ...
;             PG8_LDA(At, 1, 1); PG8_STAGE(PG8_SB(1, 0), b3, voffB); PG8_STAGE(PG8_SB(1, 1), b3 + hstep, voffB); PG8_STAGE(PG8_SA(1, 0), a3, voffA);
	s_add_i32 m0, s44, 0x2000
	s_nop 0
	global_load_lds_dwordx4 v134, s[42:43]

; #define PG8_STAGE(bufoff, gbase, voff) do { _Pragma("unroll") for (int _i = 0; _i < 2; ++_i) \
;         __builtin_amdgcn_global_load_lds((const unsigned*)((const char*)(gbase) + (voff)[_i]), (PG8_LAS unsigned*)(lds + (bufoff) + ldsw + _i * 8192), 16, 0, 0); } while (0)
; #define PG8_LDA(dst, b, h) do { _Pragma("unroll") for (int m = 0; m < 4; ++m) _Pragma("unroll") for (int k = 0; k < 2; ++k) dst[m][k] = *(const PG8_LAS bf16x8*)(lds + PG8_SA(b, h) + aoff + m * 2048 + k * 1024); } while (0)
; template <class Epi, class Sched, bool ALIGN_EPI = false, bool SP2 = false, bool ATILED = false>
; __device__ __forceinline__ void gemm_phase(PG8_LAS unsigned char* lds, const Gemm g, const Sched& S, const Epi& E) {
;     ...
;             PG8_LDA(At, 1, 1); PG8_STAGE(PG8_SB(1, 0), b3, voffB); PG8_STAGE(PG8_SB(1, 1), b3 + hstep, voffB); PG8_STAGE(PG8_SA(1, 0), a3, voffA);
	s_mov_b32 m0, s58
	s_nop 0
	global_load_lds_dwordx4 v128, s[100:101]

; #define PG8_STAGE(bufoff, gbase, voff) do { _Pragma("unroll") for (int _i = 0; _i < 2; ++_i) \
;         __builtin_amdgcn_global_load_lds((const unsigned*)((const char*)(gbase) + (voff)[_i]), (PG8_LAS unsigned*)(lds + (bufoff) + ldsw + _i * 8192), 16, 0, 0); } while (0)
; #define PG8_LDA(dst, b, h) do { _Pragma("unroll") for (int m = 0; m < 4; ++m) _Pragma("unroll") for (int k = 0; k < 2; ++k) dst[m][k] = *(const PG8_LAS bf16x8*)(lds + PG8_SA(b, h) + aoff + m * 2048 + k * 1024); } while (0)
; #define PG8_LDB(dst, b, h) do { _Pragma("unroll") for (int n = 0; n < 2; ++n) _Pragma("unroll") for (int k = 0; k < 2; ++k) dst[n][k] = *(const PG8_LAS bf16x8*)(lds + PG8_SB(b, h) + boff + n * 2048 + k * 1024); } while (0)
; #define PG8_MMA(ai, bj, At, Bt) do { __builtin_amdgcn_s_setprio(1); _Pragma("unroll") for (int m = 0; m < 4; ++m) _Pragma("unroll") for (int n = 0; n < 2; ++n) _Pragma("unroll") for (int k = 0; k < 2; ++k) \
;         acc[ai][bj][m][n] = __builtin_amdgcn_mfma_f32_16x16x32_bf16(Bt[n][k], At[m][k], acc[ai][bj][m][n], 0, 0, 0); __builtin_amdgcn_s_setprio(0); } while (0)
; #define PG8_WAIT_V(n) asm volatile("s_waitcnt vmcnt(" #n ")" ::: "memory")
; #define PG8_WAIT_L(n) asm volatile("s_waitcnt lgkmcnt(" #n ")" ::: "memory")
; #define PG8_BAR __builtin_amdgcn_s_barrier()
; template <class Epi, class Sched, bool ALIGN_EPI = false, bool SP2 = false, bool ATILED = false>
; __device__ __forceinline__ void gemm_phase(PG8_LAS unsigned char* lds, const Gemm g, const Sched& S, const Epi& E) {
;     ...
;         for (int t = 0; t < nt; t += 2) {
;             const bool last = (t == nt - 2);
;             const char* a1 = cA + (size_t)(t + 1) * kstepA;
;             const char* a2 = last ? nA : cA + (size_t)(t + 2) * kstepA; const char* b2 = last ? nB : cB + (size_t)(t + 2) * kstep;
;             const char* a3 = a2 + kstepA; const char* b3 = b2 + kstep;
;             if (last && has_next) S.a_ready(nxt);
;             if constexpr (SP2) {
;             PG8_LDB(B0, 0, 0); PG8_LDB(B1, 0, 1); PG8_SCHED; PG8_LDA(At, 0, 0); PG8_STAGE(PG8_SA(1, 1), a1 + hstepA, voffA);
;     ...
;             PG8_LDA(At, 1, 1); PG8_STAGE(PG8_SB(1, 0), b3, voffB); PG8_STAGE(PG8_SB(1, 1), b3 + hstep, voffB); PG8_STAGE(PG8_SA(1, 0), a3, voffA);
;             PG8_WAIT_V(8); PG8_WAIT_L(0); PG8_BAR; PG8_MMA(1, 0, At, B0); PG8_MMA(1, 1, At, B1); PG8_BAR; PG8_SCHED;
	s_mov_b32 m0, s59
	s_nop 0
	global_load_lds_dwordx4 v132, s[100:101]
	s_waitcnt vmcnt(8)
	s_waitcnt lgkmcnt(0)
	s_barrier
	s_setprio 1
	s_waitcnt lgkmcnt(0)
	v_mfma_f32_16x16x32_bf16 v[60:63], v[150:153], v[190:193], v[60:63]
	v_mfma_f32_16x16x32_bf16 v[56:59], v[166:169], v[190:193], v[56:59]
	v_mfma_f32_16x16x32_bf16 v[44:47], v[150:153], v[200:203], v[44:47]
	v_mfma_f32_16x16x32_bf16 v[40:43], v[166:169], v[200:203], v[40:43]
	v_mfma_f32_16x16x32_bf16 v[28:31], v[150:153], v[208:211], v[28:31]
	v_mfma_f32_16x16x32_bf16 v[24:27], v[166:169], v[208:211], v[24:27]
	v_mfma_f32_16x16x32_bf16 v[12:15], v[150:153], v[216:219], v[12:15]
	v_mfma_f32_16x16x32_bf16 v[8:11], v[166:169], v[216:219], v[8:11]
	v_mfma_f32_16x16x32_bf16 v[60:63], v[162:165], v[194:197], v[60:63]
	v_mfma_f32_16x16x32_bf16 v[56:59], v[170:173], v[194:197], v[56:59]
	v_mfma_f32_16x16x32_bf16 v[44:47], v[162:165], v[204:207], v[44:47]
	v_mfma_f32_16x16x32_bf16 v[40:43], v[170:173], v[204:207], v[40:43]
	v_mfma_f32_16x16x32_bf16 v[28:31], v[162:165], v[212:215], v[28:31]
	v_mfma_f32_16x16x32_bf16 v[24:27], v[170:173], v[212:215], v[24:27]
	v_mfma_f32_16x16x32_bf16 v[12:15], v[162:165], v[220:223], v[12:15]
	v_mfma_f32_16x16x32_bf16 v[8:11], v[170:173], v[220:223], v[8:11]
	s_setprio 0
	s_setprio 1
	v_mfma_f32_16x16x32_bf16 v[52:55], v[174:177], v[190:193], v[52:55]
	v_mfma_f32_16x16x32_bf16 v[48:51], v[182:185], v[190:193], v[48:51]
	v_mfma_f32_16x16x32_bf16 v[36:39], v[174:177], v[200:203], v[36:39]
	v_mfma_f32_16x16x32_bf16 v[32:35], v[182:185], v[200:203], v[32:35]
	v_mfma_f32_16x16x32_bf16 v[20:23], v[174:177], v[208:211], v[20:23]
	v_mfma_f32_16x16x32_bf16 v[16:19], v[182:185], v[208:211], v[16:19]
	v_mfma_f32_16x16x32_bf16 v[4:7], v[174:177], v[216:219], v[4:7]
	v_mfma_f32_16x16x32_bf16 v[0:3], v[182:185], v[216:219], v[0:3]
	v_mfma_f32_16x16x32_bf16 v[52:55], v[178:181], v[194:197], v[52:55]
	v_mfma_f32_16x16x32_bf16 v[48:51], v[186:189], v[194:197], v[48:51]
	v_mfma_f32_16x16x32_bf16 v[36:39], v[178:181], v[204:207], v[36:39]
	v_mfma_f32_16x16x32_bf16 v[32:35], v[186:189], v[204:207], v[32:35]
	v_mfma_f32_16x16x32_bf16 v[20:23], v[178:181], v[212:215], v[20:23]
	v_mfma_f32_16x16x32_bf16 v[16:19], v[186:189], v[212:215], v[16:19]
	v_mfma_f32_16x16x32_bf16 v[4:7], v[178:181], v[220:223], v[4:7]
	v_mfma_f32_16x16x32_bf16 v[0:3], v[186:189], v[220:223], v[0:3]
	s_setprio 0
	s_barrier
	s_add_i32 s68, s68, 2
	s_add_u32 s20, s20, 0x100
	s_addc_u32 s21, s21, 0
	s_add_u32 s66, s66, 0x100
	s_addc_u32 s67, s67, 0
	s_cmp_gt_u32 s68, 13
.LBB0_817:
	ds_read_b128 v[150:153], v156
	ds_read_b128 v[162:165], v156 offset:1024
	ds_read_b128 v[166:169], v156 offset:2048
	ds_read_b128 v[170:173], v156 offset:3072
	ds_read_b128 v[174:177], v157
	ds_read_b128 v[178:181], v157 offset:1024
	ds_read_b128 v[182:185], v157 offset:2048
	ds_read_b128 v[186:189], v157 offset:3072
	s_add_u32 s42, s20, 0xfffc0080
	s_addc_u32 s43, s21, -1
	s_cmp_eq_u32 s68, 12
	s_cselect_b32 s45, s13, s43
	s_cselect_b32 s44, s64, s42
	s_cselect_b32 s43, s11, s67
	s_cselect_b32 s42, s65, s66

; #define PG8_STAGE(bufoff, gbase, voff) do { _Pragma("unroll") for (int _i = 0; _i < 2; ++_i) \
;         __builtin_amdgcn_global_load_lds((const unsigned*)((const char*)(gbase) + (voff)[_i]), (PG8_LAS unsigned*)(lds + (bufoff) + ldsw + _i * 8192), 16, 0, 0); } while (0)
; #define PG8_LDA(dst, b, h) do { _Pragma("unroll") for (int m = 0; m < 4; ++m) _Pragma("unroll") for (int k = 0; k < 2; ++k) dst[m][k] = *(const PG8_LAS bf16x8*)(lds + PG8_SA(b, h) + aoff + m * 2048 + k * 1024); } while (0)
; #define PG8_LDB(dst, b, h) do { _Pragma("unroll") for (int n = 0; n < 2; ++n) _Pragma("unroll") for (int k = 0; k < 2; ++k) dst[n][k] = *(const PG8_LAS bf16x8*)(lds + PG8_SB(b, h) + boff + n * 2048 + k * 1024); } while (0)
; #define PG8_SCHED __builtin_amdgcn_sched_barrier(0)
; template <class Epi, class Sched, bool ALIGN_EPI = false, bool SP2 = false, bool ATILED = false>
; __device__ __forceinline__ void gemm_phase(PG8_LAS unsigned char* lds, const Gemm g, const Sched& S, const Epi& E) {
;     ...
;             PG8_LDB(B0, 0, 0); PG8_LDB(B1, 0, 1); PG8_SCHED; PG8_LDA(At, 0, 0); PG8_STAGE(PG8_SA(1, 1), a1 + hstepA, voffA);
	s_add_i32 m0, s19, 0xc000
	ds_read_b128 v[190:193], v158
	ds_read_b128 v[194:197], v158 offset:1024
	ds_read_b128 v[200:203], v158 offset:2048
	ds_read_b128 v[204:207], v158 offset:3072
	ds_read_b128 v[208:211], v158 offset:4096
	ds_read_b128 v[212:215], v158 offset:5120
	ds_read_b128 v[216:219], v158 offset:6144
	ds_read_b128 v[220:223], v158 offset:7168
	global_load_lds_dwordx4 v140, s[20:21]

; #define PG8_STAGE(bufoff, gbase, voff) do { _Pragma("unroll") for (int _i = 0; _i < 2; ++_i) \
;         __builtin_amdgcn_global_load_lds((const unsigned*)((const char*)(gbase) + (voff)[_i]), (PG8_LAS unsigned*)(lds + (bufoff) + ldsw + _i * 8192), 16, 0, 0); } while (0)
; #define PG8_LDA(dst, b, h) do { _Pragma("unroll") for (int m = 0; m < 4; ++m) _Pragma("unroll") for (int k = 0; k < 2; ++k) dst[m][k] = *(const PG8_LAS bf16x8*)(lds + PG8_SA(b, h) + aoff + m * 2048 + k * 1024); } while (0)
; #define PG8_LDB(dst, b, h) do { _Pragma("unroll") for (int n = 0; n < 2; ++n) _Pragma("unroll") for (int k = 0; k < 2; ++k) dst[n][k] = *(const PG8_LAS bf16x8*)(lds + PG8_SB(b, h) + boff + n * 2048 + k * 1024); } while (0)
; #define PG8_MMA(ai, bj, At, Bt) do { __builtin_amdgcn_s_setprio(1); _Pragma("unroll") for (int m = 0; m < 4; ++m) _Pragma("unroll") for (int n = 0; n < 2; ++n) _Pragma("unroll") for (int k = 0; k < 2; ++k) \
;         acc[ai][bj][m][n] = __builtin_amdgcn_mfma_f32_16x16x32_bf16(Bt[n][k], At[m][k], acc[ai][bj][m][n], 0, 0, 0); __builtin_amdgcn_s_setprio(0); } while (0)
; #define PG8_WAIT_V(n) asm volatile("s_waitcnt vmcnt(" #n ")" ::: "memory")
; #define PG8_WAIT_L(n) asm volatile("s_waitcnt lgkmcnt(" #n ")" ::: "memory")
; #define PG8_BAR __builtin_amdgcn_s_barrier()
; #define PG8_SCHED __builtin_amdgcn_sched_barrier(0)
; template <class Epi, class Sched, bool ALIGN_EPI = false, bool SP2 = false, bool ATILED = false>
; __device__ __forceinline__ void gemm_phase(PG8_LAS unsigned char* lds, const Gemm g, const Sched& S, const Epi& E) {
;     ...
;             PG8_LDB(B0, 0, 0); PG8_LDB(B1, 0, 1); PG8_SCHED; PG8_LDA(At, 0, 0); PG8_STAGE(PG8_SA(1, 1), a1 + hstepA, voffA);
;             PG8_WAIT_V(8); PG8_WAIT_L(0); PG8_BAR; PG8_MMA(0, 0, At, B0); PG8_MMA(0, 1, At, B1); PG8_BAR; PG8_SCHED;
;             PG8_LDA(At, 0, 1); PG8_STAGE(PG8_SB(0, 0), b2, voffB); PG8_STAGE(PG8_SB(0, 1), b2 + hstep, voffB); PG8_STAGE(PG8_SA(0, 0), a2, voffA);
	s_add_i32 m0, s19, 0xe000
	s_nop 0
	global_load_lds_dwordx4 v142, s[20:21]
	s_waitcnt vmcnt(8)
	s_waitcnt lgkmcnt(0)
	s_barrier
	s_setprio 1
	s_waitcnt lgkmcnt(0)
	v_mfma_f32_16x16x32_bf16 v[124:127], v[150:153], v[190:193], v[124:127]
	v_mfma_f32_16x16x32_bf16 v[120:123], v[166:169], v[190:193], v[120:123]
	v_mfma_f32_16x16x32_bf16 v[108:111], v[150:153], v[200:203], v[108:111]
	v_mfma_f32_16x16x32_bf16 v[104:107], v[166:169], v[200:203], v[104:107]
	v_mfma_f32_16x16x32_bf16 v[92:95], v[150:153], v[208:211], v[92:95]
	v_mfma_f32_16x16x32_bf16 v[88:91], v[166:169], v[208:211], v[88:91]
	v_mfma_f32_16x16x32_bf16 v[76:79], v[150:153], v[216:219], v[76:79]
	v_mfma_f32_16x16x32_bf16 v[72:75], v[166:169], v[216:219], v[72:75]
	v_mfma_f32_16x16x32_bf16 v[124:127], v[162:165], v[194:197], v[124:127]
	v_mfma_f32_16x16x32_bf16 v[120:123], v[170:173], v[194:197], v[120:123]
	v_mfma_f32_16x16x32_bf16 v[108:111], v[162:165], v[204:207], v[108:111]
	v_mfma_f32_16x16x32_bf16 v[104:107], v[170:173], v[204:207], v[104:107]
	v_mfma_f32_16x16x32_bf16 v[92:95], v[162:165], v[212:215], v[92:95]
	v_mfma_f32_16x16x32_bf16 v[88:91], v[170:173], v[212:215], v[88:91]
	v_mfma_f32_16x16x32_bf16 v[76:79], v[162:165], v[220:223], v[76:79]
	v_mfma_f32_16x16x32_bf16 v[72:75], v[170:173], v[220:223], v[72:75]
	s_setprio 0
	s_setprio 1
	v_mfma_f32_16x16x32_bf16 v[116:119], v[174:177], v[190:193], v[116:119]
	v_mfma_f32_16x16x32_bf16 v[112:115], v[182:185], v[190:193], v[112:115]
	v_mfma_f32_16x16x32_bf16 v[100:103], v[174:177], v[200:203], v[100:103]
	v_mfma_f32_16x16x32_bf16 v[96:99], v[182:185], v[200:203], v[96:99]
	v_mfma_f32_16x16x32_bf16 v[84:87], v[174:177], v[208:211], v[84:87]
	v_mfma_f32_16x16x32_bf16 v[80:83], v[182:185], v[208:211], v[80:83]
	v_mfma_f32_16x16x32_bf16 v[68:71], v[174:177], v[216:219], v[68:71]
	v_mfma_f32_16x16x32_bf16 v[64:67], v[182:185], v[216:219], v[64:67]
	v_mfma_f32_16x16x32_bf16 v[116:119], v[178:181], v[194:197], v[116:119]
	v_mfma_f32_16x16x32_bf16 v[112:115], v[186:189], v[194:197], v[112:115]
	v_mfma_f32_16x16x32_bf16 v[100:103], v[178:181], v[204:207], v[100:103]
	v_mfma_f32_16x16x32_bf16 v[96:99], v[186:189], v[204:207], v[96:99]
	v_mfma_f32_16x16x32_bf16 v[84:87], v[178:181], v[212:215], v[84:87]
	v_mfma_f32_16x16x32_bf16 v[80:83], v[186:189], v[212:215], v[80:83]
	v_mfma_f32_16x16x32_bf16 v[68:71], v[178:181], v[220:223], v[68:71]
	v_mfma_f32_16x16x32_bf16 v[64:67], v[186:189], v[220:223], v[64:67]
	s_setprio 0
	s_barrier
	s_add_u32 s98, s42, s6
	s_addc_u32 s99, s43, s7
	s_add_u32 s100, s44, s6
	s_addc_u32 s101, s45, s7
	s_add_i32 s69, s60, s46

; #define PG8_STAGE(bufoff, gbase, voff) do { _Pragma("unroll") for (int _i = 0; _i < 2; ++_i) \
;         __builtin_amdgcn_global_load_lds((const unsigned*)((const char*)(gbase) + (voff)[_i]), (PG8_LAS unsigned*)(lds + (bufoff) + ldsw + _i * 8192), 16, 0, 0); } while (0)
; #define PG8_LDA(dst, b, h) do { _Pragma("unroll") for (int m = 0; m < 4; ++m) _Pragma("unroll") for (int k = 0; k < 2; ++k) dst[m][k] = *(const PG8_LAS bf16x8*)(lds + PG8_SA(b, h) + aoff + m * 2048 + k * 1024); } while (0)
; template <class Epi, class Sched, bool ALIGN_EPI = false, bool SP2 = false, bool ATILED = false>
; __device__ __forceinline__ void gemm_phase(PG8_LAS unsigned char* lds, const Gemm g, const Sched& S, const Epi& E) {
;     ...
;             PG8_LDA(At, 0, 1); PG8_STAGE(PG8_SB(0, 0), b2, voffB); PG8_STAGE(PG8_SB(0, 1), b2 + hstep, voffB); PG8_STAGE(PG8_SA(0, 0), a2, voffA);
	s_mov_b32 m0, s69
	ds_read_b128 v[190:193], v158 offset:16384
	ds_read_b128 v[194:197], v158 offset:17408
	ds_read_b128 v[200:203], v158 offset:18432
	ds_read_b128 v[204:207], v158 offset:19456
	ds_read_b128 v[208:211], v158 offset:20480
	ds_read_b128 v[212:215], v158 offset:21504
	ds_read_b128 v[216:219], v158 offset:22528
	ds_read_b128 v[220:223], v158 offset:23552
	global_load_lds_dwordx4 v130, s[42:43]
	s_add_i32 m0, s69, 0x2000
	s_add_u32 s70, s42, 0x40000

; #define PG8_STAGE(bufoff, gbase, voff) do { _Pragma("unroll") for (int _i = 0; _i < 2; ++_i) \
;         __builtin_amdgcn_global_load_lds((const unsigned*)((const char*)(gbase) + (voff)[_i]), (PG8_LAS unsigned*)(lds + (bufoff) + ldsw + _i * 8192), 16, 0, 0); } while (0)
; #define PG8_LDA(dst, b, h) do { _Pragma("unroll") for (int m = 0; m < 4; ++m) _Pragma("unroll") for (int k = 0; k < 2; ++k) dst[m][k] = *(const PG8_LAS bf16x8*)(lds + PG8_SA(b, h) + aoff + m * 2048 + k * 1024); } while (0)
; template <class Epi, class Sched, bool ALIGN_EPI = false, bool SP2 = false, bool ATILED = false>
; __device__ __forceinline__ void gemm_phase(PG8_LAS unsigned char* lds, const Gemm g, const Sched& S, const Epi& E) {
;     ...
;             PG8_LDA(At, 0, 1); PG8_STAGE(PG8_SB(0, 0), b2, voffB); PG8_STAGE(PG8_SB(0, 1), b2 + hstep, voffB); PG8_STAGE(PG8_SA(0, 0), a2, voffA);
	s_addc_u32 s71, s43, 0
	s_add_i32 s69, s61, s46
	global_load_lds_dwordx4 v134, s[42:43]

; #define PG8_STAGE(bufoff, gbase, voff) do { _Pragma("unroll") for (int _i = 0; _i < 2; ++_i) \
;         __builtin_amdgcn_global_load_lds((const unsigned*)((const char*)(gbase) + (voff)[_i]), (PG8_LAS unsigned*)(lds + (bufoff) + ldsw + _i * 8192), 16, 0, 0); } while (0)
; #define PG8_LDA(dst, b, h) do { _Pragma("unroll") for (int m = 0; m < 4; ++m) _Pragma("unroll") for (int k = 0; k < 2; ++k) dst[m][k] = *(const PG8_LAS bf16x8*)(lds + PG8_SA(b, h) + aoff + m * 2048 + k * 1024); } while (0)
; template <class Epi, class Sched, bool ALIGN_EPI = false, bool SP2 = false, bool ATILED = false>
; __device__ __forceinline__ void gemm_phase(PG8_LAS unsigned char* lds, const Gemm g, const Sched& S, const Epi& E) {
;     ...
;             PG8_LDA(At, 0, 1); PG8_STAGE(PG8_SB(0, 0), b2, voffB); PG8_STAGE(PG8_SB(0, 1), b2 + hstep, voffB); PG8_STAGE(PG8_SA(0, 0), a2, voffA);
	s_mov_b32 m0, s69

; #define PG8_STAGE(bufoff, gbase, voff) do { _Pragma("unroll") for (int _i = 0; _i < 2; ++_i) \
;         __builtin_amdgcn_global_load_lds((const unsigned*)((const char*)(gbase) + (voff)[_i]), (PG8_LAS unsigned*)(lds + (bufoff) + ldsw + _i * 8192), 16, 0, 0); } while (0)
; #define PG8_LDA(dst, b, h) do { _Pragma("unroll") for (int m = 0; m < 4; ++m) _Pragma("unroll") for (int k = 0; k < 2; ++k) dst[m][k] = *(const PG8_LAS bf16x8*)(lds + PG8_SA(b, h) + aoff + m * 2048 + k * 1024); } while (0)
; template <class Epi, class Sched, bool ALIGN_EPI = false, bool SP2 = false, bool ATILED = false>
; __device__ __forceinline__ void gemm_phase(PG8_LAS unsigned char* lds, const Gemm g, const Sched& S, const Epi& E) {
;     ...
;             PG8_LDA(At, 0, 1); PG8_STAGE(PG8_SB(0, 0), b2, voffB); PG8_STAGE(PG8_SB(0, 1), b2 + hstep, voffB); PG8_STAGE(PG8_SA(0, 0), a2, voffA);
	s_nop 0
	global_load_lds_dwordx4 v130, s[70:71]

; #define PG8_STAGE(bufoff, gbase, voff) do { _Pragma("unroll") for (int _i = 0; _i < 2; ++_i) \
;         __builtin_amdgcn_global_load_lds((const unsigned*)((const char*)(gbase) + (voff)[_i]), (PG8_LAS unsigned*)(lds + (bufoff) + ldsw + _i * 8192), 16, 0, 0); } while (0)
; #define PG8_LDA(dst, b, h) do { _Pragma("unroll") for (int m = 0; m < 4; ++m) _Pragma("unroll") for (int k = 0; k < 2; ++k) dst[m][k] = *(const PG8_LAS bf16x8*)(lds + PG8_SA(b, h) + aoff + m * 2048 + k * 1024); } while (0)
; template <class Epi, class Sched, bool ALIGN_EPI = false, bool SP2 = false, bool ATILED = false>
; __device__ __forceinline__ void gemm_phase(PG8_LAS unsigned char* lds, const Gemm g, const Sched& S, const Epi& E) {
;     ...
;             PG8_LDA(At, 0, 1); PG8_STAGE(PG8_SB(0, 0), b2, voffB); PG8_STAGE(PG8_SB(0, 1), b2 + hstep, voffB); PG8_STAGE(PG8_SA(0, 0), a2, voffA);
	s_add_i32 m0, s69, 0x2000
	s_nop 0
	global_load_lds_dwordx4 v134, s[70:71]

; #define PG8_STAGE(bufoff, gbase, voff) do { _Pragma("unroll") for (int _i = 0; _i < 2; ++_i) \
;         __builtin_amdgcn_global_load_lds((const unsigned*)((const char*)(gbase) + (voff)[_i]), (PG8_LAS unsigned*)(lds + (bufoff) + ldsw + _i * 8192), 16, 0, 0); } while (0)
; #define PG8_LDA(dst, b, h) do { _Pragma("unroll") for (int m = 0; m < 4; ++m) _Pragma("unroll") for (int k = 0; k < 2; ++k) dst[m][k] = *(const PG8_LAS bf16x8*)(lds + PG8_SA(b, h) + aoff + m * 2048 + k * 1024); } while (0)
; #define PG8_LDB(dst, b, h) do { _Pragma("unroll") for (int n = 0; n < 2; ++n) _Pragma("unroll") for (int k = 0; k < 2; ++k) dst[n][k] = *(const PG8_LAS bf16x8*)(lds + PG8_SB(b, h) + boff + n * 2048 + k * 1024); } while (0)
; #define PG8_MMA(ai, bj, At, Bt) do { __builtin_amdgcn_s_setprio(1); _Pragma("unroll") for (int m = 0; m < 4; ++m) _Pragma("unroll") for (int n = 0; n < 2; ++n) _Pragma("unroll") for (int k = 0; k < 2; ++k) \
;         acc[ai][bj][m][n] = __builtin_amdgcn_mfma_f32_16x16x32_bf16(Bt[n][k], At[m][k], acc[ai][bj][m][n], 0, 0, 0); __builtin_amdgcn_s_setprio(0); } while (0)
; #define PG8_WAIT_V(n) asm volatile("s_waitcnt vmcnt(" #n ")" ::: "memory")
; #define PG8_WAIT_L(n) asm volatile("s_waitcnt lgkmcnt(" #n ")" ::: "memory")
; #define PG8_BAR __builtin_amdgcn_s_barrier()
; #define PG8_SCHED __builtin_amdgcn_sched_barrier(0)
; template <class Epi, class Sched, bool ALIGN_EPI = false, bool SP2 = false, bool ATILED = false>
; __device__ __forceinline__ void gemm_phase(PG8_LAS unsigned char* lds, const Gemm g, const Sched& S, const Epi& E) {
;     ...
;             PG8_LDA(At, 0, 1); PG8_STAGE(PG8_SB(0, 0), b2, voffB); PG8_STAGE(PG8_SB(0, 1), b2 + hstep, voffB); PG8_STAGE(PG8_SA(0, 0), a2, voffA);
;             PG8_WAIT_V(8); PG8_WAIT_L(0); PG8_BAR; PG8_MMA(1, 0, At, B0); PG8_MMA(1, 1, At, B1); PG8_BAR; PG8_SCHED;
;             PG8_LDB(B0, 1, 0); PG8_LDB(B1, 1, 1); PG8_SCHED; PG8_LDA(At, 1, 0); PG8_STAGE(PG8_SA(0, 1), a2 + hstepA, voffA);
	s_mov_b32 m0, s19
	s_nop 0
	global_load_lds_dwordx4 v128, s[44:45]
	s_mov_b32 m0, s48
	s_nop 0
	global_load_lds_dwordx4 v132, s[44:45]
	s_waitcnt vmcnt(8)
	s_waitcnt lgkmcnt(0)
	s_barrier
	s_setprio 1
	s_waitcnt lgkmcnt(0)
	v_mfma_f32_16x16x32_bf16 v[60:63], v[150:153], v[190:193], v[60:63]
	v_mfma_f32_16x16x32_bf16 v[56:59], v[166:169], v[190:193], v[56:59]
	v_mfma_f32_16x16x32_bf16 v[44:47], v[150:153], v[200:203], v[44:47]
	v_mfma_f32_16x16x32_bf16 v[40:43], v[166:169], v[200:203], v[40:43]
	v_mfma_f32_16x16x32_bf16 v[28:31], v[150:153], v[208:211], v[28:31]
	v_mfma_f32_16x16x32_bf16 v[24:27], v[166:169], v[208:211], v[24:27]
	v_mfma_f32_16x16x32_bf16 v[12:15], v[150:153], v[216:219], v[12:15]
	v_mfma_f32_16x16x32_bf16 v[8:11], v[166:169], v[216:219], v[8:11]
	v_mfma_f32_16x16x32_bf16 v[60:63], v[162:165], v[194:197], v[60:63]
	v_mfma_f32_16x16x32_bf16 v[56:59], v[170:173], v[194:197], v[56:59]
	v_mfma_f32_16x16x32_bf16 v[44:47], v[162:165], v[204:207], v[44:47]
	v_mfma_f32_16x16x32_bf16 v[40:43], v[170:173], v[204:207], v[40:43]
	v_mfma_f32_16x16x32_bf16 v[28:31], v[162:165], v[212:215], v[28:31]
	v_mfma_f32_16x16x32_bf16 v[24:27], v[170:173], v[212:215], v[24:27]
	v_mfma_f32_16x16x32_bf16 v[12:15], v[162:165], v[220:223], v[12:15]
	v_mfma_f32_16x16x32_bf16 v[8:11], v[170:173], v[220:223], v[8:11]
	s_setprio 0
	s_setprio 1
	v_mfma_f32_16x16x32_bf16 v[52:55], v[174:177], v[190:193], v[52:55]
	v_mfma_f32_16x16x32_bf16 v[48:51], v[182:185], v[190:193], v[48:51]
	v_mfma_f32_16x16x32_bf16 v[36:39], v[174:177], v[200:203], v[36:39]
	v_mfma_f32_16x16x32_bf16 v[32:35], v[182:185], v[200:203], v[32:35]
	v_mfma_f32_16x16x32_bf16 v[20:23], v[174:177], v[208:211], v[20:23]
	v_mfma_f32_16x16x32_bf16 v[16:19], v[182:185], v[208:211], v[16:19]
	v_mfma_f32_16x16x32_bf16 v[4:7], v[174:177], v[216:219], v[4:7]
	v_mfma_f32_16x16x32_bf16 v[0:3], v[182:185], v[216:219], v[0:3]
	v_mfma_f32_16x16x32_bf16 v[52:55], v[178:181], v[194:197], v[52:55]
	v_mfma_f32_16x16x32_bf16 v[48:51], v[186:189], v[194:197], v[48:51]
	v_mfma_f32_16x16x32_bf16 v[36:39], v[178:181], v[204:207], v[36:39]
	v_mfma_f32_16x16x32_bf16 v[32:35], v[186:189], v[204:207], v[32:35]
	v_mfma_f32_16x16x32_bf16 v[20:23], v[178:181], v[212:215], v[20:23]
	v_mfma_f32_16x16x32_bf16 v[16:19], v[186:189], v[212:215], v[16:19]
	v_mfma_f32_16x16x32_bf16 v[4:7], v[178:181], v[220:223], v[4:7]
	v_mfma_f32_16x16x32_bf16 v[0:3], v[186:189], v[220:223], v[0:3]
	s_setprio 0
	s_barrier
	s_add_i32 s69, 0, 0x18000
	v_add_u32_e32 v136, s69, v155
	s_add_i32 s70, 0, 0x1c000
	ds_read_b128 v[150:153], v136
	ds_read_b128 v[162:165], v136 offset:1024
	ds_read_b128 v[166:169], v136 offset:2048
	ds_read_b128 v[170:173], v136 offset:3072
	v_add_u32_e32 v136, s70, v155
	ds_read_b128 v[174:177], v136
	ds_read_b128 v[178:181], v136 offset:1024
	ds_read_b128 v[182:185], v136 offset:2048
	ds_read_b128 v[186:189], v136 offset:3072
	s_add_u32 s44, s44, 0x40000
	s_addc_u32 s45, s45, 0
	s_mov_b32 m0, s49

; #define PG8_STAGE(bufoff, gbase, voff) do { _Pragma("unroll") for (int _i = 0; _i < 2; ++_i) \
;         __builtin_amdgcn_global_load_lds((const unsigned*)((const char*)(gbase) + (voff)[_i]), (PG8_LAS unsigned*)(lds + (bufoff) + ldsw + _i * 8192), 16, 0, 0); } while (0)
; #define PG8_LDA(dst, b, h) do { _Pragma("unroll") for (int m = 0; m < 4; ++m) _Pragma("unroll") for (int k = 0; k < 2; ++k) dst[m][k] = *(const PG8_LAS bf16x8*)(lds + PG8_SA(b, h) + aoff + m * 2048 + k * 1024); } while (0)
; #define PG8_LDB(dst, b, h) do { _Pragma("unroll") for (int n = 0; n < 2; ++n) _Pragma("unroll") for (int k = 0; k < 2; ++k) dst[n][k] = *(const PG8_LAS bf16x8*)(lds + PG8_SB(b, h) + boff + n * 2048 + k * 1024); } while (0)
; #define PG8_SCHED __builtin_amdgcn_sched_barrier(0)
; template <class Epi, class Sched, bool ALIGN_EPI = false, bool SP2 = false, bool ATILED = false>
; __device__ __forceinline__ void gemm_phase(PG8_LAS unsigned char* lds, const Gemm g, const Sched& S, const Epi& E) {
;     ...
;             PG8_LDB(B0, 1, 0); PG8_LDB(B1, 1, 1); PG8_SCHED; PG8_LDA(At, 1, 0); PG8_STAGE(PG8_SA(0, 1), a2 + hstepA, voffA);
	ds_read_b128 v[190:193], v158 offset:32768
	ds_read_b128 v[194:197], v158 offset:33792
	ds_read_b128 v[200:203], v158 offset:34816
	ds_read_b128 v[204:207], v158 offset:35840
	ds_read_b128 v[208:211], v158 offset:36864
	ds_read_b128 v[212:215], v158 offset:37888
	ds_read_b128 v[216:219], v158 offset:38912
	ds_read_b128 v[220:223], v158 offset:39936
	global_load_lds_dwordx4 v128, s[44:45]

; #define PG8_STAGE(bufoff, gbase, voff) do { _Pragma("unroll") for (int _i = 0; _i < 2; ++_i) \
;         __builtin_amdgcn_global_load_lds((const unsigned*)((const char*)(gbase) + (voff)[_i]), (PG8_LAS unsigned*)(lds + (bufoff) + ldsw + _i * 8192), 16, 0, 0); } while (0)
; #define PG8_LDA(dst, b, h) do { _Pragma("unroll") for (int m = 0; m < 4; ++m) _Pragma("unroll") for (int k = 0; k < 2; ++k) dst[m][k] = *(const PG8_LAS bf16x8*)(lds + PG8_SA(b, h) + aoff + m * 2048 + k * 1024); } while (0)
; #define PG8_LDB(dst, b, h) do { _Pragma("unroll") for (int n = 0; n < 2; ++n) _Pragma("unroll") for (int k = 0; k < 2; ++k) dst[n][k] = *(const PG8_LAS bf16x8*)(lds + PG8_SB(b, h) + boff + n * 2048 + k * 1024); } while (0)
; #define PG8_MMA(ai, bj, At, Bt) do { __builtin_amdgcn_s_setprio(1); _Pragma("unroll") for (int m = 0; m < 4; ++m) _Pragma("unroll") for (int n = 0; n < 2; ++n) _Pragma("unroll") for (int k = 0; k < 2; ++k) \
;         acc[ai][bj][m][n] = __builtin_amdgcn_mfma_f32_16x16x32_bf16(Bt[n][k], At[m][k], acc[ai][bj][m][n], 0, 0, 0); __builtin_amdgcn_s_setprio(0); } while (0)
; #define PG8_WAIT_V(n) asm volatile("s_waitcnt vmcnt(" #n ")" ::: "memory")
; #define PG8_WAIT_L(n) asm volatile("s_waitcnt lgkmcnt(" #n ")" ::: "memory")
; #define PG8_BAR __builtin_amdgcn_s_barrier()
; #define PG8_SCHED __builtin_amdgcn_sched_barrier(0)
; template <class Epi, class Sched, bool ALIGN_EPI = false, bool SP2 = false, bool ATILED = false>
; __device__ __forceinline__ void gemm_phase(PG8_LAS unsigned char* lds, const Gemm g, const Sched& S, const Epi& E) {
;     ...
;             PG8_LDB(B0, 1, 0); PG8_LDB(B1, 1, 1); PG8_SCHED; PG8_LDA(At, 1, 0); PG8_STAGE(PG8_SA(0, 1), a2 + hstepA, voffA);
;             PG8_WAIT_V(8); PG8_WAIT_L(0); PG8_BAR; PG8_MMA(0, 0, At, B0); PG8_MMA(0, 1, At, B1); PG8_BAR; PG8_SCHED;
;             PG8_LDA(At, 1, 1); PG8_STAGE(PG8_SB(1, 0), b3, voffB); PG8_STAGE(PG8_SB(1, 1), b3 + hstep, voffB); PG8_STAGE(PG8_SA(1, 0), a3, voffA);
	s_mov_b32 m0, s50
	s_nop 0
	global_load_lds_dwordx4 v132, s[44:45]
	s_waitcnt vmcnt(8)
	s_waitcnt lgkmcnt(0)
	s_barrier
	s_setprio 1
	s_waitcnt lgkmcnt(0)
	v_mfma_f32_16x16x32_bf16 v[124:127], v[150:153], v[190:193], v[124:127]
	v_mfma_f32_16x16x32_bf16 v[120:123], v[166:169], v[190:193], v[120:123]
	v_mfma_f32_16x16x32_bf16 v[108:111], v[150:153], v[200:203], v[108:111]
	v_mfma_f32_16x16x32_bf16 v[104:107], v[166:169], v[200:203], v[104:107]
	v_mfma_f32_16x16x32_bf16 v[92:95], v[150:153], v[208:211], v[92:95]
	v_mfma_f32_16x16x32_bf16 v[88:91], v[166:169], v[208:211], v[88:91]
	v_mfma_f32_16x16x32_bf16 v[76:79], v[150:153], v[216:219], v[76:79]
	v_mfma_f32_16x16x32_bf16 v[72:75], v[166:169], v[216:219], v[72:75]
	v_mfma_f32_16x16x32_bf16 v[124:127], v[162:165], v[194:197], v[124:127]
	v_mfma_f32_16x16x32_bf16 v[120:123], v[170:173], v[194:197], v[120:123]
	v_mfma_f32_16x16x32_bf16 v[108:111], v[162:165], v[204:207], v[108:111]
	v_mfma_f32_16x16x32_bf16 v[104:107], v[170:173], v[204:207], v[104:107]
	v_mfma_f32_16x16x32_bf16 v[92:95], v[162:165], v[212:215], v[92:95]
	v_mfma_f32_16x16x32_bf16 v[88:91], v[170:173], v[212:215], v[88:91]
	v_mfma_f32_16x16x32_bf16 v[76:79], v[162:165], v[220:223], v[76:79]
	v_mfma_f32_16x16x32_bf16 v[72:75], v[170:173], v[220:223], v[72:75]
	s_setprio 0
	s_setprio 1
	v_mfma_f32_16x16x32_bf16 v[116:119], v[174:177], v[190:193], v[116:119]
	v_mfma_f32_16x16x32_bf16 v[112:115], v[182:185], v[190:193], v[112:115]
	v_mfma_f32_16x16x32_bf16 v[100:103], v[174:177], v[200:203], v[100:103]
	v_mfma_f32_16x16x32_bf16 v[96:99], v[182:185], v[200:203], v[96:99]
	v_mfma_f32_16x16x32_bf16 v[84:87], v[174:177], v[208:211], v[84:87]
	v_mfma_f32_16x16x32_bf16 v[80:83], v[182:185], v[208:211], v[80:83]
	v_mfma_f32_16x16x32_bf16 v[68:71], v[174:177], v[216:219], v[68:71]
	v_mfma_f32_16x16x32_bf16 v[64:67], v[182:185], v[216:219], v[64:67]
	v_mfma_f32_16x16x32_bf16 v[116:119], v[178:181], v[194:197], v[116:119]
	v_mfma_f32_16x16x32_bf16 v[112:115], v[186:189], v[194:197], v[112:115]
	v_mfma_f32_16x16x32_bf16 v[100:103], v[178:181], v[204:207], v[100:103]
	v_mfma_f32_16x16x32_bf16 v[96:99], v[186:189], v[204:207], v[96:99]
	v_mfma_f32_16x16x32_bf16 v[84:87], v[178:181], v[212:215], v[84:87]
	v_mfma_f32_16x16x32_bf16 v[80:83], v[186:189], v[212:215], v[80:83]
	v_mfma_f32_16x16x32_bf16 v[68:71], v[178:181], v[220:223], v[68:71]
	v_mfma_f32_16x16x32_bf16 v[64:67], v[186:189], v[220:223], v[64:67]
	s_setprio 0
	s_barrier
	s_add_i32 s44, s69, s46

; #define PG8_STAGE(bufoff, gbase, voff) do { _Pragma("unroll") for (int _i = 0; _i < 2; ++_i) \
;         __builtin_amdgcn_global_load_lds((const unsigned*)((const char*)(gbase) + (voff)[_i]), (PG8_LAS unsigned*)(lds + (bufoff) + ldsw + _i * 8192), 16, 0, 0); } while (0)
; #define PG8_LDA(dst, b, h) do { _Pragma("unroll") for (int m = 0; m < 4; ++m) _Pragma("unroll") for (int k = 0; k < 2; ++k) dst[m][k] = *(const PG8_LAS bf16x8*)(lds + PG8_SA(b, h) + aoff + m * 2048 + k * 1024); } while (0)
; template <class Epi, class Sched, bool ALIGN_EPI = false, bool SP2 = false, bool ATILED = false>
; __device__ __forceinline__ void gemm_phase(PG8_LAS unsigned char* lds, const Gemm g, const Sched& S, const Epi& E) {
;     ...
;             PG8_LDA(At, 1, 1); PG8_STAGE(PG8_SB(1, 0), b3, voffB); PG8_STAGE(PG8_SB(1, 1), b3 + hstep, voffB); PG8_STAGE(PG8_SA(1, 0), a3, voffA);
	s_mov_b32 m0, s44
	ds_read_b128 v[190:193], v158 offset:49152
	ds_read_b128 v[194:197], v158 offset:50176
	ds_read_b128 v[200:203], v158 offset:51200
	ds_read_b128 v[204:207], v158 offset:52224
	ds_read_b128 v[208:211], v158 offset:53248
	ds_read_b128 v[212:215], v158 offset:54272
	ds_read_b128 v[216:219], v158 offset:55296
	ds_read_b128 v[220:223], v158 offset:56320
	global_load_lds_dwordx4 v130, s[98:99]
	s_add_i32 m0, s44, 0x2000
	s_add_u32 s42, s42, 0x40080

; #define PG8_STAGE(bufoff, gbase, voff) do { _Pragma("unroll") for (int _i = 0; _i < 2; ++_i) \
;         __builtin_amdgcn_global_load_lds((const unsigned*)((const char*)(gbase) + (voff)[_i]), (PG8_LAS unsigned*)(lds + (bufoff) + ldsw + _i * 8192), 16, 0, 0); } while (0)
; #define PG8_LDA(dst, b, h) do { _Pragma("unroll") for (int m = 0; m < 4; ++m) _Pragma("unroll") for (int k = 0; k < 2; ++k) dst[m][k] = *(const PG8_LAS bf16x8*)(lds + PG8_SA(b, h) + aoff + m * 2048 + k * 1024); } while (0)
; template <class Epi, class Sched, bool ALIGN_EPI = false, bool SP2 = false, bool ATILED = false>
; __device__ __forceinline__ void gemm_phase(PG8_LAS unsigned char* lds, const Gemm g, const Sched& S, const Epi& E) {
;     ...
;             PG8_LDA(At, 1, 1); PG8_STAGE(PG8_SB(1, 0), b3, voffB); PG8_STAGE(PG8_SB(1, 1), b3 + hstep, voffB); PG8_STAGE(PG8_SA(1, 0), a3, voffA);
	s_addc_u32 s43, s43, 0
	s_add_i32 s44, s70, s46
	global_load_lds_dwordx4 v134, s[98:99]

; #define PG8_STAGE(bufoff, gbase, voff) do { _Pragma("unroll") for (int _i = 0; _i < 2; ++_i) \
;         __builtin_amdgcn_global_load_lds((const unsigned*)((const char*)(gbase) + (voff)[_i]), (PG8_LAS unsigned*)(lds + (bufoff) + ldsw + _i * 8192), 16, 0, 0); } while (0)
; #define PG8_LDA(dst, b, h) do { _Pragma("unroll") for (int m = 0; m < 4; ++m) _Pragma("unroll") for (int k = 0; k < 2; ++k) dst[m][k] = *(const PG8_LAS bf16x8*)(lds + PG8_SA(b, h) + aoff + m * 2048 + k * 1024); } while (0)
; template <class Epi, class Sched, bool ALIGN_EPI = false, bool SP2 = false, bool ATILED = false>
; __device__ __forceinline__ void gemm_phase(PG8_LAS unsigned char* lds, const Gemm g, const Sched& S, const Epi& E) {
;     ...
;             PG8_LDA(At, 1, 1); PG8_STAGE(PG8_SB(1, 0), b3, voffB); PG8_STAGE(PG8_SB(1, 1), b3 + hstep, voffB); PG8_STAGE(PG8_SA(1, 0), a3, voffA);
	s_mov_b32 m0, s44
	s_nop 0
	global_load_lds_dwordx4 v130, s[42:43]

; #define PG8_STAGE(bufoff, gbase, voff) do { _Pragma("unroll") for (int _i = 0; _i < 2; ++_i) \
;         __builtin_amdgcn_global_load_lds((const unsigned*)((const char*)(gbase) + (voff)[_i]), (PG8_LAS unsigned*)(lds + (bufoff) + ldsw + _i * 8192), 16, 0, 0); } while (0)
; #define PG8_LDA(dst, b, h) do { _Pragma("unroll") for (int m = 0; m < 4; ++m) _Pragma("unroll") for (int k = 0; k < 2; ++k) dst[m][k] = *(const PG8_LAS bf16x8*)(lds + PG8_SA(b, h) + aoff + m * 2048 + k * 1024); } while (0)
; template <class Epi, class Sched, bool ALIGN_EPI = false, bool SP2 = false, bool ATILED = false>
; __device__ __forceinline__ void gemm_phase(PG8_LAS unsigned char* lds, const Gemm g, const Sched& S, const Epi& E) {
;     ...
;             PG8_LDA(At, 1, 1); PG8_STAGE(PG8_SB(1, 0), b3, voffB); PG8_STAGE(PG8_SB(1, 1), b3 + hstep, voffB); PG8_STAGE(PG8_SA(1, 0), a3, voffA);
	s_add_i32 m0, s44, 0x2000
	s_nop 0
	global_load_lds_dwordx4 v134, s[42:43]

; #define PG8_STAGE(bufoff, gbase, voff) do { _Pragma("unroll") for (int _i = 0; _i < 2; ++_i) \
;         __builtin_amdgcn_global_load_lds((const unsigned*)((const char*)(gbase) + (voff)[_i]), (PG8_LAS unsigned*)(lds + (bufoff) + ldsw + _i * 8192), 16, 0, 0); } while (0)
; #define PG8_LDA(dst, b, h) do { _Pragma("unroll") for (int m = 0; m < 4; ++m) _Pragma("unroll") for (int k = 0; k < 2; ++k) dst[m][k] = *(const PG8_LAS bf16x8*)(lds + PG8_SA(b, h) + aoff + m * 2048 + k * 1024); } while (0)
; template <class Epi, class Sched, bool ALIGN_EPI = false, bool SP2 = false, bool ATILED = false>
; __device__ __forceinline__ void gemm_phase(PG8_LAS unsigned char* lds, const Gemm g, const Sched& S, const Epi& E) {
;     ...
;             PG8_LDA(At, 1, 1); PG8_STAGE(PG8_SB(1, 0), b3, voffB); PG8_STAGE(PG8_SB(1, 1), b3 + hstep, voffB); PG8_STAGE(PG8_SA(1, 0), a3, voffA);
	s_mov_b32 m0, s58
	s_nop 0
	global_load_lds_dwordx4 v128, s[100:101]

; #define PG8_STAGE(bufoff, gbase, voff) do { _Pragma("unroll") for (int _i = 0; _i < 2; ++_i) \
;         __builtin_amdgcn_global_load_lds((const unsigned*)((const char*)(gbase) + (voff)[_i]), (PG8_LAS unsigned*)(lds + (bufoff) + ldsw + _i * 8192), 16, 0, 0); } while (0)
; #define PG8_LDA(dst, b, h) do { _Pragma("unroll") for (int m = 0; m < 4; ++m) _Pragma("unroll") for (int k = 0; k < 2; ++k) dst[m][k] = *(const PG8_LAS bf16x8*)(lds + PG8_SA(b, h) + aoff + m * 2048 + k * 1024); } while (0)
; #define PG8_MMA(ai, bj, At, Bt) do { __builtin_amdgcn_s_setprio(1); _Pragma("unroll") for (int m = 0; m < 4; ++m) _Pragma("unroll") for (int n = 0; n < 2; ++n) _Pragma("unroll") for (int k = 0; k < 2; ++k) \
;         acc[ai][bj][m][n] = __builtin_amdgcn_mfma_f32_16x16x32_bf16(Bt[n][k], At[m][k], acc[ai][bj][m][n], 0, 0, 0); __builtin_amdgcn_s_setprio(0); } while (0)
; #define PG8_WAIT_V(n) asm volatile("s_waitcnt vmcnt(" #n ")" ::: "memory")
; #define PG8_WAIT_L(n) asm volatile("s_waitcnt lgkmcnt(" #n ")" ::: "memory")
; #define PG8_BAR __builtin_amdgcn_s_barrier()
; #define PG8_SCHED __builtin_amdgcn_sched_barrier(0)
; template <class Epi, class Sched, bool ALIGN_EPI = false, bool SP2 = false, bool ATILED = false>
; __device__ __forceinline__ void gemm_phase(PG8_LAS unsigned char* lds, const Gemm g, const Sched& S, const Epi& E) {
;     ...
;             PG8_LDA(At, 1, 1); PG8_STAGE(PG8_SB(1, 0), b3, voffB); PG8_STAGE(PG8_SB(1, 1), b3 + hstep, voffB); PG8_STAGE(PG8_SA(1, 0), a3, voffA);
;             PG8_WAIT_V(8); PG8_WAIT_L(0); PG8_BAR; PG8_MMA(1, 0, At, B0); PG8_MMA(1, 1, At, B1); PG8_BAR; PG8_SCHED;
;     ...
;         if constexpr (ALIGN_EPI) { if (wr == 0) PG8_BAR; }
	s_mov_b32 m0, s59
	s_nop 0
	global_load_lds_dwordx4 v132, s[100:101]
	s_waitcnt vmcnt(8)
	s_waitcnt lgkmcnt(0)
	s_barrier
	s_setprio 1
	s_waitcnt lgkmcnt(0)
	v_mfma_f32_16x16x32_bf16 v[60:63], v[150:153], v[190:193], v[60:63]
	v_mfma_f32_16x16x32_bf16 v[56:59], v[166:169], v[190:193], v[56:59]
	v_mfma_f32_16x16x32_bf16 v[44:47], v[150:153], v[200:203], v[44:47]
	v_mfma_f32_16x16x32_bf16 v[40:43], v[166:169], v[200:203], v[40:43]
	v_mfma_f32_16x16x32_bf16 v[28:31], v[150:153], v[208:211], v[28:31]
	v_mfma_f32_16x16x32_bf16 v[24:27], v[166:169], v[208:211], v[24:27]
	v_mfma_f32_16x16x32_bf16 v[12:15], v[150:153], v[216:219], v[12:15]
	v_mfma_f32_16x16x32_bf16 v[8:11], v[166:169], v[216:219], v[8:11]
	v_mfma_f32_16x16x32_bf16 v[60:63], v[162:165], v[194:197], v[60:63]
	v_mfma_f32_16x16x32_bf16 v[56:59], v[170:173], v[194:197], v[56:59]
	v_mfma_f32_16x16x32_bf16 v[44:47], v[162:165], v[204:207], v[44:47]
	v_mfma_f32_16x16x32_bf16 v[40:43], v[170:173], v[204:207], v[40:43]
	v_mfma_f32_16x16x32_bf16 v[28:31], v[162:165], v[212:215], v[28:31]
	v_mfma_f32_16x16x32_bf16 v[24:27], v[170:173], v[212:215], v[24:27]
	v_mfma_f32_16x16x32_bf16 v[12:15], v[162:165], v[220:223], v[12:15]
	v_mfma_f32_16x16x32_bf16 v[8:11], v[170:173], v[220:223], v[8:11]
	s_setprio 0
	s_setprio 1
	v_mfma_f32_16x16x32_bf16 v[52:55], v[174:177], v[190:193], v[52:55]
	v_mfma_f32_16x16x32_bf16 v[48:51], v[182:185], v[190:193], v[48:51]
	v_mfma_f32_16x16x32_bf16 v[36:39], v[174:177], v[200:203], v[36:39]
	v_mfma_f32_16x16x32_bf16 v[32:35], v[182:185], v[200:203], v[32:35]
	v_mfma_f32_16x16x32_bf16 v[20:23], v[174:177], v[208:211], v[20:23]
	v_mfma_f32_16x16x32_bf16 v[16:19], v[182:185], v[208:211], v[16:19]
	v_mfma_f32_16x16x32_bf16 v[4:7], v[174:177], v[216:219], v[4:7]
	v_mfma_f32_16x16x32_bf16 v[0:3], v[182:185], v[216:219], v[0:3]
	v_mfma_f32_16x16x32_bf16 v[52:55], v[178:181], v[194:197], v[52:55]
	v_mfma_f32_16x16x32_bf16 v[48:51], v[186:189], v[194:197], v[48:51]
	v_mfma_f32_16x16x32_bf16 v[36:39], v[178:181], v[204:207], v[36:39]
	v_mfma_f32_16x16x32_bf16 v[32:35], v[186:189], v[204:207], v[32:35]
	v_mfma_f32_16x16x32_bf16 v[20:23], v[178:181], v[212:215], v[20:23]
	v_mfma_f32_16x16x32_bf16 v[16:19], v[186:189], v[212:215], v[16:19]
	v_mfma_f32_16x16x32_bf16 v[4:7], v[178:181], v[220:223], v[4:7]
	v_mfma_f32_16x16x32_bf16 v[0:3], v[186:189], v[220:223], v[0:3]
	s_setprio 0
	s_barrier
	s_add_i32 s68, s68, 2
	s_add_u32 s20, s20, 0x100
	s_addc_u32 s21, s21, 0
	s_add_u32 s66, s66, 0x100
	s_addc_u32 s67, s67, 0
	s_cmp_gt_u32 s68, 13
	s_cbranch_scc0 .LBB0_817
	s_and_b64 vcc, exec, s[8:9]
	s_cbranch_vccz .LBB0_820
	s_barrier

; #define PG8_STAGE(bufoff, gbase, voff) do { _Pragma("unroll") for (int _i = 0; _i < 2; ++_i) \
;         __builtin_amdgcn_global_load_lds((const unsigned*)((const char*)(gbase) + (voff)[_i]), (PG8_LAS unsigned*)(lds + (bufoff) + ldsw + _i * 8192), 16, 0, 0); } while (0)
; #define PG8_LDA(dst, b, h) do { _Pragma("unroll") for (int m = 0; m < 4; ++m) _Pragma("unroll") for (int k = 0; k < 2; ++k) dst[m][k] = *(const PG8_LAS bf16x8*)(lds + PG8_SA(b, h) + aoff + m * 2048 + k * 1024); } while (0)
; #define PG8_LDB(dst, b, h) do { _Pragma("unroll") for (int n = 0; n < 2; ++n) _Pragma("unroll") for (int k = 0; k < 2; ++k) dst[n][k] = *(const PG8_LAS bf16x8*)(lds + PG8_SB(b, h) + boff + n * 2048 + k * 1024); } while (0)
; #define PG8_SCHED __builtin_amdgcn_sched_barrier(0)
; template <class Epi, class Sched, bool ALIGN_EPI = false, bool SP2 = false, bool ATILED = false>
; __device__ __forceinline__ void gemm_phase(PG8_LAS unsigned char* lds, const Gemm g, const Sched& S, const Epi& E) {
;     ...
;             const bool last = (t == nt - 2);
;             const char* a1 = cA + (size_t)(t + 1) * kstepA;
;             const char* a2 = last ? nA : cA + (size_t)(t + 2) * kstepA; const char* b2 = last ? nB : cB + (size_t)(t + 2) * kstep;
;             const char* a3 = a2 + kstepA; const char* b3 = b2 + kstep;
;             if (last && has_next) S.a_ready(nxt);
;             if constexpr (SP2) {
;             PG8_LDB(B0, 0, 0); PG8_LDB(B1, 0, 1); PG8_SCHED; PG8_LDA(At, 0, 0); PG8_STAGE(PG8_SA(1, 1), a1 + hstepA, voffA);
.LBB0_898:
	ds_read_b128 v[24:27], v210
	ds_read_b128 v[28:31], v210 offset:1024
	ds_read_b128 v[36:39], v210 offset:2048
	ds_read_b128 v[44:47], v210 offset:3072
	ds_read_b128 v[144:147], v211
	ds_read_b128 v[148:151], v211 offset:1024
	ds_read_b128 v[152:155], v211 offset:2048
	ds_read_b128 v[156:159], v211 offset:3072
	s_add_u32 s42, s40, 0x4000
	s_addc_u32 s43, s41, 0
	s_cmp_eq_u32 s63, 40
	s_cselect_b32 s46, s8, s42
	s_cselect_b32 s47, s9, s43
	s_cselect_b32 s44, s30, s35
	s_cselect_b32 s45, s31, s62
	s_add_u32 s42, s46, 0x8000
	s_addc_u32 s43, s47, 0

; #define PG8_STAGE(bufoff, gbase, voff) do { _Pragma("unroll") for (int _i = 0; _i < 2; ++_i) \
;         __builtin_amdgcn_global_load_lds((const unsigned*)((const char*)(gbase) + (voff)[_i]), (PG8_LAS unsigned*)(lds + (bufoff) + ldsw + _i * 8192), 16, 0, 0); } while (0)
; #define PG8_LDA(dst, b, h) do { _Pragma("unroll") for (int m = 0; m < 4; ++m) _Pragma("unroll") for (int k = 0; k < 2; ++k) dst[m][k] = *(const PG8_LAS bf16x8*)(lds + PG8_SA(b, h) + aoff + m * 2048 + k * 1024); } while (0)
; #define PG8_LDB(dst, b, h) do { _Pragma("unroll") for (int n = 0; n < 2; ++n) _Pragma("unroll") for (int k = 0; k < 2; ++k) dst[n][k] = *(const PG8_LAS bf16x8*)(lds + PG8_SB(b, h) + boff + n * 2048 + k * 1024); } while (0)
; #define PG8_SCHED __builtin_amdgcn_sched_barrier(0)
; template <class Epi, class Sched, bool ALIGN_EPI = false, bool SP2 = false, bool ATILED = false>
; __device__ __forceinline__ void gemm_phase(PG8_LAS unsigned char* lds, const Gemm g, const Sched& S, const Epi& E) {
;     ...
;             PG8_LDB(B0, 0, 0); PG8_LDB(B1, 0, 1); PG8_SCHED; PG8_LDA(At, 0, 0); PG8_STAGE(PG8_SA(1, 1), a1 + hstepA, voffA);
	s_add_i32 m0, s29, 0xc000
	ds_read_b128 v[160:163], v212
	ds_read_b128 v[164:167], v212 offset:1024
	ds_read_b128 v[184:187], v212 offset:2048
	ds_read_b128 v[188:191], v212 offset:3072
	ds_read_b128 v[192:195], v212 offset:4096
	ds_read_b128 v[196:199], v212 offset:5120
	ds_read_b128 v[200:203], v212 offset:6144
	ds_read_b128 v[218:221], v212 offset:7168
	global_load_lds_dwordx4 v176, s[40:41]

; #define PG8_STAGE(bufoff, gbase, voff) do { _Pragma("unroll") for (int _i = 0; _i < 2; ++_i) \
;         __builtin_amdgcn_global_load_lds((const unsigned*)((const char*)(gbase) + (voff)[_i]), (PG8_LAS unsigned*)(lds + (bufoff) + ldsw + _i * 8192), 16, 0, 0); } while (0)
; #define PG8_LDA(dst, b, h) do { _Pragma("unroll") for (int m = 0; m < 4; ++m) _Pragma("unroll") for (int k = 0; k < 2; ++k) dst[m][k] = *(const PG8_LAS bf16x8*)(lds + PG8_SA(b, h) + aoff + m * 2048 + k * 1024); } while (0)
; #define PG8_LDB(dst, b, h) do { _Pragma("unroll") for (int n = 0; n < 2; ++n) _Pragma("unroll") for (int k = 0; k < 2; ++k) dst[n][k] = *(const PG8_LAS bf16x8*)(lds + PG8_SB(b, h) + boff + n * 2048 + k * 1024); } while (0)
; #define PG8_MMA(ai, bj, At, Bt) do { __builtin_amdgcn_s_setprio(1); _Pragma("unroll") for (int m = 0; m < 4; ++m) _Pragma("unroll") for (int n = 0; n < 2; ++n) _Pragma("unroll") for (int k = 0; k < 2; ++k) \
;         acc[ai][bj][m][n] = __builtin_amdgcn_mfma_f32_16x16x32_bf16(Bt[n][k], At[m][k], acc[ai][bj][m][n], 0, 0, 0); __builtin_amdgcn_s_setprio(0); } while (0)
; #define PG8_WAIT_V(n) asm volatile("s_waitcnt vmcnt(" #n ")" ::: "memory")
; #define PG8_WAIT_L(n) asm volatile("s_waitcnt lgkmcnt(" #n ")" ::: "memory")
; #define PG8_BAR __builtin_amdgcn_s_barrier()
; #define PG8_SCHED __builtin_amdgcn_sched_barrier(0)
; template <class Epi, class Sched, bool ALIGN_EPI = false, bool SP2 = false, bool ATILED = false>
; __device__ __forceinline__ void gemm_phase(PG8_LAS unsigned char* lds, const Gemm g, const Sched& S, const Epi& E) {
;     ...
;             PG8_LDB(B0, 0, 0); PG8_LDB(B1, 0, 1); PG8_SCHED; PG8_LDA(At, 0, 0); PG8_STAGE(PG8_SA(1, 1), a1 + hstepA, voffA);
;             PG8_WAIT_V(8); PG8_WAIT_L(0); PG8_BAR; PG8_MMA(0, 0, At, B0); PG8_MMA(0, 1, At, B1); PG8_BAR; PG8_SCHED;
;             PG8_LDA(At, 0, 1); PG8_STAGE(PG8_SB(0, 0), b2, voffB); PG8_STAGE(PG8_SB(0, 1), b2 + hstep, voffB); PG8_STAGE(PG8_SA(0, 0), a2, voffA);
	s_add_i32 m0, s29, 0xe000
	s_nop 0
	global_load_lds_dwordx4 v178, s[40:41]
	s_waitcnt vmcnt(8)
	s_waitcnt lgkmcnt(0)
	s_barrier
	s_setprio 1
	s_waitcnt lgkmcnt(0)
	v_mfma_f32_16x16x32_bf16 v[140:143], v[24:27], v[160:163], v[140:143]
	v_mfma_f32_16x16x32_bf16 v[136:139], v[36:39], v[160:163], v[136:139]
	v_mfma_f32_16x16x32_bf16 v[124:127], v[24:27], v[184:187], v[124:127]
	v_mfma_f32_16x16x32_bf16 v[120:123], v[36:39], v[184:187], v[120:123]
	v_mfma_f32_16x16x32_bf16 v[108:111], v[24:27], v[192:195], v[108:111]
	v_mfma_f32_16x16x32_bf16 v[104:107], v[36:39], v[192:195], v[104:107]
	v_mfma_f32_16x16x32_bf16 v[92:95], v[24:27], v[200:203], v[92:95]
	v_mfma_f32_16x16x32_bf16 v[88:91], v[36:39], v[200:203], v[88:91]
	v_mfma_f32_16x16x32_bf16 v[140:143], v[28:31], v[164:167], v[140:143]
	v_mfma_f32_16x16x32_bf16 v[136:139], v[44:47], v[164:167], v[136:139]
	v_mfma_f32_16x16x32_bf16 v[124:127], v[28:31], v[188:191], v[124:127]
	v_mfma_f32_16x16x32_bf16 v[120:123], v[44:47], v[188:191], v[120:123]
	v_mfma_f32_16x16x32_bf16 v[108:111], v[28:31], v[196:199], v[108:111]
	v_mfma_f32_16x16x32_bf16 v[104:107], v[44:47], v[196:199], v[104:107]
	v_mfma_f32_16x16x32_bf16 v[92:95], v[28:31], v[218:221], v[92:95]
	v_mfma_f32_16x16x32_bf16 v[88:91], v[44:47], v[218:221], v[88:91]
	s_setprio 0
	s_setprio 1
	v_mfma_f32_16x16x32_bf16 v[132:135], v[144:147], v[160:163], v[132:135]
	v_mfma_f32_16x16x32_bf16 v[128:131], v[152:155], v[160:163], v[128:131]
	v_mfma_f32_16x16x32_bf16 v[116:119], v[144:147], v[184:187], v[116:119]
	v_mfma_f32_16x16x32_bf16 v[112:115], v[152:155], v[184:187], v[112:115]
	v_mfma_f32_16x16x32_bf16 v[100:103], v[144:147], v[192:195], v[100:103]
	v_mfma_f32_16x16x32_bf16 v[96:99], v[152:155], v[192:195], v[96:99]
	v_mfma_f32_16x16x32_bf16 v[84:87], v[144:147], v[200:203], v[84:87]
	v_mfma_f32_16x16x32_bf16 v[80:83], v[152:155], v[200:203], v[80:83]
	v_mfma_f32_16x16x32_bf16 v[132:135], v[148:151], v[164:167], v[132:135]
	v_mfma_f32_16x16x32_bf16 v[128:131], v[156:159], v[164:167], v[128:131]
	v_mfma_f32_16x16x32_bf16 v[116:119], v[148:151], v[188:191], v[116:119]
	v_mfma_f32_16x16x32_bf16 v[112:115], v[156:159], v[188:191], v[112:115]
	v_mfma_f32_16x16x32_bf16 v[100:103], v[148:151], v[196:199], v[100:103]
	v_mfma_f32_16x16x32_bf16 v[96:99], v[156:159], v[196:199], v[96:99]
	v_mfma_f32_16x16x32_bf16 v[84:87], v[148:151], v[218:221], v[84:87]
	v_mfma_f32_16x16x32_bf16 v[80:83], v[156:159], v[218:221], v[80:83]
	s_setprio 0
	s_barrier
	s_add_u32 s98, s44, s16
	s_addc_u32 s99, s45, s17
	s_add_i32 s64, s57, s3

; #define PG8_STAGE(bufoff, gbase, voff) do { _Pragma("unroll") for (int _i = 0; _i < 2; ++_i) \
;         __builtin_amdgcn_global_load_lds((const unsigned*)((const char*)(gbase) + (voff)[_i]), (PG8_LAS unsigned*)(lds + (bufoff) + ldsw + _i * 8192), 16, 0, 0); } while (0)
; #define PG8_LDA(dst, b, h) do { _Pragma("unroll") for (int m = 0; m < 4; ++m) _Pragma("unroll") for (int k = 0; k < 2; ++k) dst[m][k] = *(const PG8_LAS bf16x8*)(lds + PG8_SA(b, h) + aoff + m * 2048 + k * 1024); } while (0)
; template <class Epi, class Sched, bool ALIGN_EPI = false, bool SP2 = false, bool ATILED = false>
; __device__ __forceinline__ void gemm_phase(PG8_LAS unsigned char* lds, const Gemm g, const Sched& S, const Epi& E) {
;     ...
;             PG8_LDA(At, 0, 1); PG8_STAGE(PG8_SB(0, 0), b2, voffB); PG8_STAGE(PG8_SB(0, 1), b2 + hstep, voffB); PG8_STAGE(PG8_SA(0, 0), a2, voffA);
	s_mov_b32 m0, s64
	ds_read_b128 v[160:163], v212 offset:16384
	ds_read_b128 v[164:167], v212 offset:17408
	ds_read_b128 v[184:187], v212 offset:18432
	ds_read_b128 v[188:191], v212 offset:19456
	ds_read_b128 v[192:195], v212 offset:20480
	ds_read_b128 v[196:199], v212 offset:21504
	ds_read_b128 v[200:203], v212 offset:22528
	ds_read_b128 v[218:221], v212 offset:23552
	global_load_lds_dwordx4 v170, s[44:45]
	s_add_i32 m0, s64, 0x2000
	s_add_u32 s64, s44, 0xb0000

; #define PG8_STAGE(bufoff, gbase, voff) do { _Pragma("unroll") for (int _i = 0; _i < 2; ++_i) \
;         __builtin_amdgcn_global_load_lds((const unsigned*)((const char*)(gbase) + (voff)[_i]), (PG8_LAS unsigned*)(lds + (bufoff) + ldsw + _i * 8192), 16, 0, 0); } while (0)
; #define PG8_LDA(dst, b, h) do { _Pragma("unroll") for (int m = 0; m < 4; ++m) _Pragma("unroll") for (int k = 0; k < 2; ++k) dst[m][k] = *(const PG8_LAS bf16x8*)(lds + PG8_SA(b, h) + aoff + m * 2048 + k * 1024); } while (0)
; template <class Epi, class Sched, bool ALIGN_EPI = false, bool SP2 = false, bool ATILED = false>
; __device__ __forceinline__ void gemm_phase(PG8_LAS unsigned char* lds, const Gemm g, const Sched& S, const Epi& E) {
;     ...
;             PG8_LDA(At, 0, 1); PG8_STAGE(PG8_SB(0, 0), b2, voffB); PG8_STAGE(PG8_SB(0, 1), b2 + hstep, voffB); PG8_STAGE(PG8_SA(0, 0), a2, voffA);
	s_addc_u32 s65, s45, 0
	s_add_i32 s66, s58, s3
	global_load_lds_dwordx4 v174, s[44:45]

; #define PG8_STAGE(bufoff, gbase, voff) do { _Pragma("unroll") for (int _i = 0; _i < 2; ++_i) \
;         __builtin_amdgcn_global_load_lds((const unsigned*)((const char*)(gbase) + (voff)[_i]), (PG8_LAS unsigned*)(lds + (bufoff) + ldsw + _i * 8192), 16, 0, 0); } while (0)
; #define PG8_LDA(dst, b, h) do { _Pragma("unroll") for (int m = 0; m < 4; ++m) _Pragma("unroll") for (int k = 0; k < 2; ++k) dst[m][k] = *(const PG8_LAS bf16x8*)(lds + PG8_SA(b, h) + aoff + m * 2048 + k * 1024); } while (0)
; template <class Epi, class Sched, bool ALIGN_EPI = false, bool SP2 = false, bool ATILED = false>
; __device__ __forceinline__ void gemm_phase(PG8_LAS unsigned char* lds, const Gemm g, const Sched& S, const Epi& E) {
;     ...
;             PG8_LDA(At, 0, 1); PG8_STAGE(PG8_SB(0, 0), b2, voffB); PG8_STAGE(PG8_SB(0, 1), b2 + hstep, voffB); PG8_STAGE(PG8_SA(0, 0), a2, voffA);
	s_mov_b32 m0, s66
	s_nop 0
	global_load_lds_dwordx4 v170, s[64:65]

; #define PG8_STAGE(bufoff, gbase, voff) do { _Pragma("unroll") for (int _i = 0; _i < 2; ++_i) \
;         __builtin_amdgcn_global_load_lds((const unsigned*)((const char*)(gbase) + (voff)[_i]), (PG8_LAS unsigned*)(lds + (bufoff) + ldsw + _i * 8192), 16, 0, 0); } while (0)
; #define PG8_LDA(dst, b, h) do { _Pragma("unroll") for (int m = 0; m < 4; ++m) _Pragma("unroll") for (int k = 0; k < 2; ++k) dst[m][k] = *(const PG8_LAS bf16x8*)(lds + PG8_SA(b, h) + aoff + m * 2048 + k * 1024); } while (0)
; template <class Epi, class Sched, bool ALIGN_EPI = false, bool SP2 = false, bool ATILED = false>
; __device__ __forceinline__ void gemm_phase(PG8_LAS unsigned char* lds, const Gemm g, const Sched& S, const Epi& E) {
;     ...
;             PG8_LDA(At, 0, 1); PG8_STAGE(PG8_SB(0, 0), b2, voffB); PG8_STAGE(PG8_SB(0, 1), b2 + hstep, voffB); PG8_STAGE(PG8_SA(0, 0), a2, voffA);
	s_add_i32 m0, s66, 0x2000
	s_nop 0
	global_load_lds_dwordx4 v174, s[64:65]

; #define PG8_STAGE(bufoff, gbase, voff) do { _Pragma("unroll") for (int _i = 0; _i < 2; ++_i) \
;         __builtin_amdgcn_global_load_lds((const unsigned*)((const char*)(gbase) + (voff)[_i]), (PG8_LAS unsigned*)(lds + (bufoff) + ldsw + _i * 8192), 16, 0, 0); } while (0)
; #define PG8_LDA(dst, b, h) do { _Pragma("unroll") for (int m = 0; m < 4; ++m) _Pragma("unroll") for (int k = 0; k < 2; ++k) dst[m][k] = *(const PG8_LAS bf16x8*)(lds + PG8_SA(b, h) + aoff + m * 2048 + k * 1024); } while (0)
; template <class Epi, class Sched, bool ALIGN_EPI = false, bool SP2 = false, bool ATILED = false>
; __device__ __forceinline__ void gemm_phase(PG8_LAS unsigned char* lds, const Gemm g, const Sched& S, const Epi& E) {
;     ...
;             PG8_LDA(At, 0, 1); PG8_STAGE(PG8_SB(0, 0), b2, voffB); PG8_STAGE(PG8_SB(0, 1), b2 + hstep, voffB); PG8_STAGE(PG8_SA(0, 0), a2, voffA);
	s_mov_b32 m0, s29
	s_nop 0
	global_load_lds_dwordx4 v168, s[46:47]

; #define PG8_STAGE(bufoff, gbase, voff) do { _Pragma("unroll") for (int _i = 0; _i < 2; ++_i) \
;         __builtin_amdgcn_global_load_lds((const unsigned*)((const char*)(gbase) + (voff)[_i]), (PG8_LAS unsigned*)(lds + (bufoff) + ldsw + _i * 8192), 16, 0, 0); } while (0)
; #define PG8_LDA(dst, b, h) do { _Pragma("unroll") for (int m = 0; m < 4; ++m) _Pragma("unroll") for (int k = 0; k < 2; ++k) dst[m][k] = *(const PG8_LAS bf16x8*)(lds + PG8_SA(b, h) + aoff + m * 2048 + k * 1024); } while (0)
; #define PG8_LDB(dst, b, h) do { _Pragma("unroll") for (int n = 0; n < 2; ++n) _Pragma("unroll") for (int k = 0; k < 2; ++k) dst[n][k] = *(const PG8_LAS bf16x8*)(lds + PG8_SB(b, h) + boff + n * 2048 + k * 1024); } while (0)
; #define PG8_MMA(ai, bj, At, Bt) do { __builtin_amdgcn_s_setprio(1); _Pragma("unroll") for (int m = 0; m < 4; ++m) _Pragma("unroll") for (int n = 0; n < 2; ++n) _Pragma("unroll") for (int k = 0; k < 2; ++k) \
;         acc[ai][bj][m][n] = __builtin_amdgcn_mfma_f32_16x16x32_bf16(Bt[n][k], At[m][k], acc[ai][bj][m][n], 0, 0, 0); __builtin_amdgcn_s_setprio(0); } while (0)
; #define PG8_WAIT_V(n) asm volatile("s_waitcnt vmcnt(" #n ")" ::: "memory")
; #define PG8_WAIT_L(n) asm volatile("s_waitcnt lgkmcnt(" #n ")" ::: "memory")
; #define PG8_BAR __builtin_amdgcn_s_barrier()
; #define PG8_SCHED __builtin_amdgcn_sched_barrier(0)
; template <class Epi, class Sched, bool ALIGN_EPI = false, bool SP2 = false, bool ATILED = false>
; __device__ __forceinline__ void gemm_phase(PG8_LAS unsigned char* lds, const Gemm g, const Sched& S, const Epi& E) {
;     ...
;             PG8_LDA(At, 0, 1); PG8_STAGE(PG8_SB(0, 0), b2, voffB); PG8_STAGE(PG8_SB(0, 1), b2 + hstep, voffB); PG8_STAGE(PG8_SA(0, 0), a2, voffA);
;             PG8_WAIT_V(8); PG8_WAIT_L(0); PG8_BAR; PG8_MMA(1, 0, At, B0); PG8_MMA(1, 1, At, B1); PG8_BAR; PG8_SCHED;
;             PG8_LDB(B0, 1, 0); PG8_LDB(B1, 1, 1); PG8_SCHED; PG8_LDA(At, 1, 0); PG8_STAGE(PG8_SA(0, 1), a2 + hstepA, voffA);
	s_mov_b32 m0, s33
	s_nop 0
	global_load_lds_dwordx4 v172, s[46:47]
	s_waitcnt vmcnt(8)
	s_waitcnt lgkmcnt(0)
	s_barrier
	s_setprio 1
	s_waitcnt lgkmcnt(0)
	v_mfma_f32_16x16x32_bf16 v[76:79], v[24:27], v[160:163], v[76:79]
	v_mfma_f32_16x16x32_bf16 v[72:75], v[36:39], v[160:163], v[72:75]
	v_mfma_f32_16x16x32_bf16 v[60:63], v[24:27], v[184:187], v[60:63]
	v_mfma_f32_16x16x32_bf16 v[56:59], v[36:39], v[184:187], v[56:59]
	v_mfma_f32_16x16x32_bf16 v[40:43], v[24:27], v[192:195], v[40:43]
	v_mfma_f32_16x16x32_bf16 v[32:35], v[36:39], v[192:195], v[32:35]
	v_mfma_f32_16x16x32_bf16 v[12:15], v[24:27], v[200:203], v[12:15]
	v_mfma_f32_16x16x32_bf16 v[8:11], v[36:39], v[200:203], v[8:11]
	v_mfma_f32_16x16x32_bf16 v[76:79], v[28:31], v[164:167], v[76:79]
	v_mfma_f32_16x16x32_bf16 v[72:75], v[44:47], v[164:167], v[72:75]
	v_mfma_f32_16x16x32_bf16 v[60:63], v[28:31], v[188:191], v[60:63]
	v_mfma_f32_16x16x32_bf16 v[56:59], v[44:47], v[188:191], v[56:59]
	v_mfma_f32_16x16x32_bf16 v[40:43], v[28:31], v[196:199], v[40:43]
	v_mfma_f32_16x16x32_bf16 v[32:35], v[44:47], v[196:199], v[32:35]
	v_mfma_f32_16x16x32_bf16 v[12:15], v[28:31], v[218:221], v[12:15]
	v_mfma_f32_16x16x32_bf16 v[8:11], v[44:47], v[218:221], v[8:11]
	s_setprio 0
	s_setprio 1
	v_mfma_f32_16x16x32_bf16 v[20:23], v[144:147], v[192:195], v[20:23]
	v_mfma_f32_16x16x32_bf16 v[16:19], v[152:155], v[192:195], v[16:19]
	v_mfma_f32_16x16x32_bf16 v[4:7], v[144:147], v[200:203], v[4:7]
	v_mfma_f32_16x16x32_bf16 v[0:3], v[152:155], v[200:203], v[0:3]
	v_mfma_f32_16x16x32_bf16 v[24:27], v[144:147], v[160:163], v[68:71]
	v_mfma_f32_16x16x32_bf16 v[28:31], v[152:155], v[160:163], v[64:67]
	v_mfma_f32_16x16x32_bf16 v[36:39], v[144:147], v[184:187], v[52:55]
	v_mfma_f32_16x16x32_bf16 v[44:47], v[152:155], v[184:187], v[48:51]
	v_mfma_f32_16x16x32_bf16 v[20:23], v[148:151], v[196:199], v[20:23]
	v_mfma_f32_16x16x32_bf16 v[16:19], v[156:159], v[196:199], v[16:19]
	v_mfma_f32_16x16x32_bf16 v[4:7], v[148:151], v[218:221], v[4:7]
	v_mfma_f32_16x16x32_bf16 v[0:3], v[156:159], v[218:221], v[0:3]
	v_mfma_f32_16x16x32_bf16 v[24:27], v[148:151], v[164:167], v[24:27]
	v_mfma_f32_16x16x32_bf16 v[28:31], v[156:159], v[164:167], v[28:31]
	v_mfma_f32_16x16x32_bf16 v[36:39], v[148:151], v[188:191], v[36:39]
	v_mfma_f32_16x16x32_bf16 v[44:47], v[156:159], v[188:191], v[44:47]
	s_setprio 0
	s_barrier
	s_add_i32 s64, 0, 0x18000
	s_add_i32 s65, 0, 0x1c000
	v_add_u32_e32 v68, s64, v205
	v_add_u32_e32 v156, s65, v205
	ds_read_b128 v[48:51], v68
	ds_read_b128 v[52:55], v68 offset:1024
	ds_read_b128 v[64:67], v68 offset:2048
	ds_read_b128 v[68:71], v68 offset:3072
	ds_read_b128 v[144:147], v156
	ds_read_b128 v[148:151], v156 offset:1024
	ds_read_b128 v[152:155], v156 offset:2048
	ds_read_b128 v[156:159], v156 offset:3072
	s_add_u32 s46, s46, 0x4000
	s_addc_u32 s47, s47, 0
	s_mov_b32 m0, s48

; #define PG8_STAGE(bufoff, gbase, voff) do { _Pragma("unroll") for (int _i = 0; _i < 2; ++_i) \
;         __builtin_amdgcn_global_load_lds((const unsigned*)((const char*)(gbase) + (voff)[_i]), (PG8_LAS unsigned*)(lds + (bufoff) + ldsw + _i * 8192), 16, 0, 0); } while (0)
; #define PG8_LDA(dst, b, h) do { _Pragma("unroll") for (int m = 0; m < 4; ++m) _Pragma("unroll") for (int k = 0; k < 2; ++k) dst[m][k] = *(const PG8_LAS bf16x8*)(lds + PG8_SA(b, h) + aoff + m * 2048 + k * 1024); } while (0)
; #define PG8_LDB(dst, b, h) do { _Pragma("unroll") for (int n = 0; n < 2; ++n) _Pragma("unroll") for (int k = 0; k < 2; ++k) dst[n][k] = *(const PG8_LAS bf16x8*)(lds + PG8_SB(b, h) + boff + n * 2048 + k * 1024); } while (0)
; #define PG8_SCHED __builtin_amdgcn_sched_barrier(0)
; template <class Epi, class Sched, bool ALIGN_EPI = false, bool SP2 = false, bool ATILED = false>
; __device__ __forceinline__ void gemm_phase(PG8_LAS unsigned char* lds, const Gemm g, const Sched& S, const Epi& E) {
;     ...
;             PG8_LDB(B0, 1, 0); PG8_LDB(B1, 1, 1); PG8_SCHED; PG8_LDA(At, 1, 0); PG8_STAGE(PG8_SA(0, 1), a2 + hstepA, voffA);
	ds_read_b128 v[160:163], v212 offset:32768
	ds_read_b128 v[164:167], v212 offset:33792
	ds_read_b128 v[184:187], v212 offset:34816
	ds_read_b128 v[188:191], v212 offset:35840
	ds_read_b128 v[192:195], v212 offset:36864
	ds_read_b128 v[196:199], v212 offset:37888
	ds_read_b128 v[200:203], v212 offset:38912
	ds_read_b128 v[218:221], v212 offset:39936
	global_load_lds_dwordx4 v168, s[46:47]

; #define PG8_STAGE(bufoff, gbase, voff) do { _Pragma("unroll") for (int _i = 0; _i < 2; ++_i) \
;         __builtin_amdgcn_global_load_lds((const unsigned*)((const char*)(gbase) + (voff)[_i]), (PG8_LAS unsigned*)(lds + (bufoff) + ldsw + _i * 8192), 16, 0, 0); } while (0)
; #define PG8_LDA(dst, b, h) do { _Pragma("unroll") for (int m = 0; m < 4; ++m) _Pragma("unroll") for (int k = 0; k < 2; ++k) dst[m][k] = *(const PG8_LAS bf16x8*)(lds + PG8_SA(b, h) + aoff + m * 2048 + k * 1024); } while (0)
; #define PG8_LDB(dst, b, h) do { _Pragma("unroll") for (int n = 0; n < 2; ++n) _Pragma("unroll") for (int k = 0; k < 2; ++k) dst[n][k] = *(const PG8_LAS bf16x8*)(lds + PG8_SB(b, h) + boff + n * 2048 + k * 1024); } while (0)
; #define PG8_MMA(ai, bj, At, Bt) do { __builtin_amdgcn_s_setprio(1); _Pragma("unroll") for (int m = 0; m < 4; ++m) _Pragma("unroll") for (int n = 0; n < 2; ++n) _Pragma("unroll") for (int k = 0; k < 2; ++k) \
;         acc[ai][bj][m][n] = __builtin_amdgcn_mfma_f32_16x16x32_bf16(Bt[n][k], At[m][k], acc[ai][bj][m][n], 0, 0, 0); __builtin_amdgcn_s_setprio(0); } while (0)
; #define PG8_WAIT_V(n) asm volatile("s_waitcnt vmcnt(" #n ")" ::: "memory")
; #define PG8_WAIT_L(n) asm volatile("s_waitcnt lgkmcnt(" #n ")" ::: "memory")
; #define PG8_BAR __builtin_amdgcn_s_barrier()
; #define PG8_SCHED __builtin_amdgcn_sched_barrier(0)
; template <class Epi, class Sched, bool ALIGN_EPI = false, bool SP2 = false, bool ATILED = false>
; __device__ __forceinline__ void gemm_phase(PG8_LAS unsigned char* lds, const Gemm g, const Sched& S, const Epi& E) {
;     ...
;             PG8_LDB(B0, 1, 0); PG8_LDB(B1, 1, 1); PG8_SCHED; PG8_LDA(At, 1, 0); PG8_STAGE(PG8_SA(0, 1), a2 + hstepA, voffA);
;             PG8_WAIT_V(8); PG8_WAIT_L(0); PG8_BAR; PG8_MMA(0, 0, At, B0); PG8_MMA(0, 1, At, B1); PG8_BAR; PG8_SCHED;
;             PG8_LDA(At, 1, 1); PG8_STAGE(PG8_SB(1, 0), b3, voffB); PG8_STAGE(PG8_SB(1, 1), b3 + hstep, voffB); PG8_STAGE(PG8_SA(1, 0), a3, voffA);
	s_mov_b32 m0, s49
	s_nop 0
	global_load_lds_dwordx4 v172, s[46:47]
	s_waitcnt vmcnt(8)
	s_waitcnt lgkmcnt(0)
	s_barrier
	s_setprio 1
	s_waitcnt lgkmcnt(0)
	v_mfma_f32_16x16x32_bf16 v[140:143], v[48:51], v[160:163], v[140:143]
	v_mfma_f32_16x16x32_bf16 v[136:139], v[64:67], v[160:163], v[136:139]
	v_mfma_f32_16x16x32_bf16 v[124:127], v[48:51], v[184:187], v[124:127]
	v_mfma_f32_16x16x32_bf16 v[120:123], v[64:67], v[184:187], v[120:123]
	v_mfma_f32_16x16x32_bf16 v[108:111], v[48:51], v[192:195], v[108:111]
	v_mfma_f32_16x16x32_bf16 v[104:107], v[64:67], v[192:195], v[104:107]
	v_mfma_f32_16x16x32_bf16 v[92:95], v[48:51], v[200:203], v[92:95]
	v_mfma_f32_16x16x32_bf16 v[88:91], v[64:67], v[200:203], v[88:91]
	v_mfma_f32_16x16x32_bf16 v[140:143], v[52:55], v[164:167], v[140:143]
	v_mfma_f32_16x16x32_bf16 v[136:139], v[68:71], v[164:167], v[136:139]
	v_mfma_f32_16x16x32_bf16 v[124:127], v[52:55], v[188:191], v[124:127]
	v_mfma_f32_16x16x32_bf16 v[120:123], v[68:71], v[188:191], v[120:123]
	v_mfma_f32_16x16x32_bf16 v[108:111], v[52:55], v[196:199], v[108:111]
	v_mfma_f32_16x16x32_bf16 v[104:107], v[68:71], v[196:199], v[104:107]
	v_mfma_f32_16x16x32_bf16 v[92:95], v[52:55], v[218:221], v[92:95]
	v_mfma_f32_16x16x32_bf16 v[88:91], v[68:71], v[218:221], v[88:91]
	s_setprio 0
	s_setprio 1
	v_mfma_f32_16x16x32_bf16 v[132:135], v[144:147], v[160:163], v[132:135]
	v_mfma_f32_16x16x32_bf16 v[128:131], v[152:155], v[160:163], v[128:131]
	v_mfma_f32_16x16x32_bf16 v[116:119], v[144:147], v[184:187], v[116:119]
	v_mfma_f32_16x16x32_bf16 v[112:115], v[152:155], v[184:187], v[112:115]
	v_mfma_f32_16x16x32_bf16 v[100:103], v[144:147], v[192:195], v[100:103]
	v_mfma_f32_16x16x32_bf16 v[96:99], v[152:155], v[192:195], v[96:99]
	v_mfma_f32_16x16x32_bf16 v[84:87], v[144:147], v[200:203], v[84:87]
	v_mfma_f32_16x16x32_bf16 v[80:83], v[152:155], v[200:203], v[80:83]
	v_mfma_f32_16x16x32_bf16 v[132:135], v[148:151], v[164:167], v[132:135]
	v_mfma_f32_16x16x32_bf16 v[128:131], v[156:159], v[164:167], v[128:131]
	v_mfma_f32_16x16x32_bf16 v[116:119], v[148:151], v[188:191], v[116:119]
	v_mfma_f32_16x16x32_bf16 v[112:115], v[156:159], v[188:191], v[112:115]
	v_mfma_f32_16x16x32_bf16 v[100:103], v[148:151], v[196:199], v[100:103]
	v_mfma_f32_16x16x32_bf16 v[96:99], v[156:159], v[196:199], v[96:99]
	v_mfma_f32_16x16x32_bf16 v[84:87], v[148:151], v[218:221], v[84:87]
	v_mfma_f32_16x16x32_bf16 v[80:83], v[156:159], v[218:221], v[80:83]
	s_setprio 0
	s_barrier
	s_add_i32 s46, s64, s3

; #define PG8_STAGE(bufoff, gbase, voff) do { _Pragma("unroll") for (int _i = 0; _i < 2; ++_i) \
;         __builtin_amdgcn_global_load_lds((const unsigned*)((const char*)(gbase) + (voff)[_i]), (PG8_LAS unsigned*)(lds + (bufoff) + ldsw + _i * 8192), 16, 0, 0); } while (0)
; #define PG8_LDA(dst, b, h) do { _Pragma("unroll") for (int m = 0; m < 4; ++m) _Pragma("unroll") for (int k = 0; k < 2; ++k) dst[m][k] = *(const PG8_LAS bf16x8*)(lds + PG8_SA(b, h) + aoff + m * 2048 + k * 1024); } while (0)
; template <class Epi, class Sched, bool ALIGN_EPI = false, bool SP2 = false, bool ATILED = false>
; __device__ __forceinline__ void gemm_phase(PG8_LAS unsigned char* lds, const Gemm g, const Sched& S, const Epi& E) {
;     ...
;             PG8_LDA(At, 1, 1); PG8_STAGE(PG8_SB(1, 0), b3, voffB); PG8_STAGE(PG8_SB(1, 1), b3 + hstep, voffB); PG8_STAGE(PG8_SA(1, 0), a3, voffA);
	s_mov_b32 m0, s46
	ds_read_b128 v[160:163], v212 offset:49152
	ds_read_b128 v[164:167], v212 offset:50176
	ds_read_b128 v[184:187], v212 offset:51200
	ds_read_b128 v[188:191], v212 offset:52224
	ds_read_b128 v[192:195], v212 offset:53248
	ds_read_b128 v[196:199], v212 offset:54272
	ds_read_b128 v[200:203], v212 offset:55296
	ds_read_b128 v[218:221], v212 offset:56320
	global_load_lds_dwordx4 v170, s[98:99]
	s_add_i32 m0, s46, 0x2000
	s_add_u32 s44, s44, 0xb0080

; #define PG8_STAGE(bufoff, gbase, voff) do { _Pragma("unroll") for (int _i = 0; _i < 2; ++_i) \
;         __builtin_amdgcn_global_load_lds((const unsigned*)((const char*)(gbase) + (voff)[_i]), (PG8_LAS unsigned*)(lds + (bufoff) + ldsw + _i * 8192), 16, 0, 0); } while (0)
; #define PG8_LDA(dst, b, h) do { _Pragma("unroll") for (int m = 0; m < 4; ++m) _Pragma("unroll") for (int k = 0; k < 2; ++k) dst[m][k] = *(const PG8_LAS bf16x8*)(lds + PG8_SA(b, h) + aoff + m * 2048 + k * 1024); } while (0)
; template <class Epi, class Sched, bool ALIGN_EPI = false, bool SP2 = false, bool ATILED = false>
; __device__ __forceinline__ void gemm_phase(PG8_LAS unsigned char* lds, const Gemm g, const Sched& S, const Epi& E) {
;     ...
;             PG8_LDA(At, 1, 1); PG8_STAGE(PG8_SB(1, 0), b3, voffB); PG8_STAGE(PG8_SB(1, 1), b3 + hstep, voffB); PG8_STAGE(PG8_SA(1, 0), a3, voffA);
	s_addc_u32 s45, s45, 0
	s_add_i32 s46, s65, s3
	global_load_lds_dwordx4 v174, s[98:99]

; #define PG8_STAGE(bufoff, gbase, voff) do { _Pragma("unroll") for (int _i = 0; _i < 2; ++_i) \
;         __builtin_amdgcn_global_load_lds((const unsigned*)((const char*)(gbase) + (voff)[_i]), (PG8_LAS unsigned*)(lds + (bufoff) + ldsw + _i * 8192), 16, 0, 0); } while (0)
; #define PG8_LDA(dst, b, h) do { _Pragma("unroll") for (int m = 0; m < 4; ++m) _Pragma("unroll") for (int k = 0; k < 2; ++k) dst[m][k] = *(const PG8_LAS bf16x8*)(lds + PG8_SA(b, h) + aoff + m * 2048 + k * 1024); } while (0)
; template <class Epi, class Sched, bool ALIGN_EPI = false, bool SP2 = false, bool ATILED = false>
; __device__ __forceinline__ void gemm_phase(PG8_LAS unsigned char* lds, const Gemm g, const Sched& S, const Epi& E) {
;     ...
;             PG8_LDA(At, 1, 1); PG8_STAGE(PG8_SB(1, 0), b3, voffB); PG8_STAGE(PG8_SB(1, 1), b3 + hstep, voffB); PG8_STAGE(PG8_SA(1, 0), a3, voffA);
	s_mov_b32 m0, s46
	s_nop 0
	global_load_lds_dwordx4 v170, s[44:45]

; #define PG8_STAGE(bufoff, gbase, voff) do { _Pragma("unroll") for (int _i = 0; _i < 2; ++_i) \
;         __builtin_amdgcn_global_load_lds((const unsigned*)((const char*)(gbase) + (voff)[_i]), (PG8_LAS unsigned*)(lds + (bufoff) + ldsw + _i * 8192), 16, 0, 0); } while (0)
; #define PG8_LDA(dst, b, h) do { _Pragma("unroll") for (int m = 0; m < 4; ++m) _Pragma("unroll") for (int k = 0; k < 2; ++k) dst[m][k] = *(const PG8_LAS bf16x8*)(lds + PG8_SA(b, h) + aoff + m * 2048 + k * 1024); } while (0)
; template <class Epi, class Sched, bool ALIGN_EPI = false, bool SP2 = false, bool ATILED = false>
; __device__ __forceinline__ void gemm_phase(PG8_LAS unsigned char* lds, const Gemm g, const Sched& S, const Epi& E) {
;     ...
;             PG8_LDA(At, 1, 1); PG8_STAGE(PG8_SB(1, 0), b3, voffB); PG8_STAGE(PG8_SB(1, 1), b3 + hstep, voffB); PG8_STAGE(PG8_SA(1, 0), a3, voffA);
	s_add_i32 m0, s46, 0x2000
	s_nop 0
	global_load_lds_dwordx4 v174, s[44:45]

; #define PG8_STAGE(bufoff, gbase, voff) do { _Pragma("unroll") for (int _i = 0; _i < 2; ++_i) \
;         __builtin_amdgcn_global_load_lds((const unsigned*)((const char*)(gbase) + (voff)[_i]), (PG8_LAS unsigned*)(lds + (bufoff) + ldsw + _i * 8192), 16, 0, 0); } while (0)
; #define PG8_LDA(dst, b, h) do { _Pragma("unroll") for (int m = 0; m < 4; ++m) _Pragma("unroll") for (int k = 0; k < 2; ++k) dst[m][k] = *(const PG8_LAS bf16x8*)(lds + PG8_SA(b, h) + aoff + m * 2048 + k * 1024); } while (0)
; template <class Epi, class Sched, bool ALIGN_EPI = false, bool SP2 = false, bool ATILED = false>
; __device__ __forceinline__ void gemm_phase(PG8_LAS unsigned char* lds, const Gemm g, const Sched& S, const Epi& E) {
;     ...
;             PG8_LDA(At, 1, 1); PG8_STAGE(PG8_SB(1, 0), b3, voffB); PG8_STAGE(PG8_SB(1, 1), b3 + hstep, voffB); PG8_STAGE(PG8_SA(1, 0), a3, voffA);
	s_mov_b32 m0, s53
	s_nop 0
	global_load_lds_dwordx4 v168, s[42:43]

; #define PG8_STAGE(bufoff, gbase, voff) do { _Pragma("unroll") for (int _i = 0; _i < 2; ++_i) \
;         __builtin_amdgcn_global_load_lds((const unsigned*)((const char*)(gbase) + (voff)[_i]), (PG8_LAS unsigned*)(lds + (bufoff) + ldsw + _i * 8192), 16, 0, 0); } while (0)
; #define PG8_LDA(dst, b, h) do { _Pragma("unroll") for (int m = 0; m < 4; ++m) _Pragma("unroll") for (int k = 0; k < 2; ++k) dst[m][k] = *(const PG8_LAS bf16x8*)(lds + PG8_SA(b, h) + aoff + m * 2048 + k * 1024); } while (0)
; #define PG8_MMA(ai, bj, At, Bt) do { __builtin_amdgcn_s_setprio(1); _Pragma("unroll") for (int m = 0; m < 4; ++m) _Pragma("unroll") for (int n = 0; n < 2; ++n) _Pragma("unroll") for (int k = 0; k < 2; ++k) \
;         acc[ai][bj][m][n] = __builtin_amdgcn_mfma_f32_16x16x32_bf16(Bt[n][k], At[m][k], acc[ai][bj][m][n], 0, 0, 0); __builtin_amdgcn_s_setprio(0); } while (0)
; #define PG8_WAIT_V(n) asm volatile("s_waitcnt vmcnt(" #n ")" ::: "memory")
; #define PG8_WAIT_L(n) asm volatile("s_waitcnt lgkmcnt(" #n ")" ::: "memory")
; #define PG8_BAR __builtin_amdgcn_s_barrier()
; #define PG8_SCHED __builtin_amdgcn_sched_barrier(0)
; template <class Epi, class Sched, bool ALIGN_EPI = false, bool SP2 = false, bool ATILED = false>
; __device__ __forceinline__ void gemm_phase(PG8_LAS unsigned char* lds, const Gemm g, const Sched& S, const Epi& E) {
;     ...
;             PG8_LDA(At, 1, 1); PG8_STAGE(PG8_SB(1, 0), b3, voffB); PG8_STAGE(PG8_SB(1, 1), b3 + hstep, voffB); PG8_STAGE(PG8_SA(1, 0), a3, voffA);
;             PG8_WAIT_V(8); PG8_WAIT_L(0); PG8_BAR; PG8_MMA(1, 0, At, B0); PG8_MMA(1, 1, At, B1); PG8_BAR; PG8_SCHED;
;     ...
;         if constexpr (ALIGN_EPI) { if (wr == 0) PG8_BAR; }
	s_mov_b32 m0, s54
	s_nop 0
	global_load_lds_dwordx4 v172, s[42:43]
	s_waitcnt vmcnt(8)
	s_waitcnt lgkmcnt(0)
	s_barrier
	s_setprio 1
	s_waitcnt lgkmcnt(0)
	v_mfma_f32_16x16x32_bf16 v[76:79], v[48:51], v[160:163], v[76:79]
	v_mfma_f32_16x16x32_bf16 v[72:75], v[64:67], v[160:163], v[72:75]
	v_mfma_f32_16x16x32_bf16 v[60:63], v[48:51], v[184:187], v[60:63]
	v_mfma_f32_16x16x32_bf16 v[56:59], v[64:67], v[184:187], v[56:59]
	v_mfma_f32_16x16x32_bf16 v[40:43], v[48:51], v[192:195], v[40:43]
	v_mfma_f32_16x16x32_bf16 v[32:35], v[64:67], v[192:195], v[32:35]
	v_mfma_f32_16x16x32_bf16 v[12:15], v[48:51], v[200:203], v[12:15]
	v_mfma_f32_16x16x32_bf16 v[8:11], v[64:67], v[200:203], v[8:11]
	v_mfma_f32_16x16x32_bf16 v[76:79], v[52:55], v[164:167], v[76:79]
	v_mfma_f32_16x16x32_bf16 v[72:75], v[68:71], v[164:167], v[72:75]
	v_mfma_f32_16x16x32_bf16 v[60:63], v[52:55], v[188:191], v[60:63]
	v_mfma_f32_16x16x32_bf16 v[56:59], v[68:71], v[188:191], v[56:59]
	v_mfma_f32_16x16x32_bf16 v[40:43], v[52:55], v[196:199], v[40:43]
	v_mfma_f32_16x16x32_bf16 v[32:35], v[68:71], v[196:199], v[32:35]
	v_mfma_f32_16x16x32_bf16 v[12:15], v[52:55], v[218:221], v[12:15]
	v_mfma_f32_16x16x32_bf16 v[8:11], v[68:71], v[218:221], v[8:11]
	s_setprio 0
	s_setprio 1
	v_mfma_f32_16x16x32_bf16 v[24:27], v[144:147], v[160:163], v[24:27]
	v_mfma_f32_16x16x32_bf16 v[68:71], v[148:151], v[164:167], v[24:27]
	v_mfma_f32_16x16x32_bf16 v[24:27], v[152:155], v[160:163], v[28:31]
	v_mfma_f32_16x16x32_bf16 v[64:67], v[156:159], v[164:167], v[24:27]
	v_mfma_f32_16x16x32_bf16 v[24:27], v[144:147], v[184:187], v[36:39]
	v_mfma_f32_16x16x32_bf16 v[52:55], v[148:151], v[188:191], v[24:27]
	v_mfma_f32_16x16x32_bf16 v[24:27], v[152:155], v[184:187], v[44:47]
	v_mfma_f32_16x16x32_bf16 v[20:23], v[144:147], v[192:195], v[20:23]
	v_mfma_f32_16x16x32_bf16 v[16:19], v[152:155], v[192:195], v[16:19]
	v_mfma_f32_16x16x32_bf16 v[4:7], v[144:147], v[200:203], v[4:7]
	v_mfma_f32_16x16x32_bf16 v[0:3], v[152:155], v[200:203], v[0:3]
	v_mfma_f32_16x16x32_bf16 v[48:51], v[156:159], v[188:191], v[24:27]
	v_mfma_f32_16x16x32_bf16 v[20:23], v[148:151], v[196:199], v[20:23]
	v_mfma_f32_16x16x32_bf16 v[16:19], v[156:159], v[196:199], v[16:19]
	v_mfma_f32_16x16x32_bf16 v[4:7], v[148:151], v[218:221], v[4:7]
	v_mfma_f32_16x16x32_bf16 v[0:3], v[156:159], v[218:221], v[0:3]
	s_setprio 0
	s_barrier
	s_add_i32 s63, s63, 2
	s_add_u32 s35, s35, 0x100
	s_addc_u32 s62, s62, 0
	s_add_u32 s40, s40, 0x10000
	s_addc_u32 s41, s41, 0
	s_cmp_gt_u32 s63, 41
	s_cbranch_scc0 .LBB0_898
	s_and_b64 vcc, exec, s[18:19]
	s_cbranch_vccz .LBB0_901
	s_barrier
